# nt also on P8 input rows, GEMM-epilogue gate/residual loads (P4a, P4b, P5, P7), SWA-sample cache reads/writes, P3 elementwise loads
# baseline (speedup 1.0000x reference)
; __device__ __forceinline__ float bflo(unsigned w) { return __uint_as_float(w << 16); }
; __device__ __forceinline__ float bfhi(unsigned w) { return __uint_as_float(w & 0xffff0000u); }
; __device__ __forceinline__ void swa_sample_unit(const Args& a, unsigned char* lds, int unit, int tid) {
;     ...
;     for (int e = tid; e < 132 * 16; e += 512) { const int j = e >> 4, c = e & 15; f32x4 kv, vv;
;         if (j < 128) { const size_t o = ((size_t)(b * 128 + j) * 4 + kvh) * 64 + c * 4; kv = *(const f32x4*)(a.ck + o); vv = *(const f32x4*)(a.cv + o); }
;         else { const int i = j - 128; const bf16_t* kp = Z + (row0 + i) * DINP + ZKS + kvh * 64; const u32x2 kw = *(const u32x2*)(kp + c * 4); const u32x2 vw = *(const u32x2*)(Z + (row0 + i) * DINP + ZVS + kvh * 64 + c * 4);
;             kv = (f32x4){bflo(kw.x), bfhi(kw.x), bflo(kw.y), bfhi(kw.y)}; vv = (f32x4){bflo(vw.x), bfhi(vw.x), bflo(vw.y), bfhi(vw.y)};
;             if (c < 4) { const u32x2 pw = *(const u32x2*)(kp + (c ^ 2) * 4); const f32x4 pv = (f32x4){bflo(pw.x), bfhi(pw.x), bflo(pw.y), bfhi(pw.y)}; const float sg = c < 2 ? -1.f : 1.f;
;                 const f32x2* rp = ROPE + (2048 + i) * 8 + (c & 1) * 4;
; #pragma unroll
;                 for (int d = 0; d < 4; ++d) { const f32x2 cs = rp[d]; kv[d] = kv[d] * cs.x + sg * pv[d] * cs.y; }
;             } }
.LBB0_395:
	v_cmp_lt_u32_e32 vcc, s36, v37
	s_and_saveexec_b64 s[30:31], vcc
	s_xor_b64 s[30:31], exec, s[30:31]
	s_cbranch_execz .LBB0_399
	v_lshl_add_u64 v[0:1], s[22:23], 0, v[8:9]
	v_mov_b64_e32 v[2:3], s[24:25]
	v_mad_u64_u32 v[4:5], s[34:35], v0, s37, v[2:3]
	v_mad_i32_i24 v5, v1, s37, v5
	v_lshlrev_b32_e32 v0, 1, v88
	v_mov_b32_e32 v1, v9
	v_lshl_add_u64 v[0:1], v[4:5], 0, v[0:1]
	global_load_dwordx2 v[2:3], v[0:1], off offset:2048
	global_load_dwordx2 v[6:7], v[0:1], off offset:2560
	s_waitcnt vmcnt(1)
	v_lshlrev_b32_e32 v0, 16, v2
	v_and_b32_e32 v1, 0xffff0000, v2
	v_lshlrev_b32_e32 v2, 16, v3
	v_and_b32_e32 v3, 0xffff0000, v3
	s_and_saveexec_b64 s[34:35], s[6:7]
	s_cbranch_execz .LBB0_398
	v_lshlrev_b32_e32 v38, 1, v10
	v_mov_b32_e32 v39, v9
	v_lshl_add_u64 v[4:5], v[4:5], 0, v[38:39]
	v_lshl_add_u64 v[42:43], v[18:19], 0, s[28:29]
	global_load_dwordx2 v[4:5], v[4:5], off offset:2048
	v_lshl_add_u64 v[38:39], v[42:43], 0, s[18:19]
	v_add_co_u32_e32 v42, vcc, 0xbe000, v42
	global_load_dwordx4 v[38:41], v[38:39], off offset:16 nt
	s_nop 0
	v_addc_co_u32_e32 v43, vcc, 0, v43, vcc
	global_load_dwordx4 v[42:45], v[42:43], off nt
	v_mov_b32_e32 v46, v1
	v_mov_b32_e32 v48, v3
	s_waitcnt vmcnt(2)
	v_lshlrev_b32_e32 v1, 16, v4
	v_and_b32_e32 v3, 0xffff0000, v4
	v_lshlrev_b32_e32 v4, 16, v5
	v_and_b32_e32 v5, 0xffff0000, v5
	v_cndmask_b32_e64 v1, v1, -v1, s[8:9]
	v_cndmask_b32_e64 v47, v3, -v3, s[8:9]
	v_cndmask_b32_e64 v49, v5, -v5, s[8:9]
	v_cndmask_b32_e64 v3, v4, -v4, s[8:9]
	s_waitcnt vmcnt(0)
	v_pk_mul_f32 v[0:1], v[42:43], v[0:1]
	v_pk_mul_f32 v[4:5], v[44:45], v[46:47]
	v_pk_mul_f32 v[40:41], v[40:41], v[48:49]
	v_mul_f32_e32 v2, v38, v2
	v_mul_f32_e32 v38, v3, v39
	v_mov_b32_e32 v42, v1
	v_mov_b32_e32 v43, v5
	v_mov_b32_e32 v1, v4
	v_mov_b32_e32 v3, v40
	v_mov_b32_e32 v39, v41
	v_pk_add_f32 v[0:1], v[0:1], v[42:43]
	v_pk_add_f32 v[2:3], v[2:3], v[38:39]

; __device__ __forceinline__ float bflo(unsigned w) { return __uint_as_float(w << 16); }
; __device__ __forceinline__ float bfhi(unsigned w) { return __uint_as_float(w & 0xffff0000u); }
; __device__ __forceinline__ void swa_sample_unit(const Args& a, unsigned char* lds, int unit, int tid) {
;     ...
;         if (j < 128) { const size_t o = ((size_t)(b * 128 + j) * 4 + kvh) * 64 + c * 4; kv = *(const f32x4*)(a.ck + o); vv = *(const f32x4*)(a.cv + o); }
;         else { const int i = j - 128; const bf16_t* kp = Z + (row0 + i) * DINP + ZKS + kvh * 64; const u32x2 kw = *(const u32x2*)(kp + c * 4); const u32x2 vw = *(const u32x2*)(Z + (row0 + i) * DINP + ZVS + kvh * 64 + c * 4);
;             kv = (f32x4){bflo(kw.x), bfhi(kw.x), bflo(kw.y), bfhi(kw.y)}; vv = (f32x4){bflo(vw.x), bfhi(vw.x), bflo(vw.y), bfhi(vw.y)};
;             if (c < 4) { const u32x2 pw = *(const u32x2*)(kp + (c ^ 2) * 4); const f32x4 pv = (f32x4){bflo(pw.x), bfhi(pw.x), bflo(pw.y), bfhi(pw.y)}; const float sg = c < 2 ? -1.f : 1.f;
;                 const f32x2* rp = ROPE + (2048 + i) * 8 + (c & 1) * 4;
; #pragma unroll
;                 for (int d = 0; d < 4; ++d) { const f32x2 cs = rp[d]; kv[d] = kv[d] * cs.x + sg * pv[d] * cs.y; }
;             } }
;         float* kd = KS + j * 65 + c * 4; kd[0] = kv[0]; kd[1] = kv[1]; kd[2] = kv[2]; kd[3] = kv[3];
;         *(f32x4*)(VS + j * 64 + c * 4) = vv;
;         if (j >= 4) { const size_t o = ((size_t)(b * 128 + (j - 4)) * 4 + kvh) * 64 + c * 4; *(f32x4*)(a.out + OUT_KS + o) = kv; *(f32x4*)(a.out + OUT_VS + o) = vv; } }
;     if (tid < 256) { const int pr = tid >> 4, c = tid & 15, g = pr >> 2, i = pr & 3; const bf16_t* qp = Z + (row0 + i) * DINP + ZQS + (kvh * 4 + g) * 64; const u32x2 qw = *(const u32x2*)(qp + c * 4);
;         f32x4 qv = (f32x4){bflo(qw.x), bfhi(qw.x), bflo(qw.y), bfhi(qw.y)};
;         if (c < 4) { const u32x2 pw = *(const u32x2*)(qp + (c ^ 2) * 4); const f32x4 pv = (f32x4){bflo(pw.x), bfhi(pw.x), bflo(pw.y), bfhi(pw.y)}; const float sg = c < 2 ? -1.f : 1.f;
;             const f32x2* rp = ROPE + (2048 + i) * 8 + (c & 1) * 4;
; #pragma unroll
;             for (int d = 0; d < 4; ++d) { const f32x2 cs = rp[d]; qv[d] = qv[d] * cs.x + sg * pv[d] * cs.y; } }
.LBB0_399:
	s_or_saveexec_b64 s[30:31], s[30:31]
	v_add_u32_e32 v38, s42, v8
	s_xor_b64 exec, exec, s[30:31]
	s_cbranch_execz .LBB0_401
	v_add_u32_e32 v0, 0x80, v38
	v_ashrrev_i32_e32 v1, 31, v0
	v_lshlrev_b64 v[4:5], 10, v[0:1]
	v_lshl_or_b32 v4, v20, 2, v4
	v_lshl_add_u64 v[0:1], s[68:69], 0, v[4:5]
	v_lshl_add_u64 v[4:5], s[70:71], 0, v[4:5]
	global_load_dwordx4 v[0:3], v[0:1], off nt
	s_nop 0
	global_load_dwordx4 v[4:7], v[4:5], off nt
.LBB0_401:
	s_or_b64 exec, exec, s[30:31]
	v_cmp_lt_u32_e32 vcc, 63, v37
	s_waitcnt vmcnt(1)
	ds_write2_b32 v35, v0, v1 offset1:1
	ds_write2_b32 v35, v2, v3 offset0:2 offset1:3
	s_waitcnt vmcnt(0)
	ds_write_b128 v36, v[4:7]
	s_and_saveexec_b64 s[30:31], vcc
	s_cbranch_execz .LBB0_394
	v_add_u32_e32 v38, 0x7c, v38
	v_ashrrev_i32_e32 v39, 31, v38
	v_lshlrev_b64 v[38:39], 10, v[38:39]
	v_lshl_or_b32 v38, v20, 2, v38
	v_lshl_add_u64 v[40:41], s[0:1], 0, v[38:39]
	global_store_dwordx4 v[40:41], v[0:3], off nt
	s_nop 1
	v_lshl_add_u64 v[0:1], s[16:17], 0, v[38:39]
	global_store_dwordx4 v[0:1], v[4:7], off nt
	s_branch .LBB0_394
.LBB0_403:
	s_or_b64 exec, exec, s[26:27]
	s_and_saveexec_b64 s[24:25], s[4:5]
	s_cbranch_execz .LBB0_407
	v_or_b32_e32 v2, s22, v86
	v_mov_b64_e32 v[0:1], s[74:75]
	v_mad_u64_u32 v[0:1], s[26:27], v2, s37, v[0:1]
	v_mad_i32_i24 v1, s23, v32, v1
	v_lshl_or_b32 v8, s41, 9, v31
	v_lshl_add_u64 v[4:5], v[0:1], 0, v[8:9]
	v_lshlrev_b32_e32 v8, 1, v88
	v_lshl_add_u64 v[0:1], v[4:5], 0, v[8:9]
	global_load_dwordx2 v[0:1], v[0:1], off
	s_waitcnt vmcnt(0)
	v_lshlrev_b32_e32 v2, 16, v0
	v_and_b32_e32 v3, 0xffff0000, v0
	v_lshlrev_b32_e32 v0, 16, v1
	v_and_b32_e32 v1, 0xffff0000, v1
	s_and_saveexec_b64 s[26:27], s[6:7]
	s_cbranch_execz .LBB0_406
	v_lshlrev_b32_e32 v8, 1, v10
	v_lshl_add_u64 v[36:37], v[4:5], 0, v[8:9]
	global_load_dwordx4 v[4:7], v[12:13], off offset:16 nt
	global_load_dwordx2 v[40:41], v[36:37], off
	s_nop 0
	global_load_dwordx4 v[36:39], v[12:13], off nt
	v_mov_b32_e32 v44, v1
	v_mov_b32_e32 v42, v3
	s_waitcnt vmcnt(2)
	v_mul_f32_e32 v0, v4, v0
	s_waitcnt vmcnt(1)
	v_lshlrev_b32_e32 v1, 16, v40
	v_and_b32_e32 v4, 0xffff0000, v40
	v_and_b32_e32 v20, 0xffff0000, v41
	v_lshlrev_b32_e32 v8, 16, v41
	v_cndmask_b32_e64 v3, v1, -v1, s[8:9]
	v_cndmask_b32_e64 v43, v4, -v4, s[8:9]
	v_cndmask_b32_e64 v45, v20, -v20, s[8:9]
	v_cndmask_b32_e64 v1, v8, -v8, s[8:9]
	s_waitcnt vmcnt(0)
	v_pk_mul_f32 v[2:3], v[36:37], v[2:3]
	v_pk_mul_f32 v[36:37], v[38:39], v[42:43]
	v_pk_mul_f32 v[6:7], v[6:7], v[44:45]
	v_mul_f32_e32 v4, v1, v5
	v_mov_b32_e32 v38, v3
	v_mov_b32_e32 v39, v37
	v_mov_b32_e32 v3, v36
	v_mov_b32_e32 v1, v6
	v_mov_b32_e32 v5, v7
	v_pk_add_f32 v[2:3], v[2:3], v[38:39]
	v_pk_add_f32 v[0:1], v[0:1], v[4:5]

; __device__ __forceinline__ float bflo(unsigned w) { return __uint_as_float(w << 16); }
; __device__ __forceinline__ float bfhi(unsigned w) { return __uint_as_float(w & 0xffff0000u); }
; __device__ __forceinline__ float sigmoidf_(float x) { return 1.f / (1.f + __expf(-x)); }
; __global__ void __launch_bounds__(512, 2) hybrid_fwd(Args a) {
;     ...
;             const f32x4 g0 = *(const f32x4*)(a.gla_norm + lane * 8), g1 = *(const f32x4*)(a.gla_norm + lane * 8 + 4);
;             const float gn[8] = {g0[0], g0[1], g0[2], g0[3], g1[0], g1[1], g1[2], g1[3]};
; #pragma unroll
;             for (int u = 0; u < 4; ++u) { const int it = it0 + u * NGW; const int row = it >> 2, h = it & 3; const float rs = rsqrtf(wave_sum(gp[u]) * (1.0f / 512.0f) + EPS);
;                 float o[8] = {bflo(ow[u].x), bfhi(ow[u].x), bflo(ow[u].y), bfhi(ow[u].y), bflo(ow[u].z), bfhi(ow[u].z), bflo(ow[u].w), bfhi(ow[u].w)};
;                 float r[8] = {bflo(rw[u].x), bfhi(rw[u].x), bflo(rw[u].y), bfhi(rw[u].y), bflo(rw[u].z), bfhi(rw[u].z), bflo(rw[u].w), bfhi(rw[u].w)};
; #pragma unroll
;                 for (int e = 0; e < 8; ++e) o[e] = o[e] * rs * gn[e] * (r[e] * sigmoidf_(r[e]));
.LBB0_583:
	s_or_b64 exec, exec, s[0:1]
	global_load_dwordx4 v[4:7], v[44:45], off nt
	global_load_dwordx4 v[0:3], v[44:45], off offset:16 nt
	s_waitcnt vmcnt(0)
	ds_bpermute_b32 v49, v62, v73
	v_lshlrev_b32_e32 v79, 16, v37
	v_lshlrev_b32_e32 v78, 16, v33
	v_and_b32_e32 v81, 0xffff0000, v37
	v_and_b32_e32 v80, 0xffff0000, v33
	v_lshlrev_b32_e32 v37, 16, v39
	v_and_b32_e32 v33, 0xffff0000, v39
	s_waitcnt lgkmcnt(0)
	v_add_f32_e32 v39, v73, v49
	ds_bpermute_b32 v49, v63, v39
	v_lshlrev_b32_e32 v75, 16, v36
	v_and_b32_e32 v77, 0xffff0000, v36
	v_lshlrev_b32_e32 v82, 16, v34
	v_and_b32_e32 v84, 0xffff0000, v34
	s_waitcnt lgkmcnt(0)
	v_add_f32_e32 v39, v39, v49
	ds_bpermute_b32 v49, v64, v39
	v_mul_f32_e32 v34, 0xbfb8aa3b, v75
	v_lshlrev_b32_e32 v74, 16, v32
	v_and_b32_e32 v76, 0xffff0000, v32
	v_lshlrev_b32_e32 v36, 16, v35
	s_waitcnt lgkmcnt(0)
	v_add_f32_e32 v39, v39, v49
	ds_bpermute_b32 v49, v65, v39
	v_and_b32_e32 v32, 0xffff0000, v35
	v_mul_f32_e32 v35, 0xbfb8aa3b, v77
	v_exp_f32_e32 v34, v34
	v_exp_f32_e32 v35, v35
	s_waitcnt lgkmcnt(0)
	v_add_f32_e32 v39, v39, v49
	ds_bpermute_b32 v49, v66, v39
	v_lshlrev_b32_e32 v83, 16, v38
	v_and_b32_e32 v85, 0xffff0000, v38
	v_mul_f32_e32 v38, 0xbfb8aa3b, v79
	v_add_f32_e32 v34, 1.0, v34
	s_waitcnt lgkmcnt(0)
	v_add_f32_e32 v39, v39, v49
	ds_bpermute_b32 v49, v67, v39
	v_exp_f32_e32 v38, v38
	v_add_f32_e32 v73, 1.0, v35
	v_div_scale_f32 v35, s[0:1], v34, v34, 1.0
	v_rcp_f32_e32 v89, v35
	v_div_scale_f32 v87, s[0:1], v73, v73, 1.0
	v_rcp_f32_e32 v90, v87
	v_add_f32_e32 v86, 1.0, v38
	s_waitcnt lgkmcnt(0)
	v_add_f32_e32 v39, v39, v49
	v_div_scale_f32 v91, s[6:7], v86, v86, 1.0
	v_fma_f32 v93, -v35, v89, 1.0
	v_fmamk_f32 v39, v39, 0x3b000000, v69
	v_div_scale_f32 v38, vcc, 1.0, v34, 1.0
	v_fmac_f32_e32 v89, v93, v89
	v_mul_f32_e32 v49, 0x4b800000, v39
	v_cmp_gt_f32_e64 s[6:7], s18, v39
	v_fma_f32 v94, -v87, v90, 1.0
	v_mul_f32_e32 v93, v38, v89
	v_cndmask_b32_e64 v39, v39, v49, s[6:7]
	v_div_scale_f32 v88, s[0:1], 1.0, v73, 1.0
	v_fmac_f32_e32 v90, v94, v90
	v_fma_f32 v95, -v35, v93, v38
	v_rsq_f32_e32 v39, v39
	v_mul_f32_e32 v94, v88, v90
	v_fmac_f32_e32 v93, v95, v89
	v_fma_f32 v96, -v87, v94, v88
	v_fma_f32 v35, -v35, v93, v38
	v_fmac_f32_e32 v94, v96, v90
	v_div_fmas_f32 v35, v35, v89, v93
	v_rcp_f32_e32 v92, v91
	v_fma_f32 v38, -v87, v94, v88
	v_div_fixup_f32 v35, v35, v34, 1.0
	s_mov_b64 vcc, s[0:1]
	v_mul_f32_e32 v34, 0x45800000, v39
	v_div_fmas_f32 v49, v38, v90, v94
	v_cndmask_b32_e64 v34, v39, v34, s[6:7]
	v_pk_mul_f32 v[38:39], v[34:35], v[74:75]
	v_div_fixup_f32 v35, v49, v73, 1.0
	v_pk_mul_f32 v[74:75], v[34:35], v[76:77]
	v_add_u32_e32 v68, s15, v68
	v_mul_f32_e32 v35, v4, v38
	v_mul_f32_e32 v49, v35, v39
	v_fma_f32 v35, -v91, v92, 1.0
	v_mul_f32_e32 v38, v5, v74
	v_fmac_f32_e32 v92, v35, v92
	v_div_scale_f32 v35, vcc, 1.0, v86, 1.0
	v_mul_f32_e32 v73, v38, v75
	v_mul_f32_e32 v38, v35, v92
	v_fma_f32 v39, -v91, v38, v35
	v_fmac_f32_e32 v38, v39, v92
	v_mul_f32_e32 v39, 0xbfb8aa3b, v81
	v_exp_f32_e32 v39, v39
	v_fma_f32 v35, -v91, v38, v35
	v_div_fmas_f32 v35, v35, v92, v38
	v_div_fixup_f32 v35, v35, v86, 1.0
	v_add_f32_e32 v74, 1.0, v39
	v_div_scale_f32 v75, s[0:1], v74, v74, 1.0
	v_rcp_f32_e32 v76, v75
	v_pk_mul_f32 v[38:39], v[34:35], v[78:79]
	s_nop 0
	v_mul_f32_e32 v35, v6, v38
	v_mul_f32_e32 v77, v35, v39
	v_fma_f32 v35, -v75, v76, 1.0
	v_fmac_f32_e32 v76, v35, v76
	v_div_scale_f32 v35, vcc, 1.0, v74, 1.0
	v_mul_f32_e32 v38, v35, v76
	v_fma_f32 v39, -v75, v38, v35
	v_fmac_f32_e32 v38, v39, v76
	v_mul_f32_e32 v39, 0xbfb8aa3b, v83
	v_exp_f32_e32 v39, v39
	v_fma_f32 v35, -v75, v38, v35
	v_div_fmas_f32 v35, v35, v76, v38
	v_div_fixup_f32 v35, v35, v74, 1.0
	v_add_f32_e32 v74, 1.0, v39
	v_div_scale_f32 v75, s[0:1], v74, v74, 1.0
	v_rcp_f32_e32 v76, v75
	v_pk_mul_f32 v[38:39], v[34:35], v[80:81]
	s_nop 0
	v_mul_f32_e32 v35, v7, v38
	v_mul_f32_e32 v78, v35, v39
	v_fma_f32 v35, -v75, v76, 1.0
	v_fmac_f32_e32 v76, v35, v76
	v_div_scale_f32 v35, vcc, 1.0, v74, 1.0
	v_mul_f32_e32 v38, v35, v76
	v_fma_f32 v39, -v75, v38, v35
	v_fmac_f32_e32 v38, v39, v76
	v_mul_f32_e32 v39, 0xbfb8aa3b, v85
	v_exp_f32_e32 v39, v39
	v_fma_f32 v35, -v75, v38, v35
	v_div_fmas_f32 v35, v35, v76, v38
	v_div_fixup_f32 v35, v35, v74, 1.0
	v_add_f32_e32 v74, 1.0, v39
	v_div_scale_f32 v75, s[0:1], v74, v74, 1.0
	v_rcp_f32_e32 v76, v75
	v_pk_mul_f32 v[38:39], v[34:35], v[82:83]
	s_nop 0
	v_mul_f32_e32 v35, v0, v38
	v_mul_f32_e32 v79, v35, v39
	v_fma_f32 v35, -v75, v76, 1.0
	v_fmac_f32_e32 v76, v35, v76
	v_div_scale_f32 v35, vcc, 1.0, v74, 1.0
	v_mul_f32_e32 v38, v35, v76
	v_fma_f32 v39, -v75, v38, v35
	v_fmac_f32_e32 v38, v39, v76
	v_mul_f32_e32 v39, 0xbfb8aa3b, v37
	v_exp_f32_e32 v39, v39
	v_fma_f32 v35, -v75, v38, v35
	v_div_fmas_f32 v35, v35, v76, v38
	v_div_fixup_f32 v35, v35, v74, 1.0
	v_add_f32_e32 v74, 1.0, v39
	v_div_scale_f32 v75, s[0:1], v74, v74, 1.0
	v_rcp_f32_e32 v76, v75
	v_pk_mul_f32 v[38:39], v[34:35], v[84:85]
	s_nop 0
	v_mul_f32_e32 v35, v1, v38
	v_mul_f32_e32 v38, v35, v39
	v_fma_f32 v35, -v75, v76, 1.0
	v_fmac_f32_e32 v76, v35, v76
	v_div_scale_f32 v35, vcc, 1.0, v74, 1.0
	v_mul_f32_e32 v39, v35, v76
	v_fma_f32 v80, -v75, v39, v35
	v_fmac_f32_e32 v39, v80, v76
	v_fma_f32 v35, -v75, v39, v35
	v_div_fmas_f32 v35, v35, v76, v39
	v_mul_f32_e32 v39, 0xbfb8aa3b, v33
	ds_bpermute_b32 v75, v62, v72
	v_exp_f32_e32 v39, v39
	v_div_fixup_f32 v35, v35, v74, 1.0
	v_pk_mul_f32 v[36:37], v[34:35], v[36:37]
	s_nop 0
	v_mul_f32_e32 v35, v2, v36
	v_add_f32_e32 v36, 1.0, v39
	s_waitcnt lgkmcnt(0)
	v_add_f32_e32 v39, v72, v75
	ds_bpermute_b32 v72, v63, v39
	v_mul_f32_e32 v37, v35, v37
	v_div_scale_f32 v74, s[0:1], v36, v36, 1.0
	v_rcp_f32_e32 v75, v74
	s_waitcnt lgkmcnt(0)
; __device__ __forceinline__ unsigned cvt_pk_bf16(float lo, float hi) { unsigned r; asm volatile("v_cvt_pk_bf16_f32 %0, %1, %2" : "=v"(r) : "v"(lo), "v"(hi)); return r; }
; __device__ __forceinline__ float bflo(unsigned w) { return __uint_as_float(w << 16); }
; __device__ __forceinline__ float bfhi(unsigned w) { return __uint_as_float(w & 0xffff0000u); }
; __device__ __forceinline__ float sigmoidf_(float x) { return 1.f / (1.f + __expf(-x)); }
; __global__ void __launch_bounds__(512, 2) hybrid_fwd(Args a) {
;     ...
;             for (int u = 0; u < 4; ++u) { const int it = it0 + u * NGW; const int row = it >> 2, h = it & 3; const float rs = rsqrtf(wave_sum(gp[u]) * (1.0f / 512.0f) + EPS);
;                 float o[8] = {bflo(ow[u].x), bfhi(ow[u].x), bflo(ow[u].y), bfhi(ow[u].y), bflo(ow[u].z), bfhi(ow[u].z), bflo(ow[u].w), bfhi(ow[u].w)};
;                 float r[8] = {bflo(rw[u].x), bfhi(rw[u].x), bflo(rw[u].y), bfhi(rw[u].y), bflo(rw[u].z), bfhi(rw[u].z), bflo(rw[u].w), bfhi(rw[u].w)};
; #pragma unroll
;                 for (int e = 0; e < 8; ++e) o[e] = o[e] * rs * gn[e] * (r[e] * sigmoidf_(r[e]));
;                 *(u32x4*)(OCAT + (size_t)row * OC + 1024 + h * 512 + lane * 8) = (u32x4){cvt_pk_bf16(o[0], o[1]), cvt_pk_bf16(o[2], o[3]), cvt_pk_bf16(o[4], o[5]), cvt_pk_bf16(o[6], o[7])}; } }
	v_add_f32_e32 v35, v39, v72
	ds_bpermute_b32 v39, v64, v35
	v_fma_f32 v72, -v74, v75, 1.0
	v_fmac_f32_e32 v75, v72, v75
	v_div_scale_f32 v72, vcc, 1.0, v36, 1.0
	s_waitcnt lgkmcnt(0)
	v_add_f32_e32 v35, v35, v39
	ds_bpermute_b32 v39, v65, v35
	v_mul_f32_e32 v76, v72, v75
	v_fma_f32 v80, -v74, v76, v72
	v_fmac_f32_e32 v76, v80, v75
	v_fma_f32 v72, -v74, v76, v72
	s_waitcnt lgkmcnt(0)
	v_add_f32_e32 v39, v35, v39
	ds_bpermute_b32 v74, v66, v39
	v_div_fmas_f32 v35, v72, v75, v76
	v_div_fixup_f32 v35, v35, v36, 1.0
	v_pk_mul_f32 v[32:33], v[34:35], v[32:33]
	v_lshlrev_b32_e32 v72, 16, v27
	s_waitcnt lgkmcnt(0)
	v_add_f32_e32 v34, v39, v74
	ds_bpermute_b32 v35, v67, v34
	v_mul_f32_e32 v32, v3, v32
	v_mul_f32_e32 v36, v32, v33
	v_cvt_pk_bf16_f32 v32, v49, v73
	v_cvt_pk_bf16_f32 v33, v77, v78
	s_waitcnt lgkmcnt(0)
	v_add_f32_e32 v34, v34, v35
	v_fmamk_f32 v34, v34, 0x3b000000, v69
	v_mul_f32_e32 v35, 0x4b800000, v34
	v_cmp_gt_f32_e32 vcc, s18, v34
	v_lshlrev_b32_e32 v73, 16, v31
	v_and_b32_e32 v31, 0xffff0000, v31
	v_cndmask_b32_e32 v34, v34, v35, vcc
	v_rsq_f32_e32 v39, v34
	v_cvt_pk_bf16_f32 v34, v79, v38
	v_cvt_pk_bf16_f32 v35, v37, v36
	global_store_dwordx4 v[60:61], v[32:35], off offset:2048
	v_and_b32_e32 v36, 0xffff0000, v24
	v_and_b32_e32 v60, 0xffff0000, v26
	v_lshlrev_b32_e32 v35, 16, v28
	v_mul_f32_e32 v33, 0xbfb8aa3b, v35
	v_exp_f32_e32 v33, v33
	v_lshlrev_b32_e32 v34, 16, v24
	v_lshlrev_b32_e32 v24, 16, v26
	v_mul_f32_e32 v32, 0x45800000, v39
	v_add_f32_e32 v26, 1.0, v33
	v_div_scale_f32 v33, s[0:1], v26, v26, 1.0
	v_rcp_f32_e32 v49, v33
	v_and_b32_e32 v37, 0xffff0000, v28
	v_lshlrev_b32_e32 v38, 16, v25
	v_and_b32_e32 v28, 0xffff0000, v25
	v_lshlrev_b32_e32 v25, 16, v30
	v_and_b32_e32 v61, 0xffff0000, v30
	v_and_b32_e32 v30, 0xffff0000, v27
	v_fma_f32 v27, -v33, v49, 1.0
	v_cndmask_b32_e32 v32, v39, v32, vcc
	v_fmac_f32_e32 v49, v27, v49
	v_div_scale_f32 v27, vcc, 1.0, v26, 1.0
	v_mul_f32_e32 v74, v27, v49
	v_fma_f32 v75, -v33, v74, v27
	v_fmac_f32_e32 v74, v75, v49
	v_fma_f32 v27, -v33, v74, v27
	v_mul_f32_e32 v33, 0xbfb8aa3b, v37
	v_exp_f32_e32 v75, v33
	v_div_fmas_f32 v27, v27, v49, v74
	v_div_fixup_f32 v33, v27, v26, 1.0
	v_pk_mul_f32 v[26:27], v[32:33], v[34:35]
	v_add_f32_e32 v49, 1.0, v75
	v_div_scale_f32 v74, s[0:1], v49, v49, 1.0
	v_rcp_f32_e32 v75, v74
	v_mul_f32_e32 v26, v4, v26
	v_mul_f32_e32 v34, v26, v27
	v_lshlrev_b32_e32 v39, 16, v29
	v_fma_f32 v26, -v74, v75, 1.0
	v_fmac_f32_e32 v75, v26, v75
	v_div_scale_f32 v26, vcc, 1.0, v49, 1.0
	v_mul_f32_e32 v27, v26, v75
	v_fma_f32 v33, -v74, v27, v26
	v_fmac_f32_e32 v27, v33, v75
	v_mul_f32_e32 v33, 0xbfb8aa3b, v39
	v_exp_f32_e32 v35, v33
	v_fma_f32 v26, -v74, v27, v26
	v_div_fmas_f32 v26, v26, v75, v27
	v_div_fixup_f32 v33, v26, v49, 1.0
	v_add_f32_e32 v35, 1.0, v35
	v_div_scale_f32 v49, s[0:1], v35, v35, 1.0
	v_rcp_f32_e32 v74, v49
	v_pk_mul_f32 v[26:27], v[32:33], v[36:37]
	v_and_b32_e32 v29, 0xffff0000, v29
	v_mul_f32_e32 v26, v5, v26
	v_mul_f32_e32 v36, v26, v27
	v_fma_f32 v26, -v49, v74, 1.0
	v_fmac_f32_e32 v74, v26, v74
	v_div_scale_f32 v26, vcc, 1.0, v35, 1.0
	v_mul_f32_e32 v27, v26, v74
	v_fma_f32 v33, -v49, v27, v26
	v_fmac_f32_e32 v27, v33, v74
	v_mul_f32_e32 v33, 0xbfb8aa3b, v29
	v_exp_f32_e32 v37, v33
	v_fma_f32 v26, -v49, v27, v26
	v_div_fmas_f32 v26, v26, v74, v27
	v_div_fixup_f32 v33, v26, v35, 1.0
	v_add_f32_e32 v35, 1.0, v37
	v_div_scale_f32 v37, s[0:1], v35, v35, 1.0
	v_rcp_f32_e32 v49, v37
	v_pk_mul_f32 v[26:27], v[32:33], v[38:39]
	s_nop 0
	v_mul_f32_e32 v26, v6, v26
	v_mul_f32_e32 v38, v26, v27
	v_fma_f32 v26, -v37, v49, 1.0
	v_fmac_f32_e32 v49, v26, v49
	v_div_scale_f32 v26, vcc, 1.0, v35, 1.0
	v_mul_f32_e32 v27, v26, v49
	v_fma_f32 v33, -v37, v27, v26
	v_fmac_f32_e32 v27, v33, v49
	v_mul_f32_e32 v33, 0xbfb8aa3b, v25
	v_fma_f32 v26, -v37, v27, v26
	v_exp_f32_e32 v37, v33
	v_div_fmas_f32 v26, v26, v49, v27
	v_div_fixup_f32 v33, v26, v35, 1.0
	v_pk_mul_f32 v[26:27], v[32:33], v[28:29]
	v_add_f32_e32 v35, 1.0, v37
	v_div_scale_f32 v37, s[0:1], v35, v35, 1.0
	v_rcp_f32_e32 v39, v37
	v_mul_f32_e32 v26, v7, v26
	v_mul_f32_e32 v26, v26, v27
	v_fma_f32 v27, -v37, v39, 1.0
	v_fmac_f32_e32 v39, v27, v39
	v_div_scale_f32 v27, vcc, 1.0, v35, 1.0
	v_mul_f32_e32 v28, v27, v39
	v_fma_f32 v29, -v37, v28, v27
	v_fmac_f32_e32 v28, v29, v39
	v_mul_f32_e32 v29, 0xbfb8aa3b, v61
	v_exp_f32_e32 v29, v29
	v_fma_f32 v27, -v37, v28, v27
	v_div_fmas_f32 v27, v27, v39, v28
	v_div_fixup_f32 v33, v27, v35, 1.0
	v_add_f32_e32 v27, 1.0, v29
	v_div_scale_f32 v28, s[0:1], v27, v27, 1.0
	v_rcp_f32_e32 v29, v28
	v_pk_mul_f32 v[24:25], v[32:33], v[24:25]
	s_nop 0
	v_mul_f32_e32 v24, v0, v24
	v_mul_f32_e32 v35, v24, v25
	v_fma_f32 v24, -v28, v29, 1.0
	v_fmac_f32_e32 v29, v24, v29
	v_div_scale_f32 v24, vcc, 1.0, v27, 1.0
	v_mul_f32_e32 v25, v24, v29
	v_fma_f32 v33, -v28, v25, v24
	v_fmac_f32_e32 v25, v33, v29
	v_fma_f32 v24, -v28, v25, v24
	v_mul_f32_e32 v28, 0xbfb8aa3b, v73
	v_exp_f32_e32 v28, v28
	v_div_fmas_f32 v24, v24, v29, v25
	v_div_fixup_f32 v33, v24, v27, 1.0
	v_pk_mul_f32 v[24:25], v[32:33], v[60:61]
	v_add_f32_e32 v27, 1.0, v28
	v_div_scale_f32 v28, s[0:1], v27, v27, 1.0
	v_rcp_f32_e32 v29, v28
	v_mul_f32_e32 v24, v1, v24
	v_mul_f32_e32 v37, v24, v25
	v_fma_f32 v24, -v28, v29, 1.0
	v_fmac_f32_e32 v29, v24, v29
	v_div_scale_f32 v24, vcc, 1.0, v27, 1.0
	v_mul_f32_e32 v25, v24, v29
	v_fma_f32 v33, -v28, v25, v24
	v_fmac_f32_e32 v25, v33, v29
	v_fma_f32 v24, -v28, v25, v24
	v_div_fmas_f32 v24, v24, v29, v25
	v_mul_f32_e32 v25, 0xbfb8aa3b, v31
	ds_bpermute_b32 v29, v62, v71
	v_exp_f32_e32 v28, v25
	v_div_fixup_f32 v33, v24, v27, 1.0
	v_pk_mul_f32 v[24:25], v[32:33], v[72:73]
	v_add_f32_e32 v27, 1.0, v28
	s_waitcnt lgkmcnt(0)
; __device__ __forceinline__ unsigned cvt_pk_bf16(float lo, float hi) { unsigned r; asm volatile("v_cvt_pk_bf16_f32 %0, %1, %2" : "=v"(r) : "v"(lo), "v"(hi)); return r; }
; __device__ __forceinline__ float bflo(unsigned w) { return __uint_as_float(w << 16); }
; __device__ __forceinline__ float bfhi(unsigned w) { return __uint_as_float(w & 0xffff0000u); }
; __device__ __forceinline__ float sigmoidf_(float x) { return 1.f / (1.f + __expf(-x)); }
; __global__ void __launch_bounds__(512, 2) hybrid_fwd(Args a) {
;     ...
;             for (int u = 0; u < 4; ++u) { const int it = it0 + u * NGW; const int row = it >> 2, h = it & 3; const float rs = rsqrtf(wave_sum(gp[u]) * (1.0f / 512.0f) + EPS);
;                 float o[8] = {bflo(ow[u].x), bfhi(ow[u].x), bflo(ow[u].y), bfhi(ow[u].y), bflo(ow[u].z), bfhi(ow[u].z), bflo(ow[u].w), bfhi(ow[u].w)};
;                 float r[8] = {bflo(rw[u].x), bfhi(rw[u].x), bflo(rw[u].y), bfhi(rw[u].y), bflo(rw[u].z), bfhi(rw[u].z), bflo(rw[u].w), bfhi(rw[u].w)};
; #pragma unroll
;                 for (int e = 0; e < 8; ++e) o[e] = o[e] * rs * gn[e] * (r[e] * sigmoidf_(r[e]));
;                 *(u32x4*)(OCAT + (size_t)row * OC + 1024 + h * 512 + lane * 8) = (u32x4){cvt_pk_bf16(o[0], o[1]), cvt_pk_bf16(o[2], o[3]), cvt_pk_bf16(o[4], o[5]), cvt_pk_bf16(o[6], o[7])}; } }
	v_add_f32_e32 v28, v71, v29
	ds_bpermute_b32 v29, v63, v28
	v_mul_f32_e32 v24, v2, v24
	v_mul_f32_e32 v49, v24, v25
	v_div_scale_f32 v33, s[0:1], v27, v27, 1.0
	s_waitcnt lgkmcnt(0)
	v_add_f32_e32 v24, v28, v29
	ds_bpermute_b32 v25, v64, v24
	v_rcp_f32_e32 v39, v33
	s_waitcnt lgkmcnt(0)
	v_add_f32_e32 v24, v24, v25
	ds_bpermute_b32 v25, v65, v24
	v_fma_f32 v28, -v33, v39, 1.0
	v_fmac_f32_e32 v39, v28, v39
	v_div_scale_f32 v28, vcc, 1.0, v27, 1.0
	v_mul_f32_e32 v29, v28, v39
	v_fma_f32 v60, -v33, v29, v28
	v_fmac_f32_e32 v29, v60, v39
	s_waitcnt lgkmcnt(0)
	v_add_f32_e32 v60, v24, v25
	ds_bpermute_b32 v61, v66, v60
	v_fma_f32 v28, -v33, v29, v28
	v_div_fmas_f32 v24, v28, v39, v29
	v_div_fixup_f32 v33, v24, v27, 1.0
	v_pk_mul_f32 v[24:25], v[32:33], v[30:31]
	s_waitcnt lgkmcnt(0)
	v_add_f32_e32 v27, v60, v61
	ds_bpermute_b32 v28, v67, v27
	v_mul_f32_e32 v24, v3, v24
	v_mul_f32_e32 v29, v24, v25
	v_cvt_pk_bf16_f32 v24, v34, v36
	v_cvt_pk_bf16_f32 v25, v38, v26
	s_waitcnt lgkmcnt(0)
	v_add_f32_e32 v26, v27, v28
	v_fmamk_f32 v26, v26, 0x3b000000, v69
	v_mul_f32_e32 v27, 0x4b800000, v26
	v_cmp_gt_f32_e32 vcc, s18, v26
	v_and_b32_e32 v32, 0xffff0000, v18
	v_lshlrev_b32_e32 v30, 16, v17
	v_cndmask_b32_e32 v26, v26, v27, vcc
	v_rsq_f32_e32 v28, v26
	v_cvt_pk_bf16_f32 v26, v35, v37
	v_cvt_pk_bf16_f32 v27, v49, v29
	global_store_dwordx4 v[58:59], v[24:27], off offset:2048
	v_and_b32_e32 v29, 0xffff0000, v20
	v_and_b32_e32 v33, 0xffff0000, v22
	v_lshlrev_b32_e32 v27, 16, v20
	v_mul_f32_e32 v25, 0xbfb8aa3b, v27
	v_exp_f32_e32 v25, v25
	v_mul_f32_e32 v24, 0x45800000, v28
	v_cndmask_b32_e32 v24, v28, v24, vcc
	v_lshlrev_b32_e32 v26, 16, v16
	v_and_b32_e32 v28, 0xffff0000, v16
	v_lshlrev_b32_e32 v16, 16, v18
	v_add_f32_e32 v18, 1.0, v25
	v_div_scale_f32 v25, s[0:1], v18, v18, 1.0
	v_rcp_f32_e32 v36, v25
	v_and_b32_e32 v20, 0xffff0000, v17
	v_lshlrev_b32_e32 v17, 16, v22
	v_lshlrev_b32_e32 v34, 16, v19
	v_and_b32_e32 v22, 0xffff0000, v19
	v_fma_f32 v19, -v25, v36, 1.0
	v_fmac_f32_e32 v36, v19, v36
	v_div_scale_f32 v19, vcc, 1.0, v18, 1.0
	v_mul_f32_e32 v37, v19, v36
	v_fma_f32 v38, -v25, v37, v19
	v_fmac_f32_e32 v37, v38, v36
	v_fma_f32 v19, -v25, v37, v19
	v_mul_f32_e32 v25, 0xbfb8aa3b, v29
	v_exp_f32_e32 v38, v25
	v_div_fmas_f32 v19, v19, v36, v37
	v_div_fixup_f32 v25, v19, v18, 1.0
	v_pk_mul_f32 v[18:19], v[24:25], v[26:27]
	v_add_f32_e32 v36, 1.0, v38
	v_div_scale_f32 v37, s[0:1], v36, v36, 1.0
	v_rcp_f32_e32 v38, v37
	v_mul_f32_e32 v18, v4, v18
	v_mul_f32_e32 v26, v18, v19
	v_lshlrev_b32_e32 v31, 16, v21
	v_fma_f32 v18, -v37, v38, 1.0
	v_fmac_f32_e32 v38, v18, v38
	v_div_scale_f32 v18, vcc, 1.0, v36, 1.0
	v_mul_f32_e32 v19, v18, v38
	v_fma_f32 v25, -v37, v19, v18
	v_fmac_f32_e32 v19, v25, v38
	v_mul_f32_e32 v25, 0xbfb8aa3b, v31
	v_exp_f32_e32 v27, v25
	v_fma_f32 v18, -v37, v19, v18
	v_div_fmas_f32 v18, v18, v38, v19
	v_div_fixup_f32 v25, v18, v36, 1.0
	v_add_f32_e32 v27, 1.0, v27
	v_div_scale_f32 v36, s[0:1], v27, v27, 1.0
	v_rcp_f32_e32 v37, v36
	v_pk_mul_f32 v[18:19], v[24:25], v[28:29]
	v_and_b32_e32 v21, 0xffff0000, v21
	v_mul_f32_e32 v18, v5, v18
	v_mul_f32_e32 v28, v18, v19
	v_fma_f32 v18, -v36, v37, 1.0
	v_fmac_f32_e32 v37, v18, v37
	v_div_scale_f32 v18, vcc, 1.0, v27, 1.0
	v_mul_f32_e32 v19, v18, v37
	v_fma_f32 v25, -v36, v19, v18
	v_fmac_f32_e32 v19, v25, v37
	v_mul_f32_e32 v25, 0xbfb8aa3b, v21
	v_exp_f32_e32 v29, v25
	v_fma_f32 v18, -v36, v19, v18
	v_div_fmas_f32 v18, v18, v37, v19
	v_div_fixup_f32 v25, v18, v27, 1.0
	v_add_f32_e32 v27, 1.0, v29
	v_div_scale_f32 v29, s[0:1], v27, v27, 1.0
	v_rcp_f32_e32 v36, v29
	v_pk_mul_f32 v[18:19], v[24:25], v[30:31]
	v_lshlrev_b32_e32 v35, 16, v23
	v_mul_f32_e32 v18, v6, v18
	v_mul_f32_e32 v30, v18, v19
	v_fma_f32 v18, -v29, v36, 1.0
	v_fmac_f32_e32 v36, v18, v36
	v_div_scale_f32 v18, vcc, 1.0, v27, 1.0
	v_mul_f32_e32 v19, v18, v36
	v_fma_f32 v25, -v29, v19, v18
	v_fmac_f32_e32 v19, v25, v36
	v_mul_f32_e32 v25, 0xbfb8aa3b, v17
	v_fma_f32 v18, -v29, v19, v18
	v_exp_f32_e32 v29, v25
	v_div_fmas_f32 v18, v18, v36, v19
	v_div_fixup_f32 v25, v18, v27, 1.0
	v_pk_mul_f32 v[18:19], v[24:25], v[20:21]
	v_add_f32_e32 v27, 1.0, v29
	v_div_scale_f32 v29, s[0:1], v27, v27, 1.0
	v_rcp_f32_e32 v31, v29
	v_mul_f32_e32 v18, v7, v18
	v_mul_f32_e32 v18, v18, v19
	v_and_b32_e32 v23, 0xffff0000, v23
	v_fma_f32 v19, -v29, v31, 1.0
	v_fmac_f32_e32 v31, v19, v31
	v_div_scale_f32 v19, vcc, 1.0, v27, 1.0
	v_mul_f32_e32 v20, v19, v31
	v_fma_f32 v21, -v29, v20, v19
	v_fmac_f32_e32 v20, v21, v31
	v_mul_f32_e32 v21, 0xbfb8aa3b, v33
	v_exp_f32_e32 v21, v21
	v_fma_f32 v19, -v29, v20, v19
	v_div_fmas_f32 v19, v19, v31, v20
	v_div_fixup_f32 v25, v19, v27, 1.0
	v_add_f32_e32 v19, 1.0, v21
	v_div_scale_f32 v20, s[0:1], v19, v19, 1.0
	v_rcp_f32_e32 v21, v20
	v_pk_mul_f32 v[16:17], v[24:25], v[16:17]
	s_nop 0
	v_mul_f32_e32 v16, v0, v16
	v_mul_f32_e32 v27, v16, v17
	v_fma_f32 v16, -v20, v21, 1.0
	v_fmac_f32_e32 v21, v16, v21
	v_div_scale_f32 v16, vcc, 1.0, v19, 1.0
	v_mul_f32_e32 v17, v16, v21
	v_fma_f32 v25, -v20, v17, v16
	v_fmac_f32_e32 v17, v25, v21
	v_fma_f32 v16, -v20, v17, v16
	v_mul_f32_e32 v20, 0xbfb8aa3b, v35
	v_exp_f32_e32 v20, v20
	v_div_fmas_f32 v16, v16, v21, v17
	v_div_fixup_f32 v25, v16, v19, 1.0
	v_pk_mul_f32 v[16:17], v[24:25], v[32:33]
	v_add_f32_e32 v19, 1.0, v20
	v_div_scale_f32 v20, s[0:1], v19, v19, 1.0
	v_rcp_f32_e32 v21, v20
	v_mul_f32_e32 v16, v1, v16
	v_mul_f32_e32 v29, v16, v17
	v_fma_f32 v16, -v20, v21, 1.0
	v_fmac_f32_e32 v21, v16, v21
	v_div_scale_f32 v16, vcc, 1.0, v19, 1.0
	v_mul_f32_e32 v17, v16, v21
	v_fma_f32 v25, -v20, v17, v16
	v_fmac_f32_e32 v17, v25, v21
	v_fma_f32 v16, -v20, v17, v16
	v_div_fmas_f32 v16, v16, v21, v17
	v_mul_f32_e32 v17, 0xbfb8aa3b, v23
	ds_bpermute_b32 v21, v62, v40
	v_exp_f32_e32 v20, v17
	v_div_fixup_f32 v25, v16, v19, 1.0
	v_pk_mul_f32 v[16:17], v[24:25], v[34:35]
	v_add_f32_e32 v19, 1.0, v20
	s_waitcnt lgkmcnt(0)
; __device__ __forceinline__ unsigned cvt_pk_bf16(float lo, float hi) { unsigned r; asm volatile("v_cvt_pk_bf16_f32 %0, %1, %2" : "=v"(r) : "v"(lo), "v"(hi)); return r; }
; __device__ __forceinline__ float bflo(unsigned w) { return __uint_as_float(w << 16); }
; __device__ __forceinline__ float bfhi(unsigned w) { return __uint_as_float(w & 0xffff0000u); }
; __device__ __forceinline__ float sigmoidf_(float x) { return 1.f / (1.f + __expf(-x)); }
; __global__ void __launch_bounds__(512, 2) hybrid_fwd(Args a) {
;     ...
;             for (int u = 0; u < 4; ++u) { const int it = it0 + u * NGW; const int row = it >> 2, h = it & 3; const float rs = rsqrtf(wave_sum(gp[u]) * (1.0f / 512.0f) + EPS);
;                 float o[8] = {bflo(ow[u].x), bfhi(ow[u].x), bflo(ow[u].y), bfhi(ow[u].y), bflo(ow[u].z), bfhi(ow[u].z), bflo(ow[u].w), bfhi(ow[u].w)};
;                 float r[8] = {bflo(rw[u].x), bfhi(rw[u].x), bflo(rw[u].y), bfhi(rw[u].y), bflo(rw[u].z), bfhi(rw[u].z), bflo(rw[u].w), bfhi(rw[u].w)};
; #pragma unroll
;                 for (int e = 0; e < 8; ++e) o[e] = o[e] * rs * gn[e] * (r[e] * sigmoidf_(r[e]));
;                 *(u32x4*)(OCAT + (size_t)row * OC + 1024 + h * 512 + lane * 8) = (u32x4){cvt_pk_bf16(o[0], o[1]), cvt_pk_bf16(o[2], o[3]), cvt_pk_bf16(o[4], o[5]), cvt_pk_bf16(o[6], o[7])}; } }
	v_add_f32_e32 v20, v40, v21
	ds_bpermute_b32 v21, v63, v20
	v_mul_f32_e32 v16, v2, v16
	v_mul_f32_e32 v32, v16, v17
	v_div_scale_f32 v25, s[0:1], v19, v19, 1.0
	s_waitcnt lgkmcnt(0)
	v_add_f32_e32 v16, v20, v21
	ds_bpermute_b32 v17, v64, v16
	v_rcp_f32_e32 v31, v25
	s_waitcnt lgkmcnt(0)
	v_add_f32_e32 v16, v16, v17
	ds_bpermute_b32 v17, v65, v16
	v_fma_f32 v20, -v25, v31, 1.0
	v_fmac_f32_e32 v31, v20, v31
	v_div_scale_f32 v20, vcc, 1.0, v19, 1.0
	v_mul_f32_e32 v21, v20, v31
	v_fma_f32 v33, -v25, v21, v20
	v_fmac_f32_e32 v21, v33, v31
	s_waitcnt lgkmcnt(0)
	v_add_f32_e32 v33, v16, v17
	ds_bpermute_b32 v34, v66, v33
	v_fma_f32 v20, -v25, v21, v20
	v_div_fmas_f32 v16, v20, v31, v21
	v_div_fixup_f32 v25, v16, v19, 1.0
	v_pk_mul_f32 v[16:17], v[24:25], v[22:23]
	s_waitcnt lgkmcnt(0)
	v_add_f32_e32 v19, v33, v34
	ds_bpermute_b32 v20, v67, v19
	v_mul_f32_e32 v16, v3, v16
	v_mul_f32_e32 v21, v16, v17
	v_cvt_pk_bf16_f32 v16, v26, v28
	v_cvt_pk_bf16_f32 v17, v30, v18
	s_waitcnt lgkmcnt(0)
	v_add_f32_e32 v18, v19, v20
	v_fmamk_f32 v18, v18, 0x3b000000, v69
	v_mul_f32_e32 v19, 0x4b800000, v18
	v_cmp_gt_f32_e32 vcc, s18, v18
	v_and_b32_e32 v24, 0xffff0000, v10
	v_lshlrev_b32_e32 v22, 16, v9
	v_cndmask_b32_e32 v18, v18, v19, vcc
	v_rsq_f32_e32 v20, v18
	v_cvt_pk_bf16_f32 v18, v27, v29
	v_cvt_pk_bf16_f32 v19, v32, v21
	global_store_dwordx4 v[56:57], v[16:19], off offset:2048
	v_and_b32_e32 v21, 0xffff0000, v12
	v_and_b32_e32 v25, 0xffff0000, v14
	v_lshlrev_b32_e32 v19, 16, v12
	v_mul_f32_e32 v17, 0xbfb8aa3b, v19
	v_exp_f32_e32 v17, v17
	v_mul_f32_e32 v16, 0x45800000, v20
	v_cndmask_b32_e32 v16, v20, v16, vcc
	v_lshlrev_b32_e32 v18, 16, v8
	v_and_b32_e32 v20, 0xffff0000, v8
	v_lshlrev_b32_e32 v8, 16, v10
	v_add_f32_e32 v10, 1.0, v17
	v_div_scale_f32 v17, s[0:1], v10, v10, 1.0
	v_rcp_f32_e32 v28, v17
	v_and_b32_e32 v12, 0xffff0000, v9
	v_lshlrev_b32_e32 v9, 16, v14
	v_lshlrev_b32_e32 v26, 16, v11
	v_and_b32_e32 v14, 0xffff0000, v11
	v_fma_f32 v11, -v17, v28, 1.0
	v_fmac_f32_e32 v28, v11, v28
	v_div_scale_f32 v11, vcc, 1.0, v10, 1.0
	v_mul_f32_e32 v29, v11, v28
	v_fma_f32 v30, -v17, v29, v11
	v_fmac_f32_e32 v29, v30, v28
	v_fma_f32 v11, -v17, v29, v11
	v_mul_f32_e32 v17, 0xbfb8aa3b, v21
	v_exp_f32_e32 v30, v17
	v_div_fmas_f32 v11, v11, v28, v29
	v_div_fixup_f32 v17, v11, v10, 1.0
	v_pk_mul_f32 v[10:11], v[16:17], v[18:19]
	v_add_f32_e32 v28, 1.0, v30
	v_div_scale_f32 v29, s[0:1], v28, v28, 1.0
	v_rcp_f32_e32 v30, v29
	v_mul_f32_e32 v4, v4, v10
	v_mul_f32_e32 v18, v4, v11
	v_lshlrev_b32_e32 v23, 16, v13
	v_fma_f32 v4, -v29, v30, 1.0
	v_fmac_f32_e32 v30, v4, v30
	v_div_scale_f32 v4, vcc, 1.0, v28, 1.0
	v_mul_f32_e32 v10, v4, v30
	v_fma_f32 v11, -v29, v10, v4
	v_fmac_f32_e32 v10, v11, v30
	v_mul_f32_e32 v11, 0xbfb8aa3b, v23
	v_exp_f32_e32 v11, v11
	v_fma_f32 v4, -v29, v10, v4
	v_div_fmas_f32 v4, v4, v30, v10
	v_div_fixup_f32 v17, v4, v28, 1.0
	v_add_f32_e32 v4, 1.0, v11
	v_div_scale_f32 v19, s[0:1], v4, v4, 1.0
	v_rcp_f32_e32 v28, v19
	v_pk_mul_f32 v[10:11], v[16:17], v[20:21]
	v_and_b32_e32 v13, 0xffff0000, v13
	v_mul_f32_e32 v5, v5, v10
	v_mul_f32_e32 v10, v5, v11
	v_fma_f32 v5, -v19, v28, 1.0
	v_fmac_f32_e32 v28, v5, v28
	v_div_scale_f32 v5, vcc, 1.0, v4, 1.0
	v_mul_f32_e32 v11, v5, v28
	v_fma_f32 v17, -v19, v11, v5
	v_fmac_f32_e32 v11, v17, v28
	v_mul_f32_e32 v17, 0xbfb8aa3b, v13
	v_fma_f32 v5, -v19, v11, v5
	v_exp_f32_e32 v19, v17
	v_div_fmas_f32 v5, v5, v28, v11
	v_div_fixup_f32 v17, v5, v4, 1.0
	v_pk_mul_f32 v[4:5], v[16:17], v[22:23]
	v_add_f32_e32 v11, 1.0, v19
	v_div_scale_f32 v19, s[0:1], v11, v11, 1.0
	v_rcp_f32_e32 v20, v19
	v_mul_f32_e32 v4, v6, v4
	v_mul_f32_e32 v6, v4, v5
	v_lshlrev_b32_e32 v27, 16, v15
	v_fma_f32 v4, -v19, v20, 1.0
	v_fmac_f32_e32 v20, v4, v20
	v_div_scale_f32 v4, vcc, 1.0, v11, 1.0
	v_mul_f32_e32 v5, v4, v20
	v_fma_f32 v17, -v19, v5, v4
	v_fmac_f32_e32 v5, v17, v20
	v_mul_f32_e32 v17, 0xbfb8aa3b, v9
	v_fma_f32 v4, -v19, v5, v4
	v_exp_f32_e32 v19, v17
	v_div_fmas_f32 v4, v4, v20, v5
	v_div_fixup_f32 v17, v4, v11, 1.0
	v_pk_mul_f32 v[4:5], v[16:17], v[12:13]
	v_add_f32_e32 v11, 1.0, v19
	v_div_scale_f32 v19, s[0:1], v11, v11, 1.0
	v_rcp_f32_e32 v20, v19
	v_mul_f32_e32 v4, v7, v4
	v_mul_f32_e32 v7, v4, v5
	v_and_b32_e32 v15, 0xffff0000, v15
	v_fma_f32 v4, -v19, v20, 1.0
	v_fmac_f32_e32 v20, v4, v20
	v_div_scale_f32 v4, vcc, 1.0, v11, 1.0
	v_mul_f32_e32 v5, v4, v20
	v_fma_f32 v12, -v19, v5, v4
	v_fmac_f32_e32 v5, v12, v20
	v_mul_f32_e32 v12, 0xbfb8aa3b, v25
	v_exp_f32_e32 v12, v12
	v_fma_f32 v4, -v19, v5, v4
	v_div_fmas_f32 v4, v4, v20, v5
	v_div_fixup_f32 v17, v4, v11, 1.0
	v_add_f32_e32 v11, 1.0, v12
	v_div_scale_f32 v12, s[0:1], v11, v11, 1.0
	v_rcp_f32_e32 v13, v12
	v_pk_mul_f32 v[4:5], v[16:17], v[8:9]
	s_nop 0
	v_mul_f32_e32 v0, v0, v4
	v_mul_f32_e32 v8, v0, v5
	v_fma_f32 v0, -v12, v13, 1.0
	v_fmac_f32_e32 v13, v0, v13
	v_div_scale_f32 v0, vcc, 1.0, v11, 1.0
	v_mul_f32_e32 v4, v0, v13
	v_fma_f32 v5, -v12, v4, v0
	v_fmac_f32_e32 v4, v5, v13
	v_mul_f32_e32 v5, 0xbfb8aa3b, v27
	v_exp_f32_e32 v5, v5
	v_fma_f32 v0, -v12, v4, v0
	v_div_fmas_f32 v0, v0, v13, v4
	v_div_fixup_f32 v17, v0, v11, 1.0
	v_add_f32_e32 v0, 1.0, v5
	v_div_scale_f32 v9, s[0:1], v0, v0, 1.0
	v_rcp_f32_e32 v11, v9
	v_pk_mul_f32 v[4:5], v[16:17], v[24:25]
	s_nop 0
	v_mul_f32_e32 v1, v1, v4
	v_mul_f32_e32 v4, v1, v5
	v_fma_f32 v1, -v9, v11, 1.0
	v_fmac_f32_e32 v11, v1, v11
	v_div_scale_f32 v1, vcc, 1.0, v0, 1.0
	v_mul_f32_e32 v5, v1, v11
	v_fma_f32 v12, -v9, v5, v1
	v_fmac_f32_e32 v5, v12, v11
	v_fma_f32 v1, -v9, v5, v1
	v_mul_f32_e32 v9, 0xbfb8aa3b, v15
	v_exp_f32_e32 v9, v9
	v_div_fmas_f32 v1, v1, v11, v5
	v_div_fixup_f32 v17, v1, v0, 1.0
	v_pk_mul_f32 v[0:1], v[16:17], v[26:27]
	v_add_f32_e32 v5, 1.0, v9
	v_div_scale_f32 v9, s[0:1], v5, v5, 1.0
	v_rcp_f32_e32 v11, v9
	v_mul_f32_e32 v0, v2, v0
	v_mul_f32_e32 v12, v0, v1
	v_fma_f32 v0, -v9, v11, 1.0
	v_fmac_f32_e32 v11, v0, v11
	v_div_scale_f32 v0, vcc, 1.0, v5, 1.0
	v_mul_f32_e32 v1, v0, v11
	v_fma_f32 v2, -v9, v1, v0
	v_fmac_f32_e32 v1, v2, v11
	v_fma_f32 v0, -v9, v1, v0
	v_div_fmas_f32 v0, v0, v11, v1
	v_div_fixup_f32 v17, v0, v5, 1.0
	v_pk_mul_f32 v[0:1], v[16:17], v[14:15]
	s_nop 0
	v_mul_f32_e32 v0, v3, v0
	v_mul_f32_e32 v3, v0, v1
	v_cvt_pk_bf16_f32 v0, v18, v10
	v_cvt_pk_bf16_f32 v1, v6, v7
	v_cvt_pk_bf16_f32 v2, v8, v4
	v_cvt_pk_bf16_f32 v3, v12, v3
	global_store_dwordx4 v[54:55], v[0:3], off offset:2048
	s_nop 1
	v_add_u32_e32 v0, s88, v70
	v_cmp_lt_i32_e32 vcc, s19, v0
	s_or_b64 s[10:11], vcc, s[10:11]
	s_andn2_b64 exec, exec, s[10:11]
	s_cbranch_execz .LBB0_592
; __global__ void __launch_bounds__(512, 2) hybrid_fwd(Args a) {
;     ...
;         for (int it0 = gw; it0 < MP * 4; it0 += 4 * NGW) {
;             u32x4 ow[4], rw[4]; float gp[4];
; #pragma unroll
;             for (int u = 0; u < 4; ++u) { const int it = it0 + u * NGW; const int row = it >> 2, h = it & 3;
;                 ow[u] = *(const u32x4*)(OCAT + (size_t)row * OC + 1024 + h * 512 + lane * 8); rw[u] = *(const u32x4*)(Z + (size_t)row * DINP + ZRG + h * 512 + lane * 8);
;                 gp[u] = lane < 32 ? GSS[(size_t)it * 32 + lane] : 0.f; }
.LBB0_584:
	v_and_b32_e32 v1, 0x600, v68
	v_ashrrev_i32_e32 v4, 2, v0
	v_mad_i64_i32 v[2:3], s[0:1], v4, s16, v[46:47]
	v_lshlrev_b32_e32 v40, 1, v1
	v_lshl_add_u64 v[2:3], v[2:3], 0, v[40:41]
	v_lshl_add_u64 v[60:61], v[2:3], 0, v[50:51]
	v_mad_i64_i32 v[2:3], s[0:1], v4, s17, v[52:53]
	v_lshl_add_u64 v[2:3], v[2:3], 0, v[40:41]
	v_lshl_add_u64 v[2:3], v[2:3], 0, v[50:51]
	v_add_co_u32_e32 v2, vcc, 0x2000, v2
	v_mov_b32_e32 v73, v41
	s_nop 0
	v_addc_co_u32_e32 v3, vcc, 0, v3, vcc
	global_load_dwordx4 v[32:35], v[60:61], off offset:2048 nt
	global_load_dwordx4 v[36:39], v[2:3], off offset:3072 nt
	s_and_saveexec_b64 s[0:1], s[4:5]
	s_cbranch_execz .LBB0_586
	v_ashrrev_i32_e32 v1, 31, v0
	v_lshlrev_b64 v[2:3], 7, v[0:1]
	v_lshl_add_u64 v[2:3], v[42:43], 0, v[2:3]
	global_load_dword v73, v[2:3], off nt
.LBB0_586:
	s_or_b64 exec, exec, s[0:1]
	v_add_u32_e32 v2, s88, v0
	v_ashrrev_i32_e32 v1, 2, v2
	v_mad_i64_i32 v[4:5], s[0:1], v1, s16, v[46:47]
	v_lshl_add_u64 v[4:5], v[4:5], 0, v[40:41]
	v_lshl_add_u64 v[58:59], v[4:5], 0, v[50:51]
	v_mad_i64_i32 v[4:5], s[0:1], v1, s17, v[52:53]
	v_lshl_add_u64 v[4:5], v[4:5], 0, v[40:41]
	v_lshl_add_u64 v[4:5], v[4:5], 0, v[50:51]
	v_add_co_u32_e32 v4, vcc, 0x2000, v4
	v_mov_b32_e32 v71, 0
	s_nop 0
	v_addc_co_u32_e32 v5, vcc, 0, v5, vcc
	global_load_dwordx4 v[24:27], v[58:59], off offset:2048 nt
	global_load_dwordx4 v[28:31], v[4:5], off offset:3072 nt
	v_mov_b32_e32 v72, 0
	s_and_saveexec_b64 s[0:1], s[4:5]
	s_cbranch_execz .LBB0_588
	v_ashrrev_i32_e32 v3, 31, v2
	v_lshlrev_b64 v[4:5], 7, v[2:3]
	v_lshl_add_u64 v[4:5], v[42:43], 0, v[4:5]
	global_load_dword v72, v[4:5], off nt
.LBB0_588:
	s_or_b64 exec, exec, s[0:1]
	v_add_u32_e32 v1, s88, v2
	v_ashrrev_i32_e32 v4, 2, v1
	v_mov_b64_e32 v[2:3], s[50:51]
	v_mad_i64_i32 v[2:3], s[0:1], v4, s16, v[2:3]
	v_lshl_add_u64 v[2:3], v[2:3], 0, v[40:41]
	v_mov_b32_e32 v49, v41
	v_lshl_add_u64 v[56:57], v[2:3], 0, v[48:49]
	v_mov_b64_e32 v[2:3], s[74:75]
	v_mad_i64_i32 v[2:3], s[0:1], v4, s17, v[2:3]
	v_lshl_add_u64 v[2:3], v[2:3], 0, v[40:41]
	v_lshl_add_u64 v[2:3], v[2:3], 0, v[48:49]
	v_add_co_u32_e32 v2, vcc, 0x2000, v2
	s_nop 1
	v_addc_co_u32_e32 v3, vcc, 0, v3, vcc
	global_load_dwordx4 v[16:19], v[56:57], off offset:2048 nt
	global_load_dwordx4 v[20:23], v[2:3], off offset:3072 nt
	s_and_saveexec_b64 s[0:1], s[4:5]
	s_cbranch_execz .LBB0_590
	v_add_u32_e32 v2, s3, v0
	v_ashrrev_i32_e32 v3, 31, v2
	v_lshlrev_b64 v[2:3], 7, v[2:3]
	v_lshl_add_u64 v[2:3], v[42:43], 0, v[2:3]
	global_load_dword v71, v[2:3], off nt
.LBB0_590:
	s_or_b64 exec, exec, s[0:1]
	v_add_u32_e32 v70, s88, v1
	v_ashrrev_i32_e32 v1, 2, v70
	v_mov_b64_e32 v[2:3], s[50:51]
	v_mad_i64_i32 v[2:3], s[0:1], v1, s16, v[2:3]
	v_lshl_add_u64 v[2:3], v[2:3], 0, v[40:41]
	v_lshl_add_u64 v[54:55], v[2:3], 0, v[48:49]
	v_mov_b64_e32 v[2:3], s[74:75]
	v_mad_i64_i32 v[2:3], s[0:1], v1, s17, v[2:3]
	v_lshl_add_u64 v[2:3], v[2:3], 0, v[40:41]
	v_lshl_add_u64 v[2:3], v[2:3], 0, v[48:49]
	v_add_co_u32_e32 v2, vcc, 0x2000, v2
	v_mov_b32_e32 v40, 0
	s_nop 0
	v_addc_co_u32_e32 v3, vcc, 0, v3, vcc
	global_load_dwordx4 v[8:11], v[54:55], off offset:2048 nt
	global_load_dwordx4 v[12:15], v[2:3], off offset:3072 nt
	s_and_saveexec_b64 s[0:1], s[4:5]
	s_cbranch_execz .LBB0_583
	v_add_u32_e32 v0, s14, v0
	v_ashrrev_i32_e32 v1, 31, v0
	v_lshlrev_b64 v[0:1], 7, v[0:1]
	v_lshl_add_u64 v[0:1], v[42:43], 0, v[0:1]
	global_load_dword v40, v[0:1], off nt
	s_branch .LBB0_583

; __device__ __forceinline__ unsigned cvt_pk_bf16(float lo, float hi) { unsigned r; asm volatile("v_cvt_pk_bf16_f32 %0, %1, %2" : "=v"(r) : "v"(lo), "v"(hi)); return r; }
; __device__ __forceinline__ float sigmoidf_(float x) { return 1.f / (1.f + __expf(-x)); }
; __device__ __forceinline__ void unpack8(const u32x4& w, float (&f)[8]) { f[0] = bflo(w.x); f[1] = bfhi(w.x); f[2] = bflo(w.y); f[3] = bfhi(w.y); f[4] = bflo(w.z); f[5] = bfhi(w.z); f[6] = bflo(w.w); f[7] = bfhi(w.w); }
;     __device__ __forceinline__ void operator()(const f32x4 (&acc)[2][2][4][2], const Unit& u, int wr, int wc, int fr, int fq) const {
;     ...
;                 for (int bj = 0; bj < 2; ++bj) gw[m][bj] = *(const u32x4*)(gate + (size_t)(row0 + ai * HALF + m * 16) * ldg + col0 + bj * HALF);
; #pragma unroll
;             for (int m = 0; m < 4; ++m)
; #pragma unroll
;                 for (int bj = 0; bj < 2; ++bj) { float g[8]; unpack8(gw[m][bj], g); const f32x4 a0 = acc[ai][bj][m][0], a1 = acc[ai][bj][m][1]; float o[8];
; #pragma unroll
;                     for (int e = 0; e < 4; ++e) { o[e] = a0[e] * sigmoidf_(g[e]); o[4 + e] = a1[e] * sigmoidf_(g[4 + e]); }
;                     *(u32x4*)(T + (size_t)(row0 + ai * HALF + m * 16) * DM + col0 + bj * HALF) = (u32x4){cvt_pk_bf16(o[0], o[1]), cvt_pk_bf16(o[2], o[3]), cvt_pk_bf16(o[4], o[5]), cvt_pk_bf16(o[6], o[7])}; } }
.LBB0_672:
	v_lshl_or_b32 v104, s43, 8, v199
	v_ashrrev_i32_e32 v105, 31, v104
	v_lshlrev_b64 v[164:165], 1, v[104:105]
	v_lshl_add_u32 v166, s42, 8, v185
	v_lshl_add_u64 v[168:169], s[16:17], 0, v[164:165]
	v_mad_i64_i32 v[104:105], s[0:1], v166, s39, v[168:169]
	global_load_dwordx4 v[204:207], v[104:105], off nt
	v_or_b32_e32 v174, 16, v166
	v_or_b32_e32 v172, 32, v166
	v_or_b32_e32 v170, 48, v166
	v_mad_i64_i32 v[106:107], s[0:1], v174, s39, v[168:169]
	v_mad_i64_i32 v[116:117], s[0:1], v172, s39, v[168:169]
	v_mad_i64_i32 v[210:211], s[0:1], v170, s39, v[168:169]
	global_load_dwordx4 v[152:155], v[104:105], off offset:256 nt
	global_load_dwordx4 v[148:151], v[106:107], off nt
	global_load_dwordx4 v[144:147], v[106:107], off offset:256 nt
	global_load_dwordx4 v[140:143], v[116:117], off nt
	global_load_dwordx4 v[128:131], v[116:117], off offset:256 nt
	s_nop 0
	global_load_dwordx4 v[116:119], v[210:211], off nt
	global_load_dwordx4 v[104:107], v[210:211], off offset:256 nt
	v_ashrrev_i32_e32 v167, 31, v166
	v_lshlrev_b64 v[208:209], 12, v[166:167]
	v_ashrrev_i32_e32 v175, 31, v174
	v_ashrrev_i32_e32 v173, 31, v172
	v_ashrrev_i32_e32 v171, 31, v170
	s_waitcnt vmcnt(0)
	v_lshlrev_b32_e32 v167, 16, v204
	v_lshlrev_b32_e32 v210, 16, v206
	v_mul_f32_e32 v167, 0xbfb8aa3b, v167
	v_and_b32_e32 v203, 0xffff0000, v204
	v_mul_f32_e32 v210, 0xbfb8aa3b, v210
	v_exp_f32_e32 v167, v167
	v_mul_f32_e32 v203, 0xbfb8aa3b, v203
	v_exp_f32_e32 v210, v210
	v_exp_f32_e32 v203, v203
	v_add_f32_e32 v167, 1.0, v167
	v_and_b32_e32 v206, 0xffff0000, v206
	v_add_f32_e32 v210, 1.0, v210
	v_div_scale_f32 v212, s[0:1], v167, v167, 1.0
	v_mul_f32_e32 v206, 0xbfb8aa3b, v206
	v_add_f32_e32 v203, 1.0, v203
	v_div_scale_f32 v214, s[0:1], v210, v210, 1.0
	v_rcp_f32_e32 v220, v212
	v_exp_f32_e32 v206, v206
	v_div_scale_f32 v216, s[6:7], v203, v203, 1.0
	v_rcp_f32_e32 v221, v214
	v_rcp_f32_e32 v224, v216
	v_fma_f32 v226, -v212, v220, 1.0
	v_add_f32_e32 v206, 1.0, v206
	v_div_scale_f32 v213, vcc, 1.0, v167, 1.0
	v_fma_f32 v227, -v214, v221, 1.0
	v_fmac_f32_e32 v220, v226, v220
	v_div_scale_f32 v215, s[0:1], 1.0, v210, 1.0
	v_div_scale_f32 v218, s[8:9], v206, v206, 1.0
	v_fma_f32 v228, -v216, v224, 1.0
	v_fmac_f32_e32 v221, v227, v221
	v_mul_f32_e32 v226, v213, v220
	v_lshlrev_b32_e32 v204, 16, v205
	v_div_scale_f32 v217, s[6:7], 1.0, v203, 1.0
	v_rcp_f32_e32 v225, v218
	v_fmac_f32_e32 v224, v228, v224
	v_mul_f32_e32 v227, v215, v221
	v_fma_f32 v230, -v212, v226, v213
	v_mul_f32_e32 v204, 0xbfb8aa3b, v204
	v_mul_f32_e32 v228, v217, v224
	v_fma_f32 v231, -v214, v227, v215
	v_fmac_f32_e32 v226, v230, v220
	v_exp_f32_e32 v204, v204
	v_fma_f32 v232, -v216, v228, v217
	v_fmac_f32_e32 v227, v231, v221
	v_fma_f32 v212, -v212, v226, v213
	v_fmac_f32_e32 v228, v232, v224
	v_fma_f32 v213, -v214, v227, v215
	v_div_fmas_f32 v212, v212, v220, v226
	s_mov_b64 vcc, s[0:1]
	v_fma_f32 v229, -v218, v225, 1.0
	v_fma_f32 v214, -v216, v228, v217
	v_div_fixup_f32 v167, v212, v167, 1.0
	v_div_fmas_f32 v212, v213, v221, v227
	s_mov_b64 vcc, s[6:7]
	v_div_scale_f32 v219, s[8:9], 1.0, v206, 1.0
	v_fmac_f32_e32 v225, v229, v225
	v_mul_f32_e32 v136, v136, v167
	v_div_fixup_f32 v167, v212, v210, 1.0
	v_div_fmas_f32 v210, v214, v224, v228
	v_add_f32_e32 v204, 1.0, v204
	v_mul_f32_e32 v229, v219, v225
	v_mul_f32_e32 v167, v132, v167
	v_div_fixup_f32 v132, v210, v203, 1.0
	v_fma_f32 v233, -v218, v229, v219
	v_mul_f32_e32 v132, v137, v132
	v_div_scale_f32 v137, s[0:1], v204, v204, 1.0
	v_fmac_f32_e32 v229, v233, v225
	v_rcp_f32_e32 v203, v137
	v_fma_f32 v215, -v218, v229, v219
	s_mov_b64 vcc, s[8:9]
	v_div_fmas_f32 v210, v215, v225, v229
	v_lshlrev_b32_e32 v211, 16, v207
	v_div_fixup_f32 v206, v210, v206, 1.0
	v_mul_f32_e32 v206, v133, v206
	v_fma_f32 v133, -v137, v203, 1.0
	v_mul_f32_e32 v211, 0xbfb8aa3b, v211
	v_fmac_f32_e32 v203, v133, v203
	v_div_scale_f32 v133, vcc, 1.0, v204, 1.0
	v_exp_f32_e32 v211, v211
	v_mul_f32_e32 v210, v133, v203
	v_fma_f32 v212, -v137, v210, v133
	v_fmac_f32_e32 v210, v212, v203
	v_fma_f32 v133, -v137, v210, v133
	v_add_f32_e32 v137, 1.0, v211
	v_div_scale_f32 v211, s[0:1], v137, v137, 1.0
	v_rcp_f32_e32 v212, v211
	v_and_b32_e32 v205, 0xffff0000, v205
	v_div_fmas_f32 v133, v133, v203, v210
	v_div_fixup_f32 v133, v133, v204, 1.0
	v_mul_f32_e32 v204, 0xbfb8aa3b, v205
	v_exp_f32_e32 v204, v204
	v_mul_f32_e32 v133, v138, v133
	v_fma_f32 v138, -v211, v212, 1.0
	v_fmac_f32_e32 v212, v138, v212
	v_div_scale_f32 v138, vcc, 1.0, v137, 1.0
	v_mul_f32_e32 v203, v138, v212
	v_fma_f32 v205, -v211, v203, v138
	v_add_f32_e32 v204, 1.0, v204
	v_fmac_f32_e32 v203, v205, v212
	v_div_scale_f32 v205, s[0:1], v204, v204, 1.0
	v_rcp_f32_e32 v210, v205
	v_fma_f32 v138, -v211, v203, v138
	v_and_b32_e32 v207, 0xffff0000, v207
	v_div_fmas_f32 v138, v138, v212, v203
	v_div_fixup_f32 v137, v138, v137, 1.0
	v_mul_f32_e32 v203, 0xbfb8aa3b, v207
	v_mul_f32_e32 v137, v134, v137
	v_fma_f32 v134, -v205, v210, 1.0
	v_exp_f32_e32 v203, v203
	v_fmac_f32_e32 v210, v134, v210
	v_div_scale_f32 v134, vcc, 1.0, v204, 1.0
	v_mul_f32_e32 v138, v134, v210
	v_fma_f32 v207, -v205, v138, v134
	v_fmac_f32_e32 v138, v207, v210
	v_add_f32_e32 v203, 1.0, v203
	v_fma_f32 v134, -v205, v138, v134
	v_div_scale_f32 v205, s[0:1], v203, v203, 1.0
	v_rcp_f32_e32 v207, v205
	v_div_fmas_f32 v134, v134, v210, v138
	v_div_fixup_f32 v134, v134, v204, 1.0
	v_mul_f32_e32 v134, v139, v134
	v_fma_f32 v138, -v205, v207, 1.0
	v_fmac_f32_e32 v207, v138, v207
	v_div_scale_f32 v138, vcc, 1.0, v203, 1.0
	v_mul_f32_e32 v139, v138, v207
	v_fma_f32 v204, -v205, v139, v138
	v_fmac_f32_e32 v139, v204, v207
	v_fma_f32 v138, -v205, v139, v138
; __device__ __forceinline__ unsigned cvt_pk_bf16(float lo, float hi) { unsigned r; asm volatile("v_cvt_pk_bf16_f32 %0, %1, %2" : "=v"(r) : "v"(lo), "v"(hi)); return r; }
; __device__ __forceinline__ float sigmoidf_(float x) { return 1.f / (1.f + __expf(-x)); }
; __device__ __forceinline__ void unpack8(const u32x4& w, float (&f)[8]) { f[0] = bflo(w.x); f[1] = bfhi(w.x); f[2] = bflo(w.y); f[3] = bfhi(w.y); f[4] = bflo(w.z); f[5] = bfhi(w.z); f[6] = bflo(w.w); f[7] = bfhi(w.w); }
;     __device__ __forceinline__ void operator()(const f32x4 (&acc)[2][2][4][2], const Unit& u, int wr, int wc, int fr, int fq) const {
;     ...
;                 for (int bj = 0; bj < 2; ++bj) { float g[8]; unpack8(gw[m][bj], g); const f32x4 a0 = acc[ai][bj][m][0], a1 = acc[ai][bj][m][1]; float o[8];
; #pragma unroll
;                     for (int e = 0; e < 4; ++e) { o[e] = a0[e] * sigmoidf_(g[e]); o[4 + e] = a1[e] * sigmoidf_(g[4 + e]); }
;                     *(u32x4*)(T + (size_t)(row0 + ai * HALF + m * 16) * DM + col0 + bj * HALF) = (u32x4){cvt_pk_bf16(o[0], o[1]), cvt_pk_bf16(o[2], o[3]), cvt_pk_bf16(o[4], o[5]), cvt_pk_bf16(o[6], o[7])}; } }
	v_div_fmas_f32 v138, v138, v207, v139
	v_div_fixup_f32 v138, v138, v203, 1.0
	v_mul_f32_e32 v135, v135, v138
	v_cvt_pk_bf16_f32 v132, v136, v132
	v_cvt_pk_bf16_f32 v133, v133, v134
	v_cvt_pk_bf16_f32 v134, v167, v206
	v_cvt_pk_bf16_f32 v135, v137, v135
	v_lshl_add_u64 v[136:137], s[84:85], 0, v[208:209]
	v_lshl_add_u64 v[136:137], v[136:137], 0, v[164:165]
	global_store_dwordx4 v[136:137], v[132:135], off
	v_lshlrev_b32_e32 v138, 16, v154
	v_mul_f32_e32 v138, 0xbfb8aa3b, v138
	v_lshlrev_b32_e32 v132, 16, v152
	v_mul_f32_e32 v132, 0xbfb8aa3b, v132
	v_exp_f32_e32 v132, v132
	v_and_b32_e32 v133, 0xffff0000, v152
	v_exp_f32_e32 v138, v138
	v_mul_f32_e32 v133, 0xbfb8aa3b, v133
	v_add_f32_e32 v132, 1.0, v132
	v_div_scale_f32 v139, s[0:1], v132, v132, 1.0
	v_rcp_f32_e32 v152, v139
	v_add_f32_e32 v138, 1.0, v138
	v_exp_f32_e32 v133, v133
	v_lshlrev_b32_e32 v134, 16, v153
	v_fma_f32 v167, -v139, v152, 1.0
	v_fmac_f32_e32 v152, v167, v152
	v_div_scale_f32 v167, vcc, 1.0, v132, 1.0
	v_mul_f32_e32 v203, v167, v152
	v_fma_f32 v204, -v139, v203, v167
	v_fmac_f32_e32 v203, v204, v152
	v_fma_f32 v139, -v139, v203, v167
	v_div_scale_f32 v167, s[0:1], v138, v138, 1.0
	v_rcp_f32_e32 v204, v167
	v_div_fmas_f32 v139, v139, v152, v203
	v_div_fixup_f32 v132, v139, v132, 1.0
	v_mul_f32_e32 v124, v124, v132
	v_fma_f32 v132, -v167, v204, 1.0
	v_fmac_f32_e32 v204, v132, v204
	v_div_scale_f32 v132, vcc, 1.0, v138, 1.0
	v_mul_f32_e32 v139, v132, v204
	v_fma_f32 v152, -v167, v139, v132
	v_add_f32_e32 v133, 1.0, v133
	v_fmac_f32_e32 v139, v152, v204
	v_div_scale_f32 v152, s[0:1], v133, v133, 1.0
	v_fma_f32 v132, -v167, v139, v132
	v_rcp_f32_e32 v167, v152
	v_and_b32_e32 v135, 0xffff0000, v153
	v_and_b32_e32 v153, 0xffff0000, v154
	v_div_fmas_f32 v132, v132, v204, v139
	v_div_fixup_f32 v132, v132, v138, 1.0
	v_mul_f32_e32 v139, 0xbfb8aa3b, v153
	v_mul_f32_e32 v132, v120, v132
	v_fma_f32 v120, -v152, v167, 1.0
	v_exp_f32_e32 v139, v139
	v_fmac_f32_e32 v167, v120, v167
	v_div_scale_f32 v120, vcc, 1.0, v133, 1.0
	v_mul_f32_e32 v138, v120, v167
	v_fma_f32 v153, -v152, v138, v120
	v_fmac_f32_e32 v138, v153, v167
	v_add_f32_e32 v139, 1.0, v139
	v_fma_f32 v120, -v152, v138, v120
	v_div_scale_f32 v152, s[0:1], v139, v139, 1.0
	v_rcp_f32_e32 v153, v152
	v_div_fmas_f32 v120, v120, v167, v138
	v_mul_f32_e32 v134, 0xbfb8aa3b, v134
	v_div_fixup_f32 v120, v120, v133, 1.0
	v_exp_f32_e32 v134, v134
	v_mul_f32_e32 v120, v125, v120
	v_fma_f32 v125, -v152, v153, 1.0
	v_fmac_f32_e32 v153, v125, v153
	v_div_scale_f32 v125, vcc, 1.0, v139, 1.0
	v_mul_f32_e32 v133, v125, v153
	v_fma_f32 v138, -v152, v133, v125
	v_add_f32_e32 v134, 1.0, v134
	v_fmac_f32_e32 v133, v138, v153
	v_div_scale_f32 v138, s[0:1], v134, v134, 1.0
	v_fma_f32 v125, -v152, v133, v125
	v_rcp_f32_e32 v152, v138
	v_div_fmas_f32 v125, v125, v153, v133
	v_lshlrev_b32_e32 v154, 16, v155
	v_div_fixup_f32 v125, v125, v139, 1.0
	v_mul_f32_e32 v125, v121, v125
	v_fma_f32 v121, -v138, v152, 1.0
	v_mul_f32_e32 v139, 0xbfb8aa3b, v154
	v_fmac_f32_e32 v152, v121, v152
	v_div_scale_f32 v121, vcc, 1.0, v134, 1.0
	v_exp_f32_e32 v139, v139
	v_mul_f32_e32 v133, v121, v152
	v_fma_f32 v153, -v138, v133, v121
	v_fmac_f32_e32 v133, v153, v152
	v_fma_f32 v121, -v138, v133, v121
	v_add_f32_e32 v138, 1.0, v139
	v_div_scale_f32 v139, s[0:1], v138, v138, 1.0
	v_rcp_f32_e32 v153, v139
	v_div_fmas_f32 v121, v121, v152, v133
	v_div_fixup_f32 v121, v121, v134, 1.0
	v_mul_f32_e32 v134, 0xbfb8aa3b, v135
	v_exp_f32_e32 v134, v134
	v_mul_f32_e32 v121, v126, v121
	v_fma_f32 v126, -v139, v153, 1.0
	v_fmac_f32_e32 v153, v126, v153
	v_div_scale_f32 v126, vcc, 1.0, v138, 1.0
	v_mul_f32_e32 v133, v126, v153
	v_fma_f32 v135, -v139, v133, v126
	v_add_f32_e32 v134, 1.0, v134
	v_fmac_f32_e32 v133, v135, v153
	v_div_scale_f32 v135, s[0:1], v134, v134, 1.0
	v_fma_f32 v126, -v139, v133, v126
	v_rcp_f32_e32 v139, v135
	v_div_fmas_f32 v126, v126, v153, v133
	v_and_b32_e32 v155, 0xffff0000, v155
	v_div_fixup_f32 v126, v126, v138, 1.0
	v_mul_f32_e32 v126, v122, v126
	v_fma_f32 v122, -v135, v139, 1.0
	v_mul_f32_e32 v138, 0xbfb8aa3b, v155
	v_fmac_f32_e32 v139, v122, v139
	v_div_scale_f32 v122, vcc, 1.0, v134, 1.0
	v_exp_f32_e32 v138, v138
	v_mul_f32_e32 v133, v122, v139
	v_fma_f32 v152, -v135, v133, v122
	v_fmac_f32_e32 v133, v152, v139
	v_fma_f32 v122, -v135, v133, v122
	v_add_f32_e32 v135, 1.0, v138
	v_div_scale_f32 v138, s[0:1], v135, v135, 1.0
	v_rcp_f32_e32 v152, v138
	v_div_fmas_f32 v122, v122, v139, v133
	v_div_fixup_f32 v122, v122, v134, 1.0
	v_mul_f32_e32 v122, v127, v122
	v_fma_f32 v127, -v138, v152, 1.0
	v_fmac_f32_e32 v152, v127, v152
	v_div_scale_f32 v127, vcc, 1.0, v135, 1.0
	v_mul_f32_e32 v133, v127, v152
	v_fma_f32 v134, -v138, v133, v127
	v_fmac_f32_e32 v133, v134, v152
	v_fma_f32 v127, -v138, v133, v127
	v_div_fmas_f32 v127, v127, v152, v133
	v_div_fixup_f32 v127, v127, v135, 1.0
	v_mul_f32_e32 v123, v123, v127
	v_cvt_pk_bf16_f32 v120, v124, v120
	v_cvt_pk_bf16_f32 v121, v121, v122
	v_cvt_pk_bf16_f32 v122, v132, v125
	v_cvt_pk_bf16_f32 v123, v126, v123
	global_store_dwordx4 v[136:137], v[120:123], off offset:256
	v_lshlrev_b32_e32 v126, 16, v150
	v_mul_f32_e32 v126, 0xbfb8aa3b, v126
	v_lshlrev_b32_e32 v122, 16, v148
	v_mul_f32_e32 v122, 0xbfb8aa3b, v122
	v_exp_f32_e32 v122, v122
	v_exp_f32_e32 v126, v126
	v_and_b32_e32 v123, 0xffff0000, v148
	v_mul_f32_e32 v123, 0xbfb8aa3b, v123
	v_add_f32_e32 v122, 1.0, v122
	v_div_scale_f32 v127, s[0:1], v122, v122, 1.0
	v_rcp_f32_e32 v132, v127
	v_add_f32_e32 v126, 1.0, v126
	v_exp_f32_e32 v123, v123
	v_and_b32_e32 v133, 0xffff0000, v150
	v_fma_f32 v136, -v127, v132, 1.0
	v_fmac_f32_e32 v132, v136, v132
; __device__ __forceinline__ unsigned cvt_pk_bf16(float lo, float hi) { unsigned r; asm volatile("v_cvt_pk_bf16_f32 %0, %1, %2" : "=v"(r) : "v"(lo), "v"(hi)); return r; }
; __device__ __forceinline__ float sigmoidf_(float x) { return 1.f / (1.f + __expf(-x)); }
; __device__ __forceinline__ void unpack8(const u32x4& w, float (&f)[8]) { f[0] = bflo(w.x); f[1] = bfhi(w.x); f[2] = bflo(w.y); f[3] = bfhi(w.y); f[4] = bflo(w.z); f[5] = bfhi(w.z); f[6] = bflo(w.w); f[7] = bfhi(w.w); }
;     __device__ __forceinline__ void operator()(const f32x4 (&acc)[2][2][4][2], const Unit& u, int wr, int wc, int fr, int fq) const {
;     ...
;                 for (int bj = 0; bj < 2; ++bj) { float g[8]; unpack8(gw[m][bj], g); const f32x4 a0 = acc[ai][bj][m][0], a1 = acc[ai][bj][m][1]; float o[8];
; #pragma unroll
;                     for (int e = 0; e < 4; ++e) { o[e] = a0[e] * sigmoidf_(g[e]); o[4 + e] = a1[e] * sigmoidf_(g[4 + e]); }
;                     *(u32x4*)(T + (size_t)(row0 + ai * HALF + m * 16) * DM + col0 + bj * HALF) = (u32x4){cvt_pk_bf16(o[0], o[1]), cvt_pk_bf16(o[2], o[3]), cvt_pk_bf16(o[4], o[5]), cvt_pk_bf16(o[6], o[7])}; } }
	v_div_scale_f32 v136, vcc, 1.0, v122, 1.0
	v_mul_f32_e32 v137, v136, v132
	v_fma_f32 v138, -v127, v137, v136
	v_fmac_f32_e32 v137, v138, v132
	v_fma_f32 v127, -v127, v137, v136
	v_div_scale_f32 v136, s[0:1], v126, v126, 1.0
	v_rcp_f32_e32 v138, v136
	v_div_fmas_f32 v127, v127, v132, v137
	v_div_fixup_f32 v122, v127, v122, 1.0
	v_mul_f32_e32 v112, v112, v122
	v_fma_f32 v122, -v136, v138, 1.0
	v_fmac_f32_e32 v138, v122, v138
	v_div_scale_f32 v122, vcc, 1.0, v126, 1.0
	v_mul_f32_e32 v127, v122, v138
	v_fma_f32 v132, -v136, v127, v122
	v_add_f32_e32 v123, 1.0, v123
	v_fmac_f32_e32 v127, v132, v138
	v_div_scale_f32 v132, s[0:1], v123, v123, 1.0
	v_fma_f32 v122, -v136, v127, v122
	v_rcp_f32_e32 v136, v132
	v_div_fmas_f32 v122, v122, v138, v127
	v_div_fixup_f32 v122, v122, v126, 1.0
	v_mul_f32_e32 v127, 0xbfb8aa3b, v133
	v_mul_f32_e32 v122, v108, v122
	v_fma_f32 v108, -v132, v136, 1.0
	v_exp_f32_e32 v127, v127
	v_fmac_f32_e32 v136, v108, v136
	v_div_scale_f32 v108, vcc, 1.0, v123, 1.0
	v_mul_f32_e32 v126, v108, v136
	v_fma_f32 v133, -v132, v126, v108
	v_fmac_f32_e32 v126, v133, v136
	v_add_f32_e32 v127, 1.0, v127
	v_fma_f32 v108, -v132, v126, v108
	v_div_scale_f32 v132, s[0:1], v127, v127, 1.0
	v_rcp_f32_e32 v133, v132
	v_lshlrev_b32_e32 v124, 16, v149
	v_div_fmas_f32 v108, v108, v136, v126
	v_mul_f32_e32 v124, 0xbfb8aa3b, v124
	v_div_fixup_f32 v108, v108, v123, 1.0
	v_exp_f32_e32 v124, v124
	v_mul_f32_e32 v108, v113, v108
	v_fma_f32 v113, -v132, v133, 1.0
	v_fmac_f32_e32 v133, v113, v133
	v_div_scale_f32 v113, vcc, 1.0, v127, 1.0
	v_mul_f32_e32 v123, v113, v133
	v_fma_f32 v126, -v132, v123, v113
	v_add_f32_e32 v124, 1.0, v124
	v_fmac_f32_e32 v123, v126, v133
	v_div_scale_f32 v126, s[0:1], v124, v124, 1.0
	v_fma_f32 v113, -v132, v123, v113
	v_rcp_f32_e32 v132, v126
	v_div_fmas_f32 v113, v113, v133, v123
	v_lshlrev_b32_e32 v134, 16, v151
	v_div_fixup_f32 v113, v113, v127, 1.0
	v_mul_f32_e32 v113, v109, v113
	v_fma_f32 v109, -v126, v132, 1.0
	v_mul_f32_e32 v127, 0xbfb8aa3b, v134
	v_fmac_f32_e32 v132, v109, v132
	v_div_scale_f32 v109, vcc, 1.0, v124, 1.0
	v_exp_f32_e32 v127, v127
	v_mul_f32_e32 v123, v109, v132
	v_fma_f32 v133, -v126, v123, v109
	v_fmac_f32_e32 v123, v133, v132
	v_fma_f32 v109, -v126, v123, v109
	v_add_f32_e32 v126, 1.0, v127
	v_div_scale_f32 v127, s[0:1], v126, v126, 1.0
	v_rcp_f32_e32 v133, v127
	v_and_b32_e32 v125, 0xffff0000, v149
	v_div_fmas_f32 v109, v109, v132, v123
	v_div_fixup_f32 v109, v109, v124, 1.0
	v_mul_f32_e32 v124, 0xbfb8aa3b, v125
	v_exp_f32_e32 v124, v124
	v_mul_f32_e32 v109, v114, v109
	v_fma_f32 v114, -v127, v133, 1.0
	v_fmac_f32_e32 v133, v114, v133
	v_div_scale_f32 v114, vcc, 1.0, v126, 1.0
	v_mul_f32_e32 v123, v114, v133
	v_fma_f32 v125, -v127, v123, v114
	v_add_f32_e32 v124, 1.0, v124
	v_fmac_f32_e32 v123, v125, v133
	v_div_scale_f32 v125, s[0:1], v124, v124, 1.0
	v_fma_f32 v114, -v127, v123, v114
	v_rcp_f32_e32 v127, v125
	v_div_fmas_f32 v114, v114, v133, v123
	v_and_b32_e32 v135, 0xffff0000, v151
	v_div_fixup_f32 v114, v114, v126, 1.0
	v_mul_f32_e32 v114, v110, v114
	v_fma_f32 v110, -v125, v127, 1.0
	v_mul_f32_e32 v126, 0xbfb8aa3b, v135
	v_fmac_f32_e32 v127, v110, v127
	v_div_scale_f32 v110, vcc, 1.0, v124, 1.0
	v_exp_f32_e32 v126, v126
	v_mul_f32_e32 v123, v110, v127
	v_fma_f32 v132, -v125, v123, v110
	v_fmac_f32_e32 v123, v132, v127
	v_fma_f32 v110, -v125, v123, v110
	v_add_f32_e32 v125, 1.0, v126
	v_div_scale_f32 v126, s[0:1], v125, v125, 1.0
	v_rcp_f32_e32 v132, v126
	v_div_fmas_f32 v110, v110, v127, v123
	v_div_fixup_f32 v110, v110, v124, 1.0
	v_mul_f32_e32 v110, v115, v110
	v_fma_f32 v115, -v126, v132, 1.0
	v_fmac_f32_e32 v132, v115, v132
	v_div_scale_f32 v115, vcc, 1.0, v125, 1.0
	v_mul_f32_e32 v123, v115, v132
	v_fma_f32 v124, -v126, v123, v115
	v_fmac_f32_e32 v123, v124, v132
	v_fma_f32 v115, -v126, v123, v115
	v_lshlrev_b64 v[120:121], 12, v[174:175]
	v_div_fmas_f32 v115, v115, v132, v123
	v_div_fixup_f32 v115, v115, v125, 1.0
	v_cvt_pk_bf16_f32 v108, v112, v108
	v_cvt_pk_bf16_f32 v109, v109, v110
	v_cvt_pk_bf16_f32 v110, v122, v113
	v_lshl_add_u64 v[112:113], s[84:85], 0, v[120:121]
	v_mul_f32_e32 v111, v111, v115
	v_lshl_add_u64 v[112:113], v[112:113], 0, v[164:165]
	v_cvt_pk_bf16_f32 v111, v114, v111
	global_store_dwordx4 v[112:113], v[108:111], off
	v_lshlrev_b32_e32 v114, 16, v146
	v_mul_f32_e32 v114, 0xbfb8aa3b, v114
	v_lshlrev_b32_e32 v108, 16, v144
	v_mul_f32_e32 v108, 0xbfb8aa3b, v108
	v_exp_f32_e32 v108, v108
	v_exp_f32_e32 v114, v114
	v_and_b32_e32 v109, 0xffff0000, v144
	v_mul_f32_e32 v109, 0xbfb8aa3b, v109
	v_add_f32_e32 v108, 1.0, v108
	v_div_scale_f32 v115, s[0:1], v108, v108, 1.0
	v_rcp_f32_e32 v120, v115
	v_add_f32_e32 v114, 1.0, v114
	v_exp_f32_e32 v109, v109
	v_and_b32_e32 v121, 0xffff0000, v146
	v_fma_f32 v124, -v115, v120, 1.0
	v_fmac_f32_e32 v120, v124, v120
	v_div_scale_f32 v124, vcc, 1.0, v108, 1.0
	v_mul_f32_e32 v125, v124, v120
	v_fma_f32 v126, -v115, v125, v124
	v_fmac_f32_e32 v125, v126, v120
	v_fma_f32 v115, -v115, v125, v124
	v_div_scale_f32 v124, s[0:1], v114, v114, 1.0
	v_rcp_f32_e32 v126, v124
	v_div_fmas_f32 v115, v115, v120, v125
	v_div_fixup_f32 v108, v115, v108, 1.0
	v_mul_f32_e32 v100, v100, v108
	v_fma_f32 v108, -v124, v126, 1.0
	v_fmac_f32_e32 v126, v108, v126
	v_div_scale_f32 v108, vcc, 1.0, v114, 1.0
	v_mul_f32_e32 v115, v108, v126
	v_fma_f32 v120, -v124, v115, v108
	v_add_f32_e32 v109, 1.0, v109
	v_fmac_f32_e32 v115, v120, v126
	v_div_scale_f32 v120, s[0:1], v109, v109, 1.0
	v_fma_f32 v108, -v124, v115, v108
	v_rcp_f32_e32 v124, v120
	v_div_fmas_f32 v108, v108, v126, v115
	v_div_fixup_f32 v108, v108, v114, 1.0
	v_mul_f32_e32 v115, 0xbfb8aa3b, v121
; __device__ __forceinline__ unsigned cvt_pk_bf16(float lo, float hi) { unsigned r; asm volatile("v_cvt_pk_bf16_f32 %0, %1, %2" : "=v"(r) : "v"(lo), "v"(hi)); return r; }
; __device__ __forceinline__ float sigmoidf_(float x) { return 1.f / (1.f + __expf(-x)); }
; __device__ __forceinline__ void unpack8(const u32x4& w, float (&f)[8]) { f[0] = bflo(w.x); f[1] = bfhi(w.x); f[2] = bflo(w.y); f[3] = bfhi(w.y); f[4] = bflo(w.z); f[5] = bfhi(w.z); f[6] = bflo(w.w); f[7] = bfhi(w.w); }
;     __device__ __forceinline__ void operator()(const f32x4 (&acc)[2][2][4][2], const Unit& u, int wr, int wc, int fr, int fq) const {
;     ...
;                 for (int bj = 0; bj < 2; ++bj) { float g[8]; unpack8(gw[m][bj], g); const f32x4 a0 = acc[ai][bj][m][0], a1 = acc[ai][bj][m][1]; float o[8];
; #pragma unroll
;                     for (int e = 0; e < 4; ++e) { o[e] = a0[e] * sigmoidf_(g[e]); o[4 + e] = a1[e] * sigmoidf_(g[4 + e]); }
;                     *(u32x4*)(T + (size_t)(row0 + ai * HALF + m * 16) * DM + col0 + bj * HALF) = (u32x4){cvt_pk_bf16(o[0], o[1]), cvt_pk_bf16(o[2], o[3]), cvt_pk_bf16(o[4], o[5]), cvt_pk_bf16(o[6], o[7])}; } }
	v_mul_f32_e32 v108, v96, v108
	v_fma_f32 v96, -v120, v124, 1.0
	v_exp_f32_e32 v115, v115
	v_fmac_f32_e32 v124, v96, v124
	v_div_scale_f32 v96, vcc, 1.0, v109, 1.0
	v_mul_f32_e32 v114, v96, v124
	v_fma_f32 v121, -v120, v114, v96
	v_fmac_f32_e32 v114, v121, v124
	v_add_f32_e32 v115, 1.0, v115
	v_fma_f32 v96, -v120, v114, v96
	v_div_scale_f32 v120, s[0:1], v115, v115, 1.0
	v_rcp_f32_e32 v121, v120
	v_lshlrev_b32_e32 v110, 16, v145
	v_div_fmas_f32 v96, v96, v124, v114
	v_mul_f32_e32 v110, 0xbfb8aa3b, v110
	v_div_fixup_f32 v96, v96, v109, 1.0
	v_exp_f32_e32 v110, v110
	v_mul_f32_e32 v96, v101, v96
	v_fma_f32 v101, -v120, v121, 1.0
	v_fmac_f32_e32 v121, v101, v121
	v_div_scale_f32 v101, vcc, 1.0, v115, 1.0
	v_mul_f32_e32 v109, v101, v121
	v_fma_f32 v114, -v120, v109, v101
	v_add_f32_e32 v110, 1.0, v110
	v_fmac_f32_e32 v109, v114, v121
	v_div_scale_f32 v114, s[0:1], v110, v110, 1.0
	v_fma_f32 v101, -v120, v109, v101
	v_rcp_f32_e32 v120, v114
	v_div_fmas_f32 v101, v101, v121, v109
	v_lshlrev_b32_e32 v122, 16, v147
	v_div_fixup_f32 v101, v101, v115, 1.0
	v_mul_f32_e32 v101, v97, v101
	v_fma_f32 v97, -v114, v120, 1.0
	v_mul_f32_e32 v115, 0xbfb8aa3b, v122
	v_fmac_f32_e32 v120, v97, v120
	v_div_scale_f32 v97, vcc, 1.0, v110, 1.0
	v_exp_f32_e32 v115, v115
	v_mul_f32_e32 v109, v97, v120
	v_fma_f32 v121, -v114, v109, v97
	v_fmac_f32_e32 v109, v121, v120
	v_fma_f32 v97, -v114, v109, v97
	v_add_f32_e32 v114, 1.0, v115
	v_div_scale_f32 v115, s[0:1], v114, v114, 1.0
	v_rcp_f32_e32 v121, v115
	v_and_b32_e32 v111, 0xffff0000, v145
	v_div_fmas_f32 v97, v97, v120, v109
	v_div_fixup_f32 v97, v97, v110, 1.0
	v_mul_f32_e32 v110, 0xbfb8aa3b, v111
	v_exp_f32_e32 v110, v110
	v_mul_f32_e32 v97, v102, v97
	v_fma_f32 v102, -v115, v121, 1.0
	v_fmac_f32_e32 v121, v102, v121
	v_div_scale_f32 v102, vcc, 1.0, v114, 1.0
	v_mul_f32_e32 v109, v102, v121
	v_fma_f32 v111, -v115, v109, v102
	v_add_f32_e32 v110, 1.0, v110
	v_fmac_f32_e32 v109, v111, v121
	v_div_scale_f32 v111, s[0:1], v110, v110, 1.0
	v_fma_f32 v102, -v115, v109, v102
	v_rcp_f32_e32 v115, v111
	v_div_fmas_f32 v102, v102, v121, v109
	v_and_b32_e32 v123, 0xffff0000, v147
	v_div_fixup_f32 v102, v102, v114, 1.0
	v_mul_f32_e32 v102, v98, v102
	v_fma_f32 v98, -v111, v115, 1.0
	v_mul_f32_e32 v114, 0xbfb8aa3b, v123
	v_fmac_f32_e32 v115, v98, v115
	v_div_scale_f32 v98, vcc, 1.0, v110, 1.0
	v_exp_f32_e32 v114, v114
	v_mul_f32_e32 v109, v98, v115
	v_fma_f32 v120, -v111, v109, v98
	v_fmac_f32_e32 v109, v120, v115
	v_fma_f32 v98, -v111, v109, v98
	v_add_f32_e32 v111, 1.0, v114
	v_div_scale_f32 v114, s[0:1], v111, v111, 1.0
	v_rcp_f32_e32 v120, v114
	v_div_fmas_f32 v98, v98, v115, v109
	v_div_fixup_f32 v98, v98, v110, 1.0
	v_mul_f32_e32 v98, v103, v98
	v_fma_f32 v103, -v114, v120, 1.0
	v_fmac_f32_e32 v120, v103, v120
	v_div_scale_f32 v103, vcc, 1.0, v111, 1.0
	v_mul_f32_e32 v109, v103, v120
	v_fma_f32 v110, -v114, v109, v103
	v_fmac_f32_e32 v109, v110, v120
	v_fma_f32 v103, -v114, v109, v103
	v_div_fmas_f32 v103, v103, v120, v109
	v_div_fixup_f32 v103, v103, v111, 1.0
	v_mul_f32_e32 v99, v99, v103
	v_cvt_pk_bf16_f32 v96, v100, v96
	v_cvt_pk_bf16_f32 v97, v97, v98
	v_cvt_pk_bf16_f32 v98, v108, v101
	v_cvt_pk_bf16_f32 v99, v102, v99
	global_store_dwordx4 v[112:113], v[96:99], off offset:256
	v_lshlrev_b32_e32 v102, 16, v142
	v_mul_f32_e32 v102, 0xbfb8aa3b, v102
	v_lshlrev_b32_e32 v98, 16, v140
	v_mul_f32_e32 v98, 0xbfb8aa3b, v98
	v_exp_f32_e32 v98, v98
	v_exp_f32_e32 v102, v102
	v_and_b32_e32 v99, 0xffff0000, v140
	v_mul_f32_e32 v99, 0xbfb8aa3b, v99
	v_add_f32_e32 v98, 1.0, v98
	v_div_scale_f32 v103, s[0:1], v98, v98, 1.0
	v_rcp_f32_e32 v108, v103
	v_add_f32_e32 v102, 1.0, v102
	v_exp_f32_e32 v99, v99
	v_and_b32_e32 v109, 0xffff0000, v142
	v_fma_f32 v112, -v103, v108, 1.0
	v_fmac_f32_e32 v108, v112, v108
	v_div_scale_f32 v112, vcc, 1.0, v98, 1.0
	v_mul_f32_e32 v113, v112, v108
	v_fma_f32 v114, -v103, v113, v112
	v_fmac_f32_e32 v113, v114, v108
	v_fma_f32 v103, -v103, v113, v112
	v_div_scale_f32 v112, s[0:1], v102, v102, 1.0
	v_rcp_f32_e32 v114, v112
	v_div_fmas_f32 v103, v103, v108, v113
	v_div_fixup_f32 v98, v103, v98, 1.0
	v_mul_f32_e32 v92, v92, v98
	v_fma_f32 v98, -v112, v114, 1.0
	v_fmac_f32_e32 v114, v98, v114
	v_div_scale_f32 v98, vcc, 1.0, v102, 1.0
	v_mul_f32_e32 v103, v98, v114
	v_fma_f32 v108, -v112, v103, v98
	v_add_f32_e32 v99, 1.0, v99
	v_fmac_f32_e32 v103, v108, v114
	v_div_scale_f32 v108, s[0:1], v99, v99, 1.0
	v_fma_f32 v98, -v112, v103, v98
	v_rcp_f32_e32 v112, v108
	v_div_fmas_f32 v98, v98, v114, v103
	v_div_fixup_f32 v98, v98, v102, 1.0
	v_mul_f32_e32 v103, 0xbfb8aa3b, v109
	v_mul_f32_e32 v98, v88, v98
	v_fma_f32 v88, -v108, v112, 1.0
	v_exp_f32_e32 v103, v103
	v_fmac_f32_e32 v112, v88, v112
	v_div_scale_f32 v88, vcc, 1.0, v99, 1.0
	v_mul_f32_e32 v102, v88, v112
	v_fma_f32 v109, -v108, v102, v88
	v_fmac_f32_e32 v102, v109, v112
	v_add_f32_e32 v103, 1.0, v103
	v_fma_f32 v88, -v108, v102, v88
	v_div_scale_f32 v108, s[0:1], v103, v103, 1.0
	v_rcp_f32_e32 v109, v108
	v_lshlrev_b32_e32 v100, 16, v141
	v_div_fmas_f32 v88, v88, v112, v102
	v_mul_f32_e32 v100, 0xbfb8aa3b, v100
	v_div_fixup_f32 v88, v88, v99, 1.0
	v_exp_f32_e32 v100, v100
	v_mul_f32_e32 v88, v93, v88
	v_fma_f32 v93, -v108, v109, 1.0
	v_fmac_f32_e32 v109, v93, v109
	v_div_scale_f32 v93, vcc, 1.0, v103, 1.0
	v_mul_f32_e32 v99, v93, v109
	v_fma_f32 v102, -v108, v99, v93
	v_add_f32_e32 v100, 1.0, v100
	v_fmac_f32_e32 v99, v102, v109
	v_div_scale_f32 v102, s[0:1], v100, v100, 1.0
	v_fma_f32 v93, -v108, v99, v93
	v_rcp_f32_e32 v108, v102
	v_div_fmas_f32 v93, v93, v109, v99
	v_lshlrev_b32_e32 v110, 16, v143
	v_div_fixup_f32 v93, v93, v103, 1.0
; __device__ __forceinline__ unsigned cvt_pk_bf16(float lo, float hi) { unsigned r; asm volatile("v_cvt_pk_bf16_f32 %0, %1, %2" : "=v"(r) : "v"(lo), "v"(hi)); return r; }
; __device__ __forceinline__ float sigmoidf_(float x) { return 1.f / (1.f + __expf(-x)); }
; __device__ __forceinline__ void unpack8(const u32x4& w, float (&f)[8]) { f[0] = bflo(w.x); f[1] = bfhi(w.x); f[2] = bflo(w.y); f[3] = bfhi(w.y); f[4] = bflo(w.z); f[5] = bfhi(w.z); f[6] = bflo(w.w); f[7] = bfhi(w.w); }
;     __device__ __forceinline__ void operator()(const f32x4 (&acc)[2][2][4][2], const Unit& u, int wr, int wc, int fr, int fq) const {
;     ...
;                 for (int bj = 0; bj < 2; ++bj) { float g[8]; unpack8(gw[m][bj], g); const f32x4 a0 = acc[ai][bj][m][0], a1 = acc[ai][bj][m][1]; float o[8];
; #pragma unroll
;                     for (int e = 0; e < 4; ++e) { o[e] = a0[e] * sigmoidf_(g[e]); o[4 + e] = a1[e] * sigmoidf_(g[4 + e]); }
;                     *(u32x4*)(T + (size_t)(row0 + ai * HALF + m * 16) * DM + col0 + bj * HALF) = (u32x4){cvt_pk_bf16(o[0], o[1]), cvt_pk_bf16(o[2], o[3]), cvt_pk_bf16(o[4], o[5]), cvt_pk_bf16(o[6], o[7])}; } }
	v_mul_f32_e32 v93, v89, v93
	v_fma_f32 v89, -v102, v108, 1.0
	v_mul_f32_e32 v103, 0xbfb8aa3b, v110
	v_fmac_f32_e32 v108, v89, v108
	v_div_scale_f32 v89, vcc, 1.0, v100, 1.0
	v_exp_f32_e32 v103, v103
	v_mul_f32_e32 v99, v89, v108
	v_fma_f32 v109, -v102, v99, v89
	v_fmac_f32_e32 v99, v109, v108
	v_fma_f32 v89, -v102, v99, v89
	v_add_f32_e32 v102, 1.0, v103
	v_div_scale_f32 v103, s[0:1], v102, v102, 1.0
	v_rcp_f32_e32 v109, v103
	v_and_b32_e32 v101, 0xffff0000, v141
	v_div_fmas_f32 v89, v89, v108, v99
	v_div_fixup_f32 v89, v89, v100, 1.0
	v_mul_f32_e32 v100, 0xbfb8aa3b, v101
	v_exp_f32_e32 v100, v100
	v_mul_f32_e32 v89, v94, v89
	v_fma_f32 v94, -v103, v109, 1.0
	v_fmac_f32_e32 v109, v94, v109
	v_div_scale_f32 v94, vcc, 1.0, v102, 1.0
	v_mul_f32_e32 v99, v94, v109
	v_fma_f32 v101, -v103, v99, v94
	v_add_f32_e32 v100, 1.0, v100
	v_fmac_f32_e32 v99, v101, v109
	v_div_scale_f32 v101, s[0:1], v100, v100, 1.0
	v_fma_f32 v94, -v103, v99, v94
	v_rcp_f32_e32 v103, v101
	v_div_fmas_f32 v94, v94, v109, v99
	v_and_b32_e32 v111, 0xffff0000, v143
	v_div_fixup_f32 v94, v94, v102, 1.0
	v_mul_f32_e32 v94, v90, v94
	v_fma_f32 v90, -v101, v103, 1.0
	v_mul_f32_e32 v102, 0xbfb8aa3b, v111
	v_fmac_f32_e32 v103, v90, v103
	v_div_scale_f32 v90, vcc, 1.0, v100, 1.0
	v_exp_f32_e32 v102, v102
	v_mul_f32_e32 v99, v90, v103
	v_fma_f32 v108, -v101, v99, v90
	v_fmac_f32_e32 v99, v108, v103
	v_fma_f32 v90, -v101, v99, v90
	v_add_f32_e32 v101, 1.0, v102
	v_div_scale_f32 v102, s[0:1], v101, v101, 1.0
	v_rcp_f32_e32 v108, v102
	v_div_fmas_f32 v90, v90, v103, v99
	v_div_fixup_f32 v90, v90, v100, 1.0
	v_mul_f32_e32 v90, v95, v90
	v_fma_f32 v95, -v102, v108, 1.0
	v_fmac_f32_e32 v108, v95, v108
	v_div_scale_f32 v95, vcc, 1.0, v101, 1.0
	v_mul_f32_e32 v99, v95, v108
	v_fma_f32 v100, -v102, v99, v95
	v_fmac_f32_e32 v99, v100, v108
	v_fma_f32 v95, -v102, v99, v95
	v_lshlrev_b64 v[96:97], 12, v[172:173]
	v_div_fmas_f32 v95, v95, v108, v99
	v_div_fixup_f32 v95, v95, v101, 1.0
	v_cvt_pk_bf16_f32 v88, v92, v88
	v_cvt_pk_bf16_f32 v89, v89, v90
	v_cvt_pk_bf16_f32 v90, v98, v93
	v_lshl_add_u64 v[92:93], s[84:85], 0, v[96:97]
	v_mul_f32_e32 v91, v91, v95
	v_lshl_add_u64 v[92:93], v[92:93], 0, v[164:165]
	v_cvt_pk_bf16_f32 v91, v94, v91
	global_store_dwordx4 v[92:93], v[88:91], off
	v_lshlrev_b32_e32 v94, 16, v130
	v_mul_f32_e32 v94, 0xbfb8aa3b, v94
	v_lshlrev_b32_e32 v88, 16, v128
	v_mul_f32_e32 v88, 0xbfb8aa3b, v88
	v_exp_f32_e32 v88, v88
	v_exp_f32_e32 v94, v94
	v_and_b32_e32 v89, 0xffff0000, v128
	v_mul_f32_e32 v89, 0xbfb8aa3b, v89
	v_add_f32_e32 v88, 1.0, v88
	v_div_scale_f32 v95, s[0:1], v88, v88, 1.0
	v_rcp_f32_e32 v96, v95
	v_add_f32_e32 v94, 1.0, v94
	v_exp_f32_e32 v89, v89
	v_and_b32_e32 v97, 0xffff0000, v130
	v_fma_f32 v100, -v95, v96, 1.0
	v_fmac_f32_e32 v96, v100, v96
	v_div_scale_f32 v100, vcc, 1.0, v88, 1.0
	v_mul_f32_e32 v101, v100, v96
	v_fma_f32 v102, -v95, v101, v100
	v_fmac_f32_e32 v101, v102, v96
	v_fma_f32 v95, -v95, v101, v100
	v_div_scale_f32 v100, s[0:1], v94, v94, 1.0
	v_rcp_f32_e32 v102, v100
	v_div_fmas_f32 v95, v95, v96, v101
	v_div_fixup_f32 v88, v95, v88, 1.0
	v_mul_f32_e32 v84, v84, v88
	v_fma_f32 v88, -v100, v102, 1.0
	v_fmac_f32_e32 v102, v88, v102
	v_div_scale_f32 v88, vcc, 1.0, v94, 1.0
	v_mul_f32_e32 v95, v88, v102
	v_fma_f32 v96, -v100, v95, v88
	v_add_f32_e32 v89, 1.0, v89
	v_fmac_f32_e32 v95, v96, v102
	v_div_scale_f32 v96, s[0:1], v89, v89, 1.0
	v_fma_f32 v88, -v100, v95, v88
	v_rcp_f32_e32 v100, v96
	v_div_fmas_f32 v88, v88, v102, v95
	v_div_fixup_f32 v88, v88, v94, 1.0
	v_mul_f32_e32 v95, 0xbfb8aa3b, v97
	v_mul_f32_e32 v88, v80, v88
	v_fma_f32 v80, -v96, v100, 1.0
	v_exp_f32_e32 v95, v95
	v_fmac_f32_e32 v100, v80, v100
	v_div_scale_f32 v80, vcc, 1.0, v89, 1.0
	v_mul_f32_e32 v94, v80, v100
	v_fma_f32 v97, -v96, v94, v80
	v_fmac_f32_e32 v94, v97, v100
	v_add_f32_e32 v95, 1.0, v95
	v_fma_f32 v80, -v96, v94, v80
	v_div_scale_f32 v96, s[0:1], v95, v95, 1.0
	v_rcp_f32_e32 v97, v96
	v_lshlrev_b32_e32 v90, 16, v129
	v_div_fmas_f32 v80, v80, v100, v94
	v_mul_f32_e32 v90, 0xbfb8aa3b, v90
	v_div_fixup_f32 v80, v80, v89, 1.0
	v_exp_f32_e32 v90, v90
	v_mul_f32_e32 v80, v85, v80
	v_fma_f32 v85, -v96, v97, 1.0
	v_fmac_f32_e32 v97, v85, v97
	v_div_scale_f32 v85, vcc, 1.0, v95, 1.0
	v_mul_f32_e32 v89, v85, v97
	v_fma_f32 v94, -v96, v89, v85
	v_add_f32_e32 v90, 1.0, v90
	v_fmac_f32_e32 v89, v94, v97
	v_div_scale_f32 v94, s[0:1], v90, v90, 1.0
	v_fma_f32 v85, -v96, v89, v85
	v_rcp_f32_e32 v96, v94
	v_div_fmas_f32 v85, v85, v97, v89
	v_lshlrev_b32_e32 v98, 16, v131
	v_div_fixup_f32 v85, v85, v95, 1.0
	v_mul_f32_e32 v85, v81, v85
	v_fma_f32 v81, -v94, v96, 1.0
	v_mul_f32_e32 v95, 0xbfb8aa3b, v98
	v_fmac_f32_e32 v96, v81, v96
	v_div_scale_f32 v81, vcc, 1.0, v90, 1.0
	v_exp_f32_e32 v95, v95
	v_mul_f32_e32 v89, v81, v96
	v_fma_f32 v97, -v94, v89, v81
	v_fmac_f32_e32 v89, v97, v96
	v_fma_f32 v81, -v94, v89, v81
	v_add_f32_e32 v94, 1.0, v95
	v_div_scale_f32 v95, s[0:1], v94, v94, 1.0
	v_rcp_f32_e32 v97, v95
	v_and_b32_e32 v91, 0xffff0000, v129
	v_div_fmas_f32 v81, v81, v96, v89
	v_div_fixup_f32 v81, v81, v90, 1.0
	v_mul_f32_e32 v90, 0xbfb8aa3b, v91
	v_exp_f32_e32 v90, v90
	v_mul_f32_e32 v81, v86, v81
	v_fma_f32 v86, -v95, v97, 1.0
	v_fmac_f32_e32 v97, v86, v97
	v_div_scale_f32 v86, vcc, 1.0, v94, 1.0
	v_mul_f32_e32 v89, v86, v97
	v_fma_f32 v91, -v95, v89, v86
	v_add_f32_e32 v90, 1.0, v90
	v_fmac_f32_e32 v89, v91, v97
	v_div_scale_f32 v91, s[0:1], v90, v90, 1.0
	v_fma_f32 v86, -v95, v89, v86
	v_rcp_f32_e32 v95, v91
	v_div_fmas_f32 v86, v86, v97, v89
	v_and_b32_e32 v99, 0xffff0000, v131
	v_div_fixup_f32 v86, v86, v94, 1.0
	v_mul_f32_e32 v86, v82, v86
	v_fma_f32 v82, -v91, v95, 1.0
; __device__ __forceinline__ unsigned cvt_pk_bf16(float lo, float hi) { unsigned r; asm volatile("v_cvt_pk_bf16_f32 %0, %1, %2" : "=v"(r) : "v"(lo), "v"(hi)); return r; }
; __device__ __forceinline__ float sigmoidf_(float x) { return 1.f / (1.f + __expf(-x)); }
; __device__ __forceinline__ void unpack8(const u32x4& w, float (&f)[8]) { f[0] = bflo(w.x); f[1] = bfhi(w.x); f[2] = bflo(w.y); f[3] = bfhi(w.y); f[4] = bflo(w.z); f[5] = bfhi(w.z); f[6] = bflo(w.w); f[7] = bfhi(w.w); }
;     __device__ __forceinline__ void operator()(const f32x4 (&acc)[2][2][4][2], const Unit& u, int wr, int wc, int fr, int fq) const {
;     ...
;                 for (int bj = 0; bj < 2; ++bj) { float g[8]; unpack8(gw[m][bj], g); const f32x4 a0 = acc[ai][bj][m][0], a1 = acc[ai][bj][m][1]; float o[8];
; #pragma unroll
;                     for (int e = 0; e < 4; ++e) { o[e] = a0[e] * sigmoidf_(g[e]); o[4 + e] = a1[e] * sigmoidf_(g[4 + e]); }
;                     *(u32x4*)(T + (size_t)(row0 + ai * HALF + m * 16) * DM + col0 + bj * HALF) = (u32x4){cvt_pk_bf16(o[0], o[1]), cvt_pk_bf16(o[2], o[3]), cvt_pk_bf16(o[4], o[5]), cvt_pk_bf16(o[6], o[7])}; } }
	v_mul_f32_e32 v94, 0xbfb8aa3b, v99
	v_fmac_f32_e32 v95, v82, v95
	v_div_scale_f32 v82, vcc, 1.0, v90, 1.0
	v_exp_f32_e32 v94, v94
	v_mul_f32_e32 v89, v82, v95
	v_fma_f32 v96, -v91, v89, v82
	v_fmac_f32_e32 v89, v96, v95
	v_fma_f32 v82, -v91, v89, v82
	v_add_f32_e32 v91, 1.0, v94
	v_div_scale_f32 v94, s[0:1], v91, v91, 1.0
	v_rcp_f32_e32 v96, v94
	v_div_fmas_f32 v82, v82, v95, v89
	v_div_fixup_f32 v82, v82, v90, 1.0
	v_mul_f32_e32 v82, v87, v82
	v_fma_f32 v87, -v94, v96, 1.0
	v_fmac_f32_e32 v96, v87, v96
	v_div_scale_f32 v87, vcc, 1.0, v91, 1.0
	v_mul_f32_e32 v89, v87, v96
	v_fma_f32 v90, -v94, v89, v87
	v_fmac_f32_e32 v89, v90, v96
	v_fma_f32 v87, -v94, v89, v87
	v_div_fmas_f32 v87, v87, v96, v89
	v_div_fixup_f32 v87, v87, v91, 1.0
	v_mul_f32_e32 v83, v83, v87
	v_cvt_pk_bf16_f32 v80, v84, v80
	v_cvt_pk_bf16_f32 v81, v81, v82
	v_cvt_pk_bf16_f32 v82, v88, v85
	v_cvt_pk_bf16_f32 v83, v86, v83
	global_store_dwordx4 v[92:93], v[80:83], off offset:256
	v_lshlrev_b32_e32 v86, 16, v118
	v_mul_f32_e32 v86, 0xbfb8aa3b, v86
	v_lshlrev_b32_e32 v82, 16, v116
	v_mul_f32_e32 v82, 0xbfb8aa3b, v82
	v_exp_f32_e32 v82, v82
	v_exp_f32_e32 v86, v86
	v_and_b32_e32 v83, 0xffff0000, v116
	v_mul_f32_e32 v83, 0xbfb8aa3b, v83
	v_add_f32_e32 v82, 1.0, v82
	v_div_scale_f32 v87, s[0:1], v82, v82, 1.0
	v_rcp_f32_e32 v88, v87
	v_add_f32_e32 v86, 1.0, v86
	v_exp_f32_e32 v83, v83
	v_and_b32_e32 v89, 0xffff0000, v118
	v_fma_f32 v92, -v87, v88, 1.0
	v_fmac_f32_e32 v88, v92, v88
	v_div_scale_f32 v92, vcc, 1.0, v82, 1.0
	v_mul_f32_e32 v93, v92, v88
	v_fma_f32 v94, -v87, v93, v92
	v_fmac_f32_e32 v93, v94, v88
	v_fma_f32 v87, -v87, v93, v92
	v_div_scale_f32 v92, s[0:1], v86, v86, 1.0
	v_rcp_f32_e32 v94, v92
	v_div_fmas_f32 v87, v87, v88, v93
	v_div_fixup_f32 v82, v87, v82, 1.0
	v_mul_f32_e32 v76, v76, v82
	v_fma_f32 v82, -v92, v94, 1.0
	v_fmac_f32_e32 v94, v82, v94
	v_div_scale_f32 v82, vcc, 1.0, v86, 1.0
	v_mul_f32_e32 v87, v82, v94
	v_fma_f32 v88, -v92, v87, v82
	v_add_f32_e32 v83, 1.0, v83
	v_fmac_f32_e32 v87, v88, v94
	v_div_scale_f32 v88, s[0:1], v83, v83, 1.0
	v_fma_f32 v82, -v92, v87, v82
	v_rcp_f32_e32 v92, v88
	v_div_fmas_f32 v82, v82, v94, v87
	v_div_fixup_f32 v82, v82, v86, 1.0
	v_mul_f32_e32 v87, 0xbfb8aa3b, v89
	v_mul_f32_e32 v82, v72, v82
	v_fma_f32 v72, -v88, v92, 1.0
	v_exp_f32_e32 v87, v87
	v_fmac_f32_e32 v92, v72, v92
	v_div_scale_f32 v72, vcc, 1.0, v83, 1.0
	v_mul_f32_e32 v86, v72, v92
	v_fma_f32 v89, -v88, v86, v72
	v_fmac_f32_e32 v86, v89, v92
	v_add_f32_e32 v87, 1.0, v87
	v_fma_f32 v72, -v88, v86, v72
	v_div_scale_f32 v88, s[0:1], v87, v87, 1.0
	v_rcp_f32_e32 v89, v88
	v_lshlrev_b32_e32 v84, 16, v117
	v_div_fmas_f32 v72, v72, v92, v86
	v_mul_f32_e32 v84, 0xbfb8aa3b, v84
	v_div_fixup_f32 v72, v72, v83, 1.0
	v_exp_f32_e32 v84, v84
	v_mul_f32_e32 v72, v77, v72
	v_fma_f32 v77, -v88, v89, 1.0
	v_fmac_f32_e32 v89, v77, v89
	v_div_scale_f32 v77, vcc, 1.0, v87, 1.0
	v_mul_f32_e32 v83, v77, v89
	v_fma_f32 v86, -v88, v83, v77
	v_add_f32_e32 v84, 1.0, v84
	v_fmac_f32_e32 v83, v86, v89
	v_div_scale_f32 v86, s[0:1], v84, v84, 1.0
	v_fma_f32 v77, -v88, v83, v77
	v_rcp_f32_e32 v88, v86
	v_div_fmas_f32 v77, v77, v89, v83
	v_lshlrev_b32_e32 v90, 16, v119
	v_div_fixup_f32 v77, v77, v87, 1.0
	v_mul_f32_e32 v77, v73, v77
	v_fma_f32 v73, -v86, v88, 1.0
	v_mul_f32_e32 v87, 0xbfb8aa3b, v90
	v_fmac_f32_e32 v88, v73, v88
	v_div_scale_f32 v73, vcc, 1.0, v84, 1.0
	v_exp_f32_e32 v87, v87
	v_mul_f32_e32 v83, v73, v88
	v_fma_f32 v89, -v86, v83, v73
	v_fmac_f32_e32 v83, v89, v88
	v_fma_f32 v73, -v86, v83, v73
	v_add_f32_e32 v86, 1.0, v87
	v_div_scale_f32 v87, s[0:1], v86, v86, 1.0
	v_rcp_f32_e32 v89, v87
	v_and_b32_e32 v85, 0xffff0000, v117
	v_div_fmas_f32 v73, v73, v88, v83
	v_div_fixup_f32 v73, v73, v84, 1.0
	v_mul_f32_e32 v84, 0xbfb8aa3b, v85
	v_exp_f32_e32 v84, v84
	v_mul_f32_e32 v73, v78, v73
	v_fma_f32 v78, -v87, v89, 1.0
	v_fmac_f32_e32 v89, v78, v89
	v_div_scale_f32 v78, vcc, 1.0, v86, 1.0
	v_mul_f32_e32 v83, v78, v89
	v_fma_f32 v85, -v87, v83, v78
	v_add_f32_e32 v84, 1.0, v84
	v_fmac_f32_e32 v83, v85, v89
	v_div_scale_f32 v85, s[0:1], v84, v84, 1.0
	v_fma_f32 v78, -v87, v83, v78
	v_rcp_f32_e32 v87, v85
	v_div_fmas_f32 v78, v78, v89, v83
	v_and_b32_e32 v91, 0xffff0000, v119
	v_div_fixup_f32 v78, v78, v86, 1.0
	v_mul_f32_e32 v78, v74, v78
	v_fma_f32 v74, -v85, v87, 1.0
	v_mul_f32_e32 v86, 0xbfb8aa3b, v91
	v_fmac_f32_e32 v87, v74, v87
	v_div_scale_f32 v74, vcc, 1.0, v84, 1.0
	v_exp_f32_e32 v86, v86
	v_mul_f32_e32 v83, v74, v87
	v_fma_f32 v88, -v85, v83, v74
	v_fmac_f32_e32 v83, v88, v87
	v_fma_f32 v74, -v85, v83, v74
	v_add_f32_e32 v85, 1.0, v86
	v_div_scale_f32 v86, s[0:1], v85, v85, 1.0
	v_rcp_f32_e32 v88, v86
	v_div_fmas_f32 v74, v74, v87, v83
	v_div_fixup_f32 v74, v74, v84, 1.0
	v_mul_f32_e32 v74, v79, v74
	v_fma_f32 v79, -v86, v88, 1.0
	v_fmac_f32_e32 v88, v79, v88
	v_div_scale_f32 v79, vcc, 1.0, v85, 1.0
	v_mul_f32_e32 v83, v79, v88
	v_fma_f32 v84, -v86, v83, v79
	v_fmac_f32_e32 v83, v84, v88
	v_fma_f32 v79, -v86, v83, v79
	v_lshlrev_b64 v[80:81], 12, v[170:171]
	v_div_fmas_f32 v79, v79, v88, v83
	v_div_fixup_f32 v79, v79, v85, 1.0
	v_cvt_pk_bf16_f32 v72, v76, v72
	v_cvt_pk_bf16_f32 v73, v73, v74
	v_cvt_pk_bf16_f32 v74, v82, v77
	v_lshl_add_u64 v[76:77], s[84:85], 0, v[80:81]
	v_mul_f32_e32 v75, v75, v79
	v_lshl_add_u64 v[76:77], v[76:77], 0, v[164:165]
	v_cvt_pk_bf16_f32 v75, v78, v75
	global_store_dwordx4 v[76:77], v[72:75], off
	v_lshlrev_b32_e32 v78, 16, v106
	v_mul_f32_e32 v78, 0xbfb8aa3b, v78
	v_lshlrev_b32_e32 v72, 16, v104
	v_mul_f32_e32 v72, 0xbfb8aa3b, v72
	v_exp_f32_e32 v72, v72
	v_exp_f32_e32 v78, v78
	v_and_b32_e32 v73, 0xffff0000, v104
	v_mul_f32_e32 v73, 0xbfb8aa3b, v73
; __device__ __forceinline__ unsigned cvt_pk_bf16(float lo, float hi) { unsigned r; asm volatile("v_cvt_pk_bf16_f32 %0, %1, %2" : "=v"(r) : "v"(lo), "v"(hi)); return r; }
; __device__ __forceinline__ float sigmoidf_(float x) { return 1.f / (1.f + __expf(-x)); }
; __device__ __forceinline__ void unpack8(const u32x4& w, float (&f)[8]) { f[0] = bflo(w.x); f[1] = bfhi(w.x); f[2] = bflo(w.y); f[3] = bfhi(w.y); f[4] = bflo(w.z); f[5] = bfhi(w.z); f[6] = bflo(w.w); f[7] = bfhi(w.w); }
;     __device__ __forceinline__ void operator()(const f32x4 (&acc)[2][2][4][2], const Unit& u, int wr, int wc, int fr, int fq) const {
;     ...
;                 for (int bj = 0; bj < 2; ++bj) gw[m][bj] = *(const u32x4*)(gate + (size_t)(row0 + ai * HALF + m * 16) * ldg + col0 + bj * HALF);
; #pragma unroll
;             for (int m = 0; m < 4; ++m)
; #pragma unroll
;                 for (int bj = 0; bj < 2; ++bj) { float g[8]; unpack8(gw[m][bj], g); const f32x4 a0 = acc[ai][bj][m][0], a1 = acc[ai][bj][m][1]; float o[8];
; #pragma unroll
;                     for (int e = 0; e < 4; ++e) { o[e] = a0[e] * sigmoidf_(g[e]); o[4 + e] = a1[e] * sigmoidf_(g[4 + e]); }
;                     *(u32x4*)(T + (size_t)(row0 + ai * HALF + m * 16) * DM + col0 + bj * HALF) = (u32x4){cvt_pk_bf16(o[0], o[1]), cvt_pk_bf16(o[2], o[3]), cvt_pk_bf16(o[4], o[5]), cvt_pk_bf16(o[6], o[7])}; } }
	v_add_f32_e32 v72, 1.0, v72
	v_div_scale_f32 v79, s[0:1], v72, v72, 1.0
	v_rcp_f32_e32 v80, v79
	v_add_f32_e32 v78, 1.0, v78
	v_exp_f32_e32 v73, v73
	v_and_b32_e32 v81, 0xffff0000, v106
	v_fma_f32 v84, -v79, v80, 1.0
	v_fmac_f32_e32 v80, v84, v80
	v_div_scale_f32 v84, vcc, 1.0, v72, 1.0
	v_mul_f32_e32 v85, v84, v80
	v_fma_f32 v86, -v79, v85, v84
	v_fmac_f32_e32 v85, v86, v80
	v_fma_f32 v79, -v79, v85, v84
	v_div_scale_f32 v84, s[0:1], v78, v78, 1.0
	v_rcp_f32_e32 v86, v84
	v_div_fmas_f32 v79, v79, v80, v85
	v_div_fixup_f32 v72, v79, v72, 1.0
	v_mul_f32_e32 v68, v68, v72
	v_fma_f32 v72, -v84, v86, 1.0
	v_fmac_f32_e32 v86, v72, v86
	v_div_scale_f32 v72, vcc, 1.0, v78, 1.0
	v_mul_f32_e32 v79, v72, v86
	v_fma_f32 v80, -v84, v79, v72
	v_add_f32_e32 v73, 1.0, v73
	v_fmac_f32_e32 v79, v80, v86
	v_div_scale_f32 v80, s[0:1], v73, v73, 1.0
	v_fma_f32 v72, -v84, v79, v72
	v_rcp_f32_e32 v84, v80
	v_div_fmas_f32 v72, v72, v86, v79
	v_div_fixup_f32 v72, v72, v78, 1.0
	v_mul_f32_e32 v79, 0xbfb8aa3b, v81
	v_mul_f32_e32 v72, v64, v72
	v_fma_f32 v64, -v80, v84, 1.0
	v_exp_f32_e32 v79, v79
	v_fmac_f32_e32 v84, v64, v84
	v_div_scale_f32 v64, vcc, 1.0, v73, 1.0
	v_mul_f32_e32 v78, v64, v84
	v_fma_f32 v81, -v80, v78, v64
	v_fmac_f32_e32 v78, v81, v84
	v_add_f32_e32 v79, 1.0, v79
	v_fma_f32 v64, -v80, v78, v64
	v_div_scale_f32 v80, s[0:1], v79, v79, 1.0
	v_rcp_f32_e32 v81, v80
	v_lshlrev_b32_e32 v74, 16, v105
	v_div_fmas_f32 v64, v64, v84, v78
	v_mul_f32_e32 v74, 0xbfb8aa3b, v74
	v_div_fixup_f32 v64, v64, v73, 1.0
	v_exp_f32_e32 v74, v74
	v_mul_f32_e32 v64, v69, v64
	v_fma_f32 v69, -v80, v81, 1.0
	v_fmac_f32_e32 v81, v69, v81
	v_div_scale_f32 v69, vcc, 1.0, v79, 1.0
	v_mul_f32_e32 v73, v69, v81
	v_fma_f32 v78, -v80, v73, v69
	v_add_f32_e32 v74, 1.0, v74
	v_fmac_f32_e32 v73, v78, v81
	v_div_scale_f32 v78, s[0:1], v74, v74, 1.0
	v_fma_f32 v69, -v80, v73, v69
	v_rcp_f32_e32 v80, v78
	v_div_fmas_f32 v69, v69, v81, v73
	v_lshlrev_b32_e32 v82, 16, v107
	v_div_fixup_f32 v69, v69, v79, 1.0
	v_mul_f32_e32 v69, v65, v69
	v_fma_f32 v65, -v78, v80, 1.0
	v_mul_f32_e32 v79, 0xbfb8aa3b, v82
	v_fmac_f32_e32 v80, v65, v80
	v_div_scale_f32 v65, vcc, 1.0, v74, 1.0
	v_exp_f32_e32 v79, v79
	v_mul_f32_e32 v73, v65, v80
	v_fma_f32 v81, -v78, v73, v65
	v_fmac_f32_e32 v73, v81, v80
	v_fma_f32 v65, -v78, v73, v65
	v_add_f32_e32 v78, 1.0, v79
	v_div_scale_f32 v79, s[0:1], v78, v78, 1.0
	v_rcp_f32_e32 v81, v79
	v_and_b32_e32 v75, 0xffff0000, v105
	v_div_fmas_f32 v65, v65, v80, v73
	v_div_fixup_f32 v65, v65, v74, 1.0
	v_mul_f32_e32 v74, 0xbfb8aa3b, v75
	v_exp_f32_e32 v74, v74
	v_mul_f32_e32 v65, v70, v65
	v_fma_f32 v70, -v79, v81, 1.0
	v_fmac_f32_e32 v81, v70, v81
	v_div_scale_f32 v70, vcc, 1.0, v78, 1.0
	v_mul_f32_e32 v73, v70, v81
	v_fma_f32 v75, -v79, v73, v70
	v_add_f32_e32 v74, 1.0, v74
	v_fmac_f32_e32 v73, v75, v81
	v_div_scale_f32 v75, s[0:1], v74, v74, 1.0
	v_fma_f32 v70, -v79, v73, v70
	v_rcp_f32_e32 v79, v75
	v_div_fmas_f32 v70, v70, v81, v73
	v_and_b32_e32 v83, 0xffff0000, v107
	v_div_fixup_f32 v70, v70, v78, 1.0
	v_mul_f32_e32 v70, v66, v70
	v_fma_f32 v66, -v75, v79, 1.0
	v_mul_f32_e32 v78, 0xbfb8aa3b, v83
	v_fmac_f32_e32 v79, v66, v79
	v_div_scale_f32 v66, vcc, 1.0, v74, 1.0
	v_exp_f32_e32 v78, v78
	v_mul_f32_e32 v73, v66, v79
	v_fma_f32 v80, -v75, v73, v66
	v_fmac_f32_e32 v73, v80, v79
	v_fma_f32 v66, -v75, v73, v66
	v_add_f32_e32 v75, 1.0, v78
	v_div_scale_f32 v78, s[0:1], v75, v75, 1.0
	v_rcp_f32_e32 v80, v78
	v_div_fmas_f32 v66, v66, v79, v73
	v_div_fixup_f32 v66, v66, v74, 1.0
	v_mul_f32_e32 v66, v71, v66
	v_fma_f32 v71, -v78, v80, 1.0
	v_fmac_f32_e32 v80, v71, v80
	v_div_scale_f32 v71, vcc, 1.0, v75, 1.0
	v_mul_f32_e32 v73, v71, v80
	v_fma_f32 v74, -v78, v73, v71
	v_fmac_f32_e32 v73, v74, v80
	v_fma_f32 v71, -v78, v73, v71
	v_div_fmas_f32 v71, v71, v80, v73
	v_div_fixup_f32 v71, v71, v75, 1.0
	v_mul_f32_e32 v67, v67, v71
	v_cvt_pk_bf16_f32 v64, v68, v64
	v_cvt_pk_bf16_f32 v65, v65, v66
	v_add_u32_e32 v102, 0x80, v166
	v_cvt_pk_bf16_f32 v66, v72, v69
	v_cvt_pk_bf16_f32 v67, v70, v67
	global_store_dwordx4 v[76:77], v[64:67], off offset:256
	v_add_u32_e32 v96, 0x90, v166
	v_add_u32_e32 v94, 0xa0, v166
	v_mad_i64_i32 v[64:65], s[0:1], v102, s39, v[168:169]
	global_load_dwordx4 v[98:101], v[64:65], off nt
	global_load_dwordx4 v[88:91], v[64:65], off offset:256 nt
	v_mad_i64_i32 v[64:65], s[0:1], v96, s39, v[168:169]
	v_ashrrev_i32_e32 v103, 31, v102
	global_load_dwordx4 v[84:87], v[64:65], off nt
	global_load_dwordx4 v[80:83], v[64:65], off offset:256 nt
	v_mad_i64_i32 v[64:65], s[0:1], v94, s39, v[168:169]
	v_add_u32_e32 v92, 0xb0, v166
	global_load_dwordx4 v[76:79], v[64:65], off nt
	global_load_dwordx4 v[72:75], v[64:65], off offset:256 nt
	v_mad_i64_i32 v[64:65], s[0:1], v92, s39, v[168:169]
	v_lshlrev_b64 v[102:103], 12, v[102:103]
	global_load_dwordx4 v[68:71], v[64:65], off nt
	s_nop 0
	global_load_dwordx4 v[64:67], v[64:65], off offset:256 nt
	v_ashrrev_i32_e32 v97, 31, v96
	v_ashrrev_i32_e32 v95, 31, v94
	v_ashrrev_i32_e32 v93, 31, v92
	s_waitcnt vmcnt(7)
; __device__ __forceinline__ unsigned cvt_pk_bf16(float lo, float hi) { unsigned r; asm volatile("v_cvt_pk_bf16_f32 %0, %1, %2" : "=v"(r) : "v"(lo), "v"(hi)); return r; }
; __device__ __forceinline__ float sigmoidf_(float x) { return 1.f / (1.f + __expf(-x)); }
; __device__ __forceinline__ void unpack8(const u32x4& w, float (&f)[8]) { f[0] = bflo(w.x); f[1] = bfhi(w.x); f[2] = bflo(w.y); f[3] = bfhi(w.y); f[4] = bflo(w.z); f[5] = bfhi(w.z); f[6] = bflo(w.w); f[7] = bfhi(w.w); }
;     __device__ __forceinline__ void operator()(const f32x4 (&acc)[2][2][4][2], const Unit& u, int wr, int wc, int fr, int fq) const {
;     ...
;                 for (int bj = 0; bj < 2; ++bj) { float g[8]; unpack8(gw[m][bj], g); const f32x4 a0 = acc[ai][bj][m][0], a1 = acc[ai][bj][m][1]; float o[8];
; #pragma unroll
;                     for (int e = 0; e < 4; ++e) { o[e] = a0[e] * sigmoidf_(g[e]); o[4 + e] = a1[e] * sigmoidf_(g[4 + e]); }
;                     *(u32x4*)(T + (size_t)(row0 + ai * HALF + m * 16) * DM + col0 + bj * HALF) = (u32x4){cvt_pk_bf16(o[0], o[1]), cvt_pk_bf16(o[2], o[3]), cvt_pk_bf16(o[4], o[5]), cvt_pk_bf16(o[6], o[7])}; } }
	v_lshlrev_b32_e32 v104, 16, v98
	v_mul_f32_e32 v104, 0xbfb8aa3b, v104
	v_exp_f32_e32 v104, v104
	v_lshlrev_b32_e32 v106, 16, v100
	v_mul_f32_e32 v106, 0xbfb8aa3b, v106
	v_exp_f32_e32 v106, v106
	v_add_f32_e32 v104, 1.0, v104
	v_div_scale_f32 v107, s[0:1], v104, v104, 1.0
	v_rcp_f32_e32 v108, v107
	v_add_f32_e32 v106, 1.0, v106
	v_and_b32_e32 v98, 0xffff0000, v98
	v_mul_f32_e32 v98, 0xbfb8aa3b, v98
	v_fma_f32 v110, -v107, v108, 1.0
	v_fmac_f32_e32 v108, v110, v108
	v_div_scale_f32 v110, vcc, 1.0, v104, 1.0
	v_mul_f32_e32 v111, v110, v108
	v_fma_f32 v112, -v107, v111, v110
	v_fmac_f32_e32 v111, v112, v108
	v_fma_f32 v107, -v107, v111, v110
	v_div_scale_f32 v110, s[0:1], v106, v106, 1.0
	v_rcp_f32_e32 v112, v110
	v_div_fmas_f32 v107, v107, v108, v111
	v_div_fixup_f32 v104, v107, v104, 1.0
	v_exp_f32_e32 v98, v98
	v_mul_f32_e32 v60, v60, v104
	v_fma_f32 v104, -v110, v112, 1.0
	v_fmac_f32_e32 v112, v104, v112
	v_div_scale_f32 v104, vcc, 1.0, v106, 1.0
	v_mul_f32_e32 v107, v104, v112
	v_fma_f32 v108, -v110, v107, v104
	v_add_f32_e32 v98, 1.0, v98
	v_fmac_f32_e32 v107, v108, v112
	v_div_scale_f32 v108, s[0:1], v98, v98, 1.0
	v_fma_f32 v104, -v110, v107, v104
	v_rcp_f32_e32 v110, v108
	v_and_b32_e32 v100, 0xffff0000, v100
	v_div_fmas_f32 v104, v104, v112, v107
	v_mul_f32_e32 v100, 0xbfb8aa3b, v100
	v_div_fixup_f32 v104, v104, v106, 1.0
	v_exp_f32_e32 v100, v100
	v_mul_f32_e32 v104, v56, v104
	v_fma_f32 v56, -v108, v110, 1.0
	v_fmac_f32_e32 v110, v56, v110
	v_div_scale_f32 v56, vcc, 1.0, v98, 1.0
	v_mul_f32_e32 v106, v56, v110
	v_fma_f32 v107, -v108, v106, v56
	v_add_f32_e32 v100, 1.0, v100
	v_fmac_f32_e32 v106, v107, v110
	v_div_scale_f32 v107, s[0:1], v100, v100, 1.0
	v_fma_f32 v56, -v108, v106, v56
	v_rcp_f32_e32 v108, v107
	v_lshlrev_b32_e32 v105, 16, v99
	v_div_fmas_f32 v56, v56, v110, v106
	v_mul_f32_e32 v105, 0xbfb8aa3b, v105
	v_div_fixup_f32 v56, v56, v98, 1.0
	v_exp_f32_e32 v105, v105
	v_mul_f32_e32 v56, v61, v56
	v_fma_f32 v61, -v107, v108, 1.0
	v_fmac_f32_e32 v108, v61, v108
	v_div_scale_f32 v61, vcc, 1.0, v100, 1.0
	v_mul_f32_e32 v98, v61, v108
	v_fma_f32 v106, -v107, v98, v61
	v_add_f32_e32 v105, 1.0, v105
	v_fmac_f32_e32 v98, v106, v108
	v_div_scale_f32 v106, s[0:1], v105, v105, 1.0
	v_fma_f32 v61, -v107, v98, v61
	v_rcp_f32_e32 v107, v106
	v_lshlrev_b32_e32 v109, 16, v101
	v_div_fmas_f32 v61, v61, v108, v98
	v_div_fixup_f32 v61, v61, v100, 1.0
	v_mul_f32_e32 v100, 0xbfb8aa3b, v109
	v_mul_f32_e32 v61, v57, v61
	v_fma_f32 v57, -v106, v107, 1.0
	v_exp_f32_e32 v100, v100
	v_fmac_f32_e32 v107, v57, v107
	v_div_scale_f32 v57, vcc, 1.0, v105, 1.0
	v_mul_f32_e32 v98, v57, v107
	v_fma_f32 v108, -v106, v98, v57
	v_fmac_f32_e32 v98, v108, v107
	v_add_f32_e32 v100, 1.0, v100
	v_fma_f32 v57, -v106, v98, v57
	v_div_scale_f32 v106, s[0:1], v100, v100, 1.0
	v_rcp_f32_e32 v108, v106
	v_and_b32_e32 v99, 0xffff0000, v99
	v_div_fmas_f32 v57, v57, v107, v98
	v_mul_f32_e32 v99, 0xbfb8aa3b, v99
	v_div_fixup_f32 v57, v57, v105, 1.0
	v_exp_f32_e32 v99, v99
	v_mul_f32_e32 v57, v62, v57
	v_fma_f32 v62, -v106, v108, 1.0
	v_fmac_f32_e32 v108, v62, v108
	v_div_scale_f32 v62, vcc, 1.0, v100, 1.0
	v_mul_f32_e32 v98, v62, v108
	v_fma_f32 v105, -v106, v98, v62
	v_add_f32_e32 v99, 1.0, v99
	v_fmac_f32_e32 v98, v105, v108
	v_div_scale_f32 v105, s[0:1], v99, v99, 1.0
	v_fma_f32 v62, -v106, v98, v62
	v_rcp_f32_e32 v106, v105
	v_and_b32_e32 v101, 0xffff0000, v101
	v_div_fmas_f32 v62, v62, v108, v98
	v_div_fixup_f32 v62, v62, v100, 1.0
	v_mul_f32_e32 v100, 0xbfb8aa3b, v101
	v_exp_f32_e32 v100, v100
	v_mul_f32_e32 v62, v58, v62
	v_fma_f32 v58, -v105, v106, 1.0
	v_fmac_f32_e32 v106, v58, v106
	v_div_scale_f32 v58, vcc, 1.0, v99, 1.0
	v_mul_f32_e32 v98, v58, v106
	v_fma_f32 v101, -v105, v98, v58
	v_add_f32_e32 v100, 1.0, v100
	v_fmac_f32_e32 v98, v101, v106
	v_div_scale_f32 v101, s[0:1], v100, v100, 1.0
	v_fma_f32 v58, -v105, v98, v58
	v_rcp_f32_e32 v105, v101
	v_div_fmas_f32 v58, v58, v106, v98
	v_div_fixup_f32 v58, v58, v99, 1.0
	v_mul_f32_e32 v58, v63, v58
	v_fma_f32 v63, -v101, v105, 1.0
	v_fmac_f32_e32 v105, v63, v105
	v_div_scale_f32 v63, vcc, 1.0, v100, 1.0
	v_mul_f32_e32 v98, v63, v105
	v_fma_f32 v99, -v101, v98, v63
	v_fmac_f32_e32 v98, v99, v105
	v_fma_f32 v63, -v101, v98, v63
	v_div_fmas_f32 v63, v63, v105, v98
	v_div_fixup_f32 v63, v63, v100, 1.0
	v_cvt_pk_bf16_f32 v56, v60, v56
	v_cvt_pk_bf16_f32 v57, v57, v58
	v_cvt_pk_bf16_f32 v58, v104, v61
	v_lshl_add_u64 v[60:61], s[84:85], 0, v[102:103]
	v_mul_f32_e32 v59, v59, v63
	v_lshl_add_u64 v[60:61], v[60:61], 0, v[164:165]
	v_cvt_pk_bf16_f32 v59, v62, v59
	global_store_dwordx4 v[60:61], v[56:59], off
	s_waitcnt vmcnt(7)
; __device__ __forceinline__ unsigned cvt_pk_bf16(float lo, float hi) { unsigned r; asm volatile("v_cvt_pk_bf16_f32 %0, %1, %2" : "=v"(r) : "v"(lo), "v"(hi)); return r; }
; __device__ __forceinline__ float sigmoidf_(float x) { return 1.f / (1.f + __expf(-x)); }
; __device__ __forceinline__ void unpack8(const u32x4& w, float (&f)[8]) { f[0] = bflo(w.x); f[1] = bfhi(w.x); f[2] = bflo(w.y); f[3] = bfhi(w.y); f[4] = bflo(w.z); f[5] = bfhi(w.z); f[6] = bflo(w.w); f[7] = bfhi(w.w); }
;     __device__ __forceinline__ void operator()(const f32x4 (&acc)[2][2][4][2], const Unit& u, int wr, int wc, int fr, int fq) const {
;     ...
;                 for (int bj = 0; bj < 2; ++bj) { float g[8]; unpack8(gw[m][bj], g); const f32x4 a0 = acc[ai][bj][m][0], a1 = acc[ai][bj][m][1]; float o[8];
; #pragma unroll
;                     for (int e = 0; e < 4; ++e) { o[e] = a0[e] * sigmoidf_(g[e]); o[4 + e] = a1[e] * sigmoidf_(g[4 + e]); }
;                     *(u32x4*)(T + (size_t)(row0 + ai * HALF + m * 16) * DM + col0 + bj * HALF) = (u32x4){cvt_pk_bf16(o[0], o[1]), cvt_pk_bf16(o[2], o[3]), cvt_pk_bf16(o[4], o[5]), cvt_pk_bf16(o[6], o[7])}; } }
	v_lshlrev_b32_e32 v62, 16, v90
	v_mul_f32_e32 v62, 0xbfb8aa3b, v62
	v_lshlrev_b32_e32 v56, 16, v88
	v_mul_f32_e32 v56, 0xbfb8aa3b, v56
	v_exp_f32_e32 v56, v56
	v_and_b32_e32 v57, 0xffff0000, v88
	v_exp_f32_e32 v62, v62
	v_mul_f32_e32 v57, 0xbfb8aa3b, v57
	v_add_f32_e32 v56, 1.0, v56
	v_div_scale_f32 v63, s[0:1], v56, v56, 1.0
	v_rcp_f32_e32 v88, v63
	v_add_f32_e32 v62, 1.0, v62
	v_exp_f32_e32 v57, v57
	v_lshlrev_b32_e32 v58, 16, v89
	v_fma_f32 v98, -v63, v88, 1.0
	v_fmac_f32_e32 v88, v98, v88
	v_div_scale_f32 v98, vcc, 1.0, v56, 1.0
	v_mul_f32_e32 v99, v98, v88
	v_fma_f32 v100, -v63, v99, v98
	v_fmac_f32_e32 v99, v100, v88
	v_fma_f32 v63, -v63, v99, v98
	v_div_scale_f32 v98, s[0:1], v62, v62, 1.0
	v_rcp_f32_e32 v100, v98
	v_div_fmas_f32 v63, v63, v88, v99
	v_div_fixup_f32 v56, v63, v56, 1.0
	v_mul_f32_e32 v52, v52, v56
	v_fma_f32 v56, -v98, v100, 1.0
	v_fmac_f32_e32 v100, v56, v100
	v_div_scale_f32 v56, vcc, 1.0, v62, 1.0
	v_mul_f32_e32 v63, v56, v100
	v_fma_f32 v88, -v98, v63, v56
	v_add_f32_e32 v57, 1.0, v57
	v_fmac_f32_e32 v63, v88, v100
	v_div_scale_f32 v88, s[0:1], v57, v57, 1.0
	v_fma_f32 v56, -v98, v63, v56
	v_rcp_f32_e32 v98, v88
	v_and_b32_e32 v59, 0xffff0000, v89
	v_and_b32_e32 v89, 0xffff0000, v90
	v_div_fmas_f32 v56, v56, v100, v63
	v_div_fixup_f32 v56, v56, v62, 1.0
	v_mul_f32_e32 v63, 0xbfb8aa3b, v89
	v_mul_f32_e32 v56, v48, v56
	v_fma_f32 v48, -v88, v98, 1.0
	v_exp_f32_e32 v63, v63
	v_fmac_f32_e32 v98, v48, v98
	v_div_scale_f32 v48, vcc, 1.0, v57, 1.0
	v_mul_f32_e32 v62, v48, v98
	v_fma_f32 v89, -v88, v62, v48
	v_fmac_f32_e32 v62, v89, v98
	v_add_f32_e32 v63, 1.0, v63
	v_fma_f32 v48, -v88, v62, v48
	v_div_scale_f32 v88, s[0:1], v63, v63, 1.0
	v_rcp_f32_e32 v89, v88
	v_div_fmas_f32 v48, v48, v98, v62
	v_mul_f32_e32 v58, 0xbfb8aa3b, v58
	v_div_fixup_f32 v48, v48, v57, 1.0
	v_exp_f32_e32 v58, v58
	v_mul_f32_e32 v48, v53, v48
	v_fma_f32 v53, -v88, v89, 1.0
	v_fmac_f32_e32 v89, v53, v89
	v_div_scale_f32 v53, vcc, 1.0, v63, 1.0
	v_mul_f32_e32 v57, v53, v89
	v_fma_f32 v62, -v88, v57, v53
	v_add_f32_e32 v58, 1.0, v58
	v_fmac_f32_e32 v57, v62, v89
	v_div_scale_f32 v62, s[0:1], v58, v58, 1.0
	v_fma_f32 v53, -v88, v57, v53
	v_rcp_f32_e32 v88, v62
	v_div_fmas_f32 v53, v53, v89, v57
	v_lshlrev_b32_e32 v90, 16, v91
	v_div_fixup_f32 v53, v53, v63, 1.0
	v_mul_f32_e32 v53, v49, v53
	v_fma_f32 v49, -v62, v88, 1.0
	v_mul_f32_e32 v63, 0xbfb8aa3b, v90
	v_fmac_f32_e32 v88, v49, v88
	v_div_scale_f32 v49, vcc, 1.0, v58, 1.0
	v_exp_f32_e32 v63, v63
	v_mul_f32_e32 v57, v49, v88
	v_fma_f32 v89, -v62, v57, v49
	v_fmac_f32_e32 v57, v89, v88
	v_fma_f32 v49, -v62, v57, v49
	v_add_f32_e32 v62, 1.0, v63
	v_div_scale_f32 v63, s[0:1], v62, v62, 1.0
	v_rcp_f32_e32 v89, v63
	v_div_fmas_f32 v49, v49, v88, v57
	v_div_fixup_f32 v49, v49, v58, 1.0
	v_mul_f32_e32 v58, 0xbfb8aa3b, v59
	v_exp_f32_e32 v58, v58
	v_mul_f32_e32 v49, v54, v49
	v_fma_f32 v54, -v63, v89, 1.0
	v_fmac_f32_e32 v89, v54, v89
	v_div_scale_f32 v54, vcc, 1.0, v62, 1.0
	v_mul_f32_e32 v57, v54, v89
	v_fma_f32 v59, -v63, v57, v54
	v_add_f32_e32 v58, 1.0, v58
	v_fmac_f32_e32 v57, v59, v89
	v_div_scale_f32 v59, s[0:1], v58, v58, 1.0
	v_fma_f32 v54, -v63, v57, v54
	v_rcp_f32_e32 v63, v59
	v_div_fmas_f32 v54, v54, v89, v57
	v_and_b32_e32 v91, 0xffff0000, v91
	v_div_fixup_f32 v54, v54, v62, 1.0
	v_mul_f32_e32 v54, v50, v54
	v_fma_f32 v50, -v59, v63, 1.0
	v_mul_f32_e32 v62, 0xbfb8aa3b, v91
	v_fmac_f32_e32 v63, v50, v63
	v_div_scale_f32 v50, vcc, 1.0, v58, 1.0
	v_exp_f32_e32 v62, v62
	v_mul_f32_e32 v57, v50, v63
	v_fma_f32 v88, -v59, v57, v50
	v_fmac_f32_e32 v57, v88, v63
	v_fma_f32 v50, -v59, v57, v50
	v_add_f32_e32 v59, 1.0, v62
	v_div_scale_f32 v62, s[0:1], v59, v59, 1.0
	v_rcp_f32_e32 v88, v62
	v_div_fmas_f32 v50, v50, v63, v57
	v_div_fixup_f32 v50, v50, v58, 1.0
	v_mul_f32_e32 v50, v55, v50
	v_fma_f32 v55, -v62, v88, 1.0
	v_fmac_f32_e32 v88, v55, v88
	v_div_scale_f32 v55, vcc, 1.0, v59, 1.0
	v_mul_f32_e32 v57, v55, v88
	v_fma_f32 v58, -v62, v57, v55
	v_fmac_f32_e32 v57, v58, v88
	v_fma_f32 v55, -v62, v57, v55
	v_div_fmas_f32 v55, v55, v88, v57
	v_div_fixup_f32 v55, v55, v59, 1.0
	v_mul_f32_e32 v51, v51, v55
	v_cvt_pk_bf16_f32 v48, v52, v48
	v_cvt_pk_bf16_f32 v49, v49, v50
	v_cvt_pk_bf16_f32 v50, v56, v53
	v_cvt_pk_bf16_f32 v51, v54, v51
	global_store_dwordx4 v[60:61], v[48:51], off offset:256
	s_waitcnt vmcnt(7)
; __device__ __forceinline__ unsigned cvt_pk_bf16(float lo, float hi) { unsigned r; asm volatile("v_cvt_pk_bf16_f32 %0, %1, %2" : "=v"(r) : "v"(lo), "v"(hi)); return r; }
; __device__ __forceinline__ float sigmoidf_(float x) { return 1.f / (1.f + __expf(-x)); }
; __device__ __forceinline__ void unpack8(const u32x4& w, float (&f)[8]) { f[0] = bflo(w.x); f[1] = bfhi(w.x); f[2] = bflo(w.y); f[3] = bfhi(w.y); f[4] = bflo(w.z); f[5] = bfhi(w.z); f[6] = bflo(w.w); f[7] = bfhi(w.w); }
;     __device__ __forceinline__ void operator()(const f32x4 (&acc)[2][2][4][2], const Unit& u, int wr, int wc, int fr, int fq) const {
;     ...
;                 for (int bj = 0; bj < 2; ++bj) { float g[8]; unpack8(gw[m][bj], g); const f32x4 a0 = acc[ai][bj][m][0], a1 = acc[ai][bj][m][1]; float o[8];
; #pragma unroll
;                     for (int e = 0; e < 4; ++e) { o[e] = a0[e] * sigmoidf_(g[e]); o[4 + e] = a1[e] * sigmoidf_(g[4 + e]); }
;                     *(u32x4*)(T + (size_t)(row0 + ai * HALF + m * 16) * DM + col0 + bj * HALF) = (u32x4){cvt_pk_bf16(o[0], o[1]), cvt_pk_bf16(o[2], o[3]), cvt_pk_bf16(o[4], o[5]), cvt_pk_bf16(o[6], o[7])}; } }
	v_lshlrev_b32_e32 v54, 16, v86
	v_mul_f32_e32 v54, 0xbfb8aa3b, v54
	v_lshlrev_b32_e32 v50, 16, v84
	v_mul_f32_e32 v50, 0xbfb8aa3b, v50
	v_exp_f32_e32 v50, v50
	v_exp_f32_e32 v54, v54
	v_and_b32_e32 v51, 0xffff0000, v84
	v_mul_f32_e32 v51, 0xbfb8aa3b, v51
	v_add_f32_e32 v50, 1.0, v50
	v_div_scale_f32 v55, s[0:1], v50, v50, 1.0
	v_rcp_f32_e32 v56, v55
	v_add_f32_e32 v54, 1.0, v54
	v_exp_f32_e32 v51, v51
	v_and_b32_e32 v57, 0xffff0000, v86
	v_fma_f32 v60, -v55, v56, 1.0
	v_fmac_f32_e32 v56, v60, v56
	v_div_scale_f32 v60, vcc, 1.0, v50, 1.0
	v_mul_f32_e32 v61, v60, v56
	v_fma_f32 v62, -v55, v61, v60
	v_fmac_f32_e32 v61, v62, v56
	v_fma_f32 v55, -v55, v61, v60
	v_div_scale_f32 v60, s[0:1], v54, v54, 1.0
	v_rcp_f32_e32 v62, v60
	v_div_fmas_f32 v55, v55, v56, v61
	v_div_fixup_f32 v50, v55, v50, 1.0
	v_mul_f32_e32 v44, v44, v50
	v_fma_f32 v50, -v60, v62, 1.0
	v_fmac_f32_e32 v62, v50, v62
	v_div_scale_f32 v50, vcc, 1.0, v54, 1.0
	v_mul_f32_e32 v55, v50, v62
	v_fma_f32 v56, -v60, v55, v50
	v_add_f32_e32 v51, 1.0, v51
	v_fmac_f32_e32 v55, v56, v62
	v_div_scale_f32 v56, s[0:1], v51, v51, 1.0
	v_fma_f32 v50, -v60, v55, v50
	v_rcp_f32_e32 v60, v56
	v_div_fmas_f32 v50, v50, v62, v55
	v_div_fixup_f32 v50, v50, v54, 1.0
	v_mul_f32_e32 v55, 0xbfb8aa3b, v57
	v_mul_f32_e32 v50, v40, v50
	v_fma_f32 v40, -v56, v60, 1.0
	v_exp_f32_e32 v55, v55
	v_fmac_f32_e32 v60, v40, v60
	v_div_scale_f32 v40, vcc, 1.0, v51, 1.0
	v_mul_f32_e32 v54, v40, v60
	v_fma_f32 v57, -v56, v54, v40
	v_fmac_f32_e32 v54, v57, v60
	v_add_f32_e32 v55, 1.0, v55
	v_fma_f32 v40, -v56, v54, v40
	v_div_scale_f32 v56, s[0:1], v55, v55, 1.0
	v_rcp_f32_e32 v57, v56
	v_lshlrev_b32_e32 v52, 16, v85
	v_div_fmas_f32 v40, v40, v60, v54
	v_mul_f32_e32 v52, 0xbfb8aa3b, v52
	v_div_fixup_f32 v40, v40, v51, 1.0
	v_exp_f32_e32 v52, v52
	v_mul_f32_e32 v40, v45, v40
	v_fma_f32 v45, -v56, v57, 1.0
	v_fmac_f32_e32 v57, v45, v57
	v_div_scale_f32 v45, vcc, 1.0, v55, 1.0
	v_mul_f32_e32 v51, v45, v57
	v_fma_f32 v54, -v56, v51, v45
	v_add_f32_e32 v52, 1.0, v52
	v_fmac_f32_e32 v51, v54, v57
	v_div_scale_f32 v54, s[0:1], v52, v52, 1.0
	v_fma_f32 v45, -v56, v51, v45
	v_rcp_f32_e32 v56, v54
	v_div_fmas_f32 v45, v45, v57, v51
	v_lshlrev_b32_e32 v58, 16, v87
	v_div_fixup_f32 v45, v45, v55, 1.0
	v_mul_f32_e32 v45, v41, v45
	v_fma_f32 v41, -v54, v56, 1.0
	v_mul_f32_e32 v55, 0xbfb8aa3b, v58
	v_fmac_f32_e32 v56, v41, v56
	v_div_scale_f32 v41, vcc, 1.0, v52, 1.0
	v_exp_f32_e32 v55, v55
	v_mul_f32_e32 v51, v41, v56
	v_fma_f32 v57, -v54, v51, v41
	v_fmac_f32_e32 v51, v57, v56
	v_fma_f32 v41, -v54, v51, v41
	v_add_f32_e32 v54, 1.0, v55
	v_div_scale_f32 v55, s[0:1], v54, v54, 1.0
	v_rcp_f32_e32 v57, v55
	v_and_b32_e32 v53, 0xffff0000, v85
	v_div_fmas_f32 v41, v41, v56, v51
	v_div_fixup_f32 v41, v41, v52, 1.0
	v_mul_f32_e32 v52, 0xbfb8aa3b, v53
	v_exp_f32_e32 v52, v52
	v_mul_f32_e32 v41, v46, v41
	v_fma_f32 v46, -v55, v57, 1.0
	v_fmac_f32_e32 v57, v46, v57
	v_div_scale_f32 v46, vcc, 1.0, v54, 1.0
	v_mul_f32_e32 v51, v46, v57
	v_fma_f32 v53, -v55, v51, v46
	v_add_f32_e32 v52, 1.0, v52
	v_fmac_f32_e32 v51, v53, v57
	v_div_scale_f32 v53, s[0:1], v52, v52, 1.0
	v_fma_f32 v46, -v55, v51, v46
	v_rcp_f32_e32 v55, v53
	v_div_fmas_f32 v46, v46, v57, v51
	v_and_b32_e32 v59, 0xffff0000, v87
	v_div_fixup_f32 v46, v46, v54, 1.0
	v_mul_f32_e32 v46, v42, v46
	v_fma_f32 v42, -v53, v55, 1.0
	v_mul_f32_e32 v54, 0xbfb8aa3b, v59
	v_fmac_f32_e32 v55, v42, v55
	v_div_scale_f32 v42, vcc, 1.0, v52, 1.0
	v_exp_f32_e32 v54, v54
	v_mul_f32_e32 v51, v42, v55
	v_fma_f32 v56, -v53, v51, v42
	v_fmac_f32_e32 v51, v56, v55
	v_fma_f32 v42, -v53, v51, v42
	v_add_f32_e32 v53, 1.0, v54
	v_div_scale_f32 v54, s[0:1], v53, v53, 1.0
	v_rcp_f32_e32 v56, v54
	v_div_fmas_f32 v42, v42, v55, v51
	v_div_fixup_f32 v42, v42, v52, 1.0
	v_mul_f32_e32 v42, v47, v42
	v_fma_f32 v47, -v54, v56, 1.0
	v_fmac_f32_e32 v56, v47, v56
	v_div_scale_f32 v47, vcc, 1.0, v53, 1.0
	v_mul_f32_e32 v51, v47, v56
	v_fma_f32 v52, -v54, v51, v47
	v_fmac_f32_e32 v51, v52, v56
	v_fma_f32 v47, -v54, v51, v47
	v_lshlrev_b64 v[48:49], 12, v[96:97]
	v_div_fmas_f32 v47, v47, v56, v51
	v_div_fixup_f32 v47, v47, v53, 1.0
	v_cvt_pk_bf16_f32 v40, v44, v40
	v_cvt_pk_bf16_f32 v41, v41, v42
	v_cvt_pk_bf16_f32 v42, v50, v45
	v_lshl_add_u64 v[44:45], s[84:85], 0, v[48:49]
	v_mul_f32_e32 v43, v43, v47
	v_lshl_add_u64 v[44:45], v[44:45], 0, v[164:165]
	v_cvt_pk_bf16_f32 v43, v46, v43
	global_store_dwordx4 v[44:45], v[40:43], off
	s_waitcnt vmcnt(7)
; __device__ __forceinline__ unsigned cvt_pk_bf16(float lo, float hi) { unsigned r; asm volatile("v_cvt_pk_bf16_f32 %0, %1, %2" : "=v"(r) : "v"(lo), "v"(hi)); return r; }
; __device__ __forceinline__ float sigmoidf_(float x) { return 1.f / (1.f + __expf(-x)); }
; __device__ __forceinline__ void unpack8(const u32x4& w, float (&f)[8]) { f[0] = bflo(w.x); f[1] = bfhi(w.x); f[2] = bflo(w.y); f[3] = bfhi(w.y); f[4] = bflo(w.z); f[5] = bfhi(w.z); f[6] = bflo(w.w); f[7] = bfhi(w.w); }
;     __device__ __forceinline__ void operator()(const f32x4 (&acc)[2][2][4][2], const Unit& u, int wr, int wc, int fr, int fq) const {
;     ...
;                 for (int bj = 0; bj < 2; ++bj) { float g[8]; unpack8(gw[m][bj], g); const f32x4 a0 = acc[ai][bj][m][0], a1 = acc[ai][bj][m][1]; float o[8];
; #pragma unroll
;                     for (int e = 0; e < 4; ++e) { o[e] = a0[e] * sigmoidf_(g[e]); o[4 + e] = a1[e] * sigmoidf_(g[4 + e]); }
;                     *(u32x4*)(T + (size_t)(row0 + ai * HALF + m * 16) * DM + col0 + bj * HALF) = (u32x4){cvt_pk_bf16(o[0], o[1]), cvt_pk_bf16(o[2], o[3]), cvt_pk_bf16(o[4], o[5]), cvt_pk_bf16(o[6], o[7])}; } }
	v_lshlrev_b32_e32 v46, 16, v82
	v_mul_f32_e32 v46, 0xbfb8aa3b, v46
	v_lshlrev_b32_e32 v40, 16, v80
	v_mul_f32_e32 v40, 0xbfb8aa3b, v40
	v_exp_f32_e32 v40, v40
	v_exp_f32_e32 v46, v46
	v_and_b32_e32 v41, 0xffff0000, v80
	v_mul_f32_e32 v41, 0xbfb8aa3b, v41
	v_add_f32_e32 v40, 1.0, v40
	v_div_scale_f32 v47, s[0:1], v40, v40, 1.0
	v_rcp_f32_e32 v48, v47
	v_add_f32_e32 v46, 1.0, v46
	v_exp_f32_e32 v41, v41
	v_and_b32_e32 v49, 0xffff0000, v82
	v_fma_f32 v52, -v47, v48, 1.0
	v_fmac_f32_e32 v48, v52, v48
	v_div_scale_f32 v52, vcc, 1.0, v40, 1.0
	v_mul_f32_e32 v53, v52, v48
	v_fma_f32 v54, -v47, v53, v52
	v_fmac_f32_e32 v53, v54, v48
	v_fma_f32 v47, -v47, v53, v52
	v_div_scale_f32 v52, s[0:1], v46, v46, 1.0
	v_rcp_f32_e32 v54, v52
	v_div_fmas_f32 v47, v47, v48, v53
	v_div_fixup_f32 v40, v47, v40, 1.0
	v_mul_f32_e32 v36, v36, v40
	v_fma_f32 v40, -v52, v54, 1.0
	v_fmac_f32_e32 v54, v40, v54
	v_div_scale_f32 v40, vcc, 1.0, v46, 1.0
	v_mul_f32_e32 v47, v40, v54
	v_fma_f32 v48, -v52, v47, v40
	v_add_f32_e32 v41, 1.0, v41
	v_fmac_f32_e32 v47, v48, v54
	v_div_scale_f32 v48, s[0:1], v41, v41, 1.0
	v_fma_f32 v40, -v52, v47, v40
	v_rcp_f32_e32 v52, v48
	v_div_fmas_f32 v40, v40, v54, v47
	v_div_fixup_f32 v40, v40, v46, 1.0
	v_mul_f32_e32 v47, 0xbfb8aa3b, v49
	v_mul_f32_e32 v40, v32, v40
	v_fma_f32 v32, -v48, v52, 1.0
	v_exp_f32_e32 v47, v47
	v_fmac_f32_e32 v52, v32, v52
	v_div_scale_f32 v32, vcc, 1.0, v41, 1.0
	v_mul_f32_e32 v46, v32, v52
	v_fma_f32 v49, -v48, v46, v32
	v_fmac_f32_e32 v46, v49, v52
	v_add_f32_e32 v47, 1.0, v47
	v_fma_f32 v32, -v48, v46, v32
	v_div_scale_f32 v48, s[0:1], v47, v47, 1.0
	v_rcp_f32_e32 v49, v48
	v_lshlrev_b32_e32 v42, 16, v81
	v_div_fmas_f32 v32, v32, v52, v46
	v_mul_f32_e32 v42, 0xbfb8aa3b, v42
	v_div_fixup_f32 v32, v32, v41, 1.0
	v_exp_f32_e32 v42, v42
	v_mul_f32_e32 v32, v37, v32
	v_fma_f32 v37, -v48, v49, 1.0
	v_fmac_f32_e32 v49, v37, v49
	v_div_scale_f32 v37, vcc, 1.0, v47, 1.0
	v_mul_f32_e32 v41, v37, v49
	v_fma_f32 v46, -v48, v41, v37
	v_add_f32_e32 v42, 1.0, v42
	v_fmac_f32_e32 v41, v46, v49
	v_div_scale_f32 v46, s[0:1], v42, v42, 1.0
	v_fma_f32 v37, -v48, v41, v37
	v_rcp_f32_e32 v48, v46
	v_div_fmas_f32 v37, v37, v49, v41
	v_lshlrev_b32_e32 v50, 16, v83
	v_div_fixup_f32 v37, v37, v47, 1.0
	v_mul_f32_e32 v37, v33, v37
	v_fma_f32 v33, -v46, v48, 1.0
	v_mul_f32_e32 v47, 0xbfb8aa3b, v50
	v_fmac_f32_e32 v48, v33, v48
	v_div_scale_f32 v33, vcc, 1.0, v42, 1.0
	v_exp_f32_e32 v47, v47
	v_mul_f32_e32 v41, v33, v48
	v_fma_f32 v49, -v46, v41, v33
	v_fmac_f32_e32 v41, v49, v48
	v_fma_f32 v33, -v46, v41, v33
	v_add_f32_e32 v46, 1.0, v47
	v_div_scale_f32 v47, s[0:1], v46, v46, 1.0
	v_rcp_f32_e32 v49, v47
	v_and_b32_e32 v43, 0xffff0000, v81
	v_div_fmas_f32 v33, v33, v48, v41
	v_div_fixup_f32 v33, v33, v42, 1.0
	v_mul_f32_e32 v42, 0xbfb8aa3b, v43
	v_exp_f32_e32 v42, v42
	v_mul_f32_e32 v33, v38, v33
	v_fma_f32 v38, -v47, v49, 1.0
	v_fmac_f32_e32 v49, v38, v49
	v_div_scale_f32 v38, vcc, 1.0, v46, 1.0
	v_mul_f32_e32 v41, v38, v49
	v_fma_f32 v43, -v47, v41, v38
	v_add_f32_e32 v42, 1.0, v42
	v_fmac_f32_e32 v41, v43, v49
	v_div_scale_f32 v43, s[0:1], v42, v42, 1.0
	v_fma_f32 v38, -v47, v41, v38
	v_rcp_f32_e32 v47, v43
	v_div_fmas_f32 v38, v38, v49, v41
	v_and_b32_e32 v51, 0xffff0000, v83
	v_div_fixup_f32 v38, v38, v46, 1.0
	v_mul_f32_e32 v38, v34, v38
	v_fma_f32 v34, -v43, v47, 1.0
	v_mul_f32_e32 v46, 0xbfb8aa3b, v51
	v_fmac_f32_e32 v47, v34, v47
	v_div_scale_f32 v34, vcc, 1.0, v42, 1.0
	v_exp_f32_e32 v46, v46
	v_mul_f32_e32 v41, v34, v47
	v_fma_f32 v48, -v43, v41, v34
	v_fmac_f32_e32 v41, v48, v47
	v_fma_f32 v34, -v43, v41, v34
	v_add_f32_e32 v43, 1.0, v46
	v_div_scale_f32 v46, s[0:1], v43, v43, 1.0
	v_rcp_f32_e32 v48, v46
	v_div_fmas_f32 v34, v34, v47, v41
	v_div_fixup_f32 v34, v34, v42, 1.0
	v_mul_f32_e32 v34, v39, v34
	v_fma_f32 v39, -v46, v48, 1.0
	v_fmac_f32_e32 v48, v39, v48
	v_div_scale_f32 v39, vcc, 1.0, v43, 1.0
	v_mul_f32_e32 v41, v39, v48
	v_fma_f32 v42, -v46, v41, v39
	v_fmac_f32_e32 v41, v42, v48
	v_fma_f32 v39, -v46, v41, v39
	v_div_fmas_f32 v39, v39, v48, v41
	v_div_fixup_f32 v39, v39, v43, 1.0
	v_mul_f32_e32 v35, v35, v39
	v_cvt_pk_bf16_f32 v32, v36, v32
	v_cvt_pk_bf16_f32 v33, v33, v34
	v_cvt_pk_bf16_f32 v34, v40, v37
	v_cvt_pk_bf16_f32 v35, v38, v35
	global_store_dwordx4 v[44:45], v[32:35], off offset:256
	s_waitcnt vmcnt(7)
; __device__ __forceinline__ unsigned cvt_pk_bf16(float lo, float hi) { unsigned r; asm volatile("v_cvt_pk_bf16_f32 %0, %1, %2" : "=v"(r) : "v"(lo), "v"(hi)); return r; }
; __device__ __forceinline__ float sigmoidf_(float x) { return 1.f / (1.f + __expf(-x)); }
; __device__ __forceinline__ void unpack8(const u32x4& w, float (&f)[8]) { f[0] = bflo(w.x); f[1] = bfhi(w.x); f[2] = bflo(w.y); f[3] = bfhi(w.y); f[4] = bflo(w.z); f[5] = bfhi(w.z); f[6] = bflo(w.w); f[7] = bfhi(w.w); }
;     __device__ __forceinline__ void operator()(const f32x4 (&acc)[2][2][4][2], const Unit& u, int wr, int wc, int fr, int fq) const {
;     ...
;                 for (int bj = 0; bj < 2; ++bj) { float g[8]; unpack8(gw[m][bj], g); const f32x4 a0 = acc[ai][bj][m][0], a1 = acc[ai][bj][m][1]; float o[8];
; #pragma unroll
;                     for (int e = 0; e < 4; ++e) { o[e] = a0[e] * sigmoidf_(g[e]); o[4 + e] = a1[e] * sigmoidf_(g[4 + e]); }
;                     *(u32x4*)(T + (size_t)(row0 + ai * HALF + m * 16) * DM + col0 + bj * HALF) = (u32x4){cvt_pk_bf16(o[0], o[1]), cvt_pk_bf16(o[2], o[3]), cvt_pk_bf16(o[4], o[5]), cvt_pk_bf16(o[6], o[7])}; } }
	v_lshlrev_b32_e32 v38, 16, v78
	v_mul_f32_e32 v38, 0xbfb8aa3b, v38
	v_lshlrev_b32_e32 v34, 16, v76
	v_mul_f32_e32 v34, 0xbfb8aa3b, v34
	v_exp_f32_e32 v34, v34
	v_exp_f32_e32 v38, v38
	v_and_b32_e32 v35, 0xffff0000, v76
	v_mul_f32_e32 v35, 0xbfb8aa3b, v35
	v_add_f32_e32 v34, 1.0, v34
	v_div_scale_f32 v39, s[0:1], v34, v34, 1.0
	v_rcp_f32_e32 v40, v39
	v_add_f32_e32 v38, 1.0, v38
	v_exp_f32_e32 v35, v35
	v_and_b32_e32 v41, 0xffff0000, v78
	v_fma_f32 v44, -v39, v40, 1.0
	v_fmac_f32_e32 v40, v44, v40
	v_div_scale_f32 v44, vcc, 1.0, v34, 1.0
	v_mul_f32_e32 v45, v44, v40
	v_fma_f32 v46, -v39, v45, v44
	v_fmac_f32_e32 v45, v46, v40
	v_fma_f32 v39, -v39, v45, v44
	v_div_scale_f32 v44, s[0:1], v38, v38, 1.0
	v_rcp_f32_e32 v46, v44
	v_div_fmas_f32 v39, v39, v40, v45
	v_div_fixup_f32 v34, v39, v34, 1.0
	v_mul_f32_e32 v28, v28, v34
	v_fma_f32 v34, -v44, v46, 1.0
	v_fmac_f32_e32 v46, v34, v46
	v_div_scale_f32 v34, vcc, 1.0, v38, 1.0
	v_mul_f32_e32 v39, v34, v46
	v_fma_f32 v40, -v44, v39, v34
	v_add_f32_e32 v35, 1.0, v35
	v_fmac_f32_e32 v39, v40, v46
	v_div_scale_f32 v40, s[0:1], v35, v35, 1.0
	v_fma_f32 v34, -v44, v39, v34
	v_rcp_f32_e32 v44, v40
	v_div_fmas_f32 v34, v34, v46, v39
	v_div_fixup_f32 v34, v34, v38, 1.0
	v_mul_f32_e32 v39, 0xbfb8aa3b, v41
	v_mul_f32_e32 v34, v24, v34
	v_fma_f32 v24, -v40, v44, 1.0
	v_exp_f32_e32 v39, v39
	v_fmac_f32_e32 v44, v24, v44
	v_div_scale_f32 v24, vcc, 1.0, v35, 1.0
	v_mul_f32_e32 v38, v24, v44
	v_fma_f32 v41, -v40, v38, v24
	v_fmac_f32_e32 v38, v41, v44
	v_add_f32_e32 v39, 1.0, v39
	v_fma_f32 v24, -v40, v38, v24
	v_div_scale_f32 v40, s[0:1], v39, v39, 1.0
	v_rcp_f32_e32 v41, v40
	v_lshlrev_b32_e32 v36, 16, v77
	v_div_fmas_f32 v24, v24, v44, v38
	v_mul_f32_e32 v36, 0xbfb8aa3b, v36
	v_div_fixup_f32 v24, v24, v35, 1.0
	v_exp_f32_e32 v36, v36
	v_mul_f32_e32 v24, v29, v24
	v_fma_f32 v29, -v40, v41, 1.0
	v_fmac_f32_e32 v41, v29, v41
	v_div_scale_f32 v29, vcc, 1.0, v39, 1.0
	v_mul_f32_e32 v35, v29, v41
	v_fma_f32 v38, -v40, v35, v29
	v_add_f32_e32 v36, 1.0, v36
	v_fmac_f32_e32 v35, v38, v41
	v_div_scale_f32 v38, s[0:1], v36, v36, 1.0
	v_fma_f32 v29, -v40, v35, v29
	v_rcp_f32_e32 v40, v38
	v_div_fmas_f32 v29, v29, v41, v35
	v_lshlrev_b32_e32 v42, 16, v79
	v_div_fixup_f32 v29, v29, v39, 1.0
	v_mul_f32_e32 v29, v25, v29
	v_fma_f32 v25, -v38, v40, 1.0
	v_mul_f32_e32 v39, 0xbfb8aa3b, v42
	v_fmac_f32_e32 v40, v25, v40
	v_div_scale_f32 v25, vcc, 1.0, v36, 1.0
	v_exp_f32_e32 v39, v39
	v_mul_f32_e32 v35, v25, v40
	v_fma_f32 v41, -v38, v35, v25
	v_fmac_f32_e32 v35, v41, v40
	v_fma_f32 v25, -v38, v35, v25
	v_add_f32_e32 v38, 1.0, v39
	v_div_scale_f32 v39, s[0:1], v38, v38, 1.0
	v_rcp_f32_e32 v41, v39
	v_and_b32_e32 v37, 0xffff0000, v77
	v_div_fmas_f32 v25, v25, v40, v35
	v_div_fixup_f32 v25, v25, v36, 1.0
	v_mul_f32_e32 v36, 0xbfb8aa3b, v37
	v_exp_f32_e32 v36, v36
	v_mul_f32_e32 v25, v30, v25
	v_fma_f32 v30, -v39, v41, 1.0
	v_fmac_f32_e32 v41, v30, v41
	v_div_scale_f32 v30, vcc, 1.0, v38, 1.0
	v_mul_f32_e32 v35, v30, v41
	v_fma_f32 v37, -v39, v35, v30
	v_add_f32_e32 v36, 1.0, v36
	v_fmac_f32_e32 v35, v37, v41
	v_div_scale_f32 v37, s[0:1], v36, v36, 1.0
	v_fma_f32 v30, -v39, v35, v30
	v_rcp_f32_e32 v39, v37
	v_div_fmas_f32 v30, v30, v41, v35
	v_and_b32_e32 v43, 0xffff0000, v79
	v_div_fixup_f32 v30, v30, v38, 1.0
	v_mul_f32_e32 v30, v26, v30
	v_fma_f32 v26, -v37, v39, 1.0
	v_mul_f32_e32 v38, 0xbfb8aa3b, v43
	v_fmac_f32_e32 v39, v26, v39
	v_div_scale_f32 v26, vcc, 1.0, v36, 1.0
	v_exp_f32_e32 v38, v38
	v_mul_f32_e32 v35, v26, v39
	v_fma_f32 v40, -v37, v35, v26
	v_fmac_f32_e32 v35, v40, v39
	v_fma_f32 v26, -v37, v35, v26
	v_add_f32_e32 v37, 1.0, v38
	v_div_scale_f32 v38, s[0:1], v37, v37, 1.0
	v_rcp_f32_e32 v40, v38
	v_div_fmas_f32 v26, v26, v39, v35
	v_div_fixup_f32 v26, v26, v36, 1.0
	v_mul_f32_e32 v26, v31, v26
	v_fma_f32 v31, -v38, v40, 1.0
	v_fmac_f32_e32 v40, v31, v40
	v_div_scale_f32 v31, vcc, 1.0, v37, 1.0
	v_mul_f32_e32 v35, v31, v40
	v_fma_f32 v36, -v38, v35, v31
	v_fmac_f32_e32 v35, v36, v40
	v_fma_f32 v31, -v38, v35, v31
	v_lshlrev_b64 v[32:33], 12, v[94:95]
	v_div_fmas_f32 v31, v31, v40, v35
	v_div_fixup_f32 v31, v31, v37, 1.0
	v_cvt_pk_bf16_f32 v24, v28, v24
	v_cvt_pk_bf16_f32 v25, v25, v26
	v_cvt_pk_bf16_f32 v26, v34, v29
	v_lshl_add_u64 v[28:29], s[84:85], 0, v[32:33]
	v_mul_f32_e32 v27, v27, v31
	v_lshl_add_u64 v[28:29], v[28:29], 0, v[164:165]
	v_cvt_pk_bf16_f32 v27, v30, v27
	global_store_dwordx4 v[28:29], v[24:27], off
	s_waitcnt vmcnt(7)
; __device__ __forceinline__ unsigned cvt_pk_bf16(float lo, float hi) { unsigned r; asm volatile("v_cvt_pk_bf16_f32 %0, %1, %2" : "=v"(r) : "v"(lo), "v"(hi)); return r; }
; __device__ __forceinline__ float sigmoidf_(float x) { return 1.f / (1.f + __expf(-x)); }
; __device__ __forceinline__ void unpack8(const u32x4& w, float (&f)[8]) { f[0] = bflo(w.x); f[1] = bfhi(w.x); f[2] = bflo(w.y); f[3] = bfhi(w.y); f[4] = bflo(w.z); f[5] = bfhi(w.z); f[6] = bflo(w.w); f[7] = bfhi(w.w); }
;     __device__ __forceinline__ void operator()(const f32x4 (&acc)[2][2][4][2], const Unit& u, int wr, int wc, int fr, int fq) const {
;     ...
;                 for (int bj = 0; bj < 2; ++bj) { float g[8]; unpack8(gw[m][bj], g); const f32x4 a0 = acc[ai][bj][m][0], a1 = acc[ai][bj][m][1]; float o[8];
; #pragma unroll
;                     for (int e = 0; e < 4; ++e) { o[e] = a0[e] * sigmoidf_(g[e]); o[4 + e] = a1[e] * sigmoidf_(g[4 + e]); }
;                     *(u32x4*)(T + (size_t)(row0 + ai * HALF + m * 16) * DM + col0 + bj * HALF) = (u32x4){cvt_pk_bf16(o[0], o[1]), cvt_pk_bf16(o[2], o[3]), cvt_pk_bf16(o[4], o[5]), cvt_pk_bf16(o[6], o[7])}; } }
	v_lshlrev_b32_e32 v30, 16, v74
	v_mul_f32_e32 v30, 0xbfb8aa3b, v30
	v_lshlrev_b32_e32 v24, 16, v72
	v_mul_f32_e32 v24, 0xbfb8aa3b, v24
	v_exp_f32_e32 v24, v24
	v_exp_f32_e32 v30, v30
	v_and_b32_e32 v25, 0xffff0000, v72
	v_mul_f32_e32 v25, 0xbfb8aa3b, v25
	v_add_f32_e32 v24, 1.0, v24
	v_div_scale_f32 v31, s[0:1], v24, v24, 1.0
	v_rcp_f32_e32 v32, v31
	v_add_f32_e32 v30, 1.0, v30
	v_exp_f32_e32 v25, v25
	v_and_b32_e32 v33, 0xffff0000, v74
	v_fma_f32 v36, -v31, v32, 1.0
	v_fmac_f32_e32 v32, v36, v32
	v_div_scale_f32 v36, vcc, 1.0, v24, 1.0
	v_mul_f32_e32 v37, v36, v32
	v_fma_f32 v38, -v31, v37, v36
	v_fmac_f32_e32 v37, v38, v32
	v_fma_f32 v31, -v31, v37, v36
	v_div_scale_f32 v36, s[0:1], v30, v30, 1.0
	v_rcp_f32_e32 v38, v36
	v_div_fmas_f32 v31, v31, v32, v37
	v_div_fixup_f32 v24, v31, v24, 1.0
	v_mul_f32_e32 v20, v20, v24
	v_fma_f32 v24, -v36, v38, 1.0
	v_fmac_f32_e32 v38, v24, v38
	v_div_scale_f32 v24, vcc, 1.0, v30, 1.0
	v_mul_f32_e32 v31, v24, v38
	v_fma_f32 v32, -v36, v31, v24
	v_add_f32_e32 v25, 1.0, v25
	v_fmac_f32_e32 v31, v32, v38
	v_div_scale_f32 v32, s[0:1], v25, v25, 1.0
	v_fma_f32 v24, -v36, v31, v24
	v_rcp_f32_e32 v36, v32
	v_div_fmas_f32 v24, v24, v38, v31
	v_div_fixup_f32 v24, v24, v30, 1.0
	v_mul_f32_e32 v31, 0xbfb8aa3b, v33
	v_mul_f32_e32 v24, v16, v24
	v_fma_f32 v16, -v32, v36, 1.0
	v_exp_f32_e32 v31, v31
	v_fmac_f32_e32 v36, v16, v36
	v_div_scale_f32 v16, vcc, 1.0, v25, 1.0
	v_mul_f32_e32 v30, v16, v36
	v_fma_f32 v33, -v32, v30, v16
	v_fmac_f32_e32 v30, v33, v36
	v_add_f32_e32 v31, 1.0, v31
	v_fma_f32 v16, -v32, v30, v16
	v_div_scale_f32 v32, s[0:1], v31, v31, 1.0
	v_rcp_f32_e32 v33, v32
	v_lshlrev_b32_e32 v26, 16, v73
	v_div_fmas_f32 v16, v16, v36, v30
	v_mul_f32_e32 v26, 0xbfb8aa3b, v26
	v_div_fixup_f32 v16, v16, v25, 1.0
	v_exp_f32_e32 v26, v26
	v_mul_f32_e32 v16, v21, v16
	v_fma_f32 v21, -v32, v33, 1.0
	v_fmac_f32_e32 v33, v21, v33
	v_div_scale_f32 v21, vcc, 1.0, v31, 1.0
	v_mul_f32_e32 v25, v21, v33
	v_fma_f32 v30, -v32, v25, v21
	v_add_f32_e32 v26, 1.0, v26
	v_fmac_f32_e32 v25, v30, v33
	v_div_scale_f32 v30, s[0:1], v26, v26, 1.0
	v_fma_f32 v21, -v32, v25, v21
	v_rcp_f32_e32 v32, v30
	v_div_fmas_f32 v21, v21, v33, v25
	v_lshlrev_b32_e32 v34, 16, v75
	v_div_fixup_f32 v21, v21, v31, 1.0
	v_mul_f32_e32 v21, v17, v21
	v_fma_f32 v17, -v30, v32, 1.0
	v_mul_f32_e32 v31, 0xbfb8aa3b, v34
	v_fmac_f32_e32 v32, v17, v32
	v_div_scale_f32 v17, vcc, 1.0, v26, 1.0
	v_exp_f32_e32 v31, v31
	v_mul_f32_e32 v25, v17, v32
	v_fma_f32 v33, -v30, v25, v17
	v_fmac_f32_e32 v25, v33, v32
	v_fma_f32 v17, -v30, v25, v17
	v_add_f32_e32 v30, 1.0, v31
	v_div_scale_f32 v31, s[0:1], v30, v30, 1.0
	v_rcp_f32_e32 v33, v31
	v_and_b32_e32 v27, 0xffff0000, v73
	v_div_fmas_f32 v17, v17, v32, v25
	v_div_fixup_f32 v17, v17, v26, 1.0
	v_mul_f32_e32 v26, 0xbfb8aa3b, v27
	v_exp_f32_e32 v26, v26
	v_mul_f32_e32 v17, v22, v17
	v_fma_f32 v22, -v31, v33, 1.0
	v_fmac_f32_e32 v33, v22, v33
	v_div_scale_f32 v22, vcc, 1.0, v30, 1.0
	v_mul_f32_e32 v25, v22, v33
	v_fma_f32 v27, -v31, v25, v22
	v_add_f32_e32 v26, 1.0, v26
	v_fmac_f32_e32 v25, v27, v33
	v_div_scale_f32 v27, s[0:1], v26, v26, 1.0
	v_fma_f32 v22, -v31, v25, v22
	v_rcp_f32_e32 v31, v27
	v_div_fmas_f32 v22, v22, v33, v25
	v_and_b32_e32 v35, 0xffff0000, v75
	v_div_fixup_f32 v22, v22, v30, 1.0
	v_mul_f32_e32 v22, v18, v22
	v_fma_f32 v18, -v27, v31, 1.0
	v_mul_f32_e32 v30, 0xbfb8aa3b, v35
	v_fmac_f32_e32 v31, v18, v31
	v_div_scale_f32 v18, vcc, 1.0, v26, 1.0
	v_exp_f32_e32 v30, v30
	v_mul_f32_e32 v25, v18, v31
	v_fma_f32 v32, -v27, v25, v18
	v_fmac_f32_e32 v25, v32, v31
	v_fma_f32 v18, -v27, v25, v18
	v_add_f32_e32 v27, 1.0, v30
	v_div_scale_f32 v30, s[0:1], v27, v27, 1.0
	v_rcp_f32_e32 v32, v30
	v_div_fmas_f32 v18, v18, v31, v25
	v_div_fixup_f32 v18, v18, v26, 1.0
	v_mul_f32_e32 v18, v23, v18
	v_fma_f32 v23, -v30, v32, 1.0
	v_fmac_f32_e32 v32, v23, v32
	v_div_scale_f32 v23, vcc, 1.0, v27, 1.0
	v_mul_f32_e32 v25, v23, v32
	v_fma_f32 v26, -v30, v25, v23
	v_fmac_f32_e32 v25, v26, v32
	v_fma_f32 v23, -v30, v25, v23
	v_div_fmas_f32 v23, v23, v32, v25
	v_div_fixup_f32 v23, v23, v27, 1.0
	v_mul_f32_e32 v19, v19, v23
	v_cvt_pk_bf16_f32 v16, v20, v16
	v_cvt_pk_bf16_f32 v17, v17, v18
	v_cvt_pk_bf16_f32 v18, v24, v21
	v_cvt_pk_bf16_f32 v19, v22, v19
	global_store_dwordx4 v[28:29], v[16:19], off offset:256
	s_waitcnt vmcnt(7)
; __device__ __forceinline__ unsigned cvt_pk_bf16(float lo, float hi) { unsigned r; asm volatile("v_cvt_pk_bf16_f32 %0, %1, %2" : "=v"(r) : "v"(lo), "v"(hi)); return r; }
; __device__ __forceinline__ float sigmoidf_(float x) { return 1.f / (1.f + __expf(-x)); }
; __device__ __forceinline__ void unpack8(const u32x4& w, float (&f)[8]) { f[0] = bflo(w.x); f[1] = bfhi(w.x); f[2] = bflo(w.y); f[3] = bfhi(w.y); f[4] = bflo(w.z); f[5] = bfhi(w.z); f[6] = bflo(w.w); f[7] = bfhi(w.w); }
;     __device__ __forceinline__ void operator()(const f32x4 (&acc)[2][2][4][2], const Unit& u, int wr, int wc, int fr, int fq) const {
;     ...
;                 for (int bj = 0; bj < 2; ++bj) { float g[8]; unpack8(gw[m][bj], g); const f32x4 a0 = acc[ai][bj][m][0], a1 = acc[ai][bj][m][1]; float o[8];
; #pragma unroll
;                     for (int e = 0; e < 4; ++e) { o[e] = a0[e] * sigmoidf_(g[e]); o[4 + e] = a1[e] * sigmoidf_(g[4 + e]); }
;                     *(u32x4*)(T + (size_t)(row0 + ai * HALF + m * 16) * DM + col0 + bj * HALF) = (u32x4){cvt_pk_bf16(o[0], o[1]), cvt_pk_bf16(o[2], o[3]), cvt_pk_bf16(o[4], o[5]), cvt_pk_bf16(o[6], o[7])}; } }
	v_lshlrev_b32_e32 v22, 16, v70
	v_mul_f32_e32 v22, 0xbfb8aa3b, v22
	v_lshlrev_b32_e32 v18, 16, v68
	v_mul_f32_e32 v18, 0xbfb8aa3b, v18
	v_exp_f32_e32 v18, v18
	v_exp_f32_e32 v22, v22
	v_and_b32_e32 v19, 0xffff0000, v68
	v_mul_f32_e32 v19, 0xbfb8aa3b, v19
	v_add_f32_e32 v18, 1.0, v18
	v_div_scale_f32 v23, s[0:1], v18, v18, 1.0
	v_rcp_f32_e32 v24, v23
	v_add_f32_e32 v22, 1.0, v22
	v_exp_f32_e32 v19, v19
	v_and_b32_e32 v25, 0xffff0000, v70
	v_fma_f32 v28, -v23, v24, 1.0
	v_fmac_f32_e32 v24, v28, v24
	v_div_scale_f32 v28, vcc, 1.0, v18, 1.0
	v_mul_f32_e32 v29, v28, v24
	v_fma_f32 v30, -v23, v29, v28
	v_fmac_f32_e32 v29, v30, v24
	v_fma_f32 v23, -v23, v29, v28
	v_div_scale_f32 v28, s[0:1], v22, v22, 1.0
	v_rcp_f32_e32 v30, v28
	v_div_fmas_f32 v23, v23, v24, v29
	v_div_fixup_f32 v18, v23, v18, 1.0
	v_mul_f32_e32 v12, v12, v18
	v_fma_f32 v18, -v28, v30, 1.0
	v_fmac_f32_e32 v30, v18, v30
	v_div_scale_f32 v18, vcc, 1.0, v22, 1.0
	v_mul_f32_e32 v23, v18, v30
	v_fma_f32 v24, -v28, v23, v18
	v_add_f32_e32 v19, 1.0, v19
	v_fmac_f32_e32 v23, v24, v30
	v_div_scale_f32 v24, s[0:1], v19, v19, 1.0
	v_fma_f32 v18, -v28, v23, v18
	v_rcp_f32_e32 v28, v24
	v_div_fmas_f32 v18, v18, v30, v23
	v_div_fixup_f32 v18, v18, v22, 1.0
	v_mul_f32_e32 v23, 0xbfb8aa3b, v25
	v_mul_f32_e32 v18, v8, v18
	v_fma_f32 v8, -v24, v28, 1.0
	v_exp_f32_e32 v23, v23
	v_fmac_f32_e32 v28, v8, v28
	v_div_scale_f32 v8, vcc, 1.0, v19, 1.0
	v_mul_f32_e32 v22, v8, v28
	v_fma_f32 v25, -v24, v22, v8
	v_fmac_f32_e32 v22, v25, v28
	v_add_f32_e32 v23, 1.0, v23
	v_fma_f32 v8, -v24, v22, v8
	v_div_scale_f32 v24, s[0:1], v23, v23, 1.0
	v_rcp_f32_e32 v25, v24
	v_lshlrev_b32_e32 v20, 16, v69
	v_div_fmas_f32 v8, v8, v28, v22
	v_mul_f32_e32 v20, 0xbfb8aa3b, v20
	v_div_fixup_f32 v8, v8, v19, 1.0
	v_exp_f32_e32 v20, v20
	v_mul_f32_e32 v8, v13, v8
	v_fma_f32 v13, -v24, v25, 1.0
	v_fmac_f32_e32 v25, v13, v25
	v_div_scale_f32 v13, vcc, 1.0, v23, 1.0
	v_mul_f32_e32 v19, v13, v25
	v_fma_f32 v22, -v24, v19, v13
	v_add_f32_e32 v20, 1.0, v20
	v_fmac_f32_e32 v19, v22, v25
	v_div_scale_f32 v22, s[0:1], v20, v20, 1.0
	v_fma_f32 v13, -v24, v19, v13
	v_rcp_f32_e32 v24, v22
	v_div_fmas_f32 v13, v13, v25, v19
	v_lshlrev_b32_e32 v26, 16, v71
	v_div_fixup_f32 v13, v13, v23, 1.0
	v_mul_f32_e32 v13, v9, v13
	v_fma_f32 v9, -v22, v24, 1.0
	v_mul_f32_e32 v23, 0xbfb8aa3b, v26
	v_fmac_f32_e32 v24, v9, v24
	v_div_scale_f32 v9, vcc, 1.0, v20, 1.0
	v_exp_f32_e32 v23, v23
	v_mul_f32_e32 v19, v9, v24
	v_fma_f32 v25, -v22, v19, v9
	v_fmac_f32_e32 v19, v25, v24
	v_fma_f32 v9, -v22, v19, v9
	v_add_f32_e32 v22, 1.0, v23
	v_div_scale_f32 v23, s[0:1], v22, v22, 1.0
	v_rcp_f32_e32 v25, v23
	v_and_b32_e32 v21, 0xffff0000, v69
	v_div_fmas_f32 v9, v9, v24, v19
	v_div_fixup_f32 v9, v9, v20, 1.0
	v_mul_f32_e32 v20, 0xbfb8aa3b, v21
	v_exp_f32_e32 v20, v20
	v_mul_f32_e32 v9, v14, v9
	v_fma_f32 v14, -v23, v25, 1.0
	v_fmac_f32_e32 v25, v14, v25
	v_div_scale_f32 v14, vcc, 1.0, v22, 1.0
	v_mul_f32_e32 v19, v14, v25
	v_fma_f32 v21, -v23, v19, v14
	v_add_f32_e32 v20, 1.0, v20
	v_fmac_f32_e32 v19, v21, v25
	v_div_scale_f32 v21, s[0:1], v20, v20, 1.0
	v_fma_f32 v14, -v23, v19, v14
	v_rcp_f32_e32 v23, v21
	v_div_fmas_f32 v14, v14, v25, v19
	v_and_b32_e32 v27, 0xffff0000, v71
	v_div_fixup_f32 v14, v14, v22, 1.0
	v_mul_f32_e32 v14, v10, v14
	v_fma_f32 v10, -v21, v23, 1.0
	v_mul_f32_e32 v22, 0xbfb8aa3b, v27
	v_fmac_f32_e32 v23, v10, v23
	v_div_scale_f32 v10, vcc, 1.0, v20, 1.0
	v_exp_f32_e32 v22, v22
	v_mul_f32_e32 v19, v10, v23
	v_fma_f32 v24, -v21, v19, v10
	v_fmac_f32_e32 v19, v24, v23
	v_fma_f32 v10, -v21, v19, v10
	v_add_f32_e32 v21, 1.0, v22
	v_div_scale_f32 v22, s[0:1], v21, v21, 1.0
	v_rcp_f32_e32 v24, v22
	v_div_fmas_f32 v10, v10, v23, v19
	v_div_fixup_f32 v10, v10, v20, 1.0
	v_mul_f32_e32 v10, v15, v10
	v_fma_f32 v15, -v22, v24, 1.0
	v_fmac_f32_e32 v24, v15, v24
	v_div_scale_f32 v15, vcc, 1.0, v21, 1.0
	v_mul_f32_e32 v19, v15, v24
	v_fma_f32 v20, -v22, v19, v15
	v_fmac_f32_e32 v19, v20, v24
	v_fma_f32 v15, -v22, v19, v15
	v_lshlrev_b64 v[16:17], 12, v[92:93]
	v_div_fmas_f32 v15, v15, v24, v19
	v_div_fixup_f32 v15, v15, v21, 1.0
	v_cvt_pk_bf16_f32 v8, v12, v8
	v_cvt_pk_bf16_f32 v9, v9, v10
	v_cvt_pk_bf16_f32 v10, v18, v13
	v_lshl_add_u64 v[12:13], s[84:85], 0, v[16:17]
	v_mul_f32_e32 v11, v11, v15
	v_lshl_add_u64 v[12:13], v[12:13], 0, v[164:165]
	v_cvt_pk_bf16_f32 v11, v14, v11
	global_store_dwordx4 v[12:13], v[8:11], off
	s_waitcnt vmcnt(7)
; __device__ __forceinline__ unsigned cvt_pk_bf16(float lo, float hi) { unsigned r; asm volatile("v_cvt_pk_bf16_f32 %0, %1, %2" : "=v"(r) : "v"(lo), "v"(hi)); return r; }
; __device__ __forceinline__ float sigmoidf_(float x) { return 1.f / (1.f + __expf(-x)); }
; #define PG8_BAR __builtin_amdgcn_s_barrier()
; __device__ __forceinline__ void unpack8(const u32x4& w, float (&f)[8]) { f[0] = bflo(w.x); f[1] = bfhi(w.x); f[2] = bflo(w.y); f[3] = bfhi(w.y); f[4] = bflo(w.z); f[5] = bfhi(w.z); f[6] = bflo(w.w); f[7] = bfhi(w.w); }
; template <class Epi, class Sched>
; __device__ __forceinline__ void gemm_phase(LAS unsigned char* lds, const Gemm g, const Sched& S, const Epi& E) {
;     ...
;         if (!has_next) break;
; #pragma unroll
;         for (int a = 0; a < 2; ++a)
; #pragma unroll
;             for (int b = 0; b < 2; ++b)
; #pragma unroll
;                 for (int m = 0; m < 4; ++m)
; #pragma unroll
;                     for (int n = 0; n < 2; ++n) acc[a][b][m][n] = (f32x4){0.f, 0.f, 0.f, 0.f};
;         cur = nxt; cA = nA; cB = nB; ++ui;
;         if (wr == 1) PG8_BAR;
;     __device__ __forceinline__ void operator()(const f32x4 (&acc)[2][2][4][2], const Unit& u, int wr, int wc, int fr, int fq) const {
;     ...
;                 for (int bj = 0; bj < 2; ++bj) { float g[8]; unpack8(gw[m][bj], g); const f32x4 a0 = acc[ai][bj][m][0], a1 = acc[ai][bj][m][1]; float o[8];
; #pragma unroll
;                     for (int e = 0; e < 4; ++e) { o[e] = a0[e] * sigmoidf_(g[e]); o[4 + e] = a1[e] * sigmoidf_(g[4 + e]); }
;                     *(u32x4*)(T + (size_t)(row0 + ai * HALF + m * 16) * DM + col0 + bj * HALF) = (u32x4){cvt_pk_bf16(o[0], o[1]), cvt_pk_bf16(o[2], o[3]), cvt_pk_bf16(o[4], o[5]), cvt_pk_bf16(o[6], o[7])}; } }
	v_lshlrev_b32_e32 v14, 16, v66
	v_mul_f32_e32 v14, 0xbfb8aa3b, v14
	v_lshlrev_b32_e32 v8, 16, v64
	v_mul_f32_e32 v8, 0xbfb8aa3b, v8
	v_exp_f32_e32 v8, v8
	v_exp_f32_e32 v14, v14
	v_and_b32_e32 v9, 0xffff0000, v64
	v_mul_f32_e32 v9, 0xbfb8aa3b, v9
	v_add_f32_e32 v8, 1.0, v8
	v_div_scale_f32 v15, s[0:1], v8, v8, 1.0
	v_rcp_f32_e32 v16, v15
	v_add_f32_e32 v14, 1.0, v14
	v_exp_f32_e32 v9, v9
	v_and_b32_e32 v17, 0xffff0000, v66
	v_fma_f32 v20, -v15, v16, 1.0
	v_fmac_f32_e32 v16, v20, v16
	v_div_scale_f32 v20, vcc, 1.0, v8, 1.0
	v_mul_f32_e32 v21, v20, v16
	v_fma_f32 v22, -v15, v21, v20
	v_fmac_f32_e32 v21, v22, v16
	v_fma_f32 v15, -v15, v21, v20
	v_div_scale_f32 v20, s[0:1], v14, v14, 1.0
	v_rcp_f32_e32 v22, v20
	v_div_fmas_f32 v15, v15, v16, v21
	v_div_fixup_f32 v8, v15, v8, 1.0
	v_mul_f32_e32 v4, v4, v8
	v_fma_f32 v8, -v20, v22, 1.0
	v_fmac_f32_e32 v22, v8, v22
	v_div_scale_f32 v8, vcc, 1.0, v14, 1.0
	v_mul_f32_e32 v15, v8, v22
	v_fma_f32 v16, -v20, v15, v8
	v_add_f32_e32 v9, 1.0, v9
	v_fmac_f32_e32 v15, v16, v22
	v_div_scale_f32 v16, s[0:1], v9, v9, 1.0
	v_fma_f32 v8, -v20, v15, v8
	v_rcp_f32_e32 v20, v16
	v_div_fmas_f32 v8, v8, v22, v15
	v_div_fixup_f32 v8, v8, v14, 1.0
	v_mul_f32_e32 v15, 0xbfb8aa3b, v17
	v_mul_f32_e32 v8, v0, v8
	v_fma_f32 v0, -v16, v20, 1.0
	v_exp_f32_e32 v15, v15
	v_fmac_f32_e32 v20, v0, v20
	v_div_scale_f32 v0, vcc, 1.0, v9, 1.0
	v_mul_f32_e32 v14, v0, v20
	v_fma_f32 v17, -v16, v14, v0
	v_fmac_f32_e32 v14, v17, v20
	v_add_f32_e32 v15, 1.0, v15
	v_fma_f32 v0, -v16, v14, v0
	v_div_scale_f32 v16, s[0:1], v15, v15, 1.0
	v_rcp_f32_e32 v17, v16
	v_lshlrev_b32_e32 v10, 16, v65
	v_div_fmas_f32 v0, v0, v20, v14
	v_mul_f32_e32 v10, 0xbfb8aa3b, v10
	v_div_fixup_f32 v0, v0, v9, 1.0
	v_exp_f32_e32 v10, v10
	v_mul_f32_e32 v0, v5, v0
	v_fma_f32 v5, -v16, v17, 1.0
	v_fmac_f32_e32 v17, v5, v17
	v_div_scale_f32 v5, vcc, 1.0, v15, 1.0
	v_mul_f32_e32 v9, v5, v17
	v_fma_f32 v14, -v16, v9, v5
	v_add_f32_e32 v10, 1.0, v10
	v_fmac_f32_e32 v9, v14, v17
	v_div_scale_f32 v14, s[0:1], v10, v10, 1.0
	v_fma_f32 v5, -v16, v9, v5
	v_rcp_f32_e32 v16, v14
	v_div_fmas_f32 v5, v5, v17, v9
	v_lshlrev_b32_e32 v18, 16, v67
	v_div_fixup_f32 v5, v5, v15, 1.0
	v_mul_f32_e32 v5, v1, v5
	v_fma_f32 v1, -v14, v16, 1.0
	v_mul_f32_e32 v15, 0xbfb8aa3b, v18
	v_fmac_f32_e32 v16, v1, v16
	v_div_scale_f32 v1, vcc, 1.0, v10, 1.0
	v_exp_f32_e32 v15, v15
	v_mul_f32_e32 v9, v1, v16
	v_fma_f32 v17, -v14, v9, v1
	v_fmac_f32_e32 v9, v17, v16
	v_fma_f32 v1, -v14, v9, v1
	v_add_f32_e32 v14, 1.0, v15
	v_div_scale_f32 v15, s[0:1], v14, v14, 1.0
	v_rcp_f32_e32 v17, v15
	v_and_b32_e32 v11, 0xffff0000, v65
	v_div_fmas_f32 v1, v1, v16, v9
	v_div_fixup_f32 v1, v1, v10, 1.0
	v_mul_f32_e32 v10, 0xbfb8aa3b, v11
	v_exp_f32_e32 v10, v10
	v_mul_f32_e32 v1, v6, v1
	v_fma_f32 v6, -v15, v17, 1.0
	v_fmac_f32_e32 v17, v6, v17
	v_div_scale_f32 v6, vcc, 1.0, v14, 1.0
	v_mul_f32_e32 v9, v6, v17
	v_fma_f32 v11, -v15, v9, v6
	v_add_f32_e32 v10, 1.0, v10
	v_fmac_f32_e32 v9, v11, v17
	v_div_scale_f32 v11, s[0:1], v10, v10, 1.0
	v_fma_f32 v6, -v15, v9, v6
	v_rcp_f32_e32 v15, v11
	v_div_fmas_f32 v6, v6, v17, v9
	v_and_b32_e32 v19, 0xffff0000, v67
	v_div_fixup_f32 v6, v6, v14, 1.0
	v_mul_f32_e32 v6, v2, v6
	v_fma_f32 v2, -v11, v15, 1.0
	v_mul_f32_e32 v14, 0xbfb8aa3b, v19
	v_fmac_f32_e32 v15, v2, v15
	v_div_scale_f32 v2, vcc, 1.0, v10, 1.0
	v_exp_f32_e32 v14, v14
	v_mul_f32_e32 v9, v2, v15
	v_fma_f32 v16, -v11, v9, v2
	v_fmac_f32_e32 v9, v16, v15
	v_fma_f32 v2, -v11, v9, v2
	v_add_f32_e32 v11, 1.0, v14
	v_div_scale_f32 v14, s[0:1], v11, v11, 1.0
	v_rcp_f32_e32 v16, v14
	v_div_fmas_f32 v2, v2, v15, v9
	v_div_fixup_f32 v2, v2, v10, 1.0
	v_mul_f32_e32 v2, v7, v2
	v_fma_f32 v7, -v14, v16, 1.0
	v_fmac_f32_e32 v16, v7, v16
	v_div_scale_f32 v7, vcc, 1.0, v11, 1.0
	v_mul_f32_e32 v9, v7, v16
	v_fma_f32 v10, -v14, v9, v7
	v_fmac_f32_e32 v9, v10, v16
	v_fma_f32 v7, -v14, v9, v7
	v_div_fmas_f32 v7, v7, v16, v9
	v_div_fixup_f32 v7, v7, v11, 1.0
	v_mul_f32_e32 v3, v3, v7
	s_and_b64 vcc, exec, s[4:5]
	s_mov_b64 s[0:1], -1
	v_cvt_pk_bf16_f32 v0, v4, v0
	v_cvt_pk_bf16_f32 v1, v1, v2
	v_cvt_pk_bf16_f32 v2, v8, v5
	v_cvt_pk_bf16_f32 v3, v6, v3
	global_store_dwordx4 v[12:13], v[0:3], off offset:256
	s_cbranch_vccnz .LBB0_657
	s_andn2_b64 vcc, exec, s[14:15]
	s_cbranch_vccnz .LBB0_656
	s_barrier
	s_branch .LBB0_656

; __device__ __forceinline__ unsigned cvt_pk_bf16(float lo, float hi) { unsigned r; asm volatile("v_cvt_pk_bf16_f32 %0, %1, %2" : "=v"(r) : "v"(lo), "v"(hi)); return r; }
; __device__ __forceinline__ float sigmoidf_(float x) { return 1.f / (1.f + __expf(-x)); }
; __device__ __forceinline__ void unpack8(const u32x4& w, float (&f)[8]) { f[0] = bflo(w.x); f[1] = bfhi(w.x); f[2] = bflo(w.y); f[3] = bfhi(w.y); f[4] = bflo(w.z); f[5] = bfhi(w.z); f[6] = bflo(w.w); f[7] = bfhi(w.w); }
;     __device__ __forceinline__ void operator()(const f32x4 (&acc)[2][2][4][2], const Unit& u, int wr, int wc, int fr, int fq) const {
;     ...
;         for (int ai = 0; ai < 2; ++ai) { u32x4 gw[4][2], tw[4][2];
; #pragma unroll
;             for (int m = 0; m < 4; ++m)
; #pragma unroll
;                 for (int bj = 0; bj < 2; ++bj) { const size_t r = (size_t)(row0 + ai * HALF + m * 16); gw[m][bj] = *(const u32x4*)(gate + r * ldg + col0 + bj * HALF); tw[m][bj] = *(const u32x4*)(T + r * DM + col0 + bj * HALF); }
; #pragma unroll
;             for (int m = 0; m < 4; ++m)
; #pragma unroll
;                 for (int bj = 0; bj < 2; ++bj) { float g[8], t[8]; unpack8(gw[m][bj], g); unpack8(tw[m][bj], t); const f32x4 a0 = acc[ai][bj][m][0], a1 = acc[ai][bj][m][1]; float o[8];
; #pragma unroll
;                     for (int e = 0; e < 4; ++e) { o[e] = t[e] + a0[e] * sigmoidf_(g[e]); o[4 + e] = t[4 + e] + a1[e] * sigmoidf_(g[4 + e]); }
;                     *(u32x4*)(Y + (size_t)(row0 + ai * HALF + m * 16) * DM + col0 + bj * HALF) = (u32x4){cvt_pk_bf16(o[0], o[1]), cvt_pk_bf16(o[2], o[3]), cvt_pk_bf16(o[4], o[5]), cvt_pk_bf16(o[6], o[7])}; } }
.LBB0_700:
	v_lshl_or_b32 v88, s45, 8, v225
	v_ashrrev_i32_e32 v89, 31, v88
	v_lshl_add_u32 v208, s44, 8, v185
	v_lshlrev_b64 v[206:207], 1, v[88:89]
	v_lshl_add_u64 v[212:213], s[8:9], 0, v[206:207]
	v_ashrrev_i32_e32 v209, 31, v208
	v_lshl_add_u64 v[210:211], s[84:85], 0, v[206:207]
	v_mad_i64_i32 v[88:89], s[18:19], v208, s41, v[212:213]
	v_lshlrev_b64 v[220:221], 12, v[208:209]
	v_lshl_add_u64 v[90:91], v[210:211], 0, v[220:221]
	global_load_dwordx4 v[230:233], v[88:89], off nt
	global_load_dwordx4 v[238:241], v[90:91], off nt
	global_load_dwordx4 v[180:183], v[88:89], off offset:256 nt
	global_load_dwordx4 v[176:179], v[90:91], off offset:256 nt
	v_or_b32_e32 v88, 16, v208
	v_ashrrev_i32_e32 v89, 31, v88
	v_lshlrev_b64 v[218:219], 12, v[88:89]
	v_mad_i64_i32 v[90:91], s[18:19], v88, s41, v[212:213]
	v_lshl_add_u64 v[88:89], v[210:211], 0, v[218:219]
	global_load_dwordx4 v[172:175], v[90:91], off nt
	global_load_dwordx4 v[168:171], v[88:89], off nt
	global_load_dwordx4 v[156:159], v[90:91], off offset:256 nt
	global_load_dwordx4 v[152:155], v[88:89], off offset:256 nt
	v_or_b32_e32 v88, 32, v208
	v_ashrrev_i32_e32 v89, 31, v88
	v_lshlrev_b64 v[216:217], 12, v[88:89]
	v_mad_i64_i32 v[90:91], s[18:19], v88, s41, v[212:213]
	v_lshl_add_u64 v[88:89], v[210:211], 0, v[216:217]
	global_load_dwordx4 v[140:143], v[90:91], off nt
	global_load_dwordx4 v[136:139], v[88:89], off nt
	global_load_dwordx4 v[124:127], v[90:91], off offset:256 nt
	global_load_dwordx4 v[120:123], v[88:89], off offset:256 nt
	v_or_b32_e32 v88, 48, v208
	v_ashrrev_i32_e32 v89, 31, v88
	v_lshlrev_b64 v[214:215], 12, v[88:89]
	v_mad_i64_i32 v[90:91], s[18:19], v88, s41, v[212:213]
	v_lshl_add_u64 v[88:89], v[210:211], 0, v[214:215]
	global_load_dwordx4 v[108:111], v[90:91], off nt
	global_load_dwordx4 v[104:107], v[88:89], off nt
	global_load_dwordx4 v[92:95], v[90:91], off offset:256 nt
	s_nop 0
	global_load_dwordx4 v[88:91], v[88:89], off offset:256 nt
	s_waitcnt vmcnt(0)
	v_lshlrev_b32_e32 v237, 16, v230
	v_mul_f32_e32 v237, 0xbfb8aa3b, v237
	v_exp_f32_e32 v237, v237
	v_lshlrev_b32_e32 v209, 16, v238
	v_and_b32_e32 v229, 0xffff0000, v238
	v_and_b32_e32 v242, 0xffff0000, v230
	v_add_f32_e32 v237, 1.0, v237
	v_div_scale_f32 v238, s[18:19], v237, v237, 1.0
	v_lshlrev_b32_e32 v243, 16, v231
	v_and_b32_e32 v244, 0xffff0000, v231
	v_lshlrev_b32_e32 v230, 16, v239
	v_and_b32_e32 v231, 0xffff0000, v239
	v_rcp_f32_e32 v239, v238
	v_lshlrev_b32_e32 v245, 16, v232
	v_and_b32_e32 v246, 0xffff0000, v232
	v_lshlrev_b32_e32 v247, 16, v233
	v_and_b32_e32 v236, 0xffff0000, v233
	v_lshlrev_b32_e32 v232, 16, v240
	v_and_b32_e32 v233, 0xffff0000, v240
	v_fma_f32 v240, -v238, v239, 1.0
	v_fmac_f32_e32 v239, v240, v239
	v_div_scale_f32 v240, vcc, 1.0, v237, 1.0
	v_lshlrev_b32_e32 v234, 16, v241
	v_and_b32_e32 v235, 0xffff0000, v241
	v_mul_f32_e32 v241, v240, v239
	v_fma_f32 v248, -v238, v241, v240
	v_fmac_f32_e32 v241, v248, v239
	v_fma_f32 v238, -v238, v241, v240
	v_div_fmas_f32 v238, v238, v239, v241
	v_div_fixup_f32 v237, v238, v237, 1.0
	v_fmac_f32_e32 v209, v164, v237
	v_mul_f32_e32 v164, 0xbfb8aa3b, v245
	v_exp_f32_e32 v164, v164
	s_nop 0
	v_add_f32_e32 v164, 1.0, v164
	v_div_scale_f32 v237, s[18:19], v164, v164, 1.0
	v_rcp_f32_e32 v238, v237
	s_nop 0
	v_fma_f32 v239, -v237, v238, 1.0
	v_fmac_f32_e32 v238, v239, v238
	v_div_scale_f32 v239, vcc, 1.0, v164, 1.0
	v_mul_f32_e32 v240, v239, v238
	v_fma_f32 v241, -v237, v240, v239
	v_fmac_f32_e32 v240, v241, v238
	v_fma_f32 v237, -v237, v240, v239
	v_div_fmas_f32 v237, v237, v238, v240
	v_div_fixup_f32 v164, v237, v164, 1.0
	v_fmac_f32_e32 v232, v160, v164
	v_mul_f32_e32 v160, 0xbfb8aa3b, v242
	v_exp_f32_e32 v160, v160
	s_nop 0
	v_add_f32_e32 v160, 1.0, v160
	v_div_scale_f32 v164, s[18:19], v160, v160, 1.0
	v_rcp_f32_e32 v237, v164
	s_nop 0
	v_fma_f32 v238, -v164, v237, 1.0
	v_fmac_f32_e32 v237, v238, v237
	v_div_scale_f32 v238, vcc, 1.0, v160, 1.0
	v_mul_f32_e32 v239, v238, v237
	v_fma_f32 v240, -v164, v239, v238
	v_fmac_f32_e32 v239, v240, v237
	v_fma_f32 v164, -v164, v239, v238
	v_div_fmas_f32 v164, v164, v237, v239
	v_div_fixup_f32 v160, v164, v160, 1.0
	v_fmac_f32_e32 v229, v165, v160
	v_mul_f32_e32 v160, 0xbfb8aa3b, v246
	v_exp_f32_e32 v160, v160
	s_nop 0
	v_add_f32_e32 v160, 1.0, v160
	v_div_scale_f32 v164, s[18:19], v160, v160, 1.0
	v_rcp_f32_e32 v165, v164
	s_nop 0
	v_fma_f32 v237, -v164, v165, 1.0
	v_fmac_f32_e32 v165, v237, v165
	v_div_scale_f32 v237, vcc, 1.0, v160, 1.0
	v_mul_f32_e32 v238, v237, v165
	v_fma_f32 v239, -v164, v238, v237
	v_fmac_f32_e32 v238, v239, v165
	v_fma_f32 v164, -v164, v238, v237
	v_div_fmas_f32 v164, v164, v165, v238
	v_div_fixup_f32 v160, v164, v160, 1.0
	v_fmac_f32_e32 v233, v161, v160
	v_mul_f32_e32 v160, 0xbfb8aa3b, v243
	v_exp_f32_e32 v160, v160
	s_nop 0
	v_add_f32_e32 v160, 1.0, v160
	v_div_scale_f32 v161, s[18:19], v160, v160, 1.0
	v_rcp_f32_e32 v164, v161
	s_nop 0
	v_fma_f32 v165, -v161, v164, 1.0
	v_fmac_f32_e32 v164, v165, v164
	v_div_scale_f32 v165, vcc, 1.0, v160, 1.0
	v_mul_f32_e32 v237, v165, v164
	v_fma_f32 v238, -v161, v237, v165
	v_fmac_f32_e32 v237, v238, v164
	v_fma_f32 v161, -v161, v237, v165
	v_div_fmas_f32 v161, v161, v164, v237
	v_div_fixup_f32 v160, v161, v160, 1.0
	v_fmac_f32_e32 v230, v166, v160
	v_mul_f32_e32 v160, 0xbfb8aa3b, v247
	v_exp_f32_e32 v160, v160
	s_nop 0
	v_add_f32_e32 v160, 1.0, v160
	v_div_scale_f32 v161, s[18:19], v160, v160, 1.0
	v_rcp_f32_e32 v164, v161
	s_nop 0
	v_fma_f32 v165, -v161, v164, 1.0
	v_fmac_f32_e32 v164, v165, v164
	v_div_scale_f32 v165, vcc, 1.0, v160, 1.0
	v_mul_f32_e32 v166, v165, v164
	v_fma_f32 v237, -v161, v166, v165
	v_fmac_f32_e32 v166, v237, v164
; __device__ __forceinline__ unsigned cvt_pk_bf16(float lo, float hi) { unsigned r; asm volatile("v_cvt_pk_bf16_f32 %0, %1, %2" : "=v"(r) : "v"(lo), "v"(hi)); return r; }
; __device__ __forceinline__ float sigmoidf_(float x) { return 1.f / (1.f + __expf(-x)); }
; __device__ __forceinline__ void unpack8(const u32x4& w, float (&f)[8]) { f[0] = bflo(w.x); f[1] = bfhi(w.x); f[2] = bflo(w.y); f[3] = bfhi(w.y); f[4] = bflo(w.z); f[5] = bfhi(w.z); f[6] = bflo(w.w); f[7] = bfhi(w.w); }
;     __device__ __forceinline__ void operator()(const f32x4 (&acc)[2][2][4][2], const Unit& u, int wr, int wc, int fr, int fq) const {
;     ...
;                 for (int bj = 0; bj < 2; ++bj) { float g[8], t[8]; unpack8(gw[m][bj], g); unpack8(tw[m][bj], t); const f32x4 a0 = acc[ai][bj][m][0], a1 = acc[ai][bj][m][1]; float o[8];
; #pragma unroll
;                     for (int e = 0; e < 4; ++e) { o[e] = t[e] + a0[e] * sigmoidf_(g[e]); o[4 + e] = t[4 + e] + a1[e] * sigmoidf_(g[4 + e]); }
;                     *(u32x4*)(Y + (size_t)(row0 + ai * HALF + m * 16) * DM + col0 + bj * HALF) = (u32x4){cvt_pk_bf16(o[0], o[1]), cvt_pk_bf16(o[2], o[3]), cvt_pk_bf16(o[4], o[5]), cvt_pk_bf16(o[6], o[7])}; } }
	v_fma_f32 v161, -v161, v166, v165
	v_div_fmas_f32 v161, v161, v164, v166
	v_div_fixup_f32 v160, v161, v160, 1.0
	v_fmac_f32_e32 v234, v162, v160
	v_mul_f32_e32 v160, 0xbfb8aa3b, v244
	v_exp_f32_e32 v160, v160
	s_nop 0
	v_add_f32_e32 v160, 1.0, v160
	v_div_scale_f32 v161, s[18:19], v160, v160, 1.0
	v_rcp_f32_e32 v162, v161
	s_nop 0
	v_fma_f32 v164, -v161, v162, 1.0
	v_fmac_f32_e32 v162, v164, v162
	v_div_scale_f32 v164, vcc, 1.0, v160, 1.0
	v_mul_f32_e32 v165, v164, v162
	v_fma_f32 v166, -v161, v165, v164
	v_fmac_f32_e32 v165, v166, v162
	v_fma_f32 v161, -v161, v165, v164
	v_div_fmas_f32 v161, v161, v162, v165
	v_div_fixup_f32 v160, v161, v160, 1.0
	v_fmac_f32_e32 v231, v167, v160
	v_mul_f32_e32 v160, 0xbfb8aa3b, v236
	v_exp_f32_e32 v160, v160
	v_and_b32_e32 v167, 0xffff0000, v182
	v_add_f32_e32 v160, 1.0, v160
	v_div_scale_f32 v161, s[18:19], v160, v160, 1.0
	v_rcp_f32_e32 v162, v161
	s_nop 0
	v_fma_f32 v164, -v161, v162, 1.0
	v_fmac_f32_e32 v162, v164, v162
	v_div_scale_f32 v164, vcc, 1.0, v160, 1.0
	v_mul_f32_e32 v165, v164, v162
	v_fma_f32 v166, -v161, v165, v164
	v_fmac_f32_e32 v165, v166, v162
	v_fma_f32 v161, -v161, v165, v164
	v_div_fmas_f32 v161, v161, v162, v165
	v_div_fixup_f32 v160, v161, v160, 1.0
	v_fmac_f32_e32 v235, v163, v160
	v_lshl_add_u64 v[160:161], s[76:77], 0, v[220:221]
	v_cvt_pk_bf16_f32 v162, v209, v229
	v_lshl_add_u64 v[160:161], v[160:161], 0, v[206:207]
	v_cvt_pk_bf16_f32 v163, v230, v231
	v_cvt_pk_bf16_f32 v164, v232, v233
	v_cvt_pk_bf16_f32 v165, v234, v235
	global_store_dwordx4 v[160:161], v[162:165], off
	v_lshlrev_b32_e32 v166, 16, v182
	v_lshlrev_b32_e32 v182, 16, v176
	v_lshlrev_b32_e32 v162, 16, v180
	v_mul_f32_e32 v162, 0xbfb8aa3b, v162
	v_exp_f32_e32 v162, v162
	v_and_b32_e32 v163, 0xffff0000, v180
	v_lshlrev_b32_e32 v209, 16, v178
	v_and_b32_e32 v176, 0xffff0000, v176
	v_add_f32_e32 v162, 1.0, v162
	v_div_scale_f32 v221, s[18:19], v162, v162, 1.0
	v_rcp_f32_e32 v229, v221
	v_lshlrev_b32_e32 v164, 16, v181
	v_and_b32_e32 v178, 0xffff0000, v178
	v_and_b32_e32 v165, 0xffff0000, v181
	v_fma_f32 v230, -v221, v229, 1.0
	v_fmac_f32_e32 v229, v230, v229
	v_div_scale_f32 v230, vcc, 1.0, v162, 1.0
	v_mul_f32_e32 v231, v230, v229
	v_fma_f32 v232, -v221, v231, v230
	v_fmac_f32_e32 v231, v232, v229
	v_fma_f32 v221, -v221, v231, v230
	v_div_fmas_f32 v221, v221, v229, v231
	v_div_fixup_f32 v162, v221, v162, 1.0
	v_fmac_f32_e32 v182, v148, v162
	v_mul_f32_e32 v148, 0xbfb8aa3b, v166
	v_exp_f32_e32 v148, v148
	v_lshlrev_b32_e32 v180, 16, v183
	v_and_b32_e32 v181, 0xffff0000, v183
	v_lshlrev_b32_e32 v183, 16, v177
	v_add_f32_e32 v148, 1.0, v148
	v_div_scale_f32 v162, s[18:19], v148, v148, 1.0
	v_rcp_f32_e32 v166, v162
	v_lshlrev_b32_e32 v220, 16, v179
	v_and_b32_e32 v177, 0xffff0000, v177
	v_and_b32_e32 v179, 0xffff0000, v179
	v_fma_f32 v221, -v162, v166, 1.0
	v_fmac_f32_e32 v166, v221, v166
	v_div_scale_f32 v221, vcc, 1.0, v148, 1.0
	v_mul_f32_e32 v229, v221, v166
	v_fma_f32 v230, -v162, v229, v221
	v_fmac_f32_e32 v229, v230, v166
	v_fma_f32 v162, -v162, v229, v221
	v_div_fmas_f32 v162, v162, v166, v229
	v_div_fixup_f32 v148, v162, v148, 1.0
	v_fmac_f32_e32 v209, v144, v148
	v_mul_f32_e32 v144, 0xbfb8aa3b, v163
	v_exp_f32_e32 v144, v144
	s_nop 0
	v_add_f32_e32 v144, 1.0, v144
	v_div_scale_f32 v148, s[18:19], v144, v144, 1.0
	v_rcp_f32_e32 v162, v148
	s_nop 0
	v_fma_f32 v163, -v148, v162, 1.0
	v_fmac_f32_e32 v162, v163, v162
	v_div_scale_f32 v163, vcc, 1.0, v144, 1.0
	v_mul_f32_e32 v166, v163, v162
	v_fma_f32 v221, -v148, v166, v163
	v_fmac_f32_e32 v166, v221, v162
	v_fma_f32 v148, -v148, v166, v163
	v_div_fmas_f32 v148, v148, v162, v166
	v_div_fixup_f32 v144, v148, v144, 1.0
	v_fmac_f32_e32 v176, v149, v144
	v_mul_f32_e32 v144, 0xbfb8aa3b, v167
	v_exp_f32_e32 v144, v144
	v_and_b32_e32 v167, 0xffff0000, v171
	v_add_f32_e32 v144, 1.0, v144
	v_div_scale_f32 v148, s[18:19], v144, v144, 1.0
	v_rcp_f32_e32 v149, v148
	s_nop 0
	v_fma_f32 v162, -v148, v149, 1.0
	v_fmac_f32_e32 v149, v162, v149
	v_div_scale_f32 v162, vcc, 1.0, v144, 1.0
	v_mul_f32_e32 v163, v162, v149
	v_fma_f32 v166, -v148, v163, v162
	v_fmac_f32_e32 v163, v166, v149
	v_fma_f32 v148, -v148, v163, v162
	v_div_fmas_f32 v148, v148, v149, v163
	v_div_fixup_f32 v144, v148, v144, 1.0
	v_fmac_f32_e32 v178, v145, v144
	v_mul_f32_e32 v144, 0xbfb8aa3b, v164
	v_exp_f32_e32 v144, v144
	v_lshlrev_b32_e32 v164, 16, v170
	v_lshlrev_b32_e32 v166, 16, v171
	v_add_f32_e32 v144, 1.0, v144
	v_div_scale_f32 v145, s[18:19], v144, v144, 1.0
	v_rcp_f32_e32 v148, v145
	s_nop 0
	v_fma_f32 v149, -v145, v148, 1.0
	v_fmac_f32_e32 v148, v149, v148
	v_div_scale_f32 v149, vcc, 1.0, v144, 1.0
	v_mul_f32_e32 v162, v149, v148
	v_fma_f32 v163, -v145, v162, v149
	v_fmac_f32_e32 v162, v163, v148
	v_fma_f32 v145, -v145, v162, v149
	v_div_fmas_f32 v145, v145, v148, v162
	v_div_fixup_f32 v144, v145, v144, 1.0
	v_fmac_f32_e32 v183, v150, v144
	v_mul_f32_e32 v144, 0xbfb8aa3b, v180
	v_exp_f32_e32 v144, v144
	v_and_b32_e32 v163, 0xffff0000, v169
	v_add_f32_e32 v144, 1.0, v144
	v_div_scale_f32 v145, s[18:19], v144, v144, 1.0
	v_rcp_f32_e32 v148, v145
	s_nop 0
	v_fma_f32 v149, -v145, v148, 1.0
	v_fmac_f32_e32 v148, v149, v148
	v_div_scale_f32 v149, vcc, 1.0, v144, 1.0
	v_mul_f32_e32 v150, v149, v148
	v_fma_f32 v162, -v145, v150, v149
	v_fmac_f32_e32 v150, v162, v148
	v_fma_f32 v145, -v145, v150, v149
	v_div_fmas_f32 v145, v145, v148, v150
	v_div_fixup_f32 v144, v145, v144, 1.0
	v_fmac_f32_e32 v220, v146, v144
	v_mul_f32_e32 v144, 0xbfb8aa3b, v165
	v_exp_f32_e32 v144, v144
	v_lshlrev_b32_e32 v162, 16, v169
	v_and_b32_e32 v165, 0xffff0000, v170
	v_add_f32_e32 v144, 1.0, v144
	v_div_scale_f32 v145, s[18:19], v144, v144, 1.0
; __device__ __forceinline__ unsigned cvt_pk_bf16(float lo, float hi) { unsigned r; asm volatile("v_cvt_pk_bf16_f32 %0, %1, %2" : "=v"(r) : "v"(lo), "v"(hi)); return r; }
; __device__ __forceinline__ float sigmoidf_(float x) { return 1.f / (1.f + __expf(-x)); }
; __device__ __forceinline__ void unpack8(const u32x4& w, float (&f)[8]) { f[0] = bflo(w.x); f[1] = bfhi(w.x); f[2] = bflo(w.y); f[3] = bfhi(w.y); f[4] = bflo(w.z); f[5] = bfhi(w.z); f[6] = bflo(w.w); f[7] = bfhi(w.w); }
;     __device__ __forceinline__ void operator()(const f32x4 (&acc)[2][2][4][2], const Unit& u, int wr, int wc, int fr, int fq) const {
;     ...
;                 for (int bj = 0; bj < 2; ++bj) { float g[8], t[8]; unpack8(gw[m][bj], g); unpack8(tw[m][bj], t); const f32x4 a0 = acc[ai][bj][m][0], a1 = acc[ai][bj][m][1]; float o[8];
; #pragma unroll
;                     for (int e = 0; e < 4; ++e) { o[e] = t[e] + a0[e] * sigmoidf_(g[e]); o[4 + e] = t[4 + e] + a1[e] * sigmoidf_(g[4 + e]); }
;                     *(u32x4*)(Y + (size_t)(row0 + ai * HALF + m * 16) * DM + col0 + bj * HALF) = (u32x4){cvt_pk_bf16(o[0], o[1]), cvt_pk_bf16(o[2], o[3]), cvt_pk_bf16(o[4], o[5]), cvt_pk_bf16(o[6], o[7])}; } }
	v_rcp_f32_e32 v146, v145
	s_nop 0
	v_fma_f32 v148, -v145, v146, 1.0
	v_fmac_f32_e32 v146, v148, v146
	v_div_scale_f32 v148, vcc, 1.0, v144, 1.0
	v_mul_f32_e32 v149, v148, v146
	v_fma_f32 v150, -v145, v149, v148
	v_fmac_f32_e32 v149, v150, v146
	v_fma_f32 v145, -v145, v149, v148
	v_div_fmas_f32 v145, v145, v146, v149
	v_div_fixup_f32 v144, v145, v144, 1.0
	v_fmac_f32_e32 v177, v151, v144
	v_mul_f32_e32 v144, 0xbfb8aa3b, v181
	v_exp_f32_e32 v144, v144
	v_and_b32_e32 v151, 0xffff0000, v175
	v_add_f32_e32 v144, 1.0, v144
	v_div_scale_f32 v145, s[18:19], v144, v144, 1.0
	v_rcp_f32_e32 v146, v145
	s_nop 0
	v_fma_f32 v148, -v145, v146, 1.0
	v_fmac_f32_e32 v146, v148, v146
	v_div_scale_f32 v148, vcc, 1.0, v144, 1.0
	v_mul_f32_e32 v149, v148, v146
	v_fma_f32 v150, -v145, v149, v148
	v_fmac_f32_e32 v149, v150, v146
	v_fma_f32 v145, -v145, v149, v148
	v_div_fmas_f32 v145, v145, v146, v149
	v_div_fixup_f32 v144, v145, v144, 1.0
	v_fmac_f32_e32 v179, v147, v144
	v_cvt_pk_bf16_f32 v144, v182, v176
	v_cvt_pk_bf16_f32 v145, v183, v177
	v_cvt_pk_bf16_f32 v146, v209, v178
	v_cvt_pk_bf16_f32 v147, v220, v179
	global_store_dwordx4 v[160:161], v[144:147], off offset:256
	v_lshlrev_b32_e32 v160, 16, v168
	v_and_b32_e32 v161, 0xffff0000, v168
	v_lshlrev_b32_e32 v144, 16, v172
	v_mul_f32_e32 v144, 0xbfb8aa3b, v144
	v_exp_f32_e32 v144, v144
	v_and_b32_e32 v145, 0xffff0000, v172
	v_lshlrev_b32_e32 v148, 16, v174
	v_and_b32_e32 v149, 0xffff0000, v174
	v_add_f32_e32 v144, 1.0, v144
	v_div_scale_f32 v168, s[18:19], v144, v144, 1.0
	v_rcp_f32_e32 v169, v168
	v_lshlrev_b32_e32 v146, 16, v173
	v_lshlrev_b32_e32 v150, 16, v175
	v_and_b32_e32 v147, 0xffff0000, v173
	v_fma_f32 v170, -v168, v169, 1.0
	v_fmac_f32_e32 v169, v170, v169
	v_div_scale_f32 v170, vcc, 1.0, v144, 1.0
	v_mul_f32_e32 v171, v170, v169
	v_fma_f32 v172, -v168, v171, v170
	v_fmac_f32_e32 v171, v172, v169
	v_fma_f32 v168, -v168, v171, v170
	v_div_fmas_f32 v168, v168, v169, v171
	v_div_fixup_f32 v144, v168, v144, 1.0
	v_fmac_f32_e32 v160, v132, v144
	v_mul_f32_e32 v132, 0xbfb8aa3b, v148
	v_exp_f32_e32 v132, v132
	s_nop 0
	v_add_f32_e32 v132, 1.0, v132
	v_div_scale_f32 v144, s[18:19], v132, v132, 1.0
	v_rcp_f32_e32 v148, v144
	s_nop 0
	v_fma_f32 v168, -v144, v148, 1.0
	v_fmac_f32_e32 v148, v168, v148
	v_div_scale_f32 v168, vcc, 1.0, v132, 1.0
	v_mul_f32_e32 v169, v168, v148
	v_fma_f32 v170, -v144, v169, v168
	v_fmac_f32_e32 v169, v170, v148
	v_fma_f32 v144, -v144, v169, v168
	v_div_fmas_f32 v144, v144, v148, v169
	v_div_fixup_f32 v132, v144, v132, 1.0
	v_fmac_f32_e32 v164, v128, v132
	v_mul_f32_e32 v128, 0xbfb8aa3b, v145
	v_exp_f32_e32 v128, v128
	s_nop 0
	v_add_f32_e32 v128, 1.0, v128
	v_div_scale_f32 v132, s[18:19], v128, v128, 1.0
	v_rcp_f32_e32 v144, v132
	s_nop 0
	v_fma_f32 v145, -v132, v144, 1.0
	v_fmac_f32_e32 v144, v145, v144
	v_div_scale_f32 v145, vcc, 1.0, v128, 1.0
	v_mul_f32_e32 v148, v145, v144
	v_fma_f32 v168, -v132, v148, v145
	v_fmac_f32_e32 v148, v168, v144
	v_fma_f32 v132, -v132, v148, v145
	v_div_fmas_f32 v132, v132, v144, v148
	v_div_fixup_f32 v128, v132, v128, 1.0
	v_fmac_f32_e32 v161, v133, v128
	v_mul_f32_e32 v128, 0xbfb8aa3b, v149
	v_exp_f32_e32 v128, v128
	v_and_b32_e32 v149, 0xffff0000, v153
	v_add_f32_e32 v128, 1.0, v128
	v_div_scale_f32 v132, s[18:19], v128, v128, 1.0
	v_rcp_f32_e32 v133, v132
	s_nop 0
	v_fma_f32 v144, -v132, v133, 1.0
	v_fmac_f32_e32 v133, v144, v133
	v_div_scale_f32 v144, vcc, 1.0, v128, 1.0
	v_mul_f32_e32 v145, v144, v133
	v_fma_f32 v148, -v132, v145, v144
	v_fmac_f32_e32 v145, v148, v133
	v_fma_f32 v132, -v132, v145, v144
	v_div_fmas_f32 v132, v132, v133, v145
	v_div_fixup_f32 v128, v132, v128, 1.0
	v_fmac_f32_e32 v165, v129, v128
	v_mul_f32_e32 v128, 0xbfb8aa3b, v146
	v_exp_f32_e32 v128, v128
	v_lshlrev_b32_e32 v146, 16, v152
	v_lshlrev_b32_e32 v148, 16, v153
	v_and_b32_e32 v153, 0xffff0000, v155
	v_add_f32_e32 v128, 1.0, v128
	v_div_scale_f32 v129, s[18:19], v128, v128, 1.0
	v_rcp_f32_e32 v132, v129
	s_nop 0
	v_fma_f32 v133, -v129, v132, 1.0
	v_fmac_f32_e32 v132, v133, v132
	v_div_scale_f32 v133, vcc, 1.0, v128, 1.0
	v_mul_f32_e32 v144, v133, v132
	v_fma_f32 v145, -v129, v144, v133
	v_fmac_f32_e32 v144, v145, v132
	v_fma_f32 v129, -v129, v144, v133
	v_div_fmas_f32 v129, v129, v132, v144
	v_div_fixup_f32 v128, v129, v128, 1.0
	v_fmac_f32_e32 v162, v134, v128
	v_mul_f32_e32 v128, 0xbfb8aa3b, v150
	v_exp_f32_e32 v128, v128
	v_lshlrev_b32_e32 v150, 16, v154
	v_and_b32_e32 v145, 0xffff0000, v159
	v_add_f32_e32 v128, 1.0, v128
	v_div_scale_f32 v129, s[18:19], v128, v128, 1.0
	v_rcp_f32_e32 v132, v129
	s_nop 0
	v_fma_f32 v133, -v129, v132, 1.0
	v_fmac_f32_e32 v132, v133, v132
	v_div_scale_f32 v133, vcc, 1.0, v128, 1.0
	v_mul_f32_e32 v134, v133, v132
	v_fma_f32 v144, -v129, v134, v133
	v_fmac_f32_e32 v134, v144, v132
	v_fma_f32 v129, -v129, v134, v133
	v_div_fmas_f32 v129, v129, v132, v134
	v_div_fixup_f32 v128, v129, v128, 1.0
	v_fmac_f32_e32 v166, v130, v128
	v_mul_f32_e32 v128, 0xbfb8aa3b, v147
	v_exp_f32_e32 v128, v128
	v_and_b32_e32 v147, 0xffff0000, v152
	v_lshlrev_b32_e32 v152, 16, v155
	v_lshlrev_b32_e32 v144, 16, v159
	v_add_f32_e32 v128, 1.0, v128
	v_div_scale_f32 v129, s[18:19], v128, v128, 1.0
	v_rcp_f32_e32 v130, v129
	s_nop 0
	v_fma_f32 v132, -v129, v130, 1.0
	v_fmac_f32_e32 v130, v132, v130
	v_div_scale_f32 v132, vcc, 1.0, v128, 1.0
	v_mul_f32_e32 v133, v132, v130
	v_fma_f32 v134, -v129, v133, v132
	v_fmac_f32_e32 v133, v134, v130
	v_fma_f32 v129, -v129, v133, v132
	v_div_fmas_f32 v129, v129, v130, v133
	v_div_fixup_f32 v128, v129, v128, 1.0
	v_fmac_f32_e32 v163, v135, v128
	v_mul_f32_e32 v128, 0xbfb8aa3b, v151
	v_exp_f32_e32 v128, v128
; __device__ __forceinline__ unsigned cvt_pk_bf16(float lo, float hi) { unsigned r; asm volatile("v_cvt_pk_bf16_f32 %0, %1, %2" : "=v"(r) : "v"(lo), "v"(hi)); return r; }
; __device__ __forceinline__ float sigmoidf_(float x) { return 1.f / (1.f + __expf(-x)); }
; __device__ __forceinline__ void unpack8(const u32x4& w, float (&f)[8]) { f[0] = bflo(w.x); f[1] = bfhi(w.x); f[2] = bflo(w.y); f[3] = bfhi(w.y); f[4] = bflo(w.z); f[5] = bfhi(w.z); f[6] = bflo(w.w); f[7] = bfhi(w.w); }
;     __device__ __forceinline__ void operator()(const f32x4 (&acc)[2][2][4][2], const Unit& u, int wr, int wc, int fr, int fq) const {
;     ...
;                 for (int bj = 0; bj < 2; ++bj) { float g[8], t[8]; unpack8(gw[m][bj], g); unpack8(tw[m][bj], t); const f32x4 a0 = acc[ai][bj][m][0], a1 = acc[ai][bj][m][1]; float o[8];
; #pragma unroll
;                     for (int e = 0; e < 4; ++e) { o[e] = t[e] + a0[e] * sigmoidf_(g[e]); o[4 + e] = t[4 + e] + a1[e] * sigmoidf_(g[4 + e]); }
;                     *(u32x4*)(Y + (size_t)(row0 + ai * HALF + m * 16) * DM + col0 + bj * HALF) = (u32x4){cvt_pk_bf16(o[0], o[1]), cvt_pk_bf16(o[2], o[3]), cvt_pk_bf16(o[4], o[5]), cvt_pk_bf16(o[6], o[7])}; } }
	v_and_b32_e32 v151, 0xffff0000, v154
	v_and_b32_e32 v135, 0xffff0000, v158
	v_add_f32_e32 v128, 1.0, v128
	v_div_scale_f32 v129, s[18:19], v128, v128, 1.0
	v_rcp_f32_e32 v130, v129
	s_nop 0
	v_fma_f32 v132, -v129, v130, 1.0
	v_fmac_f32_e32 v130, v132, v130
	v_div_scale_f32 v132, vcc, 1.0, v128, 1.0
	v_mul_f32_e32 v133, v132, v130
	v_fma_f32 v134, -v129, v133, v132
	v_fmac_f32_e32 v133, v134, v130
	v_fma_f32 v129, -v129, v133, v132
	v_div_fmas_f32 v129, v129, v130, v133
	v_div_fixup_f32 v128, v129, v128, 1.0
	v_fmac_f32_e32 v167, v131, v128
	v_lshl_add_u64 v[128:129], s[76:77], 0, v[218:219]
	v_cvt_pk_bf16_f32 v130, v160, v161
	v_lshl_add_u64 v[128:129], v[128:129], 0, v[206:207]
	v_cvt_pk_bf16_f32 v131, v162, v163
	v_cvt_pk_bf16_f32 v132, v164, v165
	v_cvt_pk_bf16_f32 v133, v166, v167
	global_store_dwordx4 v[128:129], v[130:133], off
	v_lshlrev_b32_e32 v134, 16, v158
	s_nop 0
	v_lshlrev_b32_e32 v130, 16, v156
	v_mul_f32_e32 v130, 0xbfb8aa3b, v130
	v_exp_f32_e32 v130, v130
	v_and_b32_e32 v131, 0xffff0000, v156
	v_lshlrev_b32_e32 v132, 16, v157
	v_and_b32_e32 v133, 0xffff0000, v157
	v_add_f32_e32 v130, 1.0, v130
	v_div_scale_f32 v154, s[18:19], v130, v130, 1.0
	v_rcp_f32_e32 v155, v154
	s_nop 0
	v_fma_f32 v156, -v154, v155, 1.0
	v_fmac_f32_e32 v155, v156, v155
	v_div_scale_f32 v156, vcc, 1.0, v130, 1.0
	v_mul_f32_e32 v157, v156, v155
	v_fma_f32 v158, -v154, v157, v156
	v_fmac_f32_e32 v157, v158, v155
	v_fma_f32 v154, -v154, v157, v156
	v_div_fmas_f32 v154, v154, v155, v157
	v_div_fixup_f32 v130, v154, v130, 1.0
	v_fmac_f32_e32 v146, v116, v130
	v_mul_f32_e32 v116, 0xbfb8aa3b, v134
	v_exp_f32_e32 v116, v116
	s_nop 0
	v_add_f32_e32 v116, 1.0, v116
	v_div_scale_f32 v130, s[18:19], v116, v116, 1.0
	v_rcp_f32_e32 v134, v130
	s_nop 0
	v_fma_f32 v154, -v130, v134, 1.0
	v_fmac_f32_e32 v134, v154, v134
	v_div_scale_f32 v154, vcc, 1.0, v116, 1.0
	v_mul_f32_e32 v155, v154, v134
	v_fma_f32 v156, -v130, v155, v154
	v_fmac_f32_e32 v155, v156, v134
	v_fma_f32 v130, -v130, v155, v154
	v_div_fmas_f32 v130, v130, v134, v155
	v_div_fixup_f32 v116, v130, v116, 1.0
	v_fmac_f32_e32 v150, v112, v116
	v_mul_f32_e32 v112, 0xbfb8aa3b, v131
	v_exp_f32_e32 v112, v112
	s_nop 0
	v_add_f32_e32 v112, 1.0, v112
	v_div_scale_f32 v116, s[18:19], v112, v112, 1.0
	v_rcp_f32_e32 v130, v116
	s_nop 0
	v_fma_f32 v131, -v116, v130, 1.0
	v_fmac_f32_e32 v130, v131, v130
	v_div_scale_f32 v131, vcc, 1.0, v112, 1.0
	v_mul_f32_e32 v134, v131, v130
	v_fma_f32 v154, -v116, v134, v131
	v_fmac_f32_e32 v134, v154, v130
	v_fma_f32 v116, -v116, v134, v131
	v_div_fmas_f32 v116, v116, v130, v134
	v_div_fixup_f32 v112, v116, v112, 1.0
	v_fmac_f32_e32 v147, v117, v112
	v_mul_f32_e32 v112, 0xbfb8aa3b, v135
	v_exp_f32_e32 v112, v112
	v_and_b32_e32 v135, 0xffff0000, v139
	v_add_f32_e32 v112, 1.0, v112
	v_div_scale_f32 v116, s[18:19], v112, v112, 1.0
	v_rcp_f32_e32 v117, v116
	s_nop 0
	v_fma_f32 v130, -v116, v117, 1.0
	v_fmac_f32_e32 v117, v130, v117
	v_div_scale_f32 v130, vcc, 1.0, v112, 1.0
	v_mul_f32_e32 v131, v130, v117
	v_fma_f32 v134, -v116, v131, v130
	v_fmac_f32_e32 v131, v134, v117
	v_fma_f32 v116, -v116, v131, v130
	v_div_fmas_f32 v116, v116, v117, v131
	v_div_fixup_f32 v112, v116, v112, 1.0
	v_fmac_f32_e32 v151, v113, v112
	v_mul_f32_e32 v112, 0xbfb8aa3b, v132
	v_exp_f32_e32 v112, v112
	v_lshlrev_b32_e32 v132, 16, v138
	v_lshlrev_b32_e32 v134, 16, v139
	v_add_f32_e32 v112, 1.0, v112
	v_div_scale_f32 v113, s[18:19], v112, v112, 1.0
	v_rcp_f32_e32 v116, v113
	s_nop 0
	v_fma_f32 v117, -v113, v116, 1.0
	v_fmac_f32_e32 v116, v117, v116
	v_div_scale_f32 v117, vcc, 1.0, v112, 1.0
	v_mul_f32_e32 v130, v117, v116
	v_fma_f32 v131, -v113, v130, v117
	v_fmac_f32_e32 v130, v131, v116
	v_fma_f32 v113, -v113, v130, v117
	v_div_fmas_f32 v113, v113, v116, v130
	v_div_fixup_f32 v112, v113, v112, 1.0
	v_fmac_f32_e32 v148, v118, v112
	v_mul_f32_e32 v112, 0xbfb8aa3b, v144
	v_exp_f32_e32 v112, v112
	v_and_b32_e32 v131, 0xffff0000, v137
	v_add_f32_e32 v112, 1.0, v112
	v_div_scale_f32 v113, s[18:19], v112, v112, 1.0
	v_rcp_f32_e32 v116, v113
	s_nop 0
	v_fma_f32 v117, -v113, v116, 1.0
	v_fmac_f32_e32 v116, v117, v116
	v_div_scale_f32 v117, vcc, 1.0, v112, 1.0
	v_mul_f32_e32 v118, v117, v116
	v_fma_f32 v130, -v113, v118, v117
	v_fmac_f32_e32 v118, v130, v116
	v_fma_f32 v113, -v113, v118, v117
	v_div_fmas_f32 v113, v113, v116, v118
	v_div_fixup_f32 v112, v113, v112, 1.0
	v_fmac_f32_e32 v152, v114, v112
	v_mul_f32_e32 v112, 0xbfb8aa3b, v133
	v_exp_f32_e32 v112, v112
	v_lshlrev_b32_e32 v130, 16, v137
	v_and_b32_e32 v133, 0xffff0000, v138
	v_add_f32_e32 v112, 1.0, v112
	v_div_scale_f32 v113, s[18:19], v112, v112, 1.0
	v_rcp_f32_e32 v114, v113
	s_nop 0
	v_fma_f32 v116, -v113, v114, 1.0
	v_fmac_f32_e32 v114, v116, v114
	v_div_scale_f32 v116, vcc, 1.0, v112, 1.0
	v_mul_f32_e32 v117, v116, v114
	v_fma_f32 v118, -v113, v117, v116
	v_fmac_f32_e32 v117, v118, v114
	v_fma_f32 v113, -v113, v117, v116
	v_div_fmas_f32 v113, v113, v114, v117
	v_div_fixup_f32 v112, v113, v112, 1.0
	v_fmac_f32_e32 v149, v119, v112
	v_mul_f32_e32 v112, 0xbfb8aa3b, v145
	v_exp_f32_e32 v112, v112
	v_and_b32_e32 v119, 0xffff0000, v143
	v_add_f32_e32 v112, 1.0, v112
	v_div_scale_f32 v113, s[18:19], v112, v112, 1.0
	v_rcp_f32_e32 v114, v113
	s_nop 0
	v_fma_f32 v116, -v113, v114, 1.0
	v_fmac_f32_e32 v114, v116, v114
	v_div_scale_f32 v116, vcc, 1.0, v112, 1.0
	v_mul_f32_e32 v117, v116, v114
	v_fma_f32 v118, -v113, v117, v116
	v_fmac_f32_e32 v117, v118, v114
	v_fma_f32 v113, -v113, v117, v116
	v_div_fmas_f32 v113, v113, v114, v117
	v_div_fixup_f32 v112, v113, v112, 1.0
	v_fmac_f32_e32 v153, v115, v112
	v_cvt_pk_bf16_f32 v112, v146, v147
; __device__ __forceinline__ unsigned cvt_pk_bf16(float lo, float hi) { unsigned r; asm volatile("v_cvt_pk_bf16_f32 %0, %1, %2" : "=v"(r) : "v"(lo), "v"(hi)); return r; }
; __device__ __forceinline__ float sigmoidf_(float x) { return 1.f / (1.f + __expf(-x)); }
; __device__ __forceinline__ void unpack8(const u32x4& w, float (&f)[8]) { f[0] = bflo(w.x); f[1] = bfhi(w.x); f[2] = bflo(w.y); f[3] = bfhi(w.y); f[4] = bflo(w.z); f[5] = bfhi(w.z); f[6] = bflo(w.w); f[7] = bfhi(w.w); }
;     __device__ __forceinline__ void operator()(const f32x4 (&acc)[2][2][4][2], const Unit& u, int wr, int wc, int fr, int fq) const {
;     ...
;                 for (int bj = 0; bj < 2; ++bj) { float g[8], t[8]; unpack8(gw[m][bj], g); unpack8(tw[m][bj], t); const f32x4 a0 = acc[ai][bj][m][0], a1 = acc[ai][bj][m][1]; float o[8];
; #pragma unroll
;                     for (int e = 0; e < 4; ++e) { o[e] = t[e] + a0[e] * sigmoidf_(g[e]); o[4 + e] = t[4 + e] + a1[e] * sigmoidf_(g[4 + e]); }
;                     *(u32x4*)(Y + (size_t)(row0 + ai * HALF + m * 16) * DM + col0 + bj * HALF) = (u32x4){cvt_pk_bf16(o[0], o[1]), cvt_pk_bf16(o[2], o[3]), cvt_pk_bf16(o[4], o[5]), cvt_pk_bf16(o[6], o[7])}; } }
	v_cvt_pk_bf16_f32 v113, v148, v149
	v_cvt_pk_bf16_f32 v114, v150, v151
	v_cvt_pk_bf16_f32 v115, v152, v153
	global_store_dwordx4 v[128:129], v[112:115], off offset:256
	v_lshlrev_b32_e32 v128, 16, v136
	v_and_b32_e32 v129, 0xffff0000, v136
	v_lshlrev_b32_e32 v112, 16, v140
	v_mul_f32_e32 v112, 0xbfb8aa3b, v112
	v_exp_f32_e32 v112, v112
	v_and_b32_e32 v113, 0xffff0000, v140
	v_lshlrev_b32_e32 v116, 16, v142
	v_and_b32_e32 v117, 0xffff0000, v142
	v_add_f32_e32 v112, 1.0, v112
	v_div_scale_f32 v136, s[18:19], v112, v112, 1.0
	v_rcp_f32_e32 v137, v136
	v_lshlrev_b32_e32 v114, 16, v141
	v_lshlrev_b32_e32 v118, 16, v143
	v_and_b32_e32 v115, 0xffff0000, v141
	v_fma_f32 v138, -v136, v137, 1.0
	v_fmac_f32_e32 v137, v138, v137
	v_div_scale_f32 v138, vcc, 1.0, v112, 1.0
	v_mul_f32_e32 v139, v138, v137
	v_fma_f32 v140, -v136, v139, v138
	v_fmac_f32_e32 v139, v140, v137
	v_fma_f32 v136, -v136, v139, v138
	v_div_fmas_f32 v136, v136, v137, v139
	v_div_fixup_f32 v112, v136, v112, 1.0
	v_fmac_f32_e32 v128, v100, v112
	v_mul_f32_e32 v100, 0xbfb8aa3b, v116
	v_exp_f32_e32 v100, v100
	s_nop 0
	v_add_f32_e32 v100, 1.0, v100
	v_div_scale_f32 v112, s[18:19], v100, v100, 1.0
	v_rcp_f32_e32 v116, v112
	s_nop 0
	v_fma_f32 v136, -v112, v116, 1.0
	v_fmac_f32_e32 v116, v136, v116
	v_div_scale_f32 v136, vcc, 1.0, v100, 1.0
	v_mul_f32_e32 v137, v136, v116
	v_fma_f32 v138, -v112, v137, v136
	v_fmac_f32_e32 v137, v138, v116
	v_fma_f32 v112, -v112, v137, v136
	v_div_fmas_f32 v112, v112, v116, v137
	v_div_fixup_f32 v100, v112, v100, 1.0
	v_fmac_f32_e32 v132, v96, v100
	v_mul_f32_e32 v96, 0xbfb8aa3b, v113
	v_exp_f32_e32 v96, v96
	s_nop 0
	v_add_f32_e32 v96, 1.0, v96
	v_div_scale_f32 v100, s[18:19], v96, v96, 1.0
	v_rcp_f32_e32 v112, v100
	s_nop 0
	v_fma_f32 v113, -v100, v112, 1.0
	v_fmac_f32_e32 v112, v113, v112
	v_div_scale_f32 v113, vcc, 1.0, v96, 1.0
	v_mul_f32_e32 v116, v113, v112
	v_fma_f32 v136, -v100, v116, v113
	v_fmac_f32_e32 v116, v136, v112
	v_fma_f32 v100, -v100, v116, v113
	v_div_fmas_f32 v100, v100, v112, v116
	v_div_fixup_f32 v96, v100, v96, 1.0
	v_fmac_f32_e32 v129, v101, v96
	v_mul_f32_e32 v96, 0xbfb8aa3b, v117
	v_exp_f32_e32 v96, v96
	v_and_b32_e32 v117, 0xffff0000, v121
	v_add_f32_e32 v96, 1.0, v96
	v_div_scale_f32 v100, s[18:19], v96, v96, 1.0
	v_rcp_f32_e32 v101, v100
	s_nop 0
	v_fma_f32 v112, -v100, v101, 1.0
	v_fmac_f32_e32 v101, v112, v101
	v_div_scale_f32 v112, vcc, 1.0, v96, 1.0
	v_mul_f32_e32 v113, v112, v101
	v_fma_f32 v116, -v100, v113, v112
	v_fmac_f32_e32 v113, v116, v101
	v_fma_f32 v100, -v100, v113, v112
	v_div_fmas_f32 v100, v100, v101, v113
	v_div_fixup_f32 v96, v100, v96, 1.0
	v_fmac_f32_e32 v133, v97, v96
	v_mul_f32_e32 v96, 0xbfb8aa3b, v114
	v_exp_f32_e32 v96, v96
	v_lshlrev_b32_e32 v114, 16, v120
	v_lshlrev_b32_e32 v116, 16, v121
	v_and_b32_e32 v121, 0xffff0000, v123
	v_add_f32_e32 v96, 1.0, v96
	v_div_scale_f32 v97, s[18:19], v96, v96, 1.0
	v_rcp_f32_e32 v100, v97
	s_nop 0
	v_fma_f32 v101, -v97, v100, 1.0
	v_fmac_f32_e32 v100, v101, v100
	v_div_scale_f32 v101, vcc, 1.0, v96, 1.0
	v_mul_f32_e32 v112, v101, v100
	v_fma_f32 v113, -v97, v112, v101
	v_fmac_f32_e32 v112, v113, v100
	v_fma_f32 v97, -v97, v112, v101
	v_div_fmas_f32 v97, v97, v100, v112
	v_div_fixup_f32 v96, v97, v96, 1.0
	v_fmac_f32_e32 v130, v102, v96
	v_mul_f32_e32 v96, 0xbfb8aa3b, v118
	v_exp_f32_e32 v96, v96
	v_lshlrev_b32_e32 v118, 16, v122
	v_and_b32_e32 v113, 0xffff0000, v127
	v_add_f32_e32 v96, 1.0, v96
	v_div_scale_f32 v97, s[18:19], v96, v96, 1.0
	v_rcp_f32_e32 v100, v97
	s_nop 0
	v_fma_f32 v101, -v97, v100, 1.0
	v_fmac_f32_e32 v100, v101, v100
	v_div_scale_f32 v101, vcc, 1.0, v96, 1.0
	v_mul_f32_e32 v102, v101, v100
	v_fma_f32 v112, -v97, v102, v101
	v_fmac_f32_e32 v102, v112, v100
	v_fma_f32 v97, -v97, v102, v101
	v_div_fmas_f32 v97, v97, v100, v102
	v_div_fixup_f32 v96, v97, v96, 1.0
	v_fmac_f32_e32 v134, v98, v96
	v_mul_f32_e32 v96, 0xbfb8aa3b, v115
	v_exp_f32_e32 v96, v96
	v_and_b32_e32 v115, 0xffff0000, v120
	v_lshlrev_b32_e32 v120, 16, v123
	v_lshlrev_b32_e32 v112, 16, v127
	v_add_f32_e32 v96, 1.0, v96
	v_div_scale_f32 v97, s[18:19], v96, v96, 1.0
	v_rcp_f32_e32 v98, v97
	s_nop 0
	v_fma_f32 v100, -v97, v98, 1.0
	v_fmac_f32_e32 v98, v100, v98
	v_div_scale_f32 v100, vcc, 1.0, v96, 1.0
	v_mul_f32_e32 v101, v100, v98
	v_fma_f32 v102, -v97, v101, v100
	v_fmac_f32_e32 v101, v102, v98
	v_fma_f32 v97, -v97, v101, v100
	v_div_fmas_f32 v97, v97, v98, v101
	v_div_fixup_f32 v96, v97, v96, 1.0
	v_fmac_f32_e32 v131, v103, v96
	v_mul_f32_e32 v96, 0xbfb8aa3b, v119
	v_exp_f32_e32 v96, v96
	v_and_b32_e32 v119, 0xffff0000, v122
	v_and_b32_e32 v103, 0xffff0000, v126
	v_add_f32_e32 v96, 1.0, v96
	v_div_scale_f32 v97, s[18:19], v96, v96, 1.0
	v_rcp_f32_e32 v98, v97
	s_nop 0
	v_fma_f32 v100, -v97, v98, 1.0
	v_fmac_f32_e32 v98, v100, v98
	v_div_scale_f32 v100, vcc, 1.0, v96, 1.0
	v_mul_f32_e32 v101, v100, v98
	v_fma_f32 v102, -v97, v101, v100
	v_fmac_f32_e32 v101, v102, v98
	v_fma_f32 v97, -v97, v101, v100
	v_div_fmas_f32 v97, v97, v98, v101
	v_div_fixup_f32 v96, v97, v96, 1.0
	v_fmac_f32_e32 v135, v99, v96
	v_lshl_add_u64 v[96:97], s[76:77], 0, v[216:217]
	v_cvt_pk_bf16_f32 v98, v128, v129
	v_lshl_add_u64 v[96:97], v[96:97], 0, v[206:207]
	v_cvt_pk_bf16_f32 v99, v130, v131
	v_cvt_pk_bf16_f32 v100, v132, v133
	v_cvt_pk_bf16_f32 v101, v134, v135
	global_store_dwordx4 v[96:97], v[98:101], off
	v_lshlrev_b32_e32 v102, 16, v126
	s_nop 0
	v_lshlrev_b32_e32 v98, 16, v124
	v_mul_f32_e32 v98, 0xbfb8aa3b, v98
	v_exp_f32_e32 v98, v98
	v_and_b32_e32 v99, 0xffff0000, v124
	v_lshlrev_b32_e32 v100, 16, v125
	v_and_b32_e32 v101, 0xffff0000, v125
	v_add_f32_e32 v98, 1.0, v98
; __device__ __forceinline__ unsigned cvt_pk_bf16(float lo, float hi) { unsigned r; asm volatile("v_cvt_pk_bf16_f32 %0, %1, %2" : "=v"(r) : "v"(lo), "v"(hi)); return r; }
; __device__ __forceinline__ float sigmoidf_(float x) { return 1.f / (1.f + __expf(-x)); }
; __device__ __forceinline__ void unpack8(const u32x4& w, float (&f)[8]) { f[0] = bflo(w.x); f[1] = bfhi(w.x); f[2] = bflo(w.y); f[3] = bfhi(w.y); f[4] = bflo(w.z); f[5] = bfhi(w.z); f[6] = bflo(w.w); f[7] = bfhi(w.w); }
;     __device__ __forceinline__ void operator()(const f32x4 (&acc)[2][2][4][2], const Unit& u, int wr, int wc, int fr, int fq) const {
;     ...
;                 for (int bj = 0; bj < 2; ++bj) { float g[8], t[8]; unpack8(gw[m][bj], g); unpack8(tw[m][bj], t); const f32x4 a0 = acc[ai][bj][m][0], a1 = acc[ai][bj][m][1]; float o[8];
; #pragma unroll
;                     for (int e = 0; e < 4; ++e) { o[e] = t[e] + a0[e] * sigmoidf_(g[e]); o[4 + e] = t[4 + e] + a1[e] * sigmoidf_(g[4 + e]); }
;                     *(u32x4*)(Y + (size_t)(row0 + ai * HALF + m * 16) * DM + col0 + bj * HALF) = (u32x4){cvt_pk_bf16(o[0], o[1]), cvt_pk_bf16(o[2], o[3]), cvt_pk_bf16(o[4], o[5]), cvt_pk_bf16(o[6], o[7])}; } }
	v_div_scale_f32 v122, s[18:19], v98, v98, 1.0
	v_rcp_f32_e32 v123, v122
	s_nop 0
	v_fma_f32 v124, -v122, v123, 1.0
	v_fmac_f32_e32 v123, v124, v123
	v_div_scale_f32 v124, vcc, 1.0, v98, 1.0
	v_mul_f32_e32 v125, v124, v123
	v_fma_f32 v126, -v122, v125, v124
	v_fmac_f32_e32 v125, v126, v123
	v_fma_f32 v122, -v122, v125, v124
	v_div_fmas_f32 v122, v122, v123, v125
	v_div_fixup_f32 v98, v122, v98, 1.0
	v_fmac_f32_e32 v114, v84, v98
	v_mul_f32_e32 v84, 0xbfb8aa3b, v102
	v_exp_f32_e32 v84, v84
	s_nop 0
	v_add_f32_e32 v84, 1.0, v84
	v_div_scale_f32 v98, s[18:19], v84, v84, 1.0
	v_rcp_f32_e32 v102, v98
	s_nop 0
	v_fma_f32 v122, -v98, v102, 1.0
	v_fmac_f32_e32 v102, v122, v102
	v_div_scale_f32 v122, vcc, 1.0, v84, 1.0
	v_mul_f32_e32 v123, v122, v102
	v_fma_f32 v124, -v98, v123, v122
	v_fmac_f32_e32 v123, v124, v102
	v_fma_f32 v98, -v98, v123, v122
	v_div_fmas_f32 v98, v98, v102, v123
	v_div_fixup_f32 v84, v98, v84, 1.0
	v_fmac_f32_e32 v118, v80, v84
	v_mul_f32_e32 v80, 0xbfb8aa3b, v99
	v_exp_f32_e32 v80, v80
	s_nop 0
	v_add_f32_e32 v80, 1.0, v80
	v_div_scale_f32 v84, s[18:19], v80, v80, 1.0
	v_rcp_f32_e32 v98, v84
	s_nop 0
	v_fma_f32 v99, -v84, v98, 1.0
	v_fmac_f32_e32 v98, v99, v98
	v_div_scale_f32 v99, vcc, 1.0, v80, 1.0
	v_mul_f32_e32 v102, v99, v98
	v_fma_f32 v122, -v84, v102, v99
	v_fmac_f32_e32 v102, v122, v98
	v_fma_f32 v84, -v84, v102, v99
	v_div_fmas_f32 v84, v84, v98, v102
	v_div_fixup_f32 v80, v84, v80, 1.0
	v_fmac_f32_e32 v115, v85, v80
	v_mul_f32_e32 v80, 0xbfb8aa3b, v103
	v_exp_f32_e32 v80, v80
	v_and_b32_e32 v103, 0xffff0000, v107
	v_add_f32_e32 v80, 1.0, v80
	v_div_scale_f32 v84, s[18:19], v80, v80, 1.0
	v_rcp_f32_e32 v85, v84
	s_nop 0
	v_fma_f32 v98, -v84, v85, 1.0
	v_fmac_f32_e32 v85, v98, v85
	v_div_scale_f32 v98, vcc, 1.0, v80, 1.0
	v_mul_f32_e32 v99, v98, v85
	v_fma_f32 v102, -v84, v99, v98
	v_fmac_f32_e32 v99, v102, v85
	v_fma_f32 v84, -v84, v99, v98
	v_div_fmas_f32 v84, v84, v85, v99
	v_div_fixup_f32 v80, v84, v80, 1.0
	v_fmac_f32_e32 v119, v81, v80
	v_mul_f32_e32 v80, 0xbfb8aa3b, v100
	v_exp_f32_e32 v80, v80
	v_lshlrev_b32_e32 v100, 16, v106
	v_lshlrev_b32_e32 v102, 16, v107
	v_add_f32_e32 v80, 1.0, v80
	v_div_scale_f32 v81, s[18:19], v80, v80, 1.0
	v_rcp_f32_e32 v84, v81
	s_nop 0
	v_fma_f32 v85, -v81, v84, 1.0
	v_fmac_f32_e32 v84, v85, v84
	v_div_scale_f32 v85, vcc, 1.0, v80, 1.0
	v_mul_f32_e32 v98, v85, v84
	v_fma_f32 v99, -v81, v98, v85
	v_fmac_f32_e32 v98, v99, v84
	v_fma_f32 v81, -v81, v98, v85
	v_div_fmas_f32 v81, v81, v84, v98
	v_div_fixup_f32 v80, v81, v80, 1.0
	v_fmac_f32_e32 v116, v86, v80
	v_mul_f32_e32 v80, 0xbfb8aa3b, v112
	v_exp_f32_e32 v80, v80
	v_and_b32_e32 v99, 0xffff0000, v105
	v_add_f32_e32 v80, 1.0, v80
	v_div_scale_f32 v81, s[18:19], v80, v80, 1.0
	v_rcp_f32_e32 v84, v81
	s_nop 0
	v_fma_f32 v85, -v81, v84, 1.0
	v_fmac_f32_e32 v84, v85, v84
	v_div_scale_f32 v85, vcc, 1.0, v80, 1.0
	v_mul_f32_e32 v86, v85, v84
	v_fma_f32 v98, -v81, v86, v85
	v_fmac_f32_e32 v86, v98, v84
	v_fma_f32 v81, -v81, v86, v85
	v_div_fmas_f32 v81, v81, v84, v86
	v_div_fixup_f32 v80, v81, v80, 1.0
	v_fmac_f32_e32 v120, v82, v80
	v_mul_f32_e32 v80, 0xbfb8aa3b, v101
	v_exp_f32_e32 v80, v80
	v_lshlrev_b32_e32 v98, 16, v105
	v_and_b32_e32 v101, 0xffff0000, v106
	v_add_f32_e32 v80, 1.0, v80
	v_div_scale_f32 v81, s[18:19], v80, v80, 1.0
	v_rcp_f32_e32 v82, v81
	s_nop 0
	v_fma_f32 v84, -v81, v82, 1.0
	v_fmac_f32_e32 v82, v84, v82
	v_div_scale_f32 v84, vcc, 1.0, v80, 1.0
	v_mul_f32_e32 v85, v84, v82
	v_fma_f32 v86, -v81, v85, v84
	v_fmac_f32_e32 v85, v86, v82
	v_fma_f32 v81, -v81, v85, v84
	v_div_fmas_f32 v81, v81, v82, v85
	v_div_fixup_f32 v80, v81, v80, 1.0
	v_fmac_f32_e32 v117, v87, v80
	v_mul_f32_e32 v80, 0xbfb8aa3b, v113
	v_exp_f32_e32 v80, v80
	v_and_b32_e32 v87, 0xffff0000, v111
	v_add_f32_e32 v80, 1.0, v80
	v_div_scale_f32 v81, s[18:19], v80, v80, 1.0
	v_rcp_f32_e32 v82, v81
	s_nop 0
	v_fma_f32 v84, -v81, v82, 1.0
	v_fmac_f32_e32 v82, v84, v82
	v_div_scale_f32 v84, vcc, 1.0, v80, 1.0
	v_mul_f32_e32 v85, v84, v82
	v_fma_f32 v86, -v81, v85, v84
	v_fmac_f32_e32 v85, v86, v82
	v_fma_f32 v81, -v81, v85, v84
	v_div_fmas_f32 v81, v81, v82, v85
	v_div_fixup_f32 v80, v81, v80, 1.0
	v_fmac_f32_e32 v121, v83, v80
	v_cvt_pk_bf16_f32 v80, v114, v115
	v_cvt_pk_bf16_f32 v81, v116, v117
	v_cvt_pk_bf16_f32 v82, v118, v119
	v_cvt_pk_bf16_f32 v83, v120, v121
	global_store_dwordx4 v[96:97], v[80:83], off offset:256
	v_lshlrev_b32_e32 v96, 16, v104
	v_and_b32_e32 v97, 0xffff0000, v104
	v_lshlrev_b32_e32 v80, 16, v108
	v_mul_f32_e32 v80, 0xbfb8aa3b, v80
	v_exp_f32_e32 v80, v80
	v_and_b32_e32 v81, 0xffff0000, v108
	v_lshlrev_b32_e32 v84, 16, v110
	v_and_b32_e32 v85, 0xffff0000, v110
	v_add_f32_e32 v80, 1.0, v80
	v_div_scale_f32 v104, s[18:19], v80, v80, 1.0
	v_rcp_f32_e32 v105, v104
	v_lshlrev_b32_e32 v82, 16, v109
	v_lshlrev_b32_e32 v86, 16, v111
	v_and_b32_e32 v83, 0xffff0000, v109
	v_fma_f32 v106, -v104, v105, 1.0
	v_fmac_f32_e32 v105, v106, v105
	v_div_scale_f32 v106, vcc, 1.0, v80, 1.0
	v_mul_f32_e32 v107, v106, v105
	v_fma_f32 v108, -v104, v107, v106
	v_fmac_f32_e32 v107, v108, v105
	v_fma_f32 v104, -v104, v107, v106
	v_div_fmas_f32 v104, v104, v105, v107
	v_div_fixup_f32 v80, v104, v80, 1.0
	v_fmac_f32_e32 v96, v76, v80
	v_mul_f32_e32 v76, 0xbfb8aa3b, v84
	v_exp_f32_e32 v76, v76
	s_nop 0
	v_add_f32_e32 v76, 1.0, v76
	v_div_scale_f32 v80, s[18:19], v76, v76, 1.0
	v_rcp_f32_e32 v84, v80
	s_nop 0
	v_fma_f32 v104, -v80, v84, 1.0
	v_fmac_f32_e32 v84, v104, v84
	v_div_scale_f32 v104, vcc, 1.0, v76, 1.0
	v_mul_f32_e32 v105, v104, v84
	v_fma_f32 v106, -v80, v105, v104
	v_fmac_f32_e32 v105, v106, v84
	v_fma_f32 v80, -v80, v105, v104
; __device__ __forceinline__ unsigned cvt_pk_bf16(float lo, float hi) { unsigned r; asm volatile("v_cvt_pk_bf16_f32 %0, %1, %2" : "=v"(r) : "v"(lo), "v"(hi)); return r; }
; __device__ __forceinline__ float sigmoidf_(float x) { return 1.f / (1.f + __expf(-x)); }
; __device__ __forceinline__ void unpack8(const u32x4& w, float (&f)[8]) { f[0] = bflo(w.x); f[1] = bfhi(w.x); f[2] = bflo(w.y); f[3] = bfhi(w.y); f[4] = bflo(w.z); f[5] = bfhi(w.z); f[6] = bflo(w.w); f[7] = bfhi(w.w); }
;     __device__ __forceinline__ void operator()(const f32x4 (&acc)[2][2][4][2], const Unit& u, int wr, int wc, int fr, int fq) const {
;     ...
;                 for (int bj = 0; bj < 2; ++bj) { float g[8], t[8]; unpack8(gw[m][bj], g); unpack8(tw[m][bj], t); const f32x4 a0 = acc[ai][bj][m][0], a1 = acc[ai][bj][m][1]; float o[8];
; #pragma unroll
;                     for (int e = 0; e < 4; ++e) { o[e] = t[e] + a0[e] * sigmoidf_(g[e]); o[4 + e] = t[4 + e] + a1[e] * sigmoidf_(g[4 + e]); }
;                     *(u32x4*)(Y + (size_t)(row0 + ai * HALF + m * 16) * DM + col0 + bj * HALF) = (u32x4){cvt_pk_bf16(o[0], o[1]), cvt_pk_bf16(o[2], o[3]), cvt_pk_bf16(o[4], o[5]), cvt_pk_bf16(o[6], o[7])}; } }
	v_div_fmas_f32 v80, v80, v84, v105
	v_div_fixup_f32 v76, v80, v76, 1.0
	v_fmac_f32_e32 v100, v72, v76
	v_mul_f32_e32 v72, 0xbfb8aa3b, v81
	v_exp_f32_e32 v72, v72
	s_nop 0
	v_add_f32_e32 v72, 1.0, v72
	v_div_scale_f32 v76, s[18:19], v72, v72, 1.0
	v_rcp_f32_e32 v80, v76
	s_nop 0
	v_fma_f32 v81, -v76, v80, 1.0
	v_fmac_f32_e32 v80, v81, v80
	v_div_scale_f32 v81, vcc, 1.0, v72, 1.0
	v_mul_f32_e32 v84, v81, v80
	v_fma_f32 v104, -v76, v84, v81
	v_fmac_f32_e32 v84, v104, v80
	v_fma_f32 v76, -v76, v84, v81
	v_div_fmas_f32 v76, v76, v80, v84
	v_div_fixup_f32 v72, v76, v72, 1.0
	v_fmac_f32_e32 v97, v77, v72
	v_mul_f32_e32 v72, 0xbfb8aa3b, v85
	v_exp_f32_e32 v72, v72
	v_and_b32_e32 v85, 0xffff0000, v89
	v_add_f32_e32 v72, 1.0, v72
	v_div_scale_f32 v76, s[18:19], v72, v72, 1.0
	v_rcp_f32_e32 v77, v76
	s_nop 0
	v_fma_f32 v80, -v76, v77, 1.0
	v_fmac_f32_e32 v77, v80, v77
	v_div_scale_f32 v80, vcc, 1.0, v72, 1.0
	v_mul_f32_e32 v81, v80, v77
	v_fma_f32 v84, -v76, v81, v80
	v_fmac_f32_e32 v81, v84, v77
	v_fma_f32 v76, -v76, v81, v80
	v_div_fmas_f32 v76, v76, v77, v81
	v_div_fixup_f32 v72, v76, v72, 1.0
	v_fmac_f32_e32 v101, v73, v72
	v_mul_f32_e32 v72, 0xbfb8aa3b, v82
	v_exp_f32_e32 v72, v72
	v_lshlrev_b32_e32 v82, 16, v88
	v_lshlrev_b32_e32 v84, 16, v89
	v_and_b32_e32 v89, 0xffff0000, v91
	v_add_f32_e32 v72, 1.0, v72
	v_div_scale_f32 v73, s[18:19], v72, v72, 1.0
	v_rcp_f32_e32 v76, v73
	s_nop 0
	v_fma_f32 v77, -v73, v76, 1.0
	v_fmac_f32_e32 v76, v77, v76
	v_div_scale_f32 v77, vcc, 1.0, v72, 1.0
	v_mul_f32_e32 v80, v77, v76
	v_fma_f32 v81, -v73, v80, v77
	v_fmac_f32_e32 v80, v81, v76
	v_fma_f32 v73, -v73, v80, v77
	v_div_fmas_f32 v73, v73, v76, v80
	v_div_fixup_f32 v72, v73, v72, 1.0
	v_fmac_f32_e32 v98, v78, v72
	v_mul_f32_e32 v72, 0xbfb8aa3b, v86
	v_exp_f32_e32 v72, v72
	v_lshlrev_b32_e32 v86, 16, v90
	v_and_b32_e32 v81, 0xffff0000, v95
	v_add_f32_e32 v72, 1.0, v72
	v_div_scale_f32 v73, s[18:19], v72, v72, 1.0
	v_rcp_f32_e32 v76, v73
	s_nop 0
	v_fma_f32 v77, -v73, v76, 1.0
	v_fmac_f32_e32 v76, v77, v76
	v_div_scale_f32 v77, vcc, 1.0, v72, 1.0
	v_mul_f32_e32 v78, v77, v76
	v_fma_f32 v80, -v73, v78, v77
	v_fmac_f32_e32 v78, v80, v76
	v_fma_f32 v73, -v73, v78, v77
	v_div_fmas_f32 v73, v73, v76, v78
	v_div_fixup_f32 v72, v73, v72, 1.0
	v_fmac_f32_e32 v102, v74, v72
	v_mul_f32_e32 v72, 0xbfb8aa3b, v83
	v_exp_f32_e32 v72, v72
	v_and_b32_e32 v83, 0xffff0000, v88
	v_lshlrev_b32_e32 v88, 16, v91
	v_lshlrev_b32_e32 v80, 16, v95
	v_add_f32_e32 v72, 1.0, v72
	v_div_scale_f32 v73, s[18:19], v72, v72, 1.0
	v_rcp_f32_e32 v74, v73
	s_nop 0
	v_fma_f32 v76, -v73, v74, 1.0
	v_fmac_f32_e32 v74, v76, v74
	v_div_scale_f32 v76, vcc, 1.0, v72, 1.0
	v_mul_f32_e32 v77, v76, v74
	v_fma_f32 v78, -v73, v77, v76
	v_fmac_f32_e32 v77, v78, v74
	v_fma_f32 v73, -v73, v77, v76
	v_div_fmas_f32 v73, v73, v74, v77
	v_div_fixup_f32 v72, v73, v72, 1.0
	v_fmac_f32_e32 v99, v79, v72
	v_mul_f32_e32 v72, 0xbfb8aa3b, v87
	v_exp_f32_e32 v72, v72
	v_and_b32_e32 v87, 0xffff0000, v90
	v_and_b32_e32 v79, 0xffff0000, v94
	v_add_f32_e32 v72, 1.0, v72
	v_div_scale_f32 v73, s[18:19], v72, v72, 1.0
	v_rcp_f32_e32 v74, v73
	s_nop 0
	v_fma_f32 v76, -v73, v74, 1.0
	v_fmac_f32_e32 v74, v76, v74
	v_div_scale_f32 v76, vcc, 1.0, v72, 1.0
	v_mul_f32_e32 v77, v76, v74
	v_fma_f32 v78, -v73, v77, v76
	v_fmac_f32_e32 v77, v78, v74
	v_fma_f32 v73, -v73, v77, v76
	v_div_fmas_f32 v73, v73, v74, v77
	v_div_fixup_f32 v72, v73, v72, 1.0
	v_fmac_f32_e32 v103, v75, v72
	v_lshl_add_u64 v[72:73], s[76:77], 0, v[214:215]
	v_cvt_pk_bf16_f32 v74, v96, v97
	v_lshl_add_u64 v[72:73], v[72:73], 0, v[206:207]
	v_cvt_pk_bf16_f32 v75, v98, v99
	v_cvt_pk_bf16_f32 v76, v100, v101
	v_cvt_pk_bf16_f32 v77, v102, v103
	global_store_dwordx4 v[72:73], v[74:77], off
	v_lshlrev_b32_e32 v78, 16, v94
	s_nop 0
	v_lshlrev_b32_e32 v74, 16, v92
	v_mul_f32_e32 v74, 0xbfb8aa3b, v74
	v_exp_f32_e32 v74, v74
	v_and_b32_e32 v75, 0xffff0000, v92
	v_lshlrev_b32_e32 v76, 16, v93
	v_and_b32_e32 v77, 0xffff0000, v93
	v_add_f32_e32 v74, 1.0, v74
	v_div_scale_f32 v90, s[18:19], v74, v74, 1.0
	v_rcp_f32_e32 v91, v90
	s_nop 0
	v_fma_f32 v92, -v90, v91, 1.0
	v_fmac_f32_e32 v91, v92, v91
	v_div_scale_f32 v92, vcc, 1.0, v74, 1.0
	v_mul_f32_e32 v93, v92, v91
	v_fma_f32 v94, -v90, v93, v92
	v_fmac_f32_e32 v93, v94, v91
	v_fma_f32 v90, -v90, v93, v92
	v_div_fmas_f32 v90, v90, v91, v93
	v_div_fixup_f32 v74, v90, v74, 1.0
	v_fmac_f32_e32 v82, v68, v74
	v_mul_f32_e32 v68, 0xbfb8aa3b, v78
	v_exp_f32_e32 v68, v68
	s_nop 0
	v_add_f32_e32 v68, 1.0, v68
	v_div_scale_f32 v74, s[18:19], v68, v68, 1.0
	v_rcp_f32_e32 v78, v74
	s_nop 0
	v_fma_f32 v90, -v74, v78, 1.0
	v_fmac_f32_e32 v78, v90, v78
	v_div_scale_f32 v90, vcc, 1.0, v68, 1.0
	v_mul_f32_e32 v91, v90, v78
	v_fma_f32 v92, -v74, v91, v90
	v_fmac_f32_e32 v91, v92, v78
	v_fma_f32 v74, -v74, v91, v90
	v_div_fmas_f32 v74, v74, v78, v91
	v_div_fixup_f32 v68, v74, v68, 1.0
	v_fmac_f32_e32 v86, v64, v68
	v_mul_f32_e32 v64, 0xbfb8aa3b, v75
	v_exp_f32_e32 v64, v64
	s_nop 0
	v_add_f32_e32 v64, 1.0, v64
	v_div_scale_f32 v68, s[18:19], v64, v64, 1.0
	v_rcp_f32_e32 v74, v68
	s_nop 0
	v_fma_f32 v75, -v68, v74, 1.0
	v_fmac_f32_e32 v74, v75, v74
	v_div_scale_f32 v75, vcc, 1.0, v64, 1.0
	v_mul_f32_e32 v78, v75, v74
	v_fma_f32 v90, -v68, v78, v75
	v_fmac_f32_e32 v78, v90, v74
	v_fma_f32 v68, -v68, v78, v75
	v_div_fmas_f32 v68, v68, v74, v78
	v_div_fixup_f32 v64, v68, v64, 1.0
	v_fmac_f32_e32 v83, v69, v64
	v_mul_f32_e32 v64, 0xbfb8aa3b, v79
	v_exp_f32_e32 v64, v64
	s_nop 0
	v_add_f32_e32 v64, 1.0, v64
	v_div_scale_f32 v68, s[18:19], v64, v64, 1.0
	v_rcp_f32_e32 v69, v68
	s_nop 0
	v_fma_f32 v74, -v68, v69, 1.0
	v_fmac_f32_e32 v69, v74, v69
; __device__ __forceinline__ unsigned cvt_pk_bf16(float lo, float hi) { unsigned r; asm volatile("v_cvt_pk_bf16_f32 %0, %1, %2" : "=v"(r) : "v"(lo), "v"(hi)); return r; }
; __device__ __forceinline__ float sigmoidf_(float x) { return 1.f / (1.f + __expf(-x)); }
; __device__ __forceinline__ void unpack8(const u32x4& w, float (&f)[8]) { f[0] = bflo(w.x); f[1] = bfhi(w.x); f[2] = bflo(w.y); f[3] = bfhi(w.y); f[4] = bflo(w.z); f[5] = bfhi(w.z); f[6] = bflo(w.w); f[7] = bfhi(w.w); }
;     __device__ __forceinline__ void operator()(const f32x4 (&acc)[2][2][4][2], const Unit& u, int wr, int wc, int fr, int fq) const {
;     ...
;                 for (int bj = 0; bj < 2; ++bj) { const size_t r = (size_t)(row0 + ai * HALF + m * 16); gw[m][bj] = *(const u32x4*)(gate + r * ldg + col0 + bj * HALF); tw[m][bj] = *(const u32x4*)(T + r * DM + col0 + bj * HALF); }
; #pragma unroll
;             for (int m = 0; m < 4; ++m)
; #pragma unroll
;                 for (int bj = 0; bj < 2; ++bj) { float g[8], t[8]; unpack8(gw[m][bj], g); unpack8(tw[m][bj], t); const f32x4 a0 = acc[ai][bj][m][0], a1 = acc[ai][bj][m][1]; float o[8];
; #pragma unroll
;                     for (int e = 0; e < 4; ++e) { o[e] = t[e] + a0[e] * sigmoidf_(g[e]); o[4 + e] = t[4 + e] + a1[e] * sigmoidf_(g[4 + e]); }
;                     *(u32x4*)(Y + (size_t)(row0 + ai * HALF + m * 16) * DM + col0 + bj * HALF) = (u32x4){cvt_pk_bf16(o[0], o[1]), cvt_pk_bf16(o[2], o[3]), cvt_pk_bf16(o[4], o[5]), cvt_pk_bf16(o[6], o[7])}; } }
	v_div_scale_f32 v74, vcc, 1.0, v64, 1.0
	v_mul_f32_e32 v75, v74, v69
	v_fma_f32 v78, -v68, v75, v74
	v_fmac_f32_e32 v75, v78, v69
	v_fma_f32 v68, -v68, v75, v74
	v_div_fmas_f32 v68, v68, v69, v75
	v_div_fixup_f32 v64, v68, v64, 1.0
	v_fmac_f32_e32 v87, v65, v64
	v_mul_f32_e32 v64, 0xbfb8aa3b, v76
	v_exp_f32_e32 v64, v64
	s_nop 0
	v_add_f32_e32 v64, 1.0, v64
	v_div_scale_f32 v65, s[18:19], v64, v64, 1.0
	v_rcp_f32_e32 v68, v65
	s_nop 0
	v_fma_f32 v69, -v65, v68, 1.0
	v_fmac_f32_e32 v68, v69, v68
	v_div_scale_f32 v69, vcc, 1.0, v64, 1.0
	v_mul_f32_e32 v74, v69, v68
	v_fma_f32 v75, -v65, v74, v69
	v_fmac_f32_e32 v74, v75, v68
	v_fma_f32 v65, -v65, v74, v69
	v_div_fmas_f32 v65, v65, v68, v74
	v_div_fixup_f32 v64, v65, v64, 1.0
	v_fmac_f32_e32 v84, v70, v64
	v_mul_f32_e32 v64, 0xbfb8aa3b, v80
	v_exp_f32_e32 v64, v64
	s_nop 0
	v_add_f32_e32 v64, 1.0, v64
	v_div_scale_f32 v65, s[18:19], v64, v64, 1.0
	v_rcp_f32_e32 v68, v65
	s_nop 0
	v_fma_f32 v69, -v65, v68, 1.0
	v_fmac_f32_e32 v68, v69, v68
	v_div_scale_f32 v69, vcc, 1.0, v64, 1.0
	v_mul_f32_e32 v70, v69, v68
	v_fma_f32 v74, -v65, v70, v69
	v_fmac_f32_e32 v70, v74, v68
	v_fma_f32 v65, -v65, v70, v69
	v_div_fmas_f32 v65, v65, v68, v70
	v_div_fixup_f32 v64, v65, v64, 1.0
	v_fmac_f32_e32 v88, v66, v64
	v_mul_f32_e32 v64, 0xbfb8aa3b, v77
	v_exp_f32_e32 v64, v64
	s_nop 0
	v_add_f32_e32 v64, 1.0, v64
	v_div_scale_f32 v65, s[18:19], v64, v64, 1.0
	v_rcp_f32_e32 v66, v65
	s_nop 0
	v_fma_f32 v68, -v65, v66, 1.0
	v_fmac_f32_e32 v66, v68, v66
	v_div_scale_f32 v68, vcc, 1.0, v64, 1.0
	v_mul_f32_e32 v69, v68, v66
	v_fma_f32 v70, -v65, v69, v68
	v_fmac_f32_e32 v69, v70, v66
	v_fma_f32 v65, -v65, v69, v68
	v_div_fmas_f32 v65, v65, v66, v69
	v_div_fixup_f32 v64, v65, v64, 1.0
	v_fmac_f32_e32 v85, v71, v64
	v_mul_f32_e32 v64, 0xbfb8aa3b, v81
	v_exp_f32_e32 v64, v64
	s_nop 0
	v_add_f32_e32 v64, 1.0, v64
	v_div_scale_f32 v65, s[18:19], v64, v64, 1.0
	v_rcp_f32_e32 v66, v65
	s_nop 0
	v_fma_f32 v68, -v65, v66, 1.0
	v_fmac_f32_e32 v66, v68, v66
	v_div_scale_f32 v68, vcc, 1.0, v64, 1.0
	v_mul_f32_e32 v69, v68, v66
	v_fma_f32 v70, -v65, v69, v68
	v_fmac_f32_e32 v69, v70, v66
	v_fma_f32 v65, -v65, v69, v68
	v_div_fmas_f32 v65, v65, v66, v69
	v_div_fixup_f32 v64, v65, v64, 1.0
	v_fmac_f32_e32 v89, v67, v64
	v_cvt_pk_bf16_f32 v64, v82, v83
	v_cvt_pk_bf16_f32 v65, v84, v85
	v_cvt_pk_bf16_f32 v66, v86, v87
	v_cvt_pk_bf16_f32 v67, v88, v89
	global_store_dwordx4 v[72:73], v[64:67], off offset:256
	s_nop 1
	v_add_u32_e32 v64, 0x80, v208
	v_ashrrev_i32_e32 v65, 31, v64
	v_mad_i64_i32 v[66:67], s[18:19], v64, s41, v[212:213]
	v_lshlrev_b64 v[126:127], 12, v[64:65]
	v_lshl_add_u64 v[64:65], v[210:211], 0, v[126:127]
	global_load_dwordx4 v[128:131], v[66:67], off nt
	global_load_dwordx4 v[132:135], v[64:65], off nt
	global_load_dwordx4 v[116:119], v[66:67], off offset:256 nt
	global_load_dwordx4 v[112:115], v[64:65], off offset:256 nt
	v_add_u32_e32 v64, 0x90, v208
	v_ashrrev_i32_e32 v65, 31, v64
	v_lshlrev_b64 v[124:125], 12, v[64:65]
	v_mad_i64_i32 v[66:67], s[18:19], v64, s41, v[212:213]
	v_lshl_add_u64 v[64:65], v[210:211], 0, v[124:125]
	global_load_dwordx4 v[108:111], v[66:67], off nt
	global_load_dwordx4 v[104:107], v[64:65], off nt
	global_load_dwordx4 v[100:103], v[66:67], off offset:256 nt
	global_load_dwordx4 v[96:99], v[64:65], off offset:256 nt
	v_add_u32_e32 v64, 0xa0, v208
	v_ashrrev_i32_e32 v65, 31, v64
	v_lshlrev_b64 v[122:123], 12, v[64:65]
	v_mad_i64_i32 v[66:67], s[18:19], v64, s41, v[212:213]
	v_lshl_add_u64 v[64:65], v[210:211], 0, v[122:123]
	global_load_dwordx4 v[92:95], v[66:67], off nt
	global_load_dwordx4 v[88:91], v[64:65], off nt
	global_load_dwordx4 v[84:87], v[66:67], off offset:256 nt
	global_load_dwordx4 v[80:83], v[64:65], off offset:256 nt
	v_add_u32_e32 v64, 0xb0, v208
	v_ashrrev_i32_e32 v65, 31, v64
	v_lshlrev_b64 v[120:121], 12, v[64:65]
	v_mad_i64_i32 v[66:67], s[18:19], v64, s41, v[212:213]
	v_lshl_add_u64 v[64:65], v[210:211], 0, v[120:121]
	global_load_dwordx4 v[76:79], v[66:67], off nt
	global_load_dwordx4 v[72:75], v[64:65], off nt
	global_load_dwordx4 v[68:71], v[66:67], off offset:256 nt
	s_nop 0
	global_load_dwordx4 v[64:67], v[64:65], off offset:256 nt
	s_waitcnt vmcnt(15)
	v_lshlrev_b32_e32 v136, 16, v128
	v_mul_f32_e32 v136, 0xbfb8aa3b, v136
	v_exp_f32_e32 v136, v136
	v_lshlrev_b32_e32 v138, 16, v130
	s_waitcnt vmcnt(14)
; __device__ __forceinline__ unsigned cvt_pk_bf16(float lo, float hi) { unsigned r; asm volatile("v_cvt_pk_bf16_f32 %0, %1, %2" : "=v"(r) : "v"(lo), "v"(hi)); return r; }
; __device__ __forceinline__ float sigmoidf_(float x) { return 1.f / (1.f + __expf(-x)); }
; __device__ __forceinline__ void unpack8(const u32x4& w, float (&f)[8]) { f[0] = bflo(w.x); f[1] = bfhi(w.x); f[2] = bflo(w.y); f[3] = bfhi(w.y); f[4] = bflo(w.z); f[5] = bfhi(w.z); f[6] = bflo(w.w); f[7] = bfhi(w.w); }
;     __device__ __forceinline__ void operator()(const f32x4 (&acc)[2][2][4][2], const Unit& u, int wr, int wc, int fr, int fq) const {
;     ...
;                 for (int bj = 0; bj < 2; ++bj) { float g[8], t[8]; unpack8(gw[m][bj], g); unpack8(tw[m][bj], t); const f32x4 a0 = acc[ai][bj][m][0], a1 = acc[ai][bj][m][1]; float o[8];
; #pragma unroll
;                     for (int e = 0; e < 4; ++e) { o[e] = t[e] + a0[e] * sigmoidf_(g[e]); o[4 + e] = t[4 + e] + a1[e] * sigmoidf_(g[4 + e]); }
;                     *(u32x4*)(Y + (size_t)(row0 + ai * HALF + m * 16) * DM + col0 + bj * HALF) = (u32x4){cvt_pk_bf16(o[0], o[1]), cvt_pk_bf16(o[2], o[3]), cvt_pk_bf16(o[4], o[5]), cvt_pk_bf16(o[6], o[7])}; } }
	v_lshlrev_b32_e32 v140, 16, v132
	v_and_b32_e32 v128, 0xffff0000, v128
	v_add_f32_e32 v136, 1.0, v136
	v_div_scale_f32 v144, s[18:19], v136, v136, 1.0
	v_rcp_f32_e32 v145, v144
	v_lshlrev_b32_e32 v142, 16, v134
	v_and_b32_e32 v130, 0xffff0000, v130
	v_and_b32_e32 v132, 0xffff0000, v132
	v_fma_f32 v146, -v144, v145, 1.0
	v_fmac_f32_e32 v145, v146, v145
	v_div_scale_f32 v146, vcc, 1.0, v136, 1.0
	v_mul_f32_e32 v147, v146, v145
	v_fma_f32 v148, -v144, v147, v146
	v_fmac_f32_e32 v147, v148, v145
	v_fma_f32 v144, -v144, v147, v146
	v_div_fmas_f32 v144, v144, v145, v147
	v_div_fixup_f32 v136, v144, v136, 1.0
	v_fmac_f32_e32 v140, v60, v136
	v_mul_f32_e32 v60, 0xbfb8aa3b, v138
	v_exp_f32_e32 v60, v60
	v_lshlrev_b32_e32 v137, 16, v129
	v_and_b32_e32 v134, 0xffff0000, v134
	v_lshlrev_b32_e32 v139, 16, v131
	v_add_f32_e32 v60, 1.0, v60
	v_div_scale_f32 v136, s[18:19], v60, v60, 1.0
	v_rcp_f32_e32 v138, v136
	v_lshlrev_b32_e32 v141, 16, v133
	v_and_b32_e32 v129, 0xffff0000, v129
	v_lshlrev_b32_e32 v143, 16, v135
	v_fma_f32 v144, -v136, v138, 1.0
	v_fmac_f32_e32 v138, v144, v138
	v_div_scale_f32 v144, vcc, 1.0, v60, 1.0
	v_mul_f32_e32 v145, v144, v138
	v_fma_f32 v146, -v136, v145, v144
	v_fmac_f32_e32 v145, v146, v138
	v_fma_f32 v136, -v136, v145, v144
	v_div_fmas_f32 v136, v136, v138, v145
	v_div_fixup_f32 v60, v136, v60, 1.0
	v_fmac_f32_e32 v142, v56, v60
	v_mul_f32_e32 v56, 0xbfb8aa3b, v128
	v_exp_f32_e32 v56, v56
	v_and_b32_e32 v131, 0xffff0000, v131
	v_and_b32_e32 v133, 0xffff0000, v133
	v_and_b32_e32 v135, 0xffff0000, v135
	v_add_f32_e32 v56, 1.0, v56
	v_div_scale_f32 v60, s[18:19], v56, v56, 1.0
	v_rcp_f32_e32 v128, v60
	s_nop 0
	v_fma_f32 v136, -v60, v128, 1.0
	v_fmac_f32_e32 v128, v136, v128
	v_div_scale_f32 v136, vcc, 1.0, v56, 1.0
	v_mul_f32_e32 v138, v136, v128
	v_fma_f32 v144, -v60, v138, v136
	v_fmac_f32_e32 v138, v144, v128
	v_fma_f32 v60, -v60, v138, v136
	v_div_fmas_f32 v60, v60, v128, v138
	v_div_fixup_f32 v56, v60, v56, 1.0
	v_fmac_f32_e32 v132, v61, v56
	v_mul_f32_e32 v56, 0xbfb8aa3b, v130
	v_exp_f32_e32 v56, v56
	s_nop 0
	v_add_f32_e32 v56, 1.0, v56
	v_div_scale_f32 v60, s[18:19], v56, v56, 1.0
	v_rcp_f32_e32 v61, v60
	s_nop 0
	v_fma_f32 v128, -v60, v61, 1.0
	v_fmac_f32_e32 v61, v128, v61
	v_div_scale_f32 v128, vcc, 1.0, v56, 1.0
	v_mul_f32_e32 v130, v128, v61
	v_fma_f32 v136, -v60, v130, v128
	v_fmac_f32_e32 v130, v136, v61
	v_fma_f32 v60, -v60, v130, v128
	v_div_fmas_f32 v60, v60, v61, v130
	v_div_fixup_f32 v56, v60, v56, 1.0
	v_fmac_f32_e32 v134, v57, v56
	v_mul_f32_e32 v56, 0xbfb8aa3b, v137
	v_exp_f32_e32 v56, v56
	s_nop 0
	v_add_f32_e32 v56, 1.0, v56
	v_div_scale_f32 v57, s[18:19], v56, v56, 1.0
	v_rcp_f32_e32 v60, v57
	s_nop 0
	v_fma_f32 v61, -v57, v60, 1.0
	v_fmac_f32_e32 v60, v61, v60
	v_div_scale_f32 v61, vcc, 1.0, v56, 1.0
	v_mul_f32_e32 v128, v61, v60
	v_fma_f32 v130, -v57, v128, v61
	v_fmac_f32_e32 v128, v130, v60
	v_fma_f32 v57, -v57, v128, v61
	v_div_fmas_f32 v57, v57, v60, v128
	v_div_fixup_f32 v56, v57, v56, 1.0
	v_fmac_f32_e32 v141, v62, v56
	v_mul_f32_e32 v56, 0xbfb8aa3b, v139
	v_exp_f32_e32 v56, v56
	s_nop 0
	v_add_f32_e32 v56, 1.0, v56
	v_div_scale_f32 v57, s[18:19], v56, v56, 1.0
	v_rcp_f32_e32 v60, v57
	s_nop 0
	v_fma_f32 v61, -v57, v60, 1.0
	v_fmac_f32_e32 v60, v61, v60
	v_div_scale_f32 v61, vcc, 1.0, v56, 1.0
	v_mul_f32_e32 v62, v61, v60
	v_fma_f32 v128, -v57, v62, v61
	v_fmac_f32_e32 v62, v128, v60
	v_fma_f32 v57, -v57, v62, v61
	v_div_fmas_f32 v57, v57, v60, v62
	v_div_fixup_f32 v56, v57, v56, 1.0
	v_fmac_f32_e32 v143, v58, v56
	v_mul_f32_e32 v56, 0xbfb8aa3b, v129
	v_exp_f32_e32 v56, v56
	s_nop 0
	v_add_f32_e32 v56, 1.0, v56
	v_div_scale_f32 v57, s[18:19], v56, v56, 1.0
	v_rcp_f32_e32 v58, v57
	s_nop 0
	v_fma_f32 v60, -v57, v58, 1.0
	v_fmac_f32_e32 v58, v60, v58
	v_div_scale_f32 v60, vcc, 1.0, v56, 1.0
	v_mul_f32_e32 v61, v60, v58
	v_fma_f32 v62, -v57, v61, v60
	v_fmac_f32_e32 v61, v62, v58
	v_fma_f32 v57, -v57, v61, v60
	v_div_fmas_f32 v57, v57, v58, v61
	v_div_fixup_f32 v56, v57, v56, 1.0
	v_fmac_f32_e32 v133, v63, v56
	v_mul_f32_e32 v56, 0xbfb8aa3b, v131
	v_exp_f32_e32 v56, v56
	s_waitcnt vmcnt(13)
	v_and_b32_e32 v63, 0xffff0000, v118
	v_add_f32_e32 v56, 1.0, v56
	v_div_scale_f32 v57, s[18:19], v56, v56, 1.0
	v_rcp_f32_e32 v58, v57
	s_nop 0
	v_fma_f32 v60, -v57, v58, 1.0
	v_fmac_f32_e32 v58, v60, v58
	v_div_scale_f32 v60, vcc, 1.0, v56, 1.0
	v_mul_f32_e32 v61, v60, v58
	v_fma_f32 v62, -v57, v61, v60
	v_fmac_f32_e32 v61, v62, v58
	v_fma_f32 v57, -v57, v61, v60
	v_div_fmas_f32 v57, v57, v58, v61
	v_div_fixup_f32 v56, v57, v56, 1.0
	v_fmac_f32_e32 v135, v59, v56
	v_lshl_add_u64 v[56:57], s[76:77], 0, v[126:127]
	v_cvt_pk_bf16_f32 v58, v140, v132
	v_lshl_add_u64 v[56:57], v[56:57], 0, v[206:207]
	v_cvt_pk_bf16_f32 v59, v141, v133
	v_cvt_pk_bf16_f32 v60, v142, v134
	v_cvt_pk_bf16_f32 v61, v143, v135
	global_store_dwordx4 v[56:57], v[58:61], off
	v_lshlrev_b32_e32 v62, 16, v118
	s_waitcnt vmcnt(13)
; __device__ __forceinline__ unsigned cvt_pk_bf16(float lo, float hi) { unsigned r; asm volatile("v_cvt_pk_bf16_f32 %0, %1, %2" : "=v"(r) : "v"(lo), "v"(hi)); return r; }
; __device__ __forceinline__ float sigmoidf_(float x) { return 1.f / (1.f + __expf(-x)); }
; __device__ __forceinline__ void unpack8(const u32x4& w, float (&f)[8]) { f[0] = bflo(w.x); f[1] = bfhi(w.x); f[2] = bflo(w.y); f[3] = bfhi(w.y); f[4] = bflo(w.z); f[5] = bfhi(w.z); f[6] = bflo(w.w); f[7] = bfhi(w.w); }
;     __device__ __forceinline__ void operator()(const f32x4 (&acc)[2][2][4][2], const Unit& u, int wr, int wc, int fr, int fq) const {
;     ...
;                 for (int bj = 0; bj < 2; ++bj) { float g[8], t[8]; unpack8(gw[m][bj], g); unpack8(tw[m][bj], t); const f32x4 a0 = acc[ai][bj][m][0], a1 = acc[ai][bj][m][1]; float o[8];
; #pragma unroll
;                     for (int e = 0; e < 4; ++e) { o[e] = t[e] + a0[e] * sigmoidf_(g[e]); o[4 + e] = t[4 + e] + a1[e] * sigmoidf_(g[4 + e]); }
;                     *(u32x4*)(Y + (size_t)(row0 + ai * HALF + m * 16) * DM + col0 + bj * HALF) = (u32x4){cvt_pk_bf16(o[0], o[1]), cvt_pk_bf16(o[2], o[3]), cvt_pk_bf16(o[4], o[5]), cvt_pk_bf16(o[6], o[7])}; } }
	v_lshlrev_b32_e32 v118, 16, v112
	v_lshlrev_b32_e32 v58, 16, v116
	v_mul_f32_e32 v58, 0xbfb8aa3b, v58
	v_exp_f32_e32 v58, v58
	v_and_b32_e32 v59, 0xffff0000, v116
	v_lshlrev_b32_e32 v126, 16, v114
	v_and_b32_e32 v112, 0xffff0000, v112
	v_add_f32_e32 v58, 1.0, v58
	v_div_scale_f32 v128, s[18:19], v58, v58, 1.0
	v_rcp_f32_e32 v129, v128
	v_lshlrev_b32_e32 v60, 16, v117
	v_and_b32_e32 v114, 0xffff0000, v114
	v_and_b32_e32 v61, 0xffff0000, v117
	v_fma_f32 v130, -v128, v129, 1.0
	v_fmac_f32_e32 v129, v130, v129
	v_div_scale_f32 v130, vcc, 1.0, v58, 1.0
	v_mul_f32_e32 v131, v130, v129
	v_fma_f32 v132, -v128, v131, v130
	v_fmac_f32_e32 v131, v132, v129
	v_fma_f32 v128, -v128, v131, v130
	v_div_fmas_f32 v128, v128, v129, v131
	v_div_fixup_f32 v58, v128, v58, 1.0
	v_fmac_f32_e32 v118, v52, v58
	v_mul_f32_e32 v52, 0xbfb8aa3b, v62
	v_exp_f32_e32 v52, v52
	v_lshlrev_b32_e32 v116, 16, v119
	v_and_b32_e32 v117, 0xffff0000, v119
	v_lshlrev_b32_e32 v119, 16, v113
	v_add_f32_e32 v52, 1.0, v52
	v_div_scale_f32 v58, s[18:19], v52, v52, 1.0
	v_rcp_f32_e32 v62, v58
	v_lshlrev_b32_e32 v127, 16, v115
	v_and_b32_e32 v113, 0xffff0000, v113
	v_and_b32_e32 v115, 0xffff0000, v115
	v_fma_f32 v128, -v58, v62, 1.0
	v_fmac_f32_e32 v62, v128, v62
	v_div_scale_f32 v128, vcc, 1.0, v52, 1.0
	v_mul_f32_e32 v129, v128, v62
	v_fma_f32 v130, -v58, v129, v128
	v_fmac_f32_e32 v129, v130, v62
	v_fma_f32 v58, -v58, v129, v128
	v_div_fmas_f32 v58, v58, v62, v129
	v_div_fixup_f32 v52, v58, v52, 1.0
	v_fmac_f32_e32 v126, v48, v52
	v_mul_f32_e32 v48, 0xbfb8aa3b, v59
	v_exp_f32_e32 v48, v48
	s_nop 0
	v_add_f32_e32 v48, 1.0, v48
	v_div_scale_f32 v52, s[18:19], v48, v48, 1.0
	v_rcp_f32_e32 v58, v52
	s_nop 0
	v_fma_f32 v59, -v52, v58, 1.0
	v_fmac_f32_e32 v58, v59, v58
	v_div_scale_f32 v59, vcc, 1.0, v48, 1.0
	v_mul_f32_e32 v62, v59, v58
	v_fma_f32 v128, -v52, v62, v59
	v_fmac_f32_e32 v62, v128, v58
	v_fma_f32 v52, -v52, v62, v59
	v_div_fmas_f32 v52, v52, v58, v62
	v_div_fixup_f32 v48, v52, v48, 1.0
	v_fmac_f32_e32 v112, v53, v48
	v_mul_f32_e32 v48, 0xbfb8aa3b, v63
	v_exp_f32_e32 v48, v48
	s_waitcnt vmcnt(11)
	v_and_b32_e32 v63, 0xffff0000, v107
	v_add_f32_e32 v48, 1.0, v48
	v_div_scale_f32 v52, s[18:19], v48, v48, 1.0
	v_rcp_f32_e32 v53, v52
	s_nop 0
	v_fma_f32 v58, -v52, v53, 1.0
	v_fmac_f32_e32 v53, v58, v53
	v_div_scale_f32 v58, vcc, 1.0, v48, 1.0
	v_mul_f32_e32 v59, v58, v53
	v_fma_f32 v62, -v52, v59, v58
	v_fmac_f32_e32 v59, v62, v53
	v_fma_f32 v52, -v52, v59, v58
	v_div_fmas_f32 v52, v52, v53, v59
	v_div_fixup_f32 v48, v52, v48, 1.0
	v_fmac_f32_e32 v114, v49, v48
	v_mul_f32_e32 v48, 0xbfb8aa3b, v60
	v_exp_f32_e32 v48, v48
	v_lshlrev_b32_e32 v60, 16, v106
	v_lshlrev_b32_e32 v62, 16, v107
	v_add_f32_e32 v48, 1.0, v48
	v_div_scale_f32 v49, s[18:19], v48, v48, 1.0
	v_rcp_f32_e32 v52, v49
	s_nop 0
	v_fma_f32 v53, -v49, v52, 1.0
	v_fmac_f32_e32 v52, v53, v52
	v_div_scale_f32 v53, vcc, 1.0, v48, 1.0
	v_mul_f32_e32 v58, v53, v52
	v_fma_f32 v59, -v49, v58, v53
	v_fmac_f32_e32 v58, v59, v52
	v_fma_f32 v49, -v49, v58, v53
	v_div_fmas_f32 v49, v49, v52, v58
	v_div_fixup_f32 v48, v49, v48, 1.0
	v_fmac_f32_e32 v119, v54, v48
	v_mul_f32_e32 v48, 0xbfb8aa3b, v116
	v_exp_f32_e32 v48, v48
	v_and_b32_e32 v59, 0xffff0000, v105
	v_add_f32_e32 v48, 1.0, v48
	v_div_scale_f32 v49, s[18:19], v48, v48, 1.0
	v_rcp_f32_e32 v52, v49
	s_nop 0
	v_fma_f32 v53, -v49, v52, 1.0
	v_fmac_f32_e32 v52, v53, v52
	v_div_scale_f32 v53, vcc, 1.0, v48, 1.0
	v_mul_f32_e32 v54, v53, v52
	v_fma_f32 v58, -v49, v54, v53
	v_fmac_f32_e32 v54, v58, v52
	v_fma_f32 v49, -v49, v54, v53
	v_div_fmas_f32 v49, v49, v52, v54
	v_div_fixup_f32 v48, v49, v48, 1.0
	v_fmac_f32_e32 v127, v50, v48
	v_mul_f32_e32 v48, 0xbfb8aa3b, v61
	v_exp_f32_e32 v48, v48
	v_lshlrev_b32_e32 v58, 16, v105
	v_and_b32_e32 v61, 0xffff0000, v106
	v_add_f32_e32 v48, 1.0, v48
	v_div_scale_f32 v49, s[18:19], v48, v48, 1.0
	v_rcp_f32_e32 v50, v49
	s_nop 0
	v_fma_f32 v52, -v49, v50, 1.0
	v_fmac_f32_e32 v50, v52, v50
	v_div_scale_f32 v52, vcc, 1.0, v48, 1.0
	v_mul_f32_e32 v53, v52, v50
	v_fma_f32 v54, -v49, v53, v52
	v_fmac_f32_e32 v53, v54, v50
	v_fma_f32 v49, -v49, v53, v52
	v_div_fmas_f32 v49, v49, v50, v53
	v_div_fixup_f32 v48, v49, v48, 1.0
	v_fmac_f32_e32 v113, v55, v48
	v_mul_f32_e32 v48, 0xbfb8aa3b, v117
	v_exp_f32_e32 v48, v48
	v_and_b32_e32 v55, 0xffff0000, v111
	v_add_f32_e32 v48, 1.0, v48
	v_div_scale_f32 v49, s[18:19], v48, v48, 1.0
	v_rcp_f32_e32 v50, v49
	s_nop 0
	v_fma_f32 v52, -v49, v50, 1.0
	v_fmac_f32_e32 v50, v52, v50
	v_div_scale_f32 v52, vcc, 1.0, v48, 1.0
	v_mul_f32_e32 v53, v52, v50
	v_fma_f32 v54, -v49, v53, v52
	v_fmac_f32_e32 v53, v54, v50
	v_fma_f32 v49, -v49, v53, v52
	v_div_fmas_f32 v49, v49, v50, v53
	v_div_fixup_f32 v48, v49, v48, 1.0
	v_fmac_f32_e32 v115, v51, v48
	v_cvt_pk_bf16_f32 v48, v118, v112
	v_cvt_pk_bf16_f32 v49, v119, v113
	v_cvt_pk_bf16_f32 v50, v126, v114
	v_cvt_pk_bf16_f32 v51, v127, v115
	global_store_dwordx4 v[56:57], v[48:51], off offset:256
	v_lshlrev_b32_e32 v56, 16, v104
	v_and_b32_e32 v57, 0xffff0000, v104
	v_lshlrev_b32_e32 v48, 16, v108
	v_mul_f32_e32 v48, 0xbfb8aa3b, v48
	v_exp_f32_e32 v48, v48
	v_and_b32_e32 v49, 0xffff0000, v108
	v_lshlrev_b32_e32 v52, 16, v110
	v_and_b32_e32 v53, 0xffff0000, v110
	v_add_f32_e32 v48, 1.0, v48
	v_div_scale_f32 v104, s[18:19], v48, v48, 1.0
	v_rcp_f32_e32 v105, v104
	v_lshlrev_b32_e32 v50, 16, v109
	v_lshlrev_b32_e32 v54, 16, v111
	v_and_b32_e32 v51, 0xffff0000, v109
	v_fma_f32 v106, -v104, v105, 1.0
	v_fmac_f32_e32 v105, v106, v105
	v_div_scale_f32 v106, vcc, 1.0, v48, 1.0
	v_mul_f32_e32 v107, v106, v105
	v_fma_f32 v108, -v104, v107, v106
	v_fmac_f32_e32 v107, v108, v105
	v_fma_f32 v104, -v104, v107, v106
	v_div_fmas_f32 v104, v104, v105, v107
	v_div_fixup_f32 v48, v104, v48, 1.0
	v_fmac_f32_e32 v56, v44, v48
	v_mul_f32_e32 v44, 0xbfb8aa3b, v52
	v_exp_f32_e32 v44, v44
	s_nop 0
	v_add_f32_e32 v44, 1.0, v44
	v_div_scale_f32 v48, s[18:19], v44, v44, 1.0
	v_rcp_f32_e32 v52, v48
	s_nop 0
	v_fma_f32 v104, -v48, v52, 1.0
	v_fmac_f32_e32 v52, v104, v52
	v_div_scale_f32 v104, vcc, 1.0, v44, 1.0
	v_mul_f32_e32 v105, v104, v52
	v_fma_f32 v106, -v48, v105, v104
	v_fmac_f32_e32 v105, v106, v52
	v_fma_f32 v48, -v48, v105, v104
	v_div_fmas_f32 v48, v48, v52, v105
	v_div_fixup_f32 v44, v48, v44, 1.0
	v_fmac_f32_e32 v60, v40, v44
	v_mul_f32_e32 v40, 0xbfb8aa3b, v49
	v_exp_f32_e32 v40, v40
	s_nop 0
	v_add_f32_e32 v40, 1.0, v40
	v_div_scale_f32 v44, s[18:19], v40, v40, 1.0
	v_rcp_f32_e32 v48, v44
	s_nop 0
	v_fma_f32 v49, -v44, v48, 1.0
	v_fmac_f32_e32 v48, v49, v48
	v_div_scale_f32 v49, vcc, 1.0, v40, 1.0
	v_mul_f32_e32 v52, v49, v48
	v_fma_f32 v104, -v44, v52, v49
	v_fmac_f32_e32 v52, v104, v48
	v_fma_f32 v44, -v44, v52, v49
	v_div_fmas_f32 v44, v44, v48, v52
	v_div_fixup_f32 v40, v44, v40, 1.0
	v_fmac_f32_e32 v57, v45, v40
	v_mul_f32_e32 v40, 0xbfb8aa3b, v53
	v_exp_f32_e32 v40, v40
	s_waitcnt vmcnt(10)
; __device__ __forceinline__ unsigned cvt_pk_bf16(float lo, float hi) { unsigned r; asm volatile("v_cvt_pk_bf16_f32 %0, %1, %2" : "=v"(r) : "v"(lo), "v"(hi)); return r; }
; __device__ __forceinline__ float sigmoidf_(float x) { return 1.f / (1.f + __expf(-x)); }
; __device__ __forceinline__ void unpack8(const u32x4& w, float (&f)[8]) { f[0] = bflo(w.x); f[1] = bfhi(w.x); f[2] = bflo(w.y); f[3] = bfhi(w.y); f[4] = bflo(w.z); f[5] = bfhi(w.z); f[6] = bflo(w.w); f[7] = bfhi(w.w); }
;     __device__ __forceinline__ void operator()(const f32x4 (&acc)[2][2][4][2], const Unit& u, int wr, int wc, int fr, int fq) const {
;     ...
;                 for (int bj = 0; bj < 2; ++bj) { float g[8], t[8]; unpack8(gw[m][bj], g); unpack8(tw[m][bj], t); const f32x4 a0 = acc[ai][bj][m][0], a1 = acc[ai][bj][m][1]; float o[8];
; #pragma unroll
;                     for (int e = 0; e < 4; ++e) { o[e] = t[e] + a0[e] * sigmoidf_(g[e]); o[4 + e] = t[4 + e] + a1[e] * sigmoidf_(g[4 + e]); }
;                     *(u32x4*)(Y + (size_t)(row0 + ai * HALF + m * 16) * DM + col0 + bj * HALF) = (u32x4){cvt_pk_bf16(o[0], o[1]), cvt_pk_bf16(o[2], o[3]), cvt_pk_bf16(o[4], o[5]), cvt_pk_bf16(o[6], o[7])}; } }
	v_and_b32_e32 v53, 0xffff0000, v97
	v_add_f32_e32 v40, 1.0, v40
	v_div_scale_f32 v44, s[18:19], v40, v40, 1.0
	v_rcp_f32_e32 v45, v44
	s_nop 0
	v_fma_f32 v48, -v44, v45, 1.0
	v_fmac_f32_e32 v45, v48, v45
	v_div_scale_f32 v48, vcc, 1.0, v40, 1.0
	v_mul_f32_e32 v49, v48, v45
	v_fma_f32 v52, -v44, v49, v48
	v_fmac_f32_e32 v49, v52, v45
	v_fma_f32 v44, -v44, v49, v48
	v_div_fmas_f32 v44, v44, v45, v49
	v_div_fixup_f32 v40, v44, v40, 1.0
	v_fmac_f32_e32 v61, v41, v40
	v_mul_f32_e32 v40, 0xbfb8aa3b, v50
	v_exp_f32_e32 v40, v40
	v_lshlrev_b32_e32 v50, 16, v96
	v_lshlrev_b32_e32 v52, 16, v97
	v_add_f32_e32 v40, 1.0, v40
	v_div_scale_f32 v41, s[18:19], v40, v40, 1.0
	v_rcp_f32_e32 v44, v41
	s_nop 0
	v_fma_f32 v45, -v41, v44, 1.0
	v_fmac_f32_e32 v44, v45, v44
	v_div_scale_f32 v45, vcc, 1.0, v40, 1.0
	v_mul_f32_e32 v48, v45, v44
	v_fma_f32 v49, -v41, v48, v45
	v_fmac_f32_e32 v48, v49, v44
	v_fma_f32 v41, -v41, v48, v45
	v_div_fmas_f32 v41, v41, v44, v48
	v_div_fixup_f32 v40, v41, v40, 1.0
	v_fmac_f32_e32 v58, v46, v40
	v_mul_f32_e32 v40, 0xbfb8aa3b, v54
	v_exp_f32_e32 v40, v40
	v_lshlrev_b32_e32 v54, 16, v98
	v_and_b32_e32 v49, 0xffff0000, v103
	v_add_f32_e32 v40, 1.0, v40
	v_div_scale_f32 v41, s[18:19], v40, v40, 1.0
	v_rcp_f32_e32 v44, v41
	s_nop 0
	v_fma_f32 v45, -v41, v44, 1.0
	v_fmac_f32_e32 v44, v45, v44
	v_div_scale_f32 v45, vcc, 1.0, v40, 1.0
	v_mul_f32_e32 v46, v45, v44
	v_fma_f32 v48, -v41, v46, v45
	v_fmac_f32_e32 v46, v48, v44
	v_fma_f32 v41, -v41, v46, v45
	v_div_fmas_f32 v41, v41, v44, v46
	v_div_fixup_f32 v40, v41, v40, 1.0
	v_fmac_f32_e32 v62, v42, v40
	v_mul_f32_e32 v40, 0xbfb8aa3b, v51
	v_exp_f32_e32 v40, v40
	v_and_b32_e32 v51, 0xffff0000, v96
	v_lshlrev_b32_e32 v48, 16, v103
	v_add_f32_e32 v40, 1.0, v40
	v_div_scale_f32 v41, s[18:19], v40, v40, 1.0
	v_rcp_f32_e32 v42, v41
	s_nop 0
	v_fma_f32 v44, -v41, v42, 1.0
	v_fmac_f32_e32 v42, v44, v42
	v_div_scale_f32 v44, vcc, 1.0, v40, 1.0
	v_mul_f32_e32 v45, v44, v42
	v_fma_f32 v46, -v41, v45, v44
	v_fmac_f32_e32 v45, v46, v42
	v_fma_f32 v41, -v41, v45, v44
	v_div_fmas_f32 v41, v41, v42, v45
	v_div_fixup_f32 v40, v41, v40, 1.0
	v_fmac_f32_e32 v59, v47, v40
	v_mul_f32_e32 v40, 0xbfb8aa3b, v55
	v_exp_f32_e32 v40, v40
	v_and_b32_e32 v47, 0xffff0000, v102
	v_and_b32_e32 v55, 0xffff0000, v98
	v_add_f32_e32 v40, 1.0, v40
	v_div_scale_f32 v41, s[18:19], v40, v40, 1.0
	v_rcp_f32_e32 v42, v41
	s_nop 0
	v_fma_f32 v44, -v41, v42, 1.0
	v_fmac_f32_e32 v42, v44, v42
	v_div_scale_f32 v44, vcc, 1.0, v40, 1.0
	v_mul_f32_e32 v45, v44, v42
	v_fma_f32 v46, -v41, v45, v44
	v_fmac_f32_e32 v45, v46, v42
	v_fma_f32 v41, -v41, v45, v44
	v_div_fmas_f32 v41, v41, v42, v45
	v_div_fixup_f32 v40, v41, v40, 1.0
	v_fmac_f32_e32 v63, v43, v40
	v_lshl_add_u64 v[40:41], s[76:77], 0, v[124:125]
	v_cvt_pk_bf16_f32 v42, v56, v57
	v_lshl_add_u64 v[40:41], v[40:41], 0, v[206:207]
	v_cvt_pk_bf16_f32 v43, v58, v59
	v_cvt_pk_bf16_f32 v44, v60, v61
	v_cvt_pk_bf16_f32 v45, v62, v63
	global_store_dwordx4 v[40:41], v[42:45], off
	v_lshlrev_b32_e32 v46, 16, v102
	v_lshlrev_b32_e32 v56, 16, v99
	v_lshlrev_b32_e32 v42, 16, v100
	v_mul_f32_e32 v42, 0xbfb8aa3b, v42
	v_exp_f32_e32 v42, v42
	v_and_b32_e32 v43, 0xffff0000, v100
	v_lshlrev_b32_e32 v44, 16, v101
	v_and_b32_e32 v45, 0xffff0000, v101
	v_add_f32_e32 v42, 1.0, v42
	v_div_scale_f32 v58, s[18:19], v42, v42, 1.0
	v_rcp_f32_e32 v59, v58
	v_and_b32_e32 v57, 0xffff0000, v99
	v_fma_f32 v60, -v58, v59, 1.0
	v_fmac_f32_e32 v59, v60, v59
	v_div_scale_f32 v60, vcc, 1.0, v42, 1.0
	v_mul_f32_e32 v61, v60, v59
	v_fma_f32 v62, -v58, v61, v60
	v_fmac_f32_e32 v61, v62, v59
	v_fma_f32 v58, -v58, v61, v60
	v_div_fmas_f32 v58, v58, v59, v61
	v_div_fixup_f32 v42, v58, v42, 1.0
	v_fmac_f32_e32 v50, v36, v42
	v_mul_f32_e32 v36, 0xbfb8aa3b, v46
	v_exp_f32_e32 v36, v36
	s_nop 0
	v_add_f32_e32 v36, 1.0, v36
	v_div_scale_f32 v42, s[18:19], v36, v36, 1.0
	v_rcp_f32_e32 v46, v42
	s_nop 0
	v_fma_f32 v58, -v42, v46, 1.0
	v_fmac_f32_e32 v46, v58, v46
	v_div_scale_f32 v58, vcc, 1.0, v36, 1.0
	v_mul_f32_e32 v59, v58, v46
	v_fma_f32 v60, -v42, v59, v58
	v_fmac_f32_e32 v59, v60, v46
	v_fma_f32 v42, -v42, v59, v58
	v_div_fmas_f32 v42, v42, v46, v59
	v_div_fixup_f32 v36, v42, v36, 1.0
	v_fmac_f32_e32 v54, v32, v36
	v_mul_f32_e32 v32, 0xbfb8aa3b, v43
	v_exp_f32_e32 v32, v32
	s_nop 0
	v_add_f32_e32 v32, 1.0, v32
	v_div_scale_f32 v36, s[18:19], v32, v32, 1.0
	v_rcp_f32_e32 v42, v36
	s_nop 0
	v_fma_f32 v43, -v36, v42, 1.0
	v_fmac_f32_e32 v42, v43, v42
	v_div_scale_f32 v43, vcc, 1.0, v32, 1.0
	v_mul_f32_e32 v46, v43, v42
	v_fma_f32 v58, -v36, v46, v43
	v_fmac_f32_e32 v46, v58, v42
	v_fma_f32 v36, -v36, v46, v43
	v_div_fmas_f32 v36, v36, v42, v46
	v_div_fixup_f32 v32, v36, v32, 1.0
	v_fmac_f32_e32 v51, v37, v32
	v_mul_f32_e32 v32, 0xbfb8aa3b, v47
	v_exp_f32_e32 v32, v32
	s_waitcnt vmcnt(9)
; __device__ __forceinline__ unsigned cvt_pk_bf16(float lo, float hi) { unsigned r; asm volatile("v_cvt_pk_bf16_f32 %0, %1, %2" : "=v"(r) : "v"(lo), "v"(hi)); return r; }
; __device__ __forceinline__ float sigmoidf_(float x) { return 1.f / (1.f + __expf(-x)); }
; __device__ __forceinline__ void unpack8(const u32x4& w, float (&f)[8]) { f[0] = bflo(w.x); f[1] = bfhi(w.x); f[2] = bflo(w.y); f[3] = bfhi(w.y); f[4] = bflo(w.z); f[5] = bfhi(w.z); f[6] = bflo(w.w); f[7] = bfhi(w.w); }
;     __device__ __forceinline__ void operator()(const f32x4 (&acc)[2][2][4][2], const Unit& u, int wr, int wc, int fr, int fq) const {
;     ...
;                 for (int bj = 0; bj < 2; ++bj) { float g[8], t[8]; unpack8(gw[m][bj], g); unpack8(tw[m][bj], t); const f32x4 a0 = acc[ai][bj][m][0], a1 = acc[ai][bj][m][1]; float o[8];
; #pragma unroll
;                     for (int e = 0; e < 4; ++e) { o[e] = t[e] + a0[e] * sigmoidf_(g[e]); o[4 + e] = t[4 + e] + a1[e] * sigmoidf_(g[4 + e]); }
;                     *(u32x4*)(Y + (size_t)(row0 + ai * HALF + m * 16) * DM + col0 + bj * HALF) = (u32x4){cvt_pk_bf16(o[0], o[1]), cvt_pk_bf16(o[2], o[3]), cvt_pk_bf16(o[4], o[5]), cvt_pk_bf16(o[6], o[7])}; } }
	v_and_b32_e32 v47, 0xffff0000, v91
	v_add_f32_e32 v32, 1.0, v32
	v_div_scale_f32 v36, s[18:19], v32, v32, 1.0
	v_rcp_f32_e32 v37, v36
	s_nop 0
	v_fma_f32 v42, -v36, v37, 1.0
	v_fmac_f32_e32 v37, v42, v37
	v_div_scale_f32 v42, vcc, 1.0, v32, 1.0
	v_mul_f32_e32 v43, v42, v37
	v_fma_f32 v46, -v36, v43, v42
	v_fmac_f32_e32 v43, v46, v37
	v_fma_f32 v36, -v36, v43, v42
	v_div_fmas_f32 v36, v36, v37, v43
	v_div_fixup_f32 v32, v36, v32, 1.0
	v_fmac_f32_e32 v55, v33, v32
	v_mul_f32_e32 v32, 0xbfb8aa3b, v44
	v_exp_f32_e32 v32, v32
	v_lshlrev_b32_e32 v44, 16, v90
	v_lshlrev_b32_e32 v46, 16, v91
	v_add_f32_e32 v32, 1.0, v32
	v_div_scale_f32 v33, s[18:19], v32, v32, 1.0
	v_rcp_f32_e32 v36, v33
	s_nop 0
	v_fma_f32 v37, -v33, v36, 1.0
	v_fmac_f32_e32 v36, v37, v36
	v_div_scale_f32 v37, vcc, 1.0, v32, 1.0
	v_mul_f32_e32 v42, v37, v36
	v_fma_f32 v43, -v33, v42, v37
	v_fmac_f32_e32 v42, v43, v36
	v_fma_f32 v33, -v33, v42, v37
	v_div_fmas_f32 v33, v33, v36, v42
	v_div_fixup_f32 v32, v33, v32, 1.0
	v_fmac_f32_e32 v52, v38, v32
	v_mul_f32_e32 v32, 0xbfb8aa3b, v48
	v_exp_f32_e32 v32, v32
	v_and_b32_e32 v43, 0xffff0000, v89
	v_add_f32_e32 v32, 1.0, v32
	v_div_scale_f32 v33, s[18:19], v32, v32, 1.0
	v_rcp_f32_e32 v36, v33
	s_nop 0
	v_fma_f32 v37, -v33, v36, 1.0
	v_fmac_f32_e32 v36, v37, v36
	v_div_scale_f32 v37, vcc, 1.0, v32, 1.0
	v_mul_f32_e32 v38, v37, v36
	v_fma_f32 v42, -v33, v38, v37
	v_fmac_f32_e32 v38, v42, v36
	v_fma_f32 v33, -v33, v38, v37
	v_div_fmas_f32 v33, v33, v36, v38
	v_div_fixup_f32 v32, v33, v32, 1.0
	v_fmac_f32_e32 v56, v34, v32
	v_mul_f32_e32 v32, 0xbfb8aa3b, v45
	v_exp_f32_e32 v32, v32
	v_and_b32_e32 v45, 0xffff0000, v90
	v_lshlrev_b32_e32 v42, 16, v89
	v_add_f32_e32 v32, 1.0, v32
	v_div_scale_f32 v33, s[18:19], v32, v32, 1.0
	v_rcp_f32_e32 v34, v33
	s_nop 0
	v_fma_f32 v36, -v33, v34, 1.0
	v_fmac_f32_e32 v34, v36, v34
	v_div_scale_f32 v36, vcc, 1.0, v32, 1.0
	v_mul_f32_e32 v37, v36, v34
	v_fma_f32 v38, -v33, v37, v36
	v_fmac_f32_e32 v37, v38, v34
	v_fma_f32 v33, -v33, v37, v36
	v_div_fmas_f32 v33, v33, v34, v37
	v_div_fixup_f32 v32, v33, v32, 1.0
	v_fmac_f32_e32 v53, v39, v32
	v_mul_f32_e32 v32, 0xbfb8aa3b, v49
	v_exp_f32_e32 v32, v32
	v_and_b32_e32 v39, 0xffff0000, v95
	v_add_f32_e32 v32, 1.0, v32
	v_div_scale_f32 v33, s[18:19], v32, v32, 1.0
	v_rcp_f32_e32 v34, v33
	s_nop 0
	v_fma_f32 v36, -v33, v34, 1.0
	v_fmac_f32_e32 v34, v36, v34
	v_div_scale_f32 v36, vcc, 1.0, v32, 1.0
	v_mul_f32_e32 v37, v36, v34
	v_fma_f32 v38, -v33, v37, v36
	v_fmac_f32_e32 v37, v38, v34
	v_fma_f32 v33, -v33, v37, v36
	v_div_fmas_f32 v33, v33, v34, v37
	v_div_fixup_f32 v32, v33, v32, 1.0
	v_fmac_f32_e32 v57, v35, v32
	v_cvt_pk_bf16_f32 v32, v50, v51
	v_cvt_pk_bf16_f32 v33, v52, v53
	v_cvt_pk_bf16_f32 v34, v54, v55
	v_cvt_pk_bf16_f32 v35, v56, v57
	global_store_dwordx4 v[40:41], v[32:35], off offset:256
	v_lshlrev_b32_e32 v36, 16, v94
	v_lshlrev_b32_e32 v40, 16, v88
	v_lshlrev_b32_e32 v32, 16, v92
	v_mul_f32_e32 v32, 0xbfb8aa3b, v32
	v_exp_f32_e32 v32, v32
	v_and_b32_e32 v33, 0xffff0000, v92
	v_and_b32_e32 v37, 0xffff0000, v94
	v_and_b32_e32 v41, 0xffff0000, v88
	v_add_f32_e32 v32, 1.0, v32
	v_div_scale_f32 v48, s[18:19], v32, v32, 1.0
	v_rcp_f32_e32 v49, v48
	v_lshlrev_b32_e32 v34, 16, v93
	v_lshlrev_b32_e32 v38, 16, v95
	v_and_b32_e32 v35, 0xffff0000, v93
	v_fma_f32 v50, -v48, v49, 1.0
	v_fmac_f32_e32 v49, v50, v49
	v_div_scale_f32 v50, vcc, 1.0, v32, 1.0
	v_mul_f32_e32 v51, v50, v49
	v_fma_f32 v52, -v48, v51, v50
	v_fmac_f32_e32 v51, v52, v49
	v_fma_f32 v48, -v48, v51, v50
	v_div_fmas_f32 v48, v48, v49, v51
	v_div_fixup_f32 v32, v48, v32, 1.0
	v_fmac_f32_e32 v40, v28, v32
	v_mul_f32_e32 v28, 0xbfb8aa3b, v36
	v_exp_f32_e32 v28, v28
	s_nop 0
	v_add_f32_e32 v28, 1.0, v28
	v_div_scale_f32 v32, s[18:19], v28, v28, 1.0
	v_rcp_f32_e32 v36, v32
	s_nop 0
	v_fma_f32 v48, -v32, v36, 1.0
	v_fmac_f32_e32 v36, v48, v36
	v_div_scale_f32 v48, vcc, 1.0, v28, 1.0
	v_mul_f32_e32 v49, v48, v36
	v_fma_f32 v50, -v32, v49, v48
	v_fmac_f32_e32 v49, v50, v36
	v_fma_f32 v32, -v32, v49, v48
	v_div_fmas_f32 v32, v32, v36, v49
	v_div_fixup_f32 v28, v32, v28, 1.0
	v_fmac_f32_e32 v44, v24, v28
	v_mul_f32_e32 v24, 0xbfb8aa3b, v33
	v_exp_f32_e32 v24, v24
	s_nop 0
	v_add_f32_e32 v24, 1.0, v24
	v_div_scale_f32 v28, s[18:19], v24, v24, 1.0
	v_rcp_f32_e32 v32, v28
	s_nop 0
	v_fma_f32 v33, -v28, v32, 1.0
	v_fmac_f32_e32 v32, v33, v32
	v_div_scale_f32 v33, vcc, 1.0, v24, 1.0
	v_mul_f32_e32 v36, v33, v32
	v_fma_f32 v48, -v28, v36, v33
	v_fmac_f32_e32 v36, v48, v32
	v_fma_f32 v28, -v28, v36, v33
	v_div_fmas_f32 v28, v28, v32, v36
	v_div_fixup_f32 v24, v28, v24, 1.0
	v_fmac_f32_e32 v41, v29, v24
	v_mul_f32_e32 v24, 0xbfb8aa3b, v37
	v_exp_f32_e32 v24, v24
	s_waitcnt vmcnt(8)
; __device__ __forceinline__ unsigned cvt_pk_bf16(float lo, float hi) { unsigned r; asm volatile("v_cvt_pk_bf16_f32 %0, %1, %2" : "=v"(r) : "v"(lo), "v"(hi)); return r; }
; __device__ __forceinline__ float sigmoidf_(float x) { return 1.f / (1.f + __expf(-x)); }
; __device__ __forceinline__ void unpack8(const u32x4& w, float (&f)[8]) { f[0] = bflo(w.x); f[1] = bfhi(w.x); f[2] = bflo(w.y); f[3] = bfhi(w.y); f[4] = bflo(w.z); f[5] = bfhi(w.z); f[6] = bflo(w.w); f[7] = bfhi(w.w); }
;     __device__ __forceinline__ void operator()(const f32x4 (&acc)[2][2][4][2], const Unit& u, int wr, int wc, int fr, int fq) const {
;     ...
;                 for (int bj = 0; bj < 2; ++bj) { float g[8], t[8]; unpack8(gw[m][bj], g); unpack8(tw[m][bj], t); const f32x4 a0 = acc[ai][bj][m][0], a1 = acc[ai][bj][m][1]; float o[8];
; #pragma unroll
;                     for (int e = 0; e < 4; ++e) { o[e] = t[e] + a0[e] * sigmoidf_(g[e]); o[4 + e] = t[4 + e] + a1[e] * sigmoidf_(g[4 + e]); }
;                     *(u32x4*)(Y + (size_t)(row0 + ai * HALF + m * 16) * DM + col0 + bj * HALF) = (u32x4){cvt_pk_bf16(o[0], o[1]), cvt_pk_bf16(o[2], o[3]), cvt_pk_bf16(o[4], o[5]), cvt_pk_bf16(o[6], o[7])}; } }
	v_and_b32_e32 v37, 0xffff0000, v81
	v_add_f32_e32 v24, 1.0, v24
	v_div_scale_f32 v28, s[18:19], v24, v24, 1.0
	v_rcp_f32_e32 v29, v28
	s_nop 0
	v_fma_f32 v32, -v28, v29, 1.0
	v_fmac_f32_e32 v29, v32, v29
	v_div_scale_f32 v32, vcc, 1.0, v24, 1.0
	v_mul_f32_e32 v33, v32, v29
	v_fma_f32 v36, -v28, v33, v32
	v_fmac_f32_e32 v33, v36, v29
	v_fma_f32 v28, -v28, v33, v32
	v_div_fmas_f32 v28, v28, v29, v33
	v_div_fixup_f32 v24, v28, v24, 1.0
	v_fmac_f32_e32 v45, v25, v24
	v_mul_f32_e32 v24, 0xbfb8aa3b, v34
	v_exp_f32_e32 v24, v24
	v_lshlrev_b32_e32 v34, 16, v80
	v_lshlrev_b32_e32 v36, 16, v81
	v_add_f32_e32 v24, 1.0, v24
	v_div_scale_f32 v25, s[18:19], v24, v24, 1.0
	v_rcp_f32_e32 v28, v25
	s_nop 0
	v_fma_f32 v29, -v25, v28, 1.0
	v_fmac_f32_e32 v28, v29, v28
	v_div_scale_f32 v29, vcc, 1.0, v24, 1.0
	v_mul_f32_e32 v32, v29, v28
	v_fma_f32 v33, -v25, v32, v29
	v_fmac_f32_e32 v32, v33, v28
	v_fma_f32 v25, -v25, v32, v29
	v_div_fmas_f32 v25, v25, v28, v32
	v_div_fixup_f32 v24, v25, v24, 1.0
	v_fmac_f32_e32 v42, v30, v24
	v_mul_f32_e32 v24, 0xbfb8aa3b, v38
	v_exp_f32_e32 v24, v24
	v_lshlrev_b32_e32 v38, 16, v82
	v_and_b32_e32 v33, 0xffff0000, v87
	v_add_f32_e32 v24, 1.0, v24
	v_div_scale_f32 v25, s[18:19], v24, v24, 1.0
	v_rcp_f32_e32 v28, v25
	s_nop 0
	v_fma_f32 v29, -v25, v28, 1.0
	v_fmac_f32_e32 v28, v29, v28
	v_div_scale_f32 v29, vcc, 1.0, v24, 1.0
	v_mul_f32_e32 v30, v29, v28
	v_fma_f32 v32, -v25, v30, v29
	v_fmac_f32_e32 v30, v32, v28
	v_fma_f32 v25, -v25, v30, v29
	v_div_fmas_f32 v25, v25, v28, v30
	v_div_fixup_f32 v24, v25, v24, 1.0
	v_fmac_f32_e32 v46, v26, v24
	v_mul_f32_e32 v24, 0xbfb8aa3b, v35
	v_exp_f32_e32 v24, v24
	v_and_b32_e32 v35, 0xffff0000, v80
	v_lshlrev_b32_e32 v32, 16, v87
	v_add_f32_e32 v24, 1.0, v24
	v_div_scale_f32 v25, s[18:19], v24, v24, 1.0
	v_rcp_f32_e32 v26, v25
	s_nop 0
	v_fma_f32 v28, -v25, v26, 1.0
	v_fmac_f32_e32 v26, v28, v26
	v_div_scale_f32 v28, vcc, 1.0, v24, 1.0
	v_mul_f32_e32 v29, v28, v26
	v_fma_f32 v30, -v25, v29, v28
	v_fmac_f32_e32 v29, v30, v26
	v_fma_f32 v25, -v25, v29, v28
	v_div_fmas_f32 v25, v25, v26, v29
	v_div_fixup_f32 v24, v25, v24, 1.0
	v_fmac_f32_e32 v43, v31, v24
	v_mul_f32_e32 v24, 0xbfb8aa3b, v39
	v_exp_f32_e32 v24, v24
	v_and_b32_e32 v31, 0xffff0000, v86
	v_and_b32_e32 v39, 0xffff0000, v82
	v_add_f32_e32 v24, 1.0, v24
	v_div_scale_f32 v25, s[18:19], v24, v24, 1.0
	v_rcp_f32_e32 v26, v25
	s_nop 0
	v_fma_f32 v28, -v25, v26, 1.0
	v_fmac_f32_e32 v26, v28, v26
	v_div_scale_f32 v28, vcc, 1.0, v24, 1.0
	v_mul_f32_e32 v29, v28, v26
	v_fma_f32 v30, -v25, v29, v28
	v_fmac_f32_e32 v29, v30, v26
	v_fma_f32 v25, -v25, v29, v28
	v_div_fmas_f32 v25, v25, v26, v29
	v_div_fixup_f32 v24, v25, v24, 1.0
	v_fmac_f32_e32 v47, v27, v24
	v_lshl_add_u64 v[24:25], s[76:77], 0, v[122:123]
	v_cvt_pk_bf16_f32 v26, v40, v41
	v_lshl_add_u64 v[24:25], v[24:25], 0, v[206:207]
	v_cvt_pk_bf16_f32 v27, v42, v43
	v_cvt_pk_bf16_f32 v28, v44, v45
	v_cvt_pk_bf16_f32 v29, v46, v47
	global_store_dwordx4 v[24:25], v[26:29], off
	v_lshlrev_b32_e32 v30, 16, v86
	v_lshlrev_b32_e32 v40, 16, v83
	v_lshlrev_b32_e32 v26, 16, v84
	v_mul_f32_e32 v26, 0xbfb8aa3b, v26
	v_exp_f32_e32 v26, v26
	v_and_b32_e32 v27, 0xffff0000, v84
	v_lshlrev_b32_e32 v28, 16, v85
	v_and_b32_e32 v29, 0xffff0000, v85
	v_add_f32_e32 v26, 1.0, v26
	v_div_scale_f32 v42, s[18:19], v26, v26, 1.0
	v_rcp_f32_e32 v43, v42
	v_and_b32_e32 v41, 0xffff0000, v83
	v_fma_f32 v44, -v42, v43, 1.0
	v_fmac_f32_e32 v43, v44, v43
	v_div_scale_f32 v44, vcc, 1.0, v26, 1.0
	v_mul_f32_e32 v45, v44, v43
	v_fma_f32 v46, -v42, v45, v44
	v_fmac_f32_e32 v45, v46, v43
	v_fma_f32 v42, -v42, v45, v44
	v_div_fmas_f32 v42, v42, v43, v45
	v_div_fixup_f32 v26, v42, v26, 1.0
	v_fmac_f32_e32 v34, v20, v26
	v_mul_f32_e32 v20, 0xbfb8aa3b, v30
	v_exp_f32_e32 v20, v20
	s_nop 0
	v_add_f32_e32 v20, 1.0, v20
	v_div_scale_f32 v26, s[18:19], v20, v20, 1.0
	v_rcp_f32_e32 v30, v26
	s_nop 0
	v_fma_f32 v42, -v26, v30, 1.0
	v_fmac_f32_e32 v30, v42, v30
	v_div_scale_f32 v42, vcc, 1.0, v20, 1.0
	v_mul_f32_e32 v43, v42, v30
	v_fma_f32 v44, -v26, v43, v42
	v_fmac_f32_e32 v43, v44, v30
	v_fma_f32 v26, -v26, v43, v42
	v_div_fmas_f32 v26, v26, v30, v43
	v_div_fixup_f32 v20, v26, v20, 1.0
	v_fmac_f32_e32 v38, v16, v20
	v_mul_f32_e32 v16, 0xbfb8aa3b, v27
	v_exp_f32_e32 v16, v16
	s_nop 0
	v_add_f32_e32 v16, 1.0, v16
	v_div_scale_f32 v20, s[18:19], v16, v16, 1.0
	v_rcp_f32_e32 v26, v20
	s_nop 0
	v_fma_f32 v27, -v20, v26, 1.0
	v_fmac_f32_e32 v26, v27, v26
	v_div_scale_f32 v27, vcc, 1.0, v16, 1.0
	v_mul_f32_e32 v30, v27, v26
	v_fma_f32 v42, -v20, v30, v27
	v_fmac_f32_e32 v30, v42, v26
	v_fma_f32 v20, -v20, v30, v27
	v_div_fmas_f32 v20, v20, v26, v30
	v_div_fixup_f32 v16, v20, v16, 1.0
	v_fmac_f32_e32 v35, v21, v16
	v_mul_f32_e32 v16, 0xbfb8aa3b, v31
	v_exp_f32_e32 v16, v16
	s_waitcnt vmcnt(7)
; __device__ __forceinline__ unsigned cvt_pk_bf16(float lo, float hi) { unsigned r; asm volatile("v_cvt_pk_bf16_f32 %0, %1, %2" : "=v"(r) : "v"(lo), "v"(hi)); return r; }
; __device__ __forceinline__ float sigmoidf_(float x) { return 1.f / (1.f + __expf(-x)); }
; __device__ __forceinline__ void unpack8(const u32x4& w, float (&f)[8]) { f[0] = bflo(w.x); f[1] = bfhi(w.x); f[2] = bflo(w.y); f[3] = bfhi(w.y); f[4] = bflo(w.z); f[5] = bfhi(w.z); f[6] = bflo(w.w); f[7] = bfhi(w.w); }
;     __device__ __forceinline__ void operator()(const f32x4 (&acc)[2][2][4][2], const Unit& u, int wr, int wc, int fr, int fq) const {
;     ...
;                 for (int bj = 0; bj < 2; ++bj) { float g[8], t[8]; unpack8(gw[m][bj], g); unpack8(tw[m][bj], t); const f32x4 a0 = acc[ai][bj][m][0], a1 = acc[ai][bj][m][1]; float o[8];
; #pragma unroll
;                     for (int e = 0; e < 4; ++e) { o[e] = t[e] + a0[e] * sigmoidf_(g[e]); o[4 + e] = t[4 + e] + a1[e] * sigmoidf_(g[4 + e]); }
;                     *(u32x4*)(Y + (size_t)(row0 + ai * HALF + m * 16) * DM + col0 + bj * HALF) = (u32x4){cvt_pk_bf16(o[0], o[1]), cvt_pk_bf16(o[2], o[3]), cvt_pk_bf16(o[4], o[5]), cvt_pk_bf16(o[6], o[7])}; } }
	v_and_b32_e32 v31, 0xffff0000, v75
	v_add_f32_e32 v16, 1.0, v16
	v_div_scale_f32 v20, s[18:19], v16, v16, 1.0
	v_rcp_f32_e32 v21, v20
	s_nop 0
	v_fma_f32 v26, -v20, v21, 1.0
	v_fmac_f32_e32 v21, v26, v21
	v_div_scale_f32 v26, vcc, 1.0, v16, 1.0
	v_mul_f32_e32 v27, v26, v21
	v_fma_f32 v30, -v20, v27, v26
	v_fmac_f32_e32 v27, v30, v21
	v_fma_f32 v20, -v20, v27, v26
	v_div_fmas_f32 v20, v20, v21, v27
	v_div_fixup_f32 v16, v20, v16, 1.0
	v_fmac_f32_e32 v39, v17, v16
	v_mul_f32_e32 v16, 0xbfb8aa3b, v28
	v_exp_f32_e32 v16, v16
	v_lshlrev_b32_e32 v28, 16, v74
	v_lshlrev_b32_e32 v30, 16, v75
	v_add_f32_e32 v16, 1.0, v16
	v_div_scale_f32 v17, s[18:19], v16, v16, 1.0
	v_rcp_f32_e32 v20, v17
	s_nop 0
	v_fma_f32 v21, -v17, v20, 1.0
	v_fmac_f32_e32 v20, v21, v20
	v_div_scale_f32 v21, vcc, 1.0, v16, 1.0
	v_mul_f32_e32 v26, v21, v20
	v_fma_f32 v27, -v17, v26, v21
	v_fmac_f32_e32 v26, v27, v20
	v_fma_f32 v17, -v17, v26, v21
	v_div_fmas_f32 v17, v17, v20, v26
	v_div_fixup_f32 v16, v17, v16, 1.0
	v_fmac_f32_e32 v36, v22, v16
	v_mul_f32_e32 v16, 0xbfb8aa3b, v32
	v_exp_f32_e32 v16, v16
	v_and_b32_e32 v27, 0xffff0000, v73
	v_add_f32_e32 v16, 1.0, v16
	v_div_scale_f32 v17, s[18:19], v16, v16, 1.0
	v_rcp_f32_e32 v20, v17
	s_nop 0
	v_fma_f32 v21, -v17, v20, 1.0
	v_fmac_f32_e32 v20, v21, v20
	v_div_scale_f32 v21, vcc, 1.0, v16, 1.0
	v_mul_f32_e32 v22, v21, v20
	v_fma_f32 v26, -v17, v22, v21
	v_fmac_f32_e32 v22, v26, v20
	v_fma_f32 v17, -v17, v22, v21
	v_div_fmas_f32 v17, v17, v20, v22
	v_div_fixup_f32 v16, v17, v16, 1.0
	v_fmac_f32_e32 v40, v18, v16
	v_mul_f32_e32 v16, 0xbfb8aa3b, v29
	v_exp_f32_e32 v16, v16
	v_and_b32_e32 v29, 0xffff0000, v74
	v_lshlrev_b32_e32 v26, 16, v73
	v_add_f32_e32 v16, 1.0, v16
	v_div_scale_f32 v17, s[18:19], v16, v16, 1.0
	v_rcp_f32_e32 v18, v17
	s_nop 0
	v_fma_f32 v20, -v17, v18, 1.0
	v_fmac_f32_e32 v18, v20, v18
	v_div_scale_f32 v20, vcc, 1.0, v16, 1.0
	v_mul_f32_e32 v21, v20, v18
	v_fma_f32 v22, -v17, v21, v20
	v_fmac_f32_e32 v21, v22, v18
	v_fma_f32 v17, -v17, v21, v20
	v_div_fmas_f32 v17, v17, v18, v21
	v_div_fixup_f32 v16, v17, v16, 1.0
	v_fmac_f32_e32 v37, v23, v16
	v_mul_f32_e32 v16, 0xbfb8aa3b, v33
	v_exp_f32_e32 v16, v16
	v_and_b32_e32 v23, 0xffff0000, v79
	v_add_f32_e32 v16, 1.0, v16
	v_div_scale_f32 v17, s[18:19], v16, v16, 1.0
	v_rcp_f32_e32 v18, v17
	s_nop 0
	v_fma_f32 v20, -v17, v18, 1.0
	v_fmac_f32_e32 v18, v20, v18
	v_div_scale_f32 v20, vcc, 1.0, v16, 1.0
	v_mul_f32_e32 v21, v20, v18
	v_fma_f32 v22, -v17, v21, v20
	v_fmac_f32_e32 v21, v22, v18
	v_fma_f32 v17, -v17, v21, v20
	v_div_fmas_f32 v17, v17, v18, v21
	v_div_fixup_f32 v16, v17, v16, 1.0
	v_fmac_f32_e32 v41, v19, v16
	v_cvt_pk_bf16_f32 v16, v34, v35
	v_cvt_pk_bf16_f32 v17, v36, v37
	v_cvt_pk_bf16_f32 v18, v38, v39
	v_cvt_pk_bf16_f32 v19, v40, v41
	global_store_dwordx4 v[24:25], v[16:19], off offset:256
	v_lshlrev_b32_e32 v20, 16, v78
	v_lshlrev_b32_e32 v24, 16, v72
	v_lshlrev_b32_e32 v16, 16, v76
	v_mul_f32_e32 v16, 0xbfb8aa3b, v16
	v_exp_f32_e32 v16, v16
	v_and_b32_e32 v17, 0xffff0000, v76
	v_and_b32_e32 v21, 0xffff0000, v78
	v_and_b32_e32 v25, 0xffff0000, v72
	v_add_f32_e32 v16, 1.0, v16
	v_div_scale_f32 v32, s[18:19], v16, v16, 1.0
	v_rcp_f32_e32 v33, v32
	v_lshlrev_b32_e32 v18, 16, v77
	v_lshlrev_b32_e32 v22, 16, v79
	v_and_b32_e32 v19, 0xffff0000, v77
	v_fma_f32 v34, -v32, v33, 1.0
	v_fmac_f32_e32 v33, v34, v33
	v_div_scale_f32 v34, vcc, 1.0, v16, 1.0
	v_mul_f32_e32 v35, v34, v33
	v_fma_f32 v36, -v32, v35, v34
	v_fmac_f32_e32 v35, v36, v33
	v_fma_f32 v32, -v32, v35, v34
	v_div_fmas_f32 v32, v32, v33, v35
	v_div_fixup_f32 v16, v32, v16, 1.0
	v_fmac_f32_e32 v24, v12, v16
	v_mul_f32_e32 v12, 0xbfb8aa3b, v20
	v_exp_f32_e32 v12, v12
	s_nop 0
	v_add_f32_e32 v12, 1.0, v12
	v_div_scale_f32 v16, s[18:19], v12, v12, 1.0
	v_rcp_f32_e32 v20, v16
	s_nop 0
	v_fma_f32 v32, -v16, v20, 1.0
	v_fmac_f32_e32 v20, v32, v20
	v_div_scale_f32 v32, vcc, 1.0, v12, 1.0
	v_mul_f32_e32 v33, v32, v20
	v_fma_f32 v34, -v16, v33, v32
	v_fmac_f32_e32 v33, v34, v20
	v_fma_f32 v16, -v16, v33, v32
	v_div_fmas_f32 v16, v16, v20, v33
	v_div_fixup_f32 v12, v16, v12, 1.0
	v_fmac_f32_e32 v28, v8, v12
	v_mul_f32_e32 v8, 0xbfb8aa3b, v17
	v_exp_f32_e32 v8, v8
	s_nop 0
	v_add_f32_e32 v8, 1.0, v8
	v_div_scale_f32 v12, s[18:19], v8, v8, 1.0
	v_rcp_f32_e32 v16, v12
	s_nop 0
	v_fma_f32 v17, -v12, v16, 1.0
	v_fmac_f32_e32 v16, v17, v16
	v_div_scale_f32 v17, vcc, 1.0, v8, 1.0
	v_mul_f32_e32 v20, v17, v16
	v_fma_f32 v32, -v12, v20, v17
	v_fmac_f32_e32 v20, v32, v16
	v_fma_f32 v12, -v12, v20, v17
	v_div_fmas_f32 v12, v12, v16, v20
	v_div_fixup_f32 v8, v12, v8, 1.0
	v_fmac_f32_e32 v25, v13, v8
	v_mul_f32_e32 v8, 0xbfb8aa3b, v21
	v_exp_f32_e32 v8, v8
	s_waitcnt vmcnt(6)
; __device__ __forceinline__ unsigned cvt_pk_bf16(float lo, float hi) { unsigned r; asm volatile("v_cvt_pk_bf16_f32 %0, %1, %2" : "=v"(r) : "v"(lo), "v"(hi)); return r; }
; __device__ __forceinline__ float sigmoidf_(float x) { return 1.f / (1.f + __expf(-x)); }
; __device__ __forceinline__ void unpack8(const u32x4& w, float (&f)[8]) { f[0] = bflo(w.x); f[1] = bfhi(w.x); f[2] = bflo(w.y); f[3] = bfhi(w.y); f[4] = bflo(w.z); f[5] = bfhi(w.z); f[6] = bflo(w.w); f[7] = bfhi(w.w); }
;     __device__ __forceinline__ void operator()(const f32x4 (&acc)[2][2][4][2], const Unit& u, int wr, int wc, int fr, int fq) const {
;     ...
;                 for (int bj = 0; bj < 2; ++bj) { float g[8], t[8]; unpack8(gw[m][bj], g); unpack8(tw[m][bj], t); const f32x4 a0 = acc[ai][bj][m][0], a1 = acc[ai][bj][m][1]; float o[8];
; #pragma unroll
;                     for (int e = 0; e < 4; ++e) { o[e] = t[e] + a0[e] * sigmoidf_(g[e]); o[4 + e] = t[4 + e] + a1[e] * sigmoidf_(g[4 + e]); }
;                     *(u32x4*)(Y + (size_t)(row0 + ai * HALF + m * 16) * DM + col0 + bj * HALF) = (u32x4){cvt_pk_bf16(o[0], o[1]), cvt_pk_bf16(o[2], o[3]), cvt_pk_bf16(o[4], o[5]), cvt_pk_bf16(o[6], o[7])}; } }
	v_and_b32_e32 v21, 0xffff0000, v65
	v_add_f32_e32 v8, 1.0, v8
	v_div_scale_f32 v12, s[18:19], v8, v8, 1.0
	v_rcp_f32_e32 v13, v12
	s_nop 0
	v_fma_f32 v16, -v12, v13, 1.0
	v_fmac_f32_e32 v13, v16, v13
	v_div_scale_f32 v16, vcc, 1.0, v8, 1.0
	v_mul_f32_e32 v17, v16, v13
	v_fma_f32 v20, -v12, v17, v16
	v_fmac_f32_e32 v17, v20, v13
	v_fma_f32 v12, -v12, v17, v16
	v_div_fmas_f32 v12, v12, v13, v17
	v_div_fixup_f32 v8, v12, v8, 1.0
	v_fmac_f32_e32 v29, v9, v8
	v_mul_f32_e32 v8, 0xbfb8aa3b, v18
	v_exp_f32_e32 v8, v8
	v_lshlrev_b32_e32 v18, 16, v64
	v_lshlrev_b32_e32 v20, 16, v65
	v_add_f32_e32 v8, 1.0, v8
	v_div_scale_f32 v9, s[18:19], v8, v8, 1.0
	v_rcp_f32_e32 v12, v9
	s_nop 0
	v_fma_f32 v13, -v9, v12, 1.0
	v_fmac_f32_e32 v12, v13, v12
	v_div_scale_f32 v13, vcc, 1.0, v8, 1.0
	v_mul_f32_e32 v16, v13, v12
	v_fma_f32 v17, -v9, v16, v13
	v_fmac_f32_e32 v16, v17, v12
	v_fma_f32 v9, -v9, v16, v13
	v_div_fmas_f32 v9, v9, v12, v16
	v_div_fixup_f32 v8, v9, v8, 1.0
	v_fmac_f32_e32 v26, v14, v8
	v_mul_f32_e32 v8, 0xbfb8aa3b, v22
	v_exp_f32_e32 v8, v8
	v_lshlrev_b32_e32 v22, 16, v66
	v_and_b32_e32 v17, 0xffff0000, v71
	v_add_f32_e32 v8, 1.0, v8
	v_div_scale_f32 v9, s[18:19], v8, v8, 1.0
	v_rcp_f32_e32 v12, v9
	s_nop 0
	v_fma_f32 v13, -v9, v12, 1.0
	v_fmac_f32_e32 v12, v13, v12
	v_div_scale_f32 v13, vcc, 1.0, v8, 1.0
	v_mul_f32_e32 v14, v13, v12
	v_fma_f32 v16, -v9, v14, v13
	v_fmac_f32_e32 v14, v16, v12
	v_fma_f32 v9, -v9, v14, v13
	v_div_fmas_f32 v9, v9, v12, v14
	v_div_fixup_f32 v8, v9, v8, 1.0
	v_fmac_f32_e32 v30, v10, v8
	v_mul_f32_e32 v8, 0xbfb8aa3b, v19
	v_exp_f32_e32 v8, v8
	v_and_b32_e32 v19, 0xffff0000, v64
	v_lshlrev_b32_e32 v16, 16, v71
	v_add_f32_e32 v8, 1.0, v8
	v_div_scale_f32 v9, s[18:19], v8, v8, 1.0
	v_rcp_f32_e32 v10, v9
	s_nop 0
	v_fma_f32 v12, -v9, v10, 1.0
	v_fmac_f32_e32 v10, v12, v10
	v_div_scale_f32 v12, vcc, 1.0, v8, 1.0
	v_mul_f32_e32 v13, v12, v10
	v_fma_f32 v14, -v9, v13, v12
	v_fmac_f32_e32 v13, v14, v10
	v_fma_f32 v9, -v9, v13, v12
	v_div_fmas_f32 v9, v9, v10, v13
	v_div_fixup_f32 v8, v9, v8, 1.0
	v_fmac_f32_e32 v27, v15, v8
	v_mul_f32_e32 v8, 0xbfb8aa3b, v23
	v_exp_f32_e32 v8, v8
	v_and_b32_e32 v15, 0xffff0000, v70
	v_and_b32_e32 v23, 0xffff0000, v66
	v_add_f32_e32 v8, 1.0, v8
	v_div_scale_f32 v9, s[18:19], v8, v8, 1.0
	v_rcp_f32_e32 v10, v9
	s_nop 0
	v_fma_f32 v12, -v9, v10, 1.0
	v_fmac_f32_e32 v10, v12, v10
	v_div_scale_f32 v12, vcc, 1.0, v8, 1.0
	v_mul_f32_e32 v13, v12, v10
	v_fma_f32 v14, -v9, v13, v12
	v_fmac_f32_e32 v13, v14, v10
	v_fma_f32 v9, -v9, v13, v12
	v_div_fmas_f32 v9, v9, v10, v13
	v_div_fixup_f32 v8, v9, v8, 1.0
	v_fmac_f32_e32 v31, v11, v8
	v_lshl_add_u64 v[8:9], s[76:77], 0, v[120:121]
	v_cvt_pk_bf16_f32 v10, v24, v25
	v_lshl_add_u64 v[8:9], v[8:9], 0, v[206:207]
	v_cvt_pk_bf16_f32 v11, v26, v27
	v_cvt_pk_bf16_f32 v12, v28, v29
	v_cvt_pk_bf16_f32 v13, v30, v31
	global_store_dwordx4 v[8:9], v[10:13], off
	v_lshlrev_b32_e32 v14, 16, v70
	v_lshlrev_b32_e32 v24, 16, v67
	v_lshlrev_b32_e32 v10, 16, v68
	v_mul_f32_e32 v10, 0xbfb8aa3b, v10
	v_exp_f32_e32 v10, v10
	v_and_b32_e32 v11, 0xffff0000, v68
	v_lshlrev_b32_e32 v12, 16, v69
	v_and_b32_e32 v13, 0xffff0000, v69
	v_add_f32_e32 v10, 1.0, v10
	v_div_scale_f32 v26, s[18:19], v10, v10, 1.0
	v_rcp_f32_e32 v27, v26
	v_and_b32_e32 v25, 0xffff0000, v67
	v_fma_f32 v28, -v26, v27, 1.0
	v_fmac_f32_e32 v27, v28, v27
	v_div_scale_f32 v28, vcc, 1.0, v10, 1.0
	v_mul_f32_e32 v29, v28, v27
	v_fma_f32 v30, -v26, v29, v28
	v_fmac_f32_e32 v29, v30, v27
	v_fma_f32 v26, -v26, v29, v28
	v_div_fmas_f32 v26, v26, v27, v29
	v_div_fixup_f32 v10, v26, v10, 1.0
	v_fmac_f32_e32 v18, v4, v10
; __device__ __forceinline__ unsigned cvt_pk_bf16(float lo, float hi) { unsigned r; asm volatile("v_cvt_pk_bf16_f32 %0, %1, %2" : "=v"(r) : "v"(lo), "v"(hi)); return r; }
; __device__ __forceinline__ float sigmoidf_(float x) { return 1.f / (1.f + __expf(-x)); }
; #define PG8_BAR __builtin_amdgcn_s_barrier()
; __device__ __forceinline__ void unpack8(const u32x4& w, float (&f)[8]) { f[0] = bflo(w.x); f[1] = bfhi(w.x); f[2] = bflo(w.y); f[3] = bfhi(w.y); f[4] = bflo(w.z); f[5] = bfhi(w.z); f[6] = bflo(w.w); f[7] = bfhi(w.w); }
; template <class Epi, class Sched>
; __device__ __forceinline__ void gemm_phase(LAS unsigned char* lds, const Gemm g, const Sched& S, const Epi& E) {
;     ...
;         if (wr == 0) PG8_BAR;
;         E(acc, cur, wr, wc, fr, fq);
;         if (!has_next) break;
; #pragma unroll
;         for (int a = 0; a < 2; ++a)
; #pragma unroll
;             for (int b = 0; b < 2; ++b)
; #pragma unroll
;                 for (int m = 0; m < 4; ++m)
; #pragma unroll
;                     for (int n = 0; n < 2; ++n) acc[a][b][m][n] = (f32x4){0.f, 0.f, 0.f, 0.f};
;         cur = nxt; cA = nA; cB = nB; ++ui;
;         if (wr == 1) PG8_BAR;
;     __device__ __forceinline__ void operator()(const f32x4 (&acc)[2][2][4][2], const Unit& u, int wr, int wc, int fr, int fq) const {
;     ...
;                 for (int bj = 0; bj < 2; ++bj) { float g[8], t[8]; unpack8(gw[m][bj], g); unpack8(tw[m][bj], t); const f32x4 a0 = acc[ai][bj][m][0], a1 = acc[ai][bj][m][1]; float o[8];
; #pragma unroll
;                     for (int e = 0; e < 4; ++e) { o[e] = t[e] + a0[e] * sigmoidf_(g[e]); o[4 + e] = t[4 + e] + a1[e] * sigmoidf_(g[4 + e]); }
;                     *(u32x4*)(Y + (size_t)(row0 + ai * HALF + m * 16) * DM + col0 + bj * HALF) = (u32x4){cvt_pk_bf16(o[0], o[1]), cvt_pk_bf16(o[2], o[3]), cvt_pk_bf16(o[4], o[5]), cvt_pk_bf16(o[6], o[7])}; } }
	v_mul_f32_e32 v4, 0xbfb8aa3b, v14
	v_exp_f32_e32 v4, v4
	s_nop 0
	v_add_f32_e32 v4, 1.0, v4
	v_div_scale_f32 v10, s[18:19], v4, v4, 1.0
	v_rcp_f32_e32 v14, v10
	s_nop 0
	v_fma_f32 v26, -v10, v14, 1.0
	v_fmac_f32_e32 v14, v26, v14
	v_div_scale_f32 v26, vcc, 1.0, v4, 1.0
	v_mul_f32_e32 v27, v26, v14
	v_fma_f32 v28, -v10, v27, v26
	v_fmac_f32_e32 v27, v28, v14
	v_fma_f32 v10, -v10, v27, v26
	v_div_fmas_f32 v10, v10, v14, v27
	v_div_fixup_f32 v4, v10, v4, 1.0
	v_fmac_f32_e32 v22, v0, v4
	v_mul_f32_e32 v0, 0xbfb8aa3b, v11
	v_exp_f32_e32 v0, v0
	s_nop 0
	v_add_f32_e32 v0, 1.0, v0
	v_div_scale_f32 v4, s[18:19], v0, v0, 1.0
	v_rcp_f32_e32 v10, v4
	s_nop 0
	v_fma_f32 v11, -v4, v10, 1.0
	v_fmac_f32_e32 v10, v11, v10
	v_div_scale_f32 v11, vcc, 1.0, v0, 1.0
	v_mul_f32_e32 v14, v11, v10
	v_fma_f32 v26, -v4, v14, v11
	v_fmac_f32_e32 v14, v26, v10
	v_fma_f32 v4, -v4, v14, v11
	v_div_fmas_f32 v4, v4, v10, v14
	v_div_fixup_f32 v0, v4, v0, 1.0
	v_fmac_f32_e32 v19, v5, v0
	v_mul_f32_e32 v0, 0xbfb8aa3b, v15
	v_exp_f32_e32 v0, v0
	s_nop 0
	v_add_f32_e32 v0, 1.0, v0
	v_div_scale_f32 v4, s[18:19], v0, v0, 1.0
	v_rcp_f32_e32 v5, v4
	s_nop 0
	v_fma_f32 v10, -v4, v5, 1.0
	v_fmac_f32_e32 v5, v10, v5
	v_div_scale_f32 v10, vcc, 1.0, v0, 1.0
	v_mul_f32_e32 v11, v10, v5
	v_fma_f32 v14, -v4, v11, v10
	v_fmac_f32_e32 v11, v14, v5
	v_fma_f32 v4, -v4, v11, v10
	v_div_fmas_f32 v4, v4, v5, v11
	v_div_fixup_f32 v0, v4, v0, 1.0
	v_fmac_f32_e32 v23, v1, v0
	v_mul_f32_e32 v0, 0xbfb8aa3b, v12
	v_exp_f32_e32 v0, v0
	s_nop 0
	v_add_f32_e32 v0, 1.0, v0
	v_div_scale_f32 v1, s[18:19], v0, v0, 1.0
	v_rcp_f32_e32 v4, v1
	s_nop 0
	v_fma_f32 v5, -v1, v4, 1.0
	v_fmac_f32_e32 v4, v5, v4
	v_div_scale_f32 v5, vcc, 1.0, v0, 1.0
	v_mul_f32_e32 v10, v5, v4
	v_fma_f32 v11, -v1, v10, v5
	v_fmac_f32_e32 v10, v11, v4
	v_fma_f32 v1, -v1, v10, v5
	v_div_fmas_f32 v1, v1, v4, v10
	v_div_fixup_f32 v0, v1, v0, 1.0
	v_fmac_f32_e32 v20, v6, v0
	v_mul_f32_e32 v0, 0xbfb8aa3b, v16
	v_exp_f32_e32 v0, v0
	s_nop 0
	v_add_f32_e32 v0, 1.0, v0
	v_div_scale_f32 v1, s[18:19], v0, v0, 1.0
	v_rcp_f32_e32 v4, v1
	s_nop 0
	v_fma_f32 v5, -v1, v4, 1.0
	v_fmac_f32_e32 v4, v5, v4
	v_div_scale_f32 v5, vcc, 1.0, v0, 1.0
	v_mul_f32_e32 v6, v5, v4
	v_fma_f32 v10, -v1, v6, v5
	v_fmac_f32_e32 v6, v10, v4
	v_fma_f32 v1, -v1, v6, v5
	v_div_fmas_f32 v1, v1, v4, v6
	v_div_fixup_f32 v0, v1, v0, 1.0
	v_fmac_f32_e32 v24, v2, v0
	v_mul_f32_e32 v0, 0xbfb8aa3b, v13
	v_exp_f32_e32 v0, v0
	s_nop 0
	v_add_f32_e32 v0, 1.0, v0
	v_div_scale_f32 v1, s[18:19], v0, v0, 1.0
	v_rcp_f32_e32 v2, v1
	s_nop 0
	v_fma_f32 v4, -v1, v2, 1.0
	v_fmac_f32_e32 v2, v4, v2
	v_div_scale_f32 v4, vcc, 1.0, v0, 1.0
	v_mul_f32_e32 v5, v4, v2
	v_fma_f32 v6, -v1, v5, v4
	v_fmac_f32_e32 v5, v6, v2
	v_fma_f32 v1, -v1, v5, v4
	v_div_fmas_f32 v1, v1, v2, v5
	v_div_fixup_f32 v0, v1, v0, 1.0
	v_fmac_f32_e32 v21, v7, v0
	v_mul_f32_e32 v0, 0xbfb8aa3b, v17
	v_exp_f32_e32 v0, v0
	s_nop 0
	v_add_f32_e32 v0, 1.0, v0
	v_div_scale_f32 v1, s[18:19], v0, v0, 1.0
	v_rcp_f32_e32 v2, v1
	s_mov_b64 s[18:19], -1
	v_fma_f32 v4, -v1, v2, 1.0
	v_fmac_f32_e32 v2, v4, v2
	v_div_scale_f32 v4, vcc, 1.0, v0, 1.0
	v_mul_f32_e32 v5, v4, v2
	v_fma_f32 v6, -v1, v5, v4
	v_fmac_f32_e32 v5, v6, v2
	v_fma_f32 v1, -v1, v5, v4
	v_div_fmas_f32 v1, v1, v2, v5
	v_div_fixup_f32 v0, v1, v0, 1.0
	s_and_b64 vcc, exec, s[4:5]
	v_fmac_f32_e32 v25, v3, v0
	v_cvt_pk_bf16_f32 v0, v18, v19
	v_cvt_pk_bf16_f32 v1, v20, v21
	v_cvt_pk_bf16_f32 v2, v22, v23
	v_cvt_pk_bf16_f32 v3, v24, v25
	global_store_dwordx4 v[8:9], v[0:3], off offset:256
	s_cbranch_vccnz .LBB0_685
	s_andn2_b64 vcc, exec, s[0:1]
	s_cbranch_vccnz .LBB0_684
	s_barrier
	s_branch .LBB0_684

; __device__ __forceinline__ unsigned cvt_pk_bf16(float lo, float hi) { unsigned r; asm volatile("v_cvt_pk_bf16_f32 %0, %1, %2" : "=v"(r) : "v"(lo), "v"(hi)); return r; }
;     __device__ __forceinline__ void operator()(const f32x4 (&acc)[2][2][4][2], const Unit& u, int wr, int wc, int fr, int fq) const {
;     ...
;         for (int ai = 0; ai < 2; ++ai) {
;             f32x4 bf[MODE == 0 ? 4 : 1][2][2]; u32x4 bb[MODE == 1 ? 4 : 1][2];
; #pragma unroll
;             for (int m = 0; m < 4; ++m) { const int row = row0 + ai * HALF + m * 16;
;                 if (MODE == 0) { const float* br = row < MP ? basep + (size_t)row * DM : bases + (size_t)(row - MP) * DM;
; #pragma unroll
;                     for (int bj = 0; bj < 2; ++bj) { bf[MODE == 0 ? m : 0][bj][0] = *(const f32x4*)(br + col0 + bj * HALF); bf[MODE == 0 ? m : 0][bj][1] = *(const f32x4*)(br + col0 + bj * HALF + 4); } }
;                 else {
; #pragma unroll
;                     for (int bj = 0; bj < 2; ++bj) bb[MODE == 1 ? m : 0][bj] = *(const u32x4*)(baseb + (size_t)row * DM + col0 + bj * HALF); } }
; #pragma unroll
;             for (int m = 0; m < 4; ++m) { const int row = row0 + ai * HALF + m * 16; float s = 0.f;
; #pragma unroll
;                 for (int bj = 0; bj < 2; ++bj) { float o[8];
;                     if (MODE == 0) { const f32x4 b0 = bf[MODE == 0 ? m : 0][bj][0], b1 = bf[MODE == 0 ? m : 0][bj][1];
; #pragma unroll
;                         for (int e = 0; e < 4; ++e) { o[e] = b0[e] + acc[ai][bj][m][0][e]; o[4 + e] = b1[e] + acc[ai][bj][m][1][e]; } }
;                     else { float t[8]; unpack8(bb[MODE == 1 ? m : 0][bj], t);
; #pragma unroll
;                         for (int e = 0; e < 4; ++e) { o[e] = t[e] + acc[ai][bj][m][0][e]; o[4 + e] = t[4 + e] + acc[ai][bj][m][1][e]; } }
; #pragma unroll
;                     for (int e = 0; e < 8; ++e) s += o[e] * o[e];
;                     *(u32x4*)(ob + (size_t)row * DM + col0 + bj * HALF) = (u32x4){cvt_pk_bf16(o[0], o[1]), cvt_pk_bf16(o[2], o[3]), cvt_pk_bf16(o[4], o[5]), cvt_pk_bf16(o[6], o[7])}; }
;                 s += __shfl_xor(s, 16); s += __shfl_xor(s, 32);
;                 if (fq == 0) ss[(size_t)row * 32 + u.pn * 4 + wc] = s; } }
.LBB0_790:
	v_lshl_add_u32 v200, s28, 8, v185
	v_add_u32_e32 v128, 0xffffc000, v200
	v_ashrrev_i32_e32 v201, 31, v200
	v_cmp_gt_i32_e32 vcc, s43, v200
	v_lshl_or_b32 v198, s0, 8, v211
	v_mov_b32_e32 v132, s67
	v_cndmask_b32_e32 v129, 0, v201, vcc
	v_cndmask_b32_e32 v128, v128, v200, vcc
	v_mov_b32_e32 v133, s65
	v_mov_b32_e32 v134, s66
	v_mov_b32_e32 v135, s64
	v_ashrrev_i32_e32 v199, 31, v198
	v_cndmask_b32_e32 v131, v132, v133, vcc
	v_cndmask_b32_e32 v130, v134, v135, vcc
	v_lshlrev_b64 v[128:129], 13, v[128:129]
	v_lshl_add_u64 v[128:129], v[130:131], 0, v[128:129]
	v_lshlrev_b64 v[202:203], 2, v[198:199]
	v_lshl_add_u64 v[128:129], v[128:129], 0, v[202:203]
	global_load_dwordx4 v[216:219], v[128:129], off nt
	global_load_dwordx4 v[224:227], v[128:129], off offset:16 nt
	global_load_dwordx4 v[228:231], v[128:129], off offset:512 nt
	global_load_dwordx4 v[232:235], v[128:129], off offset:528 nt
	v_or_b32_e32 v208, 16, v200
	v_ashrrev_i32_e32 v209, 31, v208
	v_add_u32_e32 v128, 0xffffc010, v200
	v_cmp_gt_i32_e32 vcc, s43, v208
	v_or_b32_e32 v206, 32, v200
	v_ashrrev_i32_e32 v207, 31, v206
	v_cndmask_b32_e32 v129, 0, v209, vcc
	v_cndmask_b32_e32 v128, v128, v208, vcc
	v_cndmask_b32_e32 v131, v132, v133, vcc
	v_cndmask_b32_e32 v130, v134, v135, vcc
	v_lshlrev_b64 v[128:129], 13, v[128:129]
	v_lshl_add_u64 v[128:129], v[130:131], 0, v[128:129]
	v_lshl_add_u64 v[128:129], v[128:129], 0, v[202:203]
	global_load_dwordx4 v[168:171], v[128:129], off offset:16 nt
	global_load_dwordx4 v[172:175], v[128:129], off nt
	global_load_dwordx4 v[160:163], v[128:129], off offset:528 nt
	global_load_dwordx4 v[164:167], v[128:129], off offset:512 nt
	v_add_u32_e32 v128, 0xffffc020, v200
	v_cmp_gt_i32_e32 vcc, s43, v206
	v_or_b32_e32 v204, 48, v200
	v_ashrrev_i32_e32 v205, 31, v204
	v_cndmask_b32_e32 v129, 0, v207, vcc
	v_cndmask_b32_e32 v128, v128, v206, vcc
	v_cndmask_b32_e32 v131, v132, v133, vcc
	v_cndmask_b32_e32 v130, v134, v135, vcc
	v_lshlrev_b64 v[128:129], 13, v[128:129]
	v_lshl_add_u64 v[128:129], v[130:131], 0, v[128:129]
	v_lshl_add_u64 v[128:129], v[128:129], 0, v[202:203]
	global_load_dwordx4 v[152:155], v[128:129], off offset:16 nt
	global_load_dwordx4 v[156:159], v[128:129], off nt
	global_load_dwordx4 v[144:147], v[128:129], off offset:528 nt
	global_load_dwordx4 v[148:151], v[128:129], off offset:512 nt
	v_add_u32_e32 v128, 0xffffc030, v200
	v_cmp_gt_i32_e32 vcc, s43, v204
	v_lshlrev_b64 v[220:221], 12, v[200:201]
	s_lshl_b32 s28, s0, 2
	v_cndmask_b32_e32 v129, 0, v205, vcc
	v_cndmask_b32_e32 v128, v128, v204, vcc
	v_cndmask_b32_e32 v131, v132, v133, vcc
	v_cndmask_b32_e32 v130, v134, v135, vcc
	v_lshlrev_b64 v[128:129], 13, v[128:129]
	v_lshl_add_u64 v[128:129], v[130:131], 0, v[128:129]
	v_lshl_add_u64 v[132:133], v[128:129], 0, v[202:203]
	global_load_dwordx4 v[136:139], v[132:133], off offset:16 nt
	global_load_dwordx4 v[140:143], v[132:133], off nt
	global_load_dwordx4 v[128:131], v[132:133], off offset:528 nt
	s_nop 0
	global_load_dwordx4 v[132:135], v[132:133], off offset:512 nt
	s_ashr_i32 s29, s28, 31
	s_waitcnt vmcnt(0)
	v_add_f32_e32 v216, v124, v216
	v_add_f32_e32 v124, v125, v217
	v_add_f32_e32 v217, v122, v226
	v_mul_f32_e32 v226, v124, v124
	v_add_f32_e32 v126, v126, v218
	v_fmac_f32_e32 v226, v216, v216
	v_add_f32_e32 v127, v127, v219
	v_fmac_f32_e32 v226, v126, v126
	v_add_f32_e32 v120, v120, v224
	v_fmac_f32_e32 v226, v127, v127
	v_add_f32_e32 v121, v121, v225
	v_fmac_f32_e32 v226, v120, v120
	v_fmac_f32_e32 v226, v121, v121
	v_add_f32_e32 v218, v123, v227
	v_fmac_f32_e32 v226, v217, v217
	v_add_f32_e32 v116, v116, v228
	v_fmac_f32_e32 v226, v218, v218
	v_add_f32_e32 v117, v117, v229
	v_fmac_f32_e32 v226, v116, v116
	v_add_f32_e32 v225, v118, v230
	v_fmac_f32_e32 v226, v117, v117
	v_cvt_pk_bf16_f32 v122, v216, v124
	v_cvt_pk_bf16_f32 v123, v126, v127
	v_add_f32_e32 v127, v119, v231
	v_fmac_f32_e32 v226, v225, v225
	v_add_f32_e32 v219, v112, v232
	v_add_f32_e32 v224, v113, v233
	v_fmac_f32_e32 v226, v127, v127
	v_and_b32_e32 v113, 64, v215
	v_add_f32_e32 v216, v115, v235
	v_fmac_f32_e32 v226, v219, v219
	v_xor_b32_e32 v112, 16, v215
	v_add_u32_e32 v115, 64, v113
	v_add_f32_e32 v126, v114, v234
	v_fmac_f32_e32 v226, v224, v224
	v_cmp_lt_i32_e32 vcc, v112, v115
	v_fmac_f32_e32 v226, v126, v126
	v_cvt_pk_bf16_f32 v124, v120, v121
	v_fmac_f32_e32 v226, v216, v216
	v_cndmask_b32_e32 v112, v215, v112, vcc
	v_lshlrev_b32_e32 v120, 2, v112
	ds_bpermute_b32 v121, v120, v226
	v_lshl_add_u64 v[112:113], s[12:13], 0, v[220:221]
	v_lshl_add_u64 v[118:119], v[198:199], 1, v[112:113]
	v_xor_b32_e32 v113, 32, v215
	v_cmp_lt_i32_e32 vcc, v113, v115
	s_waitcnt lgkmcnt(0)
	v_add_f32_e32 v112, v226, v121
	v_cvt_pk_bf16_f32 v125, v217, v218
	global_store_dwordx4 v[118:119], v[122:125], off
	v_cndmask_b32_e32 v113, v215, v113, vcc
	v_lshlrev_b32_e32 v121, 2, v113
	ds_bpermute_b32 v113, v121, v112
	v_cvt_pk_bf16_f32 v114, v116, v117
	v_cvt_pk_bf16_f32 v115, v225, v127
	v_cvt_pk_bf16_f32 v116, v219, v224
	v_cvt_pk_bf16_f32 v117, v126, v216
	global_store_dwordx4 v[118:119], v[114:117], off offset:256
	s_and_saveexec_b64 s[30:31], s[4:5]
	s_cbranch_execz .LBB0_792
	v_lshlrev_b64 v[114:115], 7, v[200:201]
	v_lshl_add_u64 v[114:115], s[16:17], 0, v[114:115]
	v_lshl_add_u64 v[114:115], s[28:29], 2, v[114:115]
	s_lshl_b32 s0, s44, 2
	v_lshl_add_u64 v[114:115], v[114:115], 0, s[0:1]
	s_waitcnt lgkmcnt(0)
	v_add_f32_e32 v112, v112, v113
	global_store_dword v[114:115], v112, off

; __device__ __forceinline__ unsigned cvt_pk_bf16(float lo, float hi) { unsigned r; asm volatile("v_cvt_pk_bf16_f32 %0, %1, %2" : "=v"(r) : "v"(lo), "v"(hi)); return r; }
;     __device__ __forceinline__ void operator()(const f32x4 (&acc)[2][2][4][2], const Unit& u, int wr, int wc, int fr, int fq) const {
;     ...
;         for (int ai = 0; ai < 2; ++ai) {
;             f32x4 bf[MODE == 0 ? 4 : 1][2][2]; u32x4 bb[MODE == 1 ? 4 : 1][2];
; #pragma unroll
;             for (int m = 0; m < 4; ++m) { const int row = row0 + ai * HALF + m * 16;
;                 if (MODE == 0) { const float* br = row < MP ? basep + (size_t)row * DM : bases + (size_t)(row - MP) * DM;
; #pragma unroll
;                     for (int bj = 0; bj < 2; ++bj) { bf[MODE == 0 ? m : 0][bj][0] = *(const f32x4*)(br + col0 + bj * HALF); bf[MODE == 0 ? m : 0][bj][1] = *(const f32x4*)(br + col0 + bj * HALF + 4); } }
;                 else {
; #pragma unroll
;                     for (int bj = 0; bj < 2; ++bj) bb[MODE == 1 ? m : 0][bj] = *(const u32x4*)(baseb + (size_t)row * DM + col0 + bj * HALF); } }
; #pragma unroll
;             for (int m = 0; m < 4; ++m) { const int row = row0 + ai * HALF + m * 16; float s = 0.f;
; #pragma unroll
;                 for (int bj = 0; bj < 2; ++bj) { float o[8];
;                     if (MODE == 0) { const f32x4 b0 = bf[MODE == 0 ? m : 0][bj][0], b1 = bf[MODE == 0 ? m : 0][bj][1];
; #pragma unroll
;                         for (int e = 0; e < 4; ++e) { o[e] = b0[e] + acc[ai][bj][m][0][e]; o[4 + e] = b1[e] + acc[ai][bj][m][1][e]; } }
;                     else { float t[8]; unpack8(bb[MODE == 1 ? m : 0][bj], t);
; #pragma unroll
;                         for (int e = 0; e < 4; ++e) { o[e] = t[e] + acc[ai][bj][m][0][e]; o[4 + e] = t[4 + e] + acc[ai][bj][m][1][e]; } }
; #pragma unroll
;                     for (int e = 0; e < 8; ++e) s += o[e] * o[e];
;                     *(u32x4*)(ob + (size_t)row * DM + col0 + bj * HALF) = (u32x4){cvt_pk_bf16(o[0], o[1]), cvt_pk_bf16(o[2], o[3]), cvt_pk_bf16(o[4], o[5]), cvt_pk_bf16(o[6], o[7])}; }
;                 s += __shfl_xor(s, 16); s += __shfl_xor(s, 32);
;                 if (fq == 0) ss[(size_t)row * 32 + u.pn * 4 + wc] = s; } }
.LBB0_798:
	s_or_b64 exec, exec, s[30:31]
	v_add_u32_e32 v118, 0x80, v200
	v_ashrrev_i32_e32 v119, 31, v118
	v_add_u32_e32 v64, 0xffffc080, v200
	v_cmp_gt_i32_e32 vcc, s52, v200
	v_mov_b32_e32 v68, s67
	v_mov_b32_e32 v69, s65
	s_waitcnt lgkmcnt(0)
	v_cndmask_b32_e32 v65, 0, v119, vcc
	v_cndmask_b32_e32 v64, v64, v118, vcc
	v_mov_b32_e32 v70, s66
	v_mov_b32_e32 v71, s64
	v_cndmask_b32_e32 v67, v68, v69, vcc
	v_cndmask_b32_e32 v66, v70, v71, vcc
	v_lshlrev_b64 v[64:65], 13, v[64:65]
	v_lshl_add_u64 v[64:65], v[66:67], 0, v[64:65]
	v_lshl_add_u64 v[64:65], v[64:65], 0, v[202:203]
	global_load_dwordx4 v[122:125], v[64:65], off offset:16 nt
	global_load_dwordx4 v[126:129], v[64:65], off nt
	global_load_dwordx4 v[130:133], v[64:65], off offset:528 nt
	global_load_dwordx4 v[134:137], v[64:65], off offset:512 nt
	v_add_u32_e32 v116, 0x90, v200
	v_ashrrev_i32_e32 v117, 31, v116
	v_add_u32_e32 v64, 0xffffc090, v200
	v_cmp_gt_i32_e32 vcc, s53, v200
	v_add_u32_e32 v114, 0xa0, v200
	v_ashrrev_i32_e32 v115, 31, v114
	v_cndmask_b32_e32 v65, 0, v117, vcc
	v_cndmask_b32_e32 v64, v64, v116, vcc
	v_cndmask_b32_e32 v67, v68, v69, vcc
	v_cndmask_b32_e32 v66, v70, v71, vcc
	v_lshlrev_b64 v[64:65], 13, v[64:65]
	v_lshl_add_u64 v[64:65], v[66:67], 0, v[64:65]
	v_lshl_add_u64 v[64:65], v[64:65], 0, v[202:203]
	global_load_dwordx4 v[104:107], v[64:65], off offset:16 nt
	global_load_dwordx4 v[108:111], v[64:65], off nt
	global_load_dwordx4 v[96:99], v[64:65], off offset:528 nt
	global_load_dwordx4 v[100:103], v[64:65], off offset:512 nt
	v_add_u32_e32 v64, 0xffffc0a0, v200
	v_cmp_gt_i32_e32 vcc, s54, v200
	v_add_u32_e32 v112, 0xb0, v200
	v_ashrrev_i32_e32 v113, 31, v112
	v_cndmask_b32_e32 v65, 0, v115, vcc
	v_cndmask_b32_e32 v64, v64, v114, vcc
	v_cndmask_b32_e32 v67, v68, v69, vcc
	v_cndmask_b32_e32 v66, v70, v71, vcc
	v_lshlrev_b64 v[64:65], 13, v[64:65]
	v_lshl_add_u64 v[64:65], v[66:67], 0, v[64:65]
	v_lshl_add_u64 v[64:65], v[64:65], 0, v[202:203]
	global_load_dwordx4 v[88:91], v[64:65], off offset:16 nt
	global_load_dwordx4 v[92:95], v[64:65], off nt
	global_load_dwordx4 v[80:83], v[64:65], off offset:528 nt
	global_load_dwordx4 v[84:87], v[64:65], off offset:512 nt
	v_add_u32_e32 v64, 0xffffc0b0, v200
	v_cmp_gt_i32_e32 vcc, s55, v200
	v_lshlrev_b64 v[138:139], 12, v[118:119]
	s_waitcnt vmcnt(11)
	v_add_f32_e32 v56, v56, v122
	v_cndmask_b32_e32 v65, 0, v113, vcc
	v_cndmask_b32_e32 v64, v64, v112, vcc
	v_cndmask_b32_e32 v67, v68, v69, vcc
	v_cndmask_b32_e32 v66, v70, v71, vcc
	v_lshlrev_b64 v[64:65], 13, v[64:65]
	v_lshl_add_u64 v[64:65], v[66:67], 0, v[64:65]
	v_lshl_add_u64 v[68:69], v[64:65], 0, v[202:203]
	global_load_dwordx4 v[72:75], v[68:69], off offset:16 nt
	global_load_dwordx4 v[76:79], v[68:69], off nt
	global_load_dwordx4 v[64:67], v[68:69], off offset:528 nt
	s_nop 0
	global_load_dwordx4 v[68:71], v[68:69], off offset:512 nt
	s_waitcnt vmcnt(14)
	v_add_f32_e32 v61, v61, v127
	v_add_f32_e32 v60, v60, v126
	v_add_f32_e32 v63, v63, v129
	v_mul_f32_e32 v129, v61, v61
	v_add_f32_e32 v62, v62, v128
	v_fmac_f32_e32 v129, v60, v60
	v_fmac_f32_e32 v129, v62, v62
	v_fmac_f32_e32 v129, v63, v63
	v_add_f32_e32 v57, v57, v123
	v_fmac_f32_e32 v129, v56, v56
	v_add_f32_e32 v58, v58, v124
	v_fmac_f32_e32 v129, v57, v57
	v_add_f32_e32 v59, v59, v125
	v_fmac_f32_e32 v129, v58, v58
	s_waitcnt vmcnt(12)
	v_add_f32_e32 v122, v52, v134
	v_fmac_f32_e32 v129, v59, v59
	v_add_f32_e32 v124, v53, v135
	v_fmac_f32_e32 v129, v122, v122
	v_add_f32_e32 v126, v54, v136
	v_fmac_f32_e32 v129, v124, v124
	v_add_f32_e32 v128, v55, v137
	v_fmac_f32_e32 v129, v126, v126
	v_add_f32_e32 v123, v48, v130
	v_fmac_f32_e32 v129, v128, v128
	v_add_f32_e32 v125, v49, v131
	v_fmac_f32_e32 v129, v123, v123
	v_add_f32_e32 v127, v50, v132
	v_fmac_f32_e32 v129, v125, v125
	v_cvt_pk_bf16_f32 v52, v60, v61
	v_cvt_pk_bf16_f32 v53, v62, v63
	v_cvt_pk_bf16_f32 v54, v56, v57
	v_cvt_pk_bf16_f32 v55, v58, v59
	v_add_f32_e32 v58, v51, v133
	v_fmac_f32_e32 v129, v127, v127
	v_fmac_f32_e32 v129, v58, v58
	ds_bpermute_b32 v51, v120, v129
	v_lshl_add_u64 v[48:49], s[12:13], 0, v[138:139]
	v_lshl_add_u64 v[56:57], v[198:199], 1, v[48:49]
	global_store_dwordx4 v[56:57], v[52:55], off
	v_cvt_pk_bf16_f32 v50, v122, v124
	s_waitcnt lgkmcnt(0)
	v_add_f32_e32 v48, v129, v51
	ds_bpermute_b32 v49, v121, v48
	v_cvt_pk_bf16_f32 v51, v126, v128
	v_cvt_pk_bf16_f32 v52, v123, v125
	v_cvt_pk_bf16_f32 v53, v127, v58
	global_store_dwordx4 v[56:57], v[50:53], off offset:256
	s_and_saveexec_b64 s[30:31], s[4:5]
	s_cbranch_execz .LBB0_800
	v_lshlrev_b64 v[50:51], 7, v[118:119]
	v_lshl_add_u64 v[50:51], s[16:17], 0, v[50:51]
	v_lshl_add_u64 v[50:51], s[28:29], 2, v[50:51]
	s_lshl_b32 s0, s44, 2
	v_lshl_add_u64 v[50:51], v[50:51], 0, s[0:1]
	s_waitcnt lgkmcnt(0)
	v_add_f32_e32 v48, v48, v49
	global_store_dword v[50:51], v48, off

; __device__ __forceinline__ unsigned cvt_pk_bf16(float lo, float hi) { unsigned r; asm volatile("v_cvt_pk_bf16_f32 %0, %1, %2" : "=v"(r) : "v"(lo), "v"(hi)); return r; }
;     __device__ __forceinline__ void operator()(const f32x4 (&acc)[2][2][4][2], const Unit& u, int wr, int wc, int fr, int fq) const {
;     ...
;         for (int ai = 0; ai < 2; ++ai) {
;             f32x4 bf[MODE == 0 ? 4 : 1][2][2]; u32x4 bb[MODE == 1 ? 4 : 1][2];
; #pragma unroll
;             for (int m = 0; m < 4; ++m) { const int row = row0 + ai * HALF + m * 16;
;                 if (MODE == 0) { const float* br = row < MP ? basep + (size_t)row * DM : bases + (size_t)(row - MP) * DM;
; #pragma unroll
;                     for (int bj = 0; bj < 2; ++bj) { bf[MODE == 0 ? m : 0][bj][0] = *(const f32x4*)(br + col0 + bj * HALF); bf[MODE == 0 ? m : 0][bj][1] = *(const f32x4*)(br + col0 + bj * HALF + 4); } }
;                 else {
; #pragma unroll
;                     for (int bj = 0; bj < 2; ++bj) bb[MODE == 1 ? m : 0][bj] = *(const u32x4*)(baseb + (size_t)row * DM + col0 + bj * HALF); } }
; #pragma unroll
;             for (int m = 0; m < 4; ++m) { const int row = row0 + ai * HALF + m * 16; float s = 0.f;
; #pragma unroll
;                 for (int bj = 0; bj < 2; ++bj) { float o[8];
;                     if (MODE == 0) { const f32x4 b0 = bf[MODE == 0 ? m : 0][bj][0], b1 = bf[MODE == 0 ? m : 0][bj][1];
; #pragma unroll
;                         for (int e = 0; e < 4; ++e) { o[e] = b0[e] + acc[ai][bj][m][0][e]; o[4 + e] = b1[e] + acc[ai][bj][m][1][e]; } }
;                     else { float t[8]; unpack8(bb[MODE == 1 ? m : 0][bj], t);
; #pragma unroll
;                         for (int e = 0; e < 4; ++e) { o[e] = t[e] + acc[ai][bj][m][0][e]; o[4 + e] = t[4 + e] + acc[ai][bj][m][1][e]; } }
; #pragma unroll
;                     for (int e = 0; e < 8; ++e) s += o[e] * o[e];
;                     *(u32x4*)(ob + (size_t)row * DM + col0 + bj * HALF) = (u32x4){cvt_pk_bf16(o[0], o[1]), cvt_pk_bf16(o[2], o[3]), cvt_pk_bf16(o[4], o[5]), cvt_pk_bf16(o[6], o[7])}; }
;                 s += __shfl_xor(s, 16); s += __shfl_xor(s, 32);
;                 if (fq == 0) ss[(size_t)row * 32 + u.pn * 4 + wc] = s; } }
.LBB0_1031:
	v_lshl_or_b32 v168, s8, 8, v190
	v_lshl_add_u32 v172, s28, 8, v185
	v_ashrrev_i32_e32 v169, 31, v168
	v_lshlrev_b64 v[204:205], 1, v[168:169]
	v_ashrrev_i32_e32 v173, 31, v172
	v_lshl_add_u64 v[170:171], s[12:13], 0, v[204:205]
	v_lshlrev_b64 v[206:207], 12, v[172:173]
	v_lshl_add_u64 v[128:129], v[170:171], 0, v[206:207]
	global_load_dwordx4 v[196:199], v[128:129], off nt
	global_load_dwordx4 v[200:203], v[128:129], off offset:256 nt
	v_or_b32_e32 v182, 16, v172
	v_or_b32_e32 v178, 32, v172
	v_or_b32_e32 v174, 48, v172
	v_ashrrev_i32_e32 v183, 31, v182
	v_ashrrev_i32_e32 v179, 31, v178
	v_ashrrev_i32_e32 v175, 31, v174
	v_lshlrev_b64 v[188:189], 12, v[182:183]
	v_lshlrev_b64 v[180:181], 12, v[178:179]
	v_lshlrev_b64 v[176:177], 12, v[174:175]
	v_lshl_add_u64 v[128:129], v[170:171], 0, v[188:189]
	v_lshl_add_u64 v[130:131], v[170:171], 0, v[180:181]
	v_lshl_add_u64 v[208:209], v[170:171], 0, v[176:177]
	global_load_dwordx4 v[148:151], v[128:129], off nt
	global_load_dwordx4 v[144:147], v[128:129], off offset:256 nt
	global_load_dwordx4 v[140:143], v[130:131], off nt
	global_load_dwordx4 v[136:139], v[130:131], off offset:256 nt
	global_load_dwordx4 v[132:135], v[208:209], off nt
	s_nop 0
	global_load_dwordx4 v[128:131], v[208:209], off offset:256 nt
	v_lshl_add_u64 v[206:207], s[76:77], 0, v[206:207]
	v_and_b32_e32 v208, 64, v194
	v_lshl_add_u64 v[204:205], v[206:207], 0, v[204:205]
	v_xor_b32_e32 v195, 16, v194
	v_add_u32_e32 v208, 64, v208
	v_xor_b32_e32 v209, 32, v194
	v_cmp_lt_i32_e32 vcc, v195, v208
	s_lshl_b32 s28, s8, 2
	s_ashr_i32 s29, s28, 31
	v_cndmask_b32_e32 v195, v194, v195, vcc
	v_cmp_lt_i32_e32 vcc, v209, v208
	v_lshlrev_b32_e32 v195, 2, v195
	s_waitcnt vmcnt(0)
	v_lshlrev_b32_e32 v206, 16, v196
	v_and_b32_e32 v196, 0xffff0000, v196
	v_lshlrev_b32_e32 v211, 16, v200
	v_and_b32_e32 v200, 0xffff0000, v200
	v_add_f32_e32 v125, v125, v196
	v_lshlrev_b32_e32 v207, 16, v197
	v_add_f32_e32 v124, v124, v206
	v_add_f32_e32 v117, v117, v200
	v_mul_f32_e32 v200, v125, v125
	v_and_b32_e32 v197, 0xffff0000, v197
	v_add_f32_e32 v126, v126, v207
	v_fmac_f32_e32 v200, v124, v124
	v_cndmask_b32_e32 v208, v194, v209, vcc
	v_lshlrev_b32_e32 v209, 16, v198
	v_add_f32_e32 v127, v127, v197
	v_fmac_f32_e32 v200, v126, v126
	v_and_b32_e32 v198, 0xffff0000, v198
	v_add_f32_e32 v120, v120, v209
	v_fmac_f32_e32 v200, v127, v127
	v_lshlrev_b32_e32 v210, 16, v199
	v_add_f32_e32 v121, v121, v198
	v_fmac_f32_e32 v200, v120, v120
	v_and_b32_e32 v199, 0xffff0000, v199
	v_add_f32_e32 v122, v122, v210
	v_fmac_f32_e32 v200, v121, v121
	v_add_f32_e32 v123, v123, v199
	v_fmac_f32_e32 v200, v122, v122
	v_add_f32_e32 v116, v116, v211
	v_fmac_f32_e32 v200, v123, v123
	v_lshlrev_b32_e32 v212, 16, v201
	v_fmac_f32_e32 v200, v116, v116
	v_and_b32_e32 v201, 0xffff0000, v201
	v_add_f32_e32 v118, v118, v212
	v_fmac_f32_e32 v200, v117, v117
	v_lshlrev_b32_e32 v213, 16, v202
	v_add_f32_e32 v119, v119, v201
	v_fmac_f32_e32 v200, v118, v118
	v_and_b32_e32 v202, 0xffff0000, v202
	v_add_f32_e32 v196, v112, v213
	v_fmac_f32_e32 v200, v119, v119
	v_lshlrev_b32_e32 v214, 16, v203
	v_add_f32_e32 v197, v113, v202
	v_fmac_f32_e32 v200, v196, v196
	v_and_b32_e32 v203, 0xffff0000, v203
	v_add_f32_e32 v198, v114, v214
	v_fmac_f32_e32 v200, v197, v197
	v_add_f32_e32 v199, v115, v203
	v_fmac_f32_e32 v200, v198, v198
	v_fmac_f32_e32 v200, v199, v199
	v_cvt_pk_bf16_f32 v112, v124, v125
	ds_bpermute_b32 v124, v195, v200
	v_cvt_pk_bf16_f32 v113, v126, v127
	v_cvt_pk_bf16_f32 v114, v120, v121
	v_cvt_pk_bf16_f32 v115, v122, v123
	global_store_dwordx4 v[204:205], v[112:115], off
	v_cvt_pk_bf16_f32 v116, v116, v117
	v_cvt_pk_bf16_f32 v117, v118, v119
	v_cvt_pk_bf16_f32 v118, v196, v197
	v_cvt_pk_bf16_f32 v119, v198, v199
	global_store_dwordx4 v[204:205], v[116:119], off offset:256
	s_waitcnt lgkmcnt(0)
	v_add_f32_e32 v113, v200, v124
	v_lshlrev_b32_e32 v112, 2, v208
	ds_bpermute_b32 v114, v112, v113
	s_and_saveexec_b64 s[30:31], s[4:5]
	s_cbranch_execz .LBB0_1033
	v_lshlrev_b64 v[116:117], 7, v[172:173]
	v_lshl_add_u64 v[116:117], s[14:15], 0, v[116:117]
	v_lshl_add_u64 v[116:117], s[28:29], 2, v[116:117]
	s_lshl_b32 s8, s43, 2
	v_lshl_add_u64 v[116:117], v[116:117], 0, s[8:9]
	s_waitcnt lgkmcnt(0)
	v_add_f32_e32 v113, v113, v114
	global_store_dword v[116:117], v113, off

; __device__ __forceinline__ unsigned cvt_pk_bf16(float lo, float hi) { unsigned r; asm volatile("v_cvt_pk_bf16_f32 %0, %1, %2" : "=v"(r) : "v"(lo), "v"(hi)); return r; }
;     __device__ __forceinline__ void operator()(const f32x4 (&acc)[2][2][4][2], const Unit& u, int wr, int wc, int fr, int fq) const {
;     ...
;         for (int ai = 0; ai < 2; ++ai) {
;             f32x4 bf[MODE == 0 ? 4 : 1][2][2]; u32x4 bb[MODE == 1 ? 4 : 1][2];
; #pragma unroll
;             for (int m = 0; m < 4; ++m) { const int row = row0 + ai * HALF + m * 16;
;                 if (MODE == 0) { const float* br = row < MP ? basep + (size_t)row * DM : bases + (size_t)(row - MP) * DM;
; #pragma unroll
;                     for (int bj = 0; bj < 2; ++bj) { bf[MODE == 0 ? m : 0][bj][0] = *(const f32x4*)(br + col0 + bj * HALF); bf[MODE == 0 ? m : 0][bj][1] = *(const f32x4*)(br + col0 + bj * HALF + 4); } }
;                 else {
; #pragma unroll
;                     for (int bj = 0; bj < 2; ++bj) bb[MODE == 1 ? m : 0][bj] = *(const u32x4*)(baseb + (size_t)row * DM + col0 + bj * HALF); } }
; #pragma unroll
;             for (int m = 0; m < 4; ++m) { const int row = row0 + ai * HALF + m * 16; float s = 0.f;
; #pragma unroll
;                 for (int bj = 0; bj < 2; ++bj) { float o[8];
;                     if (MODE == 0) { const f32x4 b0 = bf[MODE == 0 ? m : 0][bj][0], b1 = bf[MODE == 0 ? m : 0][bj][1];
; #pragma unroll
;                         for (int e = 0; e < 4; ++e) { o[e] = b0[e] + acc[ai][bj][m][0][e]; o[4 + e] = b1[e] + acc[ai][bj][m][1][e]; } }
;                     else { float t[8]; unpack8(bb[MODE == 1 ? m : 0][bj], t);
; #pragma unroll
;                         for (int e = 0; e < 4; ++e) { o[e] = t[e] + acc[ai][bj][m][0][e]; o[4 + e] = t[4 + e] + acc[ai][bj][m][1][e]; } }
; #pragma unroll
;                     for (int e = 0; e < 8; ++e) s += o[e] * o[e];
;                     *(u32x4*)(ob + (size_t)row * DM + col0 + bj * HALF) = (u32x4){cvt_pk_bf16(o[0], o[1]), cvt_pk_bf16(o[2], o[3]), cvt_pk_bf16(o[4], o[5]), cvt_pk_bf16(o[6], o[7])}; }
;                 s += __shfl_xor(s, 16); s += __shfl_xor(s, 32);
;                 if (fq == 0) ss[(size_t)row * 32 + u.pn * 4 + wc] = s; } }
.LBB0_1039:
	s_or_b64 exec, exec, s[30:31]
	v_add_u32_e32 v100, 0x80, v172
	v_ashrrev_i32_e32 v101, 31, v100
	v_lshlrev_b64 v[110:111], 12, v[100:101]
	s_waitcnt lgkmcnt(0)
	v_lshl_add_u64 v[64:65], v[170:171], 0, v[110:111]
	global_load_dwordx4 v[102:105], v[64:65], off nt
	global_load_dwordx4 v[106:109], v[64:65], off offset:256 nt
	v_add_u32_e32 v96, 0x90, v172
	v_add_u32_e32 v92, 0xa0, v172
	v_add_u32_e32 v88, 0xb0, v172
	v_ashrrev_i32_e32 v97, 31, v96
	v_ashrrev_i32_e32 v93, 31, v92
	v_ashrrev_i32_e32 v89, 31, v88
	v_lshlrev_b64 v[98:99], 12, v[96:97]
	v_lshlrev_b64 v[94:95], 12, v[92:93]
	v_lshlrev_b64 v[90:91], 12, v[88:89]
	v_lshl_add_u64 v[64:65], v[170:171], 0, v[98:99]
	v_lshl_add_u64 v[66:67], v[170:171], 0, v[94:95]
	v_lshl_add_u64 v[114:115], v[170:171], 0, v[90:91]
	global_load_dwordx4 v[84:87], v[64:65], off nt
	global_load_dwordx4 v[80:83], v[64:65], off offset:256 nt
	global_load_dwordx4 v[76:79], v[66:67], off nt
	global_load_dwordx4 v[72:75], v[66:67], off offset:256 nt
	global_load_dwordx4 v[68:71], v[114:115], off nt
	s_nop 0
	global_load_dwordx4 v[64:67], v[114:115], off offset:256 nt
	s_waitcnt vmcnt(7)
	v_lshlrev_b32_e32 v113, 16, v102
	v_and_b32_e32 v102, 0xffff0000, v102
	v_add_f32_e32 v61, v61, v102
	v_lshlrev_b32_e32 v114, 16, v103
	v_add_f32_e32 v60, v60, v113
	v_mul_f32_e32 v113, v61, v61
	v_and_b32_e32 v103, 0xffff0000, v103
	v_add_f32_e32 v62, v62, v114
	v_fmac_f32_e32 v113, v60, v60
	v_lshlrev_b32_e32 v115, 16, v104
	v_add_f32_e32 v63, v63, v103
	v_fmac_f32_e32 v113, v62, v62
	v_and_b32_e32 v104, 0xffff0000, v104
	v_add_f32_e32 v56, v56, v115
	v_fmac_f32_e32 v113, v63, v63
	v_lshlrev_b32_e32 v116, 16, v105
	v_add_f32_e32 v57, v57, v104
	v_fmac_f32_e32 v113, v56, v56
	v_and_b32_e32 v105, 0xffff0000, v105
	v_add_f32_e32 v58, v58, v116
	v_fmac_f32_e32 v113, v57, v57
	s_waitcnt vmcnt(6)
	v_lshlrev_b32_e32 v117, 16, v106
	v_add_f32_e32 v59, v59, v105
	v_fmac_f32_e32 v113, v58, v58
	v_and_b32_e32 v106, 0xffff0000, v106
	v_add_f32_e32 v102, v52, v117
	v_fmac_f32_e32 v113, v59, v59
	v_lshlrev_b32_e32 v118, 16, v107
	v_add_f32_e32 v104, v53, v106
	v_fmac_f32_e32 v113, v102, v102
	v_and_b32_e32 v107, 0xffff0000, v107
	v_add_f32_e32 v106, v54, v118
	v_fmac_f32_e32 v113, v104, v104
	v_lshlrev_b32_e32 v119, 16, v108
	v_add_f32_e32 v107, v55, v107
	v_fmac_f32_e32 v113, v106, v106
	v_and_b32_e32 v108, 0xffff0000, v108
	v_add_f32_e32 v103, v48, v119
	v_fmac_f32_e32 v113, v107, v107
	v_lshlrev_b32_e32 v120, 16, v109
	v_add_f32_e32 v105, v49, v108
	v_fmac_f32_e32 v113, v103, v103
	v_and_b32_e32 v109, 0xffff0000, v109
	v_add_f32_e32 v108, v50, v120
	v_fmac_f32_e32 v113, v105, v105
	v_cvt_pk_bf16_f32 v52, v60, v61
	v_cvt_pk_bf16_f32 v53, v62, v63
	v_cvt_pk_bf16_f32 v54, v56, v57
	v_cvt_pk_bf16_f32 v55, v58, v59
	v_add_f32_e32 v58, v51, v109
	v_fmac_f32_e32 v113, v108, v108
	v_fmac_f32_e32 v113, v58, v58
	ds_bpermute_b32 v51, v195, v113
	v_lshl_add_u64 v[48:49], s[76:77], 0, v[110:111]
	v_lshl_add_u64 v[56:57], v[168:169], 1, v[48:49]
	global_store_dwordx4 v[56:57], v[52:55], off
	v_cvt_pk_bf16_f32 v50, v102, v104
	s_waitcnt lgkmcnt(0)
	v_add_f32_e32 v48, v113, v51
	ds_bpermute_b32 v49, v112, v48
	v_cvt_pk_bf16_f32 v51, v106, v107
	v_cvt_pk_bf16_f32 v52, v103, v105
	v_cvt_pk_bf16_f32 v53, v108, v58
	global_store_dwordx4 v[56:57], v[50:53], off offset:256
	s_and_saveexec_b64 s[30:31], s[4:5]
	s_cbranch_execz .LBB0_1041
	v_lshlrev_b64 v[50:51], 7, v[100:101]
	v_lshl_add_u64 v[50:51], s[14:15], 0, v[50:51]
	v_lshl_add_u64 v[50:51], s[28:29], 2, v[50:51]
	s_lshl_b32 s8, s43, 2
	v_lshl_add_u64 v[50:51], v[50:51], 0, s[8:9]
	s_waitcnt lgkmcnt(0)
	v_add_f32_e32 v48, v48, v49
	global_store_dword v[50:51], v48, off

; __device__ __forceinline__ void unpack8(const u32x4& w, float (&f)[8]) { f[0] = bflo(w.x); f[1] = bfhi(w.x); f[2] = bflo(w.y); f[3] = bfhi(w.y); f[4] = bflo(w.z); f[5] = bfhi(w.z); f[6] = bflo(w.w); f[7] = bfhi(w.w); }
; __global__ void __launch_bounds__(512, 2) hybrid_fwd(Args a) {
;     ...
;         for (int m = gw; m < M; m += NGW) { const float sf_ = wave_sum(lane < 32 ? SSF[(size_t)m * 32 + lane] : 0.f); const float rs = rsqrtf(sf_ * (1.0f / DM) + EPS);
;             const u32x4* xb = (const u32x4*)(Y + (size_t)m * DM); f32x4* yr = (f32x4*)(a.out + (size_t)m * DM); u32x4 xw[4];
; #pragma unroll
;             for (int j = 0; j < 4; ++j) xw[j] = xb[lane + 64 * j];
; #pragma unroll
;             for (int j = 0; j < 4; ++j) { float f[8]; pg8::unpack8(xw[j], f); const int c = (lane + 64 * j) * 8; const f32x4 w0 = *(const f32x4*)(a.fnorm + c), w1 = *(const f32x4*)(a.fnorm + c + 4);
;                 yr[(lane + 64 * j) * 2] = (f32x4){f[0] * rs * w0[0], f[1] * rs * w0[1], f[2] * rs * w0[2], f[3] * rs * w0[3]}; yr[(lane + 64 * j) * 2 + 1] = (f32x4){f[4] * rs * w1[0], f[5] * rs * w1[1], f[6] * rs * w1[2], f[7] * rs * w1[3]}; } }
.LBB0_1107:
	s_or_b64 exec, exec, s[0:1]
	v_lshl_add_u64 v[22:23], s[86:87], 0, v[8:9]
	v_add_co_u32_e64 v46, s[0:1], s11, v22
	s_waitcnt vmcnt(0)
	ds_bpermute_b32 v34, v14, v21
	v_addc_co_u32_e64 v47, s[0:1], 0, v23, s[0:1]
	global_load_dwordx4 v[22:25], v[46:47], off nt
	global_load_dwordx4 v[26:29], v[0:1], off nt
	global_load_dwordx4 v[30:33], v[0:1], off offset:16 nt
	v_add_u32_e32 v184, s88, v184
	s_waitcnt lgkmcnt(0)
	v_add_f32_e32 v21, v21, v34
	ds_bpermute_b32 v34, v15, v21
	v_lshl_add_u64 v[8:9], v[8:9], 0, s[2:3]
	v_lshl_add_u64 v[12:13], v[12:13], 0, s[6:7]
	s_waitcnt lgkmcnt(0)
	v_add_f32_e32 v21, v21, v34
	ds_bpermute_b32 v34, v16, v21
	s_waitcnt lgkmcnt(0)
	v_add_f32_e32 v21, v21, v34
	ds_bpermute_b32 v34, v17, v21
	s_waitcnt lgkmcnt(0)
	v_add_f32_e32 v21, v21, v34
	ds_bpermute_b32 v34, v18, v21
	s_waitcnt lgkmcnt(0)
	v_add_f32_e32 v21, v21, v34
	ds_bpermute_b32 v34, v19, v21
	s_waitcnt lgkmcnt(0)
	v_add_f32_e32 v21, v21, v34
	v_fmamk_f32 v21, v21, 0x3a000000, v20
	v_mul_f32_e32 v34, 0x4b800000, v21
	v_cmp_gt_f32_e64 s[0:1], s10, v21
	s_waitcnt vmcnt(2)
	v_lshlrev_b32_e32 v48, 16, v22
	v_cndmask_b32_e64 v21, v21, v34, s[0:1]
	v_rsq_f32_e32 v21, v21
	global_load_dwordx4 v[34:37], v[46:47], off offset:1024 nt
	global_load_dwordx4 v[38:41], v[46:47], off offset:2048 nt
	global_load_dwordx4 v[42:45], v[46:47], off offset:3072 nt
	v_and_b32_e32 v49, 0xffff0000, v22
	v_lshlrev_b32_e32 v22, 16, v23
	v_mul_f32_e32 v46, 0x45800000, v21
	v_cndmask_b32_e64 v46, v21, v46, s[0:1]
	v_and_b32_e32 v23, 0xffff0000, v23
	v_lshlrev_b32_e32 v50, 16, v24
	v_and_b32_e32 v51, 0xffff0000, v24
	v_lshlrev_b32_e32 v24, 16, v25
	v_and_b32_e32 v25, 0xffff0000, v25
	v_pk_mul_f32 v[48:49], v[46:47], v[48:49] op_sel_hi:[0,1]
	v_pk_mul_f32 v[52:53], v[46:47], v[22:23] op_sel_hi:[0,1]
	v_pk_mul_f32 v[50:51], v[46:47], v[50:51] op_sel_hi:[0,1]
	v_pk_mul_f32 v[54:55], v[46:47], v[24:25] op_sel_hi:[0,1]
	s_waitcnt vmcnt(4)
	v_pk_mul_f32 v[22:23], v[26:27], v[48:49]
	v_pk_mul_f32 v[24:25], v[28:29], v[52:53]
	s_waitcnt vmcnt(3)
	v_pk_mul_f32 v[26:27], v[30:31], v[50:51]
	v_pk_mul_f32 v[28:29], v[32:33], v[54:55]
	global_store_dwordx4 v[10:11], v[22:25], off offset:-4096 nt
	global_store_dwordx4 v[10:11], v[26:29], off offset:-4080 nt
	global_load_dwordx4 v[22:25], v[2:3], off nt
	s_nop 0
	global_load_dwordx4 v[26:29], v[2:3], off offset:16 nt
	v_cmp_lt_i32_e64 s[0:1], s12, v184
	s_or_b64 s[8:9], s[0:1], s[8:9]
	s_waitcnt vmcnt(6)
	v_lshlrev_b32_e32 v30, 16, v34
	v_and_b32_e32 v31, 0xffff0000, v34
	v_lshlrev_b32_e32 v32, 16, v35
	v_and_b32_e32 v33, 0xffff0000, v35
	v_lshlrev_b32_e32 v34, 16, v36
	v_and_b32_e32 v35, 0xffff0000, v36
	v_lshlrev_b32_e32 v36, 16, v37
	v_and_b32_e32 v37, 0xffff0000, v37
	v_pk_mul_f32 v[30:31], v[46:47], v[30:31] op_sel_hi:[0,1]
	v_pk_mul_f32 v[32:33], v[46:47], v[32:33] op_sel_hi:[0,1]
	v_pk_mul_f32 v[34:35], v[46:47], v[34:35] op_sel_hi:[0,1]
	v_pk_mul_f32 v[36:37], v[46:47], v[36:37] op_sel_hi:[0,1]
	s_waitcnt vmcnt(1)
	v_pk_mul_f32 v[22:23], v[22:23], v[30:31]
	v_pk_mul_f32 v[24:25], v[24:25], v[32:33]
	s_waitcnt vmcnt(0)
	v_pk_mul_f32 v[26:27], v[26:27], v[34:35]
	v_pk_mul_f32 v[28:29], v[28:29], v[36:37]
	global_store_dwordx4 v[10:11], v[22:25], off offset:-2048 nt
	global_store_dwordx4 v[10:11], v[26:29], off offset:-2032 nt
	global_load_dwordx4 v[22:25], v[4:5], off nt
	s_nop 0
	global_load_dwordx4 v[26:29], v[4:5], off offset:16 nt
	v_lshlrev_b32_e32 v30, 16, v38
	v_and_b32_e32 v31, 0xffff0000, v38
	v_lshlrev_b32_e32 v32, 16, v39
	v_and_b32_e32 v33, 0xffff0000, v39
	v_lshlrev_b32_e32 v34, 16, v40
	v_and_b32_e32 v35, 0xffff0000, v40
	v_lshlrev_b32_e32 v36, 16, v41
	v_and_b32_e32 v37, 0xffff0000, v41
	v_pk_mul_f32 v[30:31], v[46:47], v[30:31] op_sel_hi:[0,1]
	v_pk_mul_f32 v[32:33], v[46:47], v[32:33] op_sel_hi:[0,1]
	v_pk_mul_f32 v[34:35], v[46:47], v[34:35] op_sel_hi:[0,1]
	v_pk_mul_f32 v[36:37], v[46:47], v[36:37] op_sel_hi:[0,1]
	s_waitcnt vmcnt(1)
	v_pk_mul_f32 v[22:23], v[22:23], v[30:31]
	v_pk_mul_f32 v[24:25], v[24:25], v[32:33]
	s_waitcnt vmcnt(0)
	v_pk_mul_f32 v[26:27], v[26:27], v[34:35]
	v_pk_mul_f32 v[28:29], v[28:29], v[36:37]
	global_store_dwordx4 v[10:11], v[22:25], off nt
	global_store_dwordx4 v[10:11], v[26:29], off offset:16 nt
	global_load_dwordx4 v[22:25], v[6:7], off nt
	s_nop 0
	global_load_dwordx4 v[26:29], v[6:7], off offset:16 nt
	v_lshlrev_b32_e32 v30, 16, v42
	v_and_b32_e32 v31, 0xffff0000, v42
	v_lshlrev_b32_e32 v32, 16, v43
	v_and_b32_e32 v33, 0xffff0000, v43
	v_lshlrev_b32_e32 v34, 16, v44
	v_and_b32_e32 v35, 0xffff0000, v44
	v_lshlrev_b32_e32 v36, 16, v45
	v_and_b32_e32 v37, 0xffff0000, v45
	v_pk_mul_f32 v[30:31], v[46:47], v[30:31] op_sel_hi:[0,1]
	v_pk_mul_f32 v[32:33], v[46:47], v[32:33] op_sel_hi:[0,1]
	v_pk_mul_f32 v[34:35], v[46:47], v[34:35] op_sel_hi:[0,1]
	v_pk_mul_f32 v[36:37], v[46:47], v[36:37] op_sel_hi:[0,1]
	s_waitcnt vmcnt(1)
	v_pk_mul_f32 v[22:23], v[22:23], v[30:31]
	v_pk_mul_f32 v[24:25], v[24:25], v[32:33]
	s_waitcnt vmcnt(0)
	v_pk_mul_f32 v[26:27], v[26:27], v[34:35]
	v_pk_mul_f32 v[28:29], v[28:29], v[36:37]
	global_store_dwordx4 v[10:11], v[22:25], off offset:2048 nt
	global_store_dwordx4 v[10:11], v[26:29], off offset:2064 nt
	v_lshl_add_u64 v[10:11], v[10:11], 0, s[4:5]
	s_andn2_b64 exec, exec, s[8:9]
	s_cbranch_execz .LBB0_1110
.LBB0_1108:
	v_mov_b32_e32 v21, 0
	s_and_saveexec_b64 s[0:1], vcc
	s_cbranch_execz .LBB0_1107
	v_lshl_add_u64 v[22:23], s[86:87], 0, v[12:13]
	global_load_dword v21, v[22:23], off nt
	s_branch .LBB0_1107
